# strategy 4: static s_setprio 1 for waves 4-7 at entry, all 310 per-segment priority flips deleted (on v_rm_m1)
# speedup vs baseline: 1.0108x; 1.0108x over previous
_Z6mk_fwd4Args:
	v_readfirstlane_b32 s99, v0
	s_nop 3
	s_and_b32 s99, s99, 0x3ff
	s_lshr_b32 s99, s99, 6
	s_cmp_ge_u32 s99, 4
	s_cbranch_scc0 .Lprio_done
	s_setprio 1
.Lprio_done:
	s_load_dword s56, s[0:1], 0xe8
	s_load_dwordx2 s[100:101], s[0:1], 0xd8
	v_lshrrev_b32_e32 v1, 6, v0
	s_mov_b32 s13, s2
	v_readfirstlane_b32 s52, v1
	s_waitcnt lgkmcnt(0)
	s_and_b32 s3, s56, 7
	s_cmp_lg_u32 s3, 0
	s_cbranch_scc1 .LBB0_2
	s_ashr_i32 s4, s2, 31
	s_lshr_b32 s4, s4, 29
	s_add_i32 s4, s2, s4
	s_ashr_i32 s5, s4, 3
	s_and_b32 s4, s4, -8
	s_ashr_i32 s3, s56, 3
	s_sub_i32 s4, s2, s4
	s_mul_i32 s3, s3, s4
	s_add_i32 s13, s3, s5

.LBB0_398:
	s_lshl_b32 s86, s15, 10
	s_lshl_b64 s[2:3], s[86:87], 2
	v_readlane_b32 s6, v254, 35
	v_readlane_b32 s7, v254, 36
	s_add_u32 s2, s6, s2
	v_readlane_b32 s5, v254, 37
	s_addc_u32 s3, s7, s3
	s_add_i32 s5, s5, s18
	v_or_b32_e32 v78, s5, v154
	v_ashrrev_i32_e32 v79, 31, v78
	v_lshlrev_b32_e32 v70, 9, v74
	v_lshl_add_u64 v[74:75], v[78:79], 2, s[2:3]
	v_or_b32_e32 v168, s4, v5
	v_readlane_b32 s2, v254, 39
	v_readlane_b32 s3, v254, 40
	v_ashrrev_i32_e32 v169, 31, v168
	v_add_u32_e32 v70, 0, v70
	v_lshl_add_u64 v[166:167], v[78:79], 1, s[2:3]
	v_lshlrev_b64 v[78:79], 11, v[168:169]
	v_lshl_add_u64 v[176:177], v[166:167], 0, v[78:79]
	v_or_b32_e32 v78, 16, v168
	v_ashrrev_i32_e32 v79, 31, v78
	v_lshlrev_b64 v[78:79], 11, v[78:79]
	v_add3_u32 v70, v70, v138, v150
	v_lshl_add_u64 v[78:79], v[166:167], 0, v[78:79]
	ds_write_b64 v70, v[72:73]
	s_waitcnt lgkmcnt(0)
	s_barrier
	global_load_dwordx4 v[70:73], v[74:75], off offset:16
	s_nop 0
	global_load_dwordx4 v[74:77], v[74:75], off
	v_or_b32_e32 v174, 0x50, v168
	global_load_dwordx4 v[138:141], v[176:177], off
	global_load_dwordx4 v[122:125], v[78:79], off
	v_or_b32_e32 v78, 32, v168
	v_ashrrev_i32_e32 v79, 31, v78
	v_lshlrev_b64 v[78:79], 11, v[78:79]
	v_lshl_add_u64 v[78:79], v[166:167], 0, v[78:79]
	global_load_dwordx4 v[106:109], v[78:79], off
	v_or_b32_e32 v78, 48, v168
	v_ashrrev_i32_e32 v79, 31, v78
	v_lshlrev_b64 v[78:79], 11, v[78:79]
	v_lshl_add_u64 v[78:79], v[166:167], 0, v[78:79]
	global_load_dwordx4 v[94:97], v[78:79], off
	v_or_b32_e32 v78, 64, v168
	v_ashrrev_i32_e32 v79, 31, v78
	v_lshlrev_b64 v[78:79], 11, v[78:79]
	v_lshl_add_u64 v[78:79], v[166:167], 0, v[78:79]
	v_ashrrev_i32_e32 v175, 31, v174
	global_load_dwordx4 v[90:93], v[78:79], off
	v_lshlrev_b64 v[78:79], 11, v[174:175]
	v_or_b32_e32 v172, 0x60, v168
	v_lshl_add_u64 v[78:79], v[166:167], 0, v[78:79]
	v_ashrrev_i32_e32 v173, 31, v172
	global_load_dwordx4 v[86:89], v[78:79], off
	v_lshlrev_b64 v[78:79], 11, v[172:173]
	v_or_b32_e32 v170, 0x70, v168
	v_lshl_add_u64 v[78:79], v[166:167], 0, v[78:79]
	v_ashrrev_i32_e32 v171, 31, v170
	global_load_dwordx4 v[82:85], v[78:79], off
	v_lshlrev_b64 v[78:79], 11, v[170:171]
	v_lshl_add_u64 v[78:79], v[166:167], 0, v[78:79]
	global_load_dwordx4 v[78:81], v[78:79], off
	v_xor_b32_e32 v98, v152, v5
	v_bitop3_b32 v102, v152, v5, 4 bitop3:0x36
	v_bitop3_b32 v110, v152, v5, 8 bitop3:0x36
	v_bitop3_b32 v114, v152, v5, 12 bitop3:0x36
	v_bitop3_b32 v118, v152, v5, 16 bitop3:0x36
	v_bitop3_b32 v126, v152, v5, 20 bitop3:0x36
	v_bitop3_b32 v130, v152, v5, 24 bitop3:0x36
	v_bitop3_b32 v134, v152, v5, 28 bitop3:0x36
	v_lshl_add_u32 v183, v5, 9, 0
	v_lshlrev_b32_e32 v184, 4, v98
	v_lshlrev_b32_e32 v185, 4, v102
	v_lshlrev_b32_e32 v187, 4, v110
	v_lshlrev_b32_e32 v189, 4, v114
	v_lshlrev_b32_e32 v186, 4, v118
	v_lshlrev_b32_e32 v188, 4, v126
	v_lshlrev_b32_e32 v190, 4, v130
	v_lshlrev_b32_e32 v191, 4, v134
	v_add_u32_e32 v169, v183, v184
	v_add_u32_e32 v182, v183, v185
	v_add_u32_e32 v216, v183, v187
	v_add_u32_e32 v217, v183, v189
	v_add_u32_e32 v220, v183, v186
	v_add_u32_e32 v221, v183, v188
	v_add_u32_e32 v222, v183, v190
	v_add_u32_e32 v223, v183, v191
	ds_read_b128 v[98:101], v169
	ds_read_b128 v[102:105], v182
	ds_read_b128 v[110:113], v216
	ds_read_b128 v[114:117], v217
	ds_read_b128 v[118:121], v220
	ds_read_b128 v[126:129], v221
	ds_read_b128 v[130:133], v222
	ds_read_b128 v[134:137], v223
	s_lshl_b32 s2, s52, 10
	s_add_i32 s2, s2, 0
	v_cmp_gt_u32_e32 vcc, 16, v153
	s_add_i32 s2, s2, 0x21000
	s_waitcnt vmcnt(25) lgkmcnt(7)
	v_mfma_f32_16x16x32_bf16 v[142:145], v[34:37], v[98:101], 0
	s_waitcnt vmcnt(17)
	v_mfma_f32_16x16x32_bf16 v[98:101], v[66:69], v[98:101], 0
	s_waitcnt lgkmcnt(6)
	v_mfma_f32_16x16x32_bf16 v[142:145], v[30:33], v[102:105], v[142:145]
	s_waitcnt vmcnt(16)
	v_mfma_f32_16x16x32_bf16 v[98:101], v[62:65], v[102:105], v[98:101]
	s_waitcnt lgkmcnt(5)
	v_mfma_f32_16x16x32_bf16 v[102:105], v[26:29], v[110:113], v[142:145]
	s_waitcnt vmcnt(15)
	v_mfma_f32_16x16x32_bf16 v[98:101], v[58:61], v[110:113], v[98:101]
	s_waitcnt lgkmcnt(4)
	v_mfma_f32_16x16x32_bf16 v[102:105], v[22:25], v[114:117], v[102:105]
	s_waitcnt vmcnt(14)
	v_mfma_f32_16x16x32_bf16 v[98:101], v[54:57], v[114:117], v[98:101]
	ds_read_b128 v[110:113], v169 offset:8192
	ds_read_b128 v[114:117], v182 offset:8192
	ds_read_b128 v[142:145], v216 offset:8192
	ds_read_b128 v[146:149], v217 offset:8192
	s_waitcnt lgkmcnt(7)
	v_mfma_f32_16x16x32_bf16 v[102:105], v[18:21], v[118:121], v[102:105]
	s_waitcnt vmcnt(13)
	v_mfma_f32_16x16x32_bf16 v[98:101], v[50:53], v[118:121], v[98:101]
	s_waitcnt lgkmcnt(6)
	v_mfma_f32_16x16x32_bf16 v[102:105], v[14:17], v[126:129], v[102:105]
	s_waitcnt vmcnt(12)
	v_mfma_f32_16x16x32_bf16 v[98:101], v[46:49], v[126:129], v[98:101]
	s_waitcnt lgkmcnt(5)
	v_mfma_f32_16x16x32_bf16 v[102:105], v[10:13], v[130:133], v[102:105]
	s_waitcnt vmcnt(11)
	v_mfma_f32_16x16x32_bf16 v[98:101], v[42:45], v[130:133], v[98:101]
	s_waitcnt lgkmcnt(4)
	v_mfma_f32_16x16x32_bf16 v[178:181], v[6:9], v[134:137], v[102:105]
	s_waitcnt vmcnt(10)
	v_mfma_f32_16x16x32_bf16 v[192:195], v[38:41], v[134:137], v[98:101]
	s_nop 2
	ds_read_b128 v[98:101], v220 offset:8192
	ds_read_b128 v[102:105], v221 offset:8192
	ds_read_b128 v[118:121], v222 offset:8192
	ds_read_b128 v[126:129], v223 offset:8192
	s_waitcnt lgkmcnt(7)
	v_mfma_f32_16x16x32_bf16 v[130:133], v[34:37], v[110:113], 0
	v_mfma_f32_16x16x32_bf16 v[110:113], v[66:69], v[110:113], 0
	s_waitcnt lgkmcnt(6)
	v_mfma_f32_16x16x32_bf16 v[130:133], v[30:33], v[114:117], v[130:133]
	v_mfma_f32_16x16x32_bf16 v[110:113], v[62:65], v[114:117], v[110:113]
	s_waitcnt lgkmcnt(5)
	v_mfma_f32_16x16x32_bf16 v[114:117], v[26:29], v[142:145], v[130:133]
	v_mfma_f32_16x16x32_bf16 v[110:113], v[58:61], v[142:145], v[110:113]
	s_waitcnt lgkmcnt(4)
	v_mfma_f32_16x16x32_bf16 v[114:117], v[22:25], v[146:149], v[114:117]
	v_mfma_f32_16x16x32_bf16 v[110:113], v[54:57], v[146:149], v[110:113]
	ds_read_b128 v[130:133], v169 offset:16384
	ds_read_b128 v[134:137], v182 offset:16384
	ds_read_b128 v[142:145], v216 offset:16384
	ds_read_b128 v[146:149], v217 offset:16384
	s_waitcnt lgkmcnt(7)
	v_mfma_f32_16x16x32_bf16 v[114:117], v[18:21], v[98:101], v[114:117]
	v_mfma_f32_16x16x32_bf16 v[98:101], v[50:53], v[98:101], v[110:113]
	s_waitcnt lgkmcnt(6)
	v_mfma_f32_16x16x32_bf16 v[110:113], v[14:17], v[102:105], v[114:117]
	v_mfma_f32_16x16x32_bf16 v[98:101], v[46:49], v[102:105], v[98:101]
	s_waitcnt lgkmcnt(5)
	v_mfma_f32_16x16x32_bf16 v[102:105], v[10:13], v[118:121], v[110:113]
	v_mfma_f32_16x16x32_bf16 v[98:101], v[42:45], v[118:121], v[98:101]
	s_waitcnt lgkmcnt(4)
	v_mfma_f32_16x16x32_bf16 v[162:165], v[6:9], v[126:129], v[102:105]
	v_mfma_f32_16x16x32_bf16 v[158:161], v[38:41], v[126:129], v[98:101]
	s_nop 3
	ds_read_b128 v[98:101], v220 offset:16384
	ds_read_b128 v[102:105], v221 offset:16384
	ds_read_b128 v[110:113], v222 offset:16384
	ds_read_b128 v[114:117], v223 offset:16384
	s_waitcnt lgkmcnt(7)
	v_mfma_f32_16x16x32_bf16 v[118:121], v[34:37], v[130:133], 0
	v_mfma_f32_16x16x32_bf16 v[126:129], v[66:69], v[130:133], 0
	s_waitcnt lgkmcnt(6)
	v_mfma_f32_16x16x32_bf16 v[118:121], v[30:33], v[134:137], v[118:121]
	v_mfma_f32_16x16x32_bf16 v[126:129], v[62:65], v[134:137], v[126:129]
	s_waitcnt lgkmcnt(5)
	v_mfma_f32_16x16x32_bf16 v[118:121], v[26:29], v[142:145], v[118:121]
	v_mfma_f32_16x16x32_bf16 v[126:129], v[58:61], v[142:145], v[126:129]
	s_waitcnt lgkmcnt(4)
	v_mfma_f32_16x16x32_bf16 v[118:121], v[22:25], v[146:149], v[118:121]
	v_mfma_f32_16x16x32_bf16 v[126:129], v[54:57], v[146:149], v[126:129]
	ds_read_b128 v[130:133], v169 offset:24576
	ds_read_b128 v[134:137], v182 offset:24576
	ds_read_b128 v[142:145], v216 offset:24576
	ds_read_b128 v[146:149], v217 offset:24576
	s_waitcnt lgkmcnt(7)
	v_mfma_f32_16x16x32_bf16 v[118:121], v[18:21], v[98:101], v[118:121]
	v_mfma_f32_16x16x32_bf16 v[98:101], v[50:53], v[98:101], v[126:129]
	s_waitcnt lgkmcnt(6)
	v_mfma_f32_16x16x32_bf16 v[118:121], v[14:17], v[102:105], v[118:121]
	v_mfma_f32_16x16x32_bf16 v[98:101], v[46:49], v[102:105], v[98:101]
	s_waitcnt lgkmcnt(5)
	v_mfma_f32_16x16x32_bf16 v[102:105], v[10:13], v[110:113], v[118:121]
	v_mfma_f32_16x16x32_bf16 v[98:101], v[42:45], v[110:113], v[98:101]
	s_waitcnt lgkmcnt(4)
	v_mfma_f32_16x16x32_bf16 v[154:157], v[6:9], v[114:117], v[102:105]
	v_mfma_f32_16x16x32_bf16 v[150:153], v[38:41], v[114:117], v[98:101]
	s_nop 3
	ds_read_b128 v[98:101], v220 offset:24576
	ds_read_b128 v[102:105], v221 offset:24576
	ds_read_b128 v[110:113], v222 offset:24576
	ds_read_b128 v[114:117], v223 offset:24576
	s_waitcnt lgkmcnt(7)
	v_mfma_f32_16x16x32_bf16 v[118:121], v[34:37], v[130:133], 0
	v_mfma_f32_16x16x32_bf16 v[126:129], v[66:69], v[130:133], 0
	s_waitcnt lgkmcnt(6)
	v_mfma_f32_16x16x32_bf16 v[118:121], v[30:33], v[134:137], v[118:121]
	v_mfma_f32_16x16x32_bf16 v[126:129], v[62:65], v[134:137], v[126:129]
	s_waitcnt lgkmcnt(5)
	v_mfma_f32_16x16x32_bf16 v[118:121], v[26:29], v[142:145], v[118:121]
	v_mfma_f32_16x16x32_bf16 v[126:129], v[58:61], v[142:145], v[126:129]
	s_waitcnt lgkmcnt(4)
	v_mfma_f32_16x16x32_bf16 v[118:121], v[22:25], v[146:149], v[118:121]
	v_mfma_f32_16x16x32_bf16 v[126:129], v[54:57], v[146:149], v[126:129]
	ds_read_b128 v[130:133], v169 offset:32768
	ds_read_b128 v[134:137], v182 offset:32768
	ds_read_b128 v[196:199], v216 offset:32768
	ds_read_b128 v[200:203], v217 offset:32768
	s_waitcnt lgkmcnt(7)
	v_mfma_f32_16x16x32_bf16 v[118:121], v[18:21], v[98:101], v[118:121]
	v_mfma_f32_16x16x32_bf16 v[98:101], v[50:53], v[98:101], v[126:129]
	s_waitcnt lgkmcnt(6)
	v_mfma_f32_16x16x32_bf16 v[118:121], v[14:17], v[102:105], v[118:121]
	v_mfma_f32_16x16x32_bf16 v[98:101], v[46:49], v[102:105], v[98:101]
	s_waitcnt lgkmcnt(5)
	v_mfma_f32_16x16x32_bf16 v[102:105], v[10:13], v[110:113], v[118:121]
	v_mfma_f32_16x16x32_bf16 v[98:101], v[42:45], v[110:113], v[98:101]
	s_waitcnt lgkmcnt(4)
	v_mfma_f32_16x16x32_bf16 v[146:149], v[6:9], v[114:117], v[102:105]
	v_mfma_f32_16x16x32_bf16 v[142:145], v[38:41], v[114:117], v[98:101]
	s_nop 3
	ds_read_b128 v[98:101], v220 offset:32768
	ds_read_b128 v[102:105], v221 offset:32768
	ds_read_b128 v[110:113], v222 offset:32768
	ds_read_b128 v[114:117], v223 offset:32768
	s_waitcnt lgkmcnt(7)
	v_mfma_f32_16x16x32_bf16 v[118:121], v[34:37], v[130:133], 0
	v_mfma_f32_16x16x32_bf16 v[126:129], v[66:69], v[130:133], 0
	s_waitcnt lgkmcnt(6)
	v_mfma_f32_16x16x32_bf16 v[118:121], v[30:33], v[134:137], v[118:121]
	v_mfma_f32_16x16x32_bf16 v[126:129], v[62:65], v[134:137], v[126:129]
	s_waitcnt lgkmcnt(5)
	v_mfma_f32_16x16x32_bf16 v[118:121], v[26:29], v[196:199], v[118:121]
	v_mfma_f32_16x16x32_bf16 v[126:129], v[58:61], v[196:199], v[126:129]
	s_waitcnt lgkmcnt(4)
	v_mfma_f32_16x16x32_bf16 v[118:121], v[22:25], v[200:203], v[118:121]
	v_mfma_f32_16x16x32_bf16 v[126:129], v[54:57], v[200:203], v[126:129]
	ds_read_b128 v[196:199], v169 offset:40960
	ds_read_b128 v[200:203], v182 offset:40960
	ds_read_b128 v[204:207], v216 offset:40960
	ds_read_b128 v[208:211], v217 offset:40960
	s_waitcnt lgkmcnt(7)
	v_mfma_f32_16x16x32_bf16 v[118:121], v[18:21], v[98:101], v[118:121]
	v_mfma_f32_16x16x32_bf16 v[98:101], v[50:53], v[98:101], v[126:129]
	s_waitcnt lgkmcnt(6)
	v_mfma_f32_16x16x32_bf16 v[118:121], v[14:17], v[102:105], v[118:121]
	v_mfma_f32_16x16x32_bf16 v[98:101], v[46:49], v[102:105], v[98:101]
	s_waitcnt lgkmcnt(5)
	v_mfma_f32_16x16x32_bf16 v[102:105], v[10:13], v[110:113], v[118:121]
	v_mfma_f32_16x16x32_bf16 v[98:101], v[42:45], v[110:113], v[98:101]
	s_waitcnt lgkmcnt(4)
	v_mfma_f32_16x16x32_bf16 v[134:137], v[6:9], v[114:117], v[102:105]
	v_mfma_f32_16x16x32_bf16 v[130:133], v[38:41], v[114:117], v[98:101]
	s_nop 3
	ds_read_b128 v[98:101], v220 offset:40960
	ds_read_b128 v[102:105], v221 offset:40960
	ds_read_b128 v[110:113], v222 offset:40960
	ds_read_b128 v[114:117], v223 offset:40960
	s_waitcnt lgkmcnt(7)
	v_mfma_f32_16x16x32_bf16 v[118:121], v[34:37], v[196:199], 0
	v_mfma_f32_16x16x32_bf16 v[126:129], v[66:69], v[196:199], 0
	s_waitcnt lgkmcnt(6)
	v_mfma_f32_16x16x32_bf16 v[118:121], v[30:33], v[200:203], v[118:121]
	v_mfma_f32_16x16x32_bf16 v[126:129], v[62:65], v[200:203], v[126:129]
	s_waitcnt lgkmcnt(5)
	v_mfma_f32_16x16x32_bf16 v[118:121], v[26:29], v[204:207], v[118:121]
	v_mfma_f32_16x16x32_bf16 v[126:129], v[58:61], v[204:207], v[126:129]
	s_waitcnt lgkmcnt(4)
	v_mfma_f32_16x16x32_bf16 v[118:121], v[22:25], v[208:211], v[118:121]
	v_mfma_f32_16x16x32_bf16 v[126:129], v[54:57], v[208:211], v[126:129]
	ds_read_b128 v[196:199], v169 offset:49152
	ds_read_b128 v[200:203], v182 offset:49152
	ds_read_b128 v[204:207], v216 offset:49152
	ds_read_b128 v[208:211], v217 offset:49152
	s_waitcnt lgkmcnt(7)
	v_mfma_f32_16x16x32_bf16 v[118:121], v[18:21], v[98:101], v[118:121]
	v_mfma_f32_16x16x32_bf16 v[98:101], v[50:53], v[98:101], v[126:129]
	s_waitcnt lgkmcnt(6)
	v_mfma_f32_16x16x32_bf16 v[118:121], v[14:17], v[102:105], v[118:121]
	v_mfma_f32_16x16x32_bf16 v[98:101], v[46:49], v[102:105], v[98:101]
	s_waitcnt lgkmcnt(5)
	v_mfma_f32_16x16x32_bf16 v[102:105], v[10:13], v[110:113], v[118:121]
	v_mfma_f32_16x16x32_bf16 v[98:101], v[42:45], v[110:113], v[98:101]
	s_waitcnt lgkmcnt(4)
	v_mfma_f32_16x16x32_bf16 v[126:129], v[6:9], v[114:117], v[102:105]
	v_mfma_f32_16x16x32_bf16 v[118:121], v[38:41], v[114:117], v[98:101]
	s_nop 3
	ds_read_b128 v[98:101], v220 offset:49152
	ds_read_b128 v[102:105], v221 offset:49152
	ds_read_b128 v[110:113], v222 offset:49152
	ds_read_b128 v[212:215], v223 offset:49152
	s_waitcnt lgkmcnt(7)
	v_mfma_f32_16x16x32_bf16 v[114:117], v[34:37], v[196:199], 0
	v_mfma_f32_16x16x32_bf16 v[196:199], v[66:69], v[196:199], 0
	s_waitcnt lgkmcnt(6)
	v_mfma_f32_16x16x32_bf16 v[114:117], v[30:33], v[200:203], v[114:117]
	v_mfma_f32_16x16x32_bf16 v[196:199], v[62:65], v[200:203], v[196:199]
	s_waitcnt lgkmcnt(5)
	v_mfma_f32_16x16x32_bf16 v[114:117], v[26:29], v[204:207], v[114:117]
	v_mfma_f32_16x16x32_bf16 v[196:199], v[58:61], v[204:207], v[196:199]
	s_waitcnt lgkmcnt(4)
	v_mfma_f32_16x16x32_bf16 v[114:117], v[22:25], v[208:211], v[114:117]
	v_mfma_f32_16x16x32_bf16 v[196:199], v[54:57], v[208:211], v[196:199]
	ds_read_b128 v[200:203], v169 offset:57344
	ds_read_b128 v[204:207], v182 offset:57344
	ds_read_b128 v[208:211], v216 offset:57344
	ds_read_b128 v[216:219], v217 offset:57344
	s_waitcnt lgkmcnt(7)
	v_mfma_f32_16x16x32_bf16 v[114:117], v[18:21], v[98:101], v[114:117]
	v_mfma_f32_16x16x32_bf16 v[98:101], v[50:53], v[98:101], v[196:199]
	s_waitcnt lgkmcnt(6)
	v_mfma_f32_16x16x32_bf16 v[114:117], v[14:17], v[102:105], v[114:117]
	v_mfma_f32_16x16x32_bf16 v[98:101], v[46:49], v[102:105], v[98:101]
	s_waitcnt lgkmcnt(5)
	v_mfma_f32_16x16x32_bf16 v[102:105], v[10:13], v[110:113], v[114:117]
	v_mfma_f32_16x16x32_bf16 v[98:101], v[42:45], v[110:113], v[98:101]
	s_waitcnt lgkmcnt(4)
	v_mfma_f32_16x16x32_bf16 v[114:117], v[6:9], v[212:215], v[102:105]
	v_mfma_f32_16x16x32_bf16 v[110:113], v[38:41], v[212:215], v[98:101]
	s_nop 3
	ds_read_b128 v[98:101], v220 offset:57344
	ds_read_b128 v[102:105], v221 offset:57344
	ds_read_b128 v[196:199], v222 offset:57344
	ds_read_b128 v[212:215], v223 offset:57344
	s_waitcnt lgkmcnt(7)
	v_mfma_f32_16x16x32_bf16 v[220:223], v[34:37], v[200:203], 0
	v_mfma_f32_16x16x32_bf16 v[200:203], v[66:69], v[200:203], 0
	s_waitcnt lgkmcnt(6)
	v_mfma_f32_16x16x32_bf16 v[220:223], v[30:33], v[204:207], v[220:223]
	v_mfma_f32_16x16x32_bf16 v[200:203], v[62:65], v[204:207], v[200:203]
	s_waitcnt lgkmcnt(5)
	v_mfma_f32_16x16x32_bf16 v[204:207], v[26:29], v[208:211], v[220:223]
	v_mfma_f32_16x16x32_bf16 v[200:203], v[58:61], v[208:211], v[200:203]
	s_waitcnt lgkmcnt(4)
	v_mfma_f32_16x16x32_bf16 v[204:207], v[22:25], v[216:219], v[204:207]
	v_mfma_f32_16x16x32_bf16 v[200:203], v[54:57], v[216:219], v[200:203]
	s_waitcnt lgkmcnt(3)
	v_mfma_f32_16x16x32_bf16 v[204:207], v[18:21], v[98:101], v[204:207]
	v_mfma_f32_16x16x32_bf16 v[98:101], v[50:53], v[98:101], v[200:203]
	s_waitcnt lgkmcnt(2)
	v_mfma_f32_16x16x32_bf16 v[200:203], v[14:17], v[102:105], v[204:207]
	v_mfma_f32_16x16x32_bf16 v[98:101], v[46:49], v[102:105], v[98:101]
	s_waitcnt lgkmcnt(1)
	v_mfma_f32_16x16x32_bf16 v[102:105], v[10:13], v[196:199], v[200:203]
	v_mfma_f32_16x16x32_bf16 v[98:101], v[42:45], v[196:199], v[98:101]
	s_waitcnt lgkmcnt(0)
	v_mfma_f32_16x16x32_bf16 v[102:105], v[6:9], v[212:215], v[102:105]
	v_mfma_f32_16x16x32_bf16 v[98:101], v[38:41], v[212:215], v[98:101]
	s_waitcnt vmcnt(7)
	v_lshlrev_b32_e32 v196, 16, v138
	v_and_b32_e32 v197, 0xffff0000, v138
	v_lshlrev_b32_e32 v138, 16, v139
	v_and_b32_e32 v139, 0xffff0000, v139
	v_pk_fma_f32 v[180:181], v[76:77], v[180:181], v[138:139]
	v_pk_fma_f32 v[138:139], v[74:75], v[178:179], v[196:197]
	v_lshlrev_b32_e32 v178, 16, v140
	v_and_b32_e32 v179, 0xffff0000, v140
	v_lshlrev_b32_e32 v140, 16, v141
	v_and_b32_e32 v141, 0xffff0000, v141
	v_pk_fma_f32 v[194:195], v[72:73], v[194:195], v[140:141]
	v_pk_fma_f32 v[140:141], v[70:71], v[192:193], v[178:179]
	v_mul_f32_e32 v169, v139, v139
	v_mul_f32_e32 v178, v181, v181
	v_fmac_f32_e32 v169, v138, v138
	v_fmac_f32_e32 v178, v180, v180
	v_add_f32_e32 v169, v169, v178
	v_mul_f32_e32 v178, v141, v141
	v_mul_f32_e32 v179, v195, v195
	v_fmac_f32_e32 v178, v140, v140
	v_fmac_f32_e32 v179, v194, v194
	v_add_f32_e32 v178, v178, v179
	v_add_f32_e32 v169, v169, v178
	v_cvt_pk_bf16_f32 v138, v138, v139
	v_cvt_pk_bf16_f32 v139, v180, v181
	v_cvt_pk_bf16_f32 v140, v140, v141
	v_cvt_pk_bf16_f32 v141, v194, v195
	global_store_dwordx4 v[176:177], v[138:141], off sc1
	v_lshl_add_u32 v182, v5, 2, s2
	s_nop 0
	v_mov_b32_e32 v138, v169
	s_nop 1
	v_permlane16_swap_b32_e32 v169, v138
	v_add_f32_e32 v138, v169, v138
	v_mov_b32_e32 v139, v138
	s_nop 1
	v_permlane32_swap_b32_e32 v138, v139
	s_and_saveexec_b64 s[2:3], vcc
	v_add_f32_e32 v138, v138, v139
	ds_write_b32 v182, v138
	s_or_b64 exec, exec, s[2:3]
	s_waitcnt vmcnt(7)
	v_lshlrev_b32_e32 v138, 16, v122
	v_and_b32_e32 v139, 0xffff0000, v122
	v_lshlrev_b32_e32 v122, 16, v123
	v_and_b32_e32 v123, 0xffff0000, v123
	v_pk_fma_f32 v[140:141], v[76:77], v[164:165], v[122:123]
	v_pk_fma_f32 v[122:123], v[74:75], v[162:163], v[138:139]
	v_lshlrev_b32_e32 v138, 16, v124
	v_and_b32_e32 v139, 0xffff0000, v124
	v_lshlrev_b32_e32 v124, 16, v125
	v_and_b32_e32 v125, 0xffff0000, v125
	v_pk_fma_f32 v[160:161], v[72:73], v[160:161], v[124:125]
	v_pk_fma_f32 v[124:125], v[70:71], v[158:159], v[138:139]
	v_mul_f32_e32 v138, v123, v123
	v_mul_f32_e32 v139, v141, v141
	v_fmac_f32_e32 v138, v122, v122
	v_fmac_f32_e32 v139, v140, v140
	v_add_f32_e32 v138, v138, v139
	v_mul_f32_e32 v139, v125, v125
	v_mul_f32_e32 v158, v161, v161
	v_fmac_f32_e32 v139, v124, v124
	v_fmac_f32_e32 v158, v160, v160
	v_add_f32_e32 v139, v139, v158
	v_add_f32_e32 v158, v138, v139
	v_or3_b32 v138, v5, s4, 16
	v_ashrrev_i32_e32 v139, 31, v138
	v_lshlrev_b64 v[138:139], 11, v[138:139]
	v_lshl_add_u64 v[138:139], v[166:167], 0, v[138:139]
	v_cvt_pk_bf16_f32 v122, v122, v123
	v_cvt_pk_bf16_f32 v123, v140, v141
	v_cvt_pk_bf16_f32 v124, v124, v125
	v_cvt_pk_bf16_f32 v125, v160, v161
	global_store_dwordx4 v[138:139], v[122:125], off sc1
	s_nop 1
	v_mov_b32_e32 v122, v158
	s_nop 1
	v_permlane16_swap_b32_e32 v158, v122
	v_add_f32_e32 v122, v158, v122
	v_mov_b32_e32 v123, v122
	s_nop 1
	v_permlane32_swap_b32_e32 v122, v123
	s_and_saveexec_b64 s[2:3], vcc
	v_readlane_b32 s86, v254, 13
	v_add_f32_e32 v122, v122, v123
	ds_write_b32 v182, v122 offset:64
	s_or_b64 exec, exec, s[2:3]
	s_waitcnt vmcnt(7)
	v_lshlrev_b32_e32 v122, 16, v106
	v_and_b32_e32 v123, 0xffff0000, v106
	v_lshlrev_b32_e32 v106, 16, v107
	v_and_b32_e32 v107, 0xffff0000, v107
	v_pk_fma_f32 v[124:125], v[76:77], v[156:157], v[106:107]
	v_pk_fma_f32 v[106:107], v[74:75], v[154:155], v[122:123]
	v_lshlrev_b32_e32 v122, 16, v108
	v_and_b32_e32 v123, 0xffff0000, v108
	v_lshlrev_b32_e32 v108, 16, v109
	v_and_b32_e32 v109, 0xffff0000, v109
	v_pk_fma_f32 v[138:139], v[72:73], v[152:153], v[108:109]
	v_pk_fma_f32 v[108:109], v[70:71], v[150:151], v[122:123]
	v_mul_f32_e32 v122, v107, v107
	v_mul_f32_e32 v123, v125, v125
	v_fmac_f32_e32 v122, v106, v106
	v_fmac_f32_e32 v123, v124, v124
	v_add_f32_e32 v122, v122, v123
	v_mul_f32_e32 v123, v109, v109
	v_mul_f32_e32 v140, v139, v139
	v_fmac_f32_e32 v123, v108, v108
	v_fmac_f32_e32 v140, v138, v138
	v_add_f32_e32 v123, v123, v140
	v_add_f32_e32 v140, v122, v123
	v_or3_b32 v122, v5, s4, 32
	v_ashrrev_i32_e32 v123, 31, v122
	v_lshlrev_b64 v[122:123], 11, v[122:123]
	v_lshl_add_u64 v[122:123], v[166:167], 0, v[122:123]
	v_cvt_pk_bf16_f32 v106, v106, v107
	v_cvt_pk_bf16_f32 v107, v124, v125
	v_cvt_pk_bf16_f32 v108, v108, v109
	v_cvt_pk_bf16_f32 v109, v138, v139
	global_store_dwordx4 v[122:123], v[106:109], off sc1
	s_nop 1
	v_mov_b32_e32 v106, v140
	s_nop 1
	v_permlane16_swap_b32_e32 v140, v106
	v_add_f32_e32 v106, v140, v106
	v_mov_b32_e32 v107, v106
	s_nop 1
	v_permlane32_swap_b32_e32 v106, v107
	s_and_saveexec_b64 s[2:3], vcc
	v_add_f32_e32 v106, v106, v107
	ds_write_b32 v182, v106 offset:128
	s_or_b64 exec, exec, s[2:3]
	s_waitcnt vmcnt(7)
	v_lshlrev_b32_e32 v106, 16, v94
	v_and_b32_e32 v107, 0xffff0000, v94
	v_lshlrev_b32_e32 v94, 16, v95
	v_and_b32_e32 v95, 0xffff0000, v95
	v_pk_fma_f32 v[108:109], v[76:77], v[148:149], v[94:95]
	v_pk_fma_f32 v[94:95], v[74:75], v[146:147], v[106:107]
	v_lshlrev_b32_e32 v106, 16, v96
	v_and_b32_e32 v107, 0xffff0000, v96
	v_lshlrev_b32_e32 v96, 16, v97
	v_and_b32_e32 v97, 0xffff0000, v97
	v_pk_fma_f32 v[122:123], v[72:73], v[144:145], v[96:97]
	v_pk_fma_f32 v[96:97], v[70:71], v[142:143], v[106:107]
	v_mul_f32_e32 v106, v95, v95
	v_mul_f32_e32 v107, v109, v109
	v_fmac_f32_e32 v106, v94, v94
	v_fmac_f32_e32 v107, v108, v108
	v_add_f32_e32 v106, v106, v107
	v_mul_f32_e32 v107, v97, v97
	v_mul_f32_e32 v124, v123, v123
	v_fmac_f32_e32 v107, v96, v96
	v_fmac_f32_e32 v124, v122, v122
	v_add_f32_e32 v107, v107, v124
	v_add_f32_e32 v124, v106, v107
	v_or3_b32 v106, v5, s4, 48
	v_ashrrev_i32_e32 v107, 31, v106
	v_lshlrev_b64 v[106:107], 11, v[106:107]
	v_lshl_add_u64 v[106:107], v[166:167], 0, v[106:107]
	v_cvt_pk_bf16_f32 v94, v94, v95
	v_cvt_pk_bf16_f32 v95, v108, v109
	v_cvt_pk_bf16_f32 v96, v96, v97
	v_cvt_pk_bf16_f32 v97, v122, v123
	global_store_dwordx4 v[106:107], v[94:97], off sc1
	s_nop 1
	v_mov_b32_e32 v94, v124
	s_nop 1
	v_permlane16_swap_b32_e32 v124, v94
	v_add_f32_e32 v94, v124, v94
	v_mov_b32_e32 v95, v94
	s_nop 1
	v_permlane32_swap_b32_e32 v94, v95
	s_and_saveexec_b64 s[2:3], vcc
	v_add_f32_e32 v94, v94, v95
	ds_write_b32 v182, v94 offset:192
	s_or_b64 exec, exec, s[2:3]
	s_waitcnt vmcnt(7)
	v_lshlrev_b32_e32 v94, 16, v90
	v_and_b32_e32 v95, 0xffff0000, v90
	v_lshlrev_b32_e32 v90, 16, v91
	v_and_b32_e32 v91, 0xffff0000, v91
	v_pk_fma_f32 v[96:97], v[76:77], v[136:137], v[90:91]
	v_pk_fma_f32 v[90:91], v[74:75], v[134:135], v[94:95]
	v_lshlrev_b32_e32 v94, 16, v92
	v_and_b32_e32 v95, 0xffff0000, v92
	v_lshlrev_b32_e32 v92, 16, v93
	v_and_b32_e32 v93, 0xffff0000, v93
	v_pk_fma_f32 v[106:107], v[72:73], v[132:133], v[92:93]
	v_pk_fma_f32 v[92:93], v[70:71], v[130:131], v[94:95]
	v_mul_f32_e32 v94, v91, v91
	v_mul_f32_e32 v95, v97, v97
	v_fmac_f32_e32 v94, v90, v90
	v_fmac_f32_e32 v95, v96, v96
	v_add_f32_e32 v94, v94, v95
	v_mul_f32_e32 v95, v93, v93
	v_mul_f32_e32 v108, v107, v107
	v_fmac_f32_e32 v95, v92, v92
	v_fmac_f32_e32 v108, v106, v106
	v_add_f32_e32 v95, v95, v108
	v_add_f32_e32 v108, v94, v95
	v_or3_b32 v94, v5, s4, 64
	v_ashrrev_i32_e32 v95, 31, v94
	v_lshlrev_b64 v[94:95], 11, v[94:95]
	v_lshl_add_u64 v[94:95], v[166:167], 0, v[94:95]
	v_cvt_pk_bf16_f32 v90, v90, v91
	v_cvt_pk_bf16_f32 v91, v96, v97
	v_cvt_pk_bf16_f32 v92, v92, v93
	v_cvt_pk_bf16_f32 v93, v106, v107
	global_store_dwordx4 v[94:95], v[90:93], off sc1
	s_nop 1
	v_mov_b32_e32 v90, v108
	s_nop 1
	v_permlane16_swap_b32_e32 v108, v90
	v_add_f32_e32 v90, v108, v90
	v_mov_b32_e32 v91, v90
	s_nop 1
	v_permlane32_swap_b32_e32 v90, v91
	s_and_saveexec_b64 s[2:3], vcc
	v_add_f32_e32 v90, v90, v91
	ds_write_b32 v182, v90 offset:256
	s_or_b64 exec, exec, s[2:3]
	s_waitcnt vmcnt(7)
	v_lshlrev_b32_e32 v90, 16, v86
	v_and_b32_e32 v91, 0xffff0000, v86
	v_lshlrev_b32_e32 v86, 16, v87
	v_and_b32_e32 v87, 0xffff0000, v87
	v_pk_fma_f32 v[92:93], v[76:77], v[128:129], v[86:87]
	v_pk_fma_f32 v[86:87], v[74:75], v[126:127], v[90:91]
	v_lshlrev_b32_e32 v90, 16, v88
	v_and_b32_e32 v91, 0xffff0000, v88
	v_lshlrev_b32_e32 v88, 16, v89
	v_and_b32_e32 v89, 0xffff0000, v89
	v_pk_fma_f32 v[94:95], v[72:73], v[120:121], v[88:89]
	v_pk_fma_f32 v[88:89], v[70:71], v[118:119], v[90:91]
	v_mul_f32_e32 v90, v87, v87
	v_mul_f32_e32 v91, v93, v93
	v_fmac_f32_e32 v90, v86, v86
	v_fmac_f32_e32 v91, v92, v92
	v_add_f32_e32 v90, v90, v91
	v_mul_f32_e32 v91, v89, v89
	v_mul_f32_e32 v96, v95, v95
	v_fmac_f32_e32 v91, v88, v88
	v_fmac_f32_e32 v96, v94, v94
	v_add_f32_e32 v91, v91, v96
	v_add_f32_e32 v96, v90, v91
	v_lshlrev_b64 v[90:91], 11, v[174:175]
	v_lshl_add_u64 v[90:91], v[166:167], 0, v[90:91]
	v_cvt_pk_bf16_f32 v86, v86, v87
	v_cvt_pk_bf16_f32 v87, v92, v93
	v_cvt_pk_bf16_f32 v88, v88, v89
	v_cvt_pk_bf16_f32 v89, v94, v95
	global_store_dwordx4 v[90:91], v[86:89], off sc1
	s_nop 1
	v_mov_b32_e32 v86, v96
	s_nop 1
	v_permlane16_swap_b32_e32 v96, v86
	v_add_f32_e32 v86, v96, v86
	v_mov_b32_e32 v87, v86
	s_nop 1
	v_permlane32_swap_b32_e32 v86, v87
	s_and_saveexec_b64 s[2:3], vcc
	v_add_f32_e32 v86, v86, v87
	ds_write_b32 v182, v86 offset:320
	s_or_b64 exec, exec, s[2:3]
	s_waitcnt vmcnt(7)
	v_lshlrev_b32_e32 v86, 16, v82
	v_and_b32_e32 v87, 0xffff0000, v82
	v_lshlrev_b32_e32 v82, 16, v83
	v_and_b32_e32 v83, 0xffff0000, v83
	v_pk_fma_f32 v[88:89], v[76:77], v[116:117], v[82:83]
	v_pk_fma_f32 v[82:83], v[74:75], v[114:115], v[86:87]
	v_lshlrev_b32_e32 v86, 16, v84
	v_and_b32_e32 v87, 0xffff0000, v84
	v_lshlrev_b32_e32 v84, 16, v85
	v_and_b32_e32 v85, 0xffff0000, v85
	v_pk_fma_f32 v[90:91], v[72:73], v[112:113], v[84:85]
	v_pk_fma_f32 v[84:85], v[70:71], v[110:111], v[86:87]
	v_mul_f32_e32 v86, v83, v83
	v_mul_f32_e32 v87, v89, v89
	v_fmac_f32_e32 v86, v82, v82
	v_fmac_f32_e32 v87, v88, v88
	v_add_f32_e32 v86, v86, v87
	v_mul_f32_e32 v87, v85, v85
	v_mul_f32_e32 v92, v91, v91
	v_fmac_f32_e32 v87, v84, v84
	v_fmac_f32_e32 v92, v90, v90
	v_add_f32_e32 v87, v87, v92
	v_add_f32_e32 v92, v86, v87
	v_lshlrev_b64 v[86:87], 11, v[172:173]
	v_lshl_add_u64 v[86:87], v[166:167], 0, v[86:87]
	v_cvt_pk_bf16_f32 v82, v82, v83
	v_cvt_pk_bf16_f32 v83, v88, v89
	v_cvt_pk_bf16_f32 v84, v84, v85
	v_cvt_pk_bf16_f32 v85, v90, v91
	global_store_dwordx4 v[86:87], v[82:85], off sc1
	s_nop 1
	v_mov_b32_e32 v82, v92
	s_nop 1
	v_permlane16_swap_b32_e32 v92, v82
	v_add_f32_e32 v82, v92, v82
	v_mov_b32_e32 v83, v82
	s_nop 1
	v_permlane32_swap_b32_e32 v82, v83
	s_and_saveexec_b64 s[2:3], vcc
	v_add_f32_e32 v82, v82, v83
	ds_write_b32 v182, v82 offset:384
	s_or_b64 exec, exec, s[2:3]
	s_waitcnt vmcnt(7)
	v_lshlrev_b32_e32 v82, 16, v78
	v_and_b32_e32 v83, 0xffff0000, v78
	v_lshlrev_b32_e32 v78, 16, v79
	v_and_b32_e32 v79, 0xffff0000, v79
	v_pk_fma_f32 v[84:85], v[76:77], v[104:105], v[78:79]
	v_pk_fma_f32 v[78:79], v[74:75], v[102:103], v[82:83]
	v_lshlrev_b32_e32 v82, 16, v80
	v_and_b32_e32 v83, 0xffff0000, v80
	v_lshlrev_b32_e32 v80, 16, v81
	v_and_b32_e32 v81, 0xffff0000, v81
	v_pk_fma_f32 v[86:87], v[72:73], v[100:101], v[80:81]
	v_pk_fma_f32 v[80:81], v[70:71], v[98:99], v[82:83]
	v_mul_f32_e32 v82, v79, v79
	v_mul_f32_e32 v83, v85, v85
	v_fmac_f32_e32 v82, v78, v78
	v_fmac_f32_e32 v83, v84, v84
	v_add_f32_e32 v82, v82, v83
	v_mul_f32_e32 v83, v81, v81
	v_mul_f32_e32 v88, v87, v87
	v_fmac_f32_e32 v83, v80, v80
	v_fmac_f32_e32 v88, v86, v86
	v_add_f32_e32 v83, v83, v88
	v_add_f32_e32 v88, v82, v83
	v_lshlrev_b64 v[82:83], 11, v[170:171]
	v_lshl_add_u64 v[82:83], v[166:167], 0, v[82:83]
	v_cvt_pk_bf16_f32 v78, v78, v79
	v_cvt_pk_bf16_f32 v79, v84, v85
	v_cvt_pk_bf16_f32 v80, v80, v81
	v_cvt_pk_bf16_f32 v81, v86, v87
	global_store_dwordx4 v[82:83], v[78:81], off sc1
	s_nop 1
	v_mov_b32_e32 v78, v88
	s_nop 1
	v_permlane16_swap_b32_e32 v88, v78
	v_add_f32_e32 v78, v88, v78
	v_mov_b32_e32 v79, v78
	s_nop 1
	v_permlane32_swap_b32_e32 v78, v79
	s_and_saveexec_b64 s[2:3], vcc
	v_add_f32_e32 v78, v78, v79
	ds_write_b32 v182, v78 offset:448
	s_or_b64 exec, exec, s[2:3]
	v_or_b32_e32 v78, 0x80, v168
	v_ashrrev_i32_e32 v79, 31, v78
	v_or_b32_e32 v80, 0x90, v168
	v_lshlrev_b64 v[78:79], 11, v[78:79]
	v_ashrrev_i32_e32 v81, 31, v80
	v_or_b32_e32 v178, 0xa0, v168
	v_or_b32_e32 v176, 0xb0, v168
	v_lshl_add_u64 v[78:79], v[166:167], 0, v[78:79]
	v_lshlrev_b64 v[80:81], 11, v[80:81]
	v_ashrrev_i32_e32 v179, 31, v178
	v_ashrrev_i32_e32 v177, 31, v176
	v_lshl_add_u64 v[180:181], v[166:167], 0, v[80:81]
	global_load_dwordx4 v[134:137], v[78:79], off
	global_load_dwordx4 v[110:113], v[180:181], off
	v_lshlrev_b64 v[78:79], 11, v[178:179]
	v_lshlrev_b64 v[80:81], 11, v[176:177]
	v_or_b32_e32 v174, 0xc0, v168
	v_or_b32_e32 v172, 0xd0, v168
	v_lshl_add_u64 v[78:79], v[166:167], 0, v[78:79]
	v_lshl_add_u64 v[80:81], v[166:167], 0, v[80:81]
	v_ashrrev_i32_e32 v175, 31, v174
	v_ashrrev_i32_e32 v173, 31, v172
	global_load_dwordx4 v[98:101], v[78:79], off
	global_load_dwordx4 v[94:97], v[80:81], off
	v_lshlrev_b64 v[78:79], 11, v[174:175]
	v_lshlrev_b64 v[80:81], 11, v[172:173]
	v_or_b32_e32 v170, 0xe0, v168
	v_or_b32_e32 v168, 0xf0, v168
	v_lshl_add_u64 v[78:79], v[166:167], 0, v[78:79]
	v_lshl_add_u64 v[80:81], v[166:167], 0, v[80:81]
	v_ashrrev_i32_e32 v171, 31, v170
	v_ashrrev_i32_e32 v169, 31, v168
	global_load_dwordx4 v[90:93], v[78:79], off
	global_load_dwordx4 v[86:89], v[80:81], off
	v_lshlrev_b64 v[78:79], 11, v[170:171]
	v_lshlrev_b64 v[80:81], 11, v[168:169]
	v_lshl_add_u64 v[78:79], v[166:167], 0, v[78:79]
	v_lshl_add_u64 v[80:81], v[166:167], 0, v[80:81]
	global_load_dwordx4 v[82:85], v[78:79], off
	s_nop 0
	global_load_dwordx4 v[78:81], v[80:81], off
	v_or_b32_e32 v5, 0x80, v5
	v_add_u32_e32 v114, 0x10000, v183
	v_lshl_add_u32 v130, v5, 9, 0
	v_add_u32_e32 v102, v114, v184
	v_add_u32_e32 v106, v114, v185
	v_add_u32_e32 v115, v114, v187
	v_add_u32_e32 v118, v114, v189
	v_add_u32_e32 v122, v130, v186
	v_add_u32_e32 v126, v130, v188
	v_add_u32_e32 v131, v130, v190
	v_add_u32_e32 v138, v130, v191
	ds_read_b128 v[102:105], v102
	ds_read_b128 v[106:109], v106
	ds_read_b128 v[114:117], v115
	ds_read_b128 v[118:121], v118
	ds_read_b128 v[122:125], v122
	ds_read_b128 v[126:129], v126
	ds_read_b128 v[130:133], v131
	ds_read_b128 v[138:141], v138
	s_waitcnt lgkmcnt(7)
	v_mfma_f32_16x16x32_bf16 v[142:145], v[34:37], v[102:105], 0
	v_mfma_f32_16x16x32_bf16 v[102:105], v[66:69], v[102:105], 0
	s_waitcnt lgkmcnt(6)
	v_mfma_f32_16x16x32_bf16 v[142:145], v[30:33], v[106:109], v[142:145]
	v_mfma_f32_16x16x32_bf16 v[102:105], v[62:65], v[106:109], v[102:105]
	s_waitcnt lgkmcnt(5)
	v_mfma_f32_16x16x32_bf16 v[106:109], v[26:29], v[114:117], v[142:145]
	v_mfma_f32_16x16x32_bf16 v[102:105], v[58:61], v[114:117], v[102:105]
	s_waitcnt lgkmcnt(4)
	v_mfma_f32_16x16x32_bf16 v[106:109], v[22:25], v[118:121], v[106:109]
	v_mfma_f32_16x16x32_bf16 v[102:105], v[54:57], v[118:121], v[102:105]
	v_add_u32_e32 v150, 0x12000, v183
	v_add_u32_e32 v114, v150, v184
	v_add_u32_e32 v118, v150, v185
	v_add_u32_e32 v142, v150, v187
	v_add_u32_e32 v146, v150, v189
	ds_read_b128 v[114:117], v114
	ds_read_b128 v[118:121], v118
	ds_read_b128 v[142:145], v142
	ds_read_b128 v[146:149], v146
	s_waitcnt lgkmcnt(7)
	v_mfma_f32_16x16x32_bf16 v[106:109], v[18:21], v[122:125], v[106:109]
	v_mfma_f32_16x16x32_bf16 v[102:105], v[50:53], v[122:125], v[102:105]
	s_waitcnt lgkmcnt(6)
	v_mfma_f32_16x16x32_bf16 v[106:109], v[14:17], v[126:129], v[106:109]
	v_mfma_f32_16x16x32_bf16 v[102:105], v[46:49], v[126:129], v[102:105]
	s_waitcnt lgkmcnt(5)
	v_mfma_f32_16x16x32_bf16 v[106:109], v[10:13], v[130:133], v[106:109]
	v_mfma_f32_16x16x32_bf16 v[102:105], v[42:45], v[130:133], v[102:105]
	s_waitcnt lgkmcnt(4)
	v_mfma_f32_16x16x32_bf16 v[162:165], v[6:9], v[138:141], v[106:109]
	v_mfma_f32_16x16x32_bf16 v[158:161], v[38:41], v[138:141], v[102:105]
	s_nop 3
	v_add_u32_e32 v102, v150, v186
	v_add_u32_e32 v106, v150, v188
	v_add_u32_e32 v122, v150, v190
	v_add_u32_e32 v126, v150, v191
	ds_read_b128 v[102:105], v102
	ds_read_b128 v[106:109], v106
	ds_read_b128 v[122:125], v122
	ds_read_b128 v[126:129], v126
	s_waitcnt lgkmcnt(7)
	v_mfma_f32_16x16x32_bf16 v[130:133], v[34:37], v[114:117], 0
	v_mfma_f32_16x16x32_bf16 v[114:117], v[66:69], v[114:117], 0
	s_waitcnt lgkmcnt(6)
	v_mfma_f32_16x16x32_bf16 v[130:133], v[30:33], v[118:121], v[130:133]
	v_mfma_f32_16x16x32_bf16 v[114:117], v[62:65], v[118:121], v[114:117]
	s_waitcnt lgkmcnt(5)
	v_mfma_f32_16x16x32_bf16 v[118:121], v[26:29], v[142:145], v[130:133]
	v_mfma_f32_16x16x32_bf16 v[114:117], v[58:61], v[142:145], v[114:117]
	s_waitcnt lgkmcnt(4)
	v_mfma_f32_16x16x32_bf16 v[118:121], v[22:25], v[146:149], v[118:121]
	v_mfma_f32_16x16x32_bf16 v[114:117], v[54:57], v[146:149], v[114:117]
	v_add_u32_e32 v192, 0x14000, v183
	v_add_u32_e32 v130, v192, v184
	v_add_u32_e32 v138, v192, v185
	v_add_u32_e32 v142, v192, v187
	v_add_u32_e32 v146, v192, v189
	ds_read_b128 v[130:133], v130
	ds_read_b128 v[138:141], v138
	ds_read_b128 v[142:145], v142
	ds_read_b128 v[146:149], v146
	s_waitcnt lgkmcnt(7)
	v_mfma_f32_16x16x32_bf16 v[118:121], v[18:21], v[102:105], v[118:121]
	v_mfma_f32_16x16x32_bf16 v[102:105], v[50:53], v[102:105], v[114:117]
	s_waitcnt lgkmcnt(6)
	v_mfma_f32_16x16x32_bf16 v[114:117], v[14:17], v[106:109], v[118:121]
	v_mfma_f32_16x16x32_bf16 v[102:105], v[46:49], v[106:109], v[102:105]
	s_waitcnt lgkmcnt(5)
	v_mfma_f32_16x16x32_bf16 v[106:109], v[10:13], v[122:125], v[114:117]
	v_mfma_f32_16x16x32_bf16 v[102:105], v[42:45], v[122:125], v[102:105]
	s_waitcnt lgkmcnt(4)
	v_mfma_f32_16x16x32_bf16 v[154:157], v[6:9], v[126:129], v[106:109]
	v_mfma_f32_16x16x32_bf16 v[150:153], v[38:41], v[126:129], v[102:105]
	s_nop 3
	v_add_u32_e32 v102, v192, v186
	v_add_u32_e32 v106, v192, v188
	v_add_u32_e32 v114, v192, v190
	v_add_u32_e32 v118, v192, v191
	ds_read_b128 v[102:105], v102
	ds_read_b128 v[106:109], v106
	ds_read_b128 v[114:117], v114
	ds_read_b128 v[118:121], v118
	s_waitcnt lgkmcnt(7)
	v_mfma_f32_16x16x32_bf16 v[122:125], v[34:37], v[130:133], 0
	v_mfma_f32_16x16x32_bf16 v[126:129], v[66:69], v[130:133], 0
	s_waitcnt lgkmcnt(6)
	v_mfma_f32_16x16x32_bf16 v[122:125], v[30:33], v[138:141], v[122:125]
	v_mfma_f32_16x16x32_bf16 v[126:129], v[62:65], v[138:141], v[126:129]
	s_waitcnt lgkmcnt(5)
	v_mfma_f32_16x16x32_bf16 v[122:125], v[26:29], v[142:145], v[122:125]
	v_mfma_f32_16x16x32_bf16 v[126:129], v[58:61], v[142:145], v[126:129]
	s_waitcnt lgkmcnt(4)
	v_mfma_f32_16x16x32_bf16 v[122:125], v[22:25], v[146:149], v[122:125]
	v_mfma_f32_16x16x32_bf16 v[126:129], v[54:57], v[146:149], v[126:129]
	v_add_u32_e32 v200, 0x16000, v183
	v_add_u32_e32 v130, v200, v184
	v_add_u32_e32 v138, v200, v185
	v_add_u32_e32 v142, v200, v187
	ds_read_b128 v[130:133], v130
	ds_read_b128 v[138:141], v138
	v_add_u32_e32 v143, v200, v189
	ds_read_b128 v[192:195], v142
	ds_read_b128 v[196:199], v143
	s_waitcnt lgkmcnt(7)
	v_mfma_f32_16x16x32_bf16 v[122:125], v[18:21], v[102:105], v[122:125]
	v_mfma_f32_16x16x32_bf16 v[102:105], v[50:53], v[102:105], v[126:129]
	s_waitcnt lgkmcnt(6)
	v_mfma_f32_16x16x32_bf16 v[122:125], v[14:17], v[106:109], v[122:125]
	v_mfma_f32_16x16x32_bf16 v[102:105], v[46:49], v[106:109], v[102:105]
	s_waitcnt lgkmcnt(5)
	v_mfma_f32_16x16x32_bf16 v[106:109], v[10:13], v[114:117], v[122:125]
	v_mfma_f32_16x16x32_bf16 v[102:105], v[42:45], v[114:117], v[102:105]
	s_waitcnt lgkmcnt(4)
	v_mfma_f32_16x16x32_bf16 v[146:149], v[6:9], v[118:121], v[106:109]
	v_mfma_f32_16x16x32_bf16 v[142:145], v[38:41], v[118:121], v[102:105]
	s_nop 3
	v_add_u32_e32 v102, v200, v186
	v_add_u32_e32 v106, v200, v188
	v_add_u32_e32 v114, v200, v190
	v_add_u32_e32 v118, v200, v191
	ds_read_b128 v[102:105], v102
	ds_read_b128 v[106:109], v106
	ds_read_b128 v[114:117], v114
	ds_read_b128 v[118:121], v118
	s_waitcnt lgkmcnt(7)
	v_mfma_f32_16x16x32_bf16 v[122:125], v[34:37], v[130:133], 0
	v_mfma_f32_16x16x32_bf16 v[126:129], v[66:69], v[130:133], 0
	s_waitcnt lgkmcnt(6)
	v_mfma_f32_16x16x32_bf16 v[122:125], v[30:33], v[138:141], v[122:125]
	v_mfma_f32_16x16x32_bf16 v[126:129], v[62:65], v[138:141], v[126:129]
	s_waitcnt lgkmcnt(5)
	v_mfma_f32_16x16x32_bf16 v[122:125], v[26:29], v[192:195], v[122:125]
	v_mfma_f32_16x16x32_bf16 v[126:129], v[58:61], v[192:195], v[126:129]
	s_waitcnt lgkmcnt(4)
	v_mfma_f32_16x16x32_bf16 v[122:125], v[22:25], v[196:199], v[122:125]
	v_mfma_f32_16x16x32_bf16 v[126:129], v[54:57], v[196:199], v[126:129]
	v_add_u32_e32 v208, 0x18000, v183
	v_add_u32_e32 v130, v208, v184
	v_add_u32_e32 v131, v208, v185
	ds_read_b128 v[192:195], v130
	ds_read_b128 v[196:199], v131
	v_add_u32_e32 v130, v208, v187
	v_add_u32_e32 v131, v208, v189
	ds_read_b128 v[200:203], v130
	ds_read_b128 v[204:207], v131
	s_waitcnt lgkmcnt(7)
	v_mfma_f32_16x16x32_bf16 v[122:125], v[18:21], v[102:105], v[122:125]
	v_mfma_f32_16x16x32_bf16 v[102:105], v[50:53], v[102:105], v[126:129]
	s_waitcnt lgkmcnt(6)
	v_mfma_f32_16x16x32_bf16 v[122:125], v[14:17], v[106:109], v[122:125]
	v_mfma_f32_16x16x32_bf16 v[102:105], v[46:49], v[106:109], v[102:105]
	s_waitcnt lgkmcnt(5)
	v_mfma_f32_16x16x32_bf16 v[106:109], v[10:13], v[114:117], v[122:125]
	v_mfma_f32_16x16x32_bf16 v[102:105], v[42:45], v[114:117], v[102:105]
	s_waitcnt lgkmcnt(4)
	v_mfma_f32_16x16x32_bf16 v[138:141], v[6:9], v[118:121], v[106:109]
	v_mfma_f32_16x16x32_bf16 v[130:133], v[38:41], v[118:121], v[102:105]
	s_nop 3
	v_add_u32_e32 v102, v208, v186
	v_add_u32_e32 v106, v208, v188
	v_add_u32_e32 v114, v208, v190
	v_add_u32_e32 v118, v208, v191
	ds_read_b128 v[102:105], v102
	ds_read_b128 v[106:109], v106
	ds_read_b128 v[114:117], v114
	ds_read_b128 v[118:121], v118
	s_waitcnt lgkmcnt(7)
	v_mfma_f32_16x16x32_bf16 v[122:125], v[34:37], v[192:195], 0
	v_mfma_f32_16x16x32_bf16 v[126:129], v[66:69], v[192:195], 0
	s_waitcnt lgkmcnt(6)
	v_mfma_f32_16x16x32_bf16 v[122:125], v[30:33], v[196:199], v[122:125]
	v_mfma_f32_16x16x32_bf16 v[126:129], v[62:65], v[196:199], v[126:129]
	s_waitcnt lgkmcnt(5)
	v_mfma_f32_16x16x32_bf16 v[122:125], v[26:29], v[200:203], v[122:125]
	v_mfma_f32_16x16x32_bf16 v[126:129], v[58:61], v[200:203], v[126:129]
	s_waitcnt lgkmcnt(4)
	v_mfma_f32_16x16x32_bf16 v[122:125], v[22:25], v[204:207], v[122:125]
	v_mfma_f32_16x16x32_bf16 v[126:129], v[54:57], v[204:207], v[126:129]
	v_add_u32_e32 v208, 0x1a000, v183
	v_add_u32_e32 v192, v208, v184
	v_add_u32_e32 v196, v208, v185
	v_add_u32_e32 v200, v208, v187
	v_add_u32_e32 v204, v208, v189
	ds_read_b128 v[192:195], v192
	ds_read_b128 v[196:199], v196
	ds_read_b128 v[200:203], v200
	ds_read_b128 v[204:207], v204
	s_waitcnt lgkmcnt(7)
	v_mfma_f32_16x16x32_bf16 v[122:125], v[18:21], v[102:105], v[122:125]
	v_mfma_f32_16x16x32_bf16 v[102:105], v[50:53], v[102:105], v[126:129]
	s_waitcnt lgkmcnt(6)
	v_mfma_f32_16x16x32_bf16 v[122:125], v[14:17], v[106:109], v[122:125]
	v_mfma_f32_16x16x32_bf16 v[102:105], v[46:49], v[106:109], v[102:105]
	s_waitcnt lgkmcnt(5)
	v_mfma_f32_16x16x32_bf16 v[106:109], v[10:13], v[114:117], v[122:125]
	v_mfma_f32_16x16x32_bf16 v[102:105], v[42:45], v[114:117], v[102:105]
	s_waitcnt lgkmcnt(4)
	v_mfma_f32_16x16x32_bf16 v[126:129], v[6:9], v[118:121], v[106:109]
	v_mfma_f32_16x16x32_bf16 v[122:125], v[38:41], v[118:121], v[102:105]
	s_nop 3
	v_add_u32_e32 v102, v208, v186
	v_add_u32_e32 v106, v208, v188
	v_add_u32_e32 v114, v208, v190
	ds_read_b128 v[102:105], v102
	ds_read_b128 v[106:109], v106
	v_add_u32_e32 v118, v208, v191
	ds_read_b128 v[114:117], v114
	ds_read_b128 v[208:211], v118
	s_waitcnt lgkmcnt(7)
	v_mfma_f32_16x16x32_bf16 v[118:121], v[34:37], v[192:195], 0
	v_mfma_f32_16x16x32_bf16 v[192:195], v[66:69], v[192:195], 0
	s_waitcnt lgkmcnt(6)
	v_mfma_f32_16x16x32_bf16 v[118:121], v[30:33], v[196:199], v[118:121]
	v_mfma_f32_16x16x32_bf16 v[192:195], v[62:65], v[196:199], v[192:195]
	s_waitcnt lgkmcnt(5)
	v_mfma_f32_16x16x32_bf16 v[118:121], v[26:29], v[200:203], v[118:121]
	v_mfma_f32_16x16x32_bf16 v[192:195], v[58:61], v[200:203], v[192:195]
	s_waitcnt lgkmcnt(4)
	v_mfma_f32_16x16x32_bf16 v[118:121], v[22:25], v[204:207], v[118:121]
	v_mfma_f32_16x16x32_bf16 v[192:195], v[54:57], v[204:207], v[192:195]
	v_add_u32_e32 v216, 0x1c000, v183
	v_add_u32_e32 v196, v216, v184
	v_add_u32_e32 v200, v216, v185
	v_add_u32_e32 v204, v216, v187
	v_add_u32_e32 v212, v216, v189
	ds_read_b128 v[196:199], v196
	ds_read_b128 v[200:203], v200
	ds_read_b128 v[204:207], v204
	ds_read_b128 v[212:215], v212
	s_waitcnt lgkmcnt(7)
	v_mfma_f32_16x16x32_bf16 v[118:121], v[18:21], v[102:105], v[118:121]
	v_mfma_f32_16x16x32_bf16 v[102:105], v[50:53], v[102:105], v[192:195]
	s_waitcnt lgkmcnt(6)
	v_mfma_f32_16x16x32_bf16 v[118:121], v[14:17], v[106:109], v[118:121]
	v_mfma_f32_16x16x32_bf16 v[102:105], v[46:49], v[106:109], v[102:105]
	s_waitcnt lgkmcnt(5)
	v_mfma_f32_16x16x32_bf16 v[106:109], v[10:13], v[114:117], v[118:121]
	v_mfma_f32_16x16x32_bf16 v[102:105], v[42:45], v[114:117], v[102:105]
	s_waitcnt lgkmcnt(4)
	v_mfma_f32_16x16x32_bf16 v[118:121], v[6:9], v[208:211], v[106:109]
	v_mfma_f32_16x16x32_bf16 v[114:117], v[38:41], v[208:211], v[102:105]
	s_nop 3
	v_add_u32_e32 v102, v216, v186
	v_add_u32_e32 v106, v216, v188
	v_add_u32_e32 v192, v216, v190
	v_add_u32_e32 v208, v216, v191
	ds_read_b128 v[102:105], v102
	ds_read_b128 v[106:109], v106
	ds_read_b128 v[192:195], v192
	ds_read_b128 v[208:211], v208
	s_waitcnt lgkmcnt(7)
	v_mfma_f32_16x16x32_bf16 v[216:219], v[34:37], v[196:199], 0
	v_mfma_f32_16x16x32_bf16 v[196:199], v[66:69], v[196:199], 0
	s_waitcnt lgkmcnt(6)
	v_mfma_f32_16x16x32_bf16 v[216:219], v[30:33], v[200:203], v[216:219]
	v_mfma_f32_16x16x32_bf16 v[196:199], v[62:65], v[200:203], v[196:199]
	s_waitcnt lgkmcnt(5)
	v_mfma_f32_16x16x32_bf16 v[200:203], v[26:29], v[204:207], v[216:219]
	v_mfma_f32_16x16x32_bf16 v[196:199], v[58:61], v[204:207], v[196:199]
	s_waitcnt lgkmcnt(4)
	v_mfma_f32_16x16x32_bf16 v[200:203], v[22:25], v[212:215], v[200:203]
	v_mfma_f32_16x16x32_bf16 v[196:199], v[54:57], v[212:215], v[196:199]
	v_add_u32_e32 v183, 0x1e000, v183
	v_add_u32_e32 v184, v183, v184
	v_add_u32_e32 v185, v183, v185
	ds_read_b128 v[204:207], v184
	ds_read_b128 v[212:215], v185
	v_add_u32_e32 v184, v183, v187
	v_add_u32_e32 v185, v183, v189
	ds_read_b128 v[216:219], v184
	ds_read_b128 v[220:223], v185
	s_waitcnt lgkmcnt(7)
	v_mfma_f32_16x16x32_bf16 v[200:203], v[18:21], v[102:105], v[200:203]
	v_mfma_f32_16x16x32_bf16 v[102:105], v[50:53], v[102:105], v[196:199]
	s_waitcnt lgkmcnt(6)
	v_mfma_f32_16x16x32_bf16 v[196:199], v[14:17], v[106:109], v[200:203]
	v_mfma_f32_16x16x32_bf16 v[102:105], v[46:49], v[106:109], v[102:105]
	s_waitcnt lgkmcnt(5)
	v_mfma_f32_16x16x32_bf16 v[106:109], v[10:13], v[192:195], v[196:199]
	v_mfma_f32_16x16x32_bf16 v[102:105], v[42:45], v[192:195], v[102:105]
	s_waitcnt lgkmcnt(4)
	v_mfma_f32_16x16x32_bf16 v[106:109], v[6:9], v[208:211], v[106:109]
	v_mfma_f32_16x16x32_bf16 v[102:105], v[38:41], v[208:211], v[102:105]
	v_add_u32_e32 v184, v183, v186
	v_add_u32_e32 v188, v183, v188
	ds_read_b128 v[184:187], v184
	ds_read_b128 v[192:195], v188
	v_add_u32_e32 v188, v183, v190
	v_add_u32_e32 v183, v183, v191
	ds_read_b128 v[188:191], v188
	ds_read_b128 v[196:199], v183
	s_waitcnt lgkmcnt(7)
	v_mfma_f32_16x16x32_bf16 v[34:37], v[34:37], v[204:207], 0
	v_mfma_f32_16x16x32_bf16 v[66:69], v[66:69], v[204:207], 0
	s_waitcnt lgkmcnt(6)
	v_mfma_f32_16x16x32_bf16 v[30:33], v[30:33], v[212:215], v[34:37]
	v_mfma_f32_16x16x32_bf16 v[34:37], v[62:65], v[212:215], v[66:69]
	s_waitcnt lgkmcnt(5)
	v_mfma_f32_16x16x32_bf16 v[26:29], v[26:29], v[216:219], v[30:33]
	v_mfma_f32_16x16x32_bf16 v[30:33], v[58:61], v[216:219], v[34:37]
	s_waitcnt lgkmcnt(4)
	v_mfma_f32_16x16x32_bf16 v[22:25], v[22:25], v[220:223], v[26:29]
	v_mfma_f32_16x16x32_bf16 v[26:29], v[54:57], v[220:223], v[30:33]
	s_waitcnt lgkmcnt(3)
	v_mfma_f32_16x16x32_bf16 v[18:21], v[18:21], v[184:187], v[22:25]
	v_mfma_f32_16x16x32_bf16 v[22:25], v[50:53], v[184:187], v[26:29]
	s_waitcnt lgkmcnt(2)
	v_mfma_f32_16x16x32_bf16 v[14:17], v[14:17], v[192:195], v[18:21]
	v_mfma_f32_16x16x32_bf16 v[18:21], v[46:49], v[192:195], v[22:25]
	s_waitcnt lgkmcnt(1)
	v_mfma_f32_16x16x32_bf16 v[10:13], v[10:13], v[188:191], v[14:17]
	v_mfma_f32_16x16x32_bf16 v[14:17], v[42:45], v[188:191], v[18:21]
	s_waitcnt lgkmcnt(0)
	v_mfma_f32_16x16x32_bf16 v[10:13], v[6:9], v[196:199], v[10:13]
	v_mfma_f32_16x16x32_bf16 v[6:9], v[38:41], v[196:199], v[14:17]
	s_waitcnt vmcnt(7)
	s_nop 2
	v_lshlrev_b32_e32 v14, 16, v134
	v_and_b32_e32 v15, 0xffff0000, v134
	v_lshlrev_b32_e32 v16, 16, v135
	v_and_b32_e32 v17, 0xffff0000, v135
	v_pk_fma_f32 v[16:17], v[76:77], v[164:165], v[16:17]
	v_pk_fma_f32 v[14:15], v[74:75], v[162:163], v[14:15]
	v_lshlrev_b32_e32 v18, 16, v136
	v_and_b32_e32 v19, 0xffff0000, v136
	v_lshlrev_b32_e32 v20, 16, v137
	v_and_b32_e32 v21, 0xffff0000, v137
	v_mul_f32_e32 v22, v15, v15
	v_mul_f32_e32 v23, v17, v17
	v_pk_fma_f32 v[20:21], v[72:73], v[160:161], v[20:21]
	v_pk_fma_f32 v[18:19], v[70:71], v[158:159], v[18:19]
	v_fmac_f32_e32 v22, v14, v14
	v_fmac_f32_e32 v23, v16, v16
	v_add_f32_e32 v22, v22, v23
	v_mul_f32_e32 v23, v19, v19
	v_mul_f32_e32 v24, v21, v21
	v_fmac_f32_e32 v23, v18, v18
	v_fmac_f32_e32 v24, v20, v20
	v_add_f32_e32 v23, v23, v24
	v_add_f32_e32 v24, v22, v23
	v_or_b32_e32 v22, s4, v5
	v_ashrrev_i32_e32 v23, 31, v22
	v_mov_b32_e32 v5, v24
	v_lshlrev_b64 v[22:23], 11, v[22:23]
	s_nop 0
	v_permlane16_swap_b32_e32 v24, v5
	v_lshl_add_u64 v[22:23], v[166:167], 0, v[22:23]
	v_cvt_pk_bf16_f32 v14, v14, v15
	v_add_f32_e32 v5, v24, v5
	v_cvt_pk_bf16_f32 v15, v16, v17
	v_cvt_pk_bf16_f32 v16, v18, v19
	v_cvt_pk_bf16_f32 v17, v20, v21
	global_store_dwordx4 v[22:23], v[14:17], off sc1
	s_nop 1
	v_mov_b32_e32 v14, v5
	s_nop 1
	v_permlane32_swap_b32_e32 v5, v14
	s_and_saveexec_b64 s[2:3], vcc
	v_add_f32_e32 v5, v5, v14
	ds_write_b32 v182, v5 offset:512
	s_or_b64 exec, exec, s[2:3]
	s_waitcnt vmcnt(7)
	v_lshlrev_b32_e32 v14, 16, v110
	v_and_b32_e32 v15, 0xffff0000, v110
	v_lshlrev_b32_e32 v16, 16, v111
	v_and_b32_e32 v17, 0xffff0000, v111
	v_pk_fma_f32 v[16:17], v[76:77], v[156:157], v[16:17]
	v_pk_fma_f32 v[14:15], v[74:75], v[154:155], v[14:15]
	v_lshlrev_b32_e32 v18, 16, v112
	v_and_b32_e32 v19, 0xffff0000, v112
	v_lshlrev_b32_e32 v20, 16, v113
	v_and_b32_e32 v21, 0xffff0000, v113
	v_mul_f32_e32 v5, v15, v15
	v_mul_f32_e32 v22, v17, v17
	v_pk_fma_f32 v[20:21], v[72:73], v[152:153], v[20:21]
	v_pk_fma_f32 v[18:19], v[70:71], v[150:151], v[18:19]
	v_fmac_f32_e32 v5, v14, v14
	v_fmac_f32_e32 v22, v16, v16
	v_add_f32_e32 v5, v5, v22
	v_mul_f32_e32 v22, v19, v19
	v_mul_f32_e32 v23, v21, v21
	v_fmac_f32_e32 v22, v18, v18
	v_fmac_f32_e32 v23, v20, v20
	v_add_f32_e32 v22, v22, v23
	v_add_f32_e32 v5, v5, v22
	v_cvt_pk_bf16_f32 v14, v14, v15
	v_cvt_pk_bf16_f32 v15, v16, v17
	v_cvt_pk_bf16_f32 v16, v18, v19
	v_cvt_pk_bf16_f32 v17, v20, v21
	global_store_dwordx4 v[180:181], v[14:17], off sc1
	s_nop 1
	v_mov_b32_e32 v14, v5
	s_nop 1
	v_permlane16_swap_b32_e32 v5, v14
	v_add_f32_e32 v5, v5, v14
	v_mov_b32_e32 v14, v5
	s_nop 1
	v_permlane32_swap_b32_e32 v5, v14
	s_and_saveexec_b64 s[2:3], vcc
	v_add_f32_e32 v5, v5, v14
	ds_write_b32 v182, v5 offset:576
	s_or_b64 exec, exec, s[2:3]
	s_waitcnt vmcnt(7)
	v_lshlrev_b32_e32 v14, 16, v98
	v_and_b32_e32 v15, 0xffff0000, v98
	v_lshlrev_b32_e32 v16, 16, v99
	v_and_b32_e32 v17, 0xffff0000, v99
	v_pk_fma_f32 v[16:17], v[76:77], v[148:149], v[16:17]
	v_pk_fma_f32 v[14:15], v[74:75], v[146:147], v[14:15]
	v_lshlrev_b32_e32 v18, 16, v100
	v_and_b32_e32 v19, 0xffff0000, v100
	v_lshlrev_b32_e32 v20, 16, v101
	v_and_b32_e32 v21, 0xffff0000, v101
	v_mul_f32_e32 v5, v15, v15
	v_mul_f32_e32 v22, v17, v17
	v_pk_fma_f32 v[20:21], v[72:73], v[144:145], v[20:21]
	v_pk_fma_f32 v[18:19], v[70:71], v[142:143], v[18:19]
	v_fmac_f32_e32 v5, v14, v14
	v_fmac_f32_e32 v22, v16, v16
	v_add_f32_e32 v5, v5, v22
	v_mul_f32_e32 v22, v19, v19
	v_mul_f32_e32 v23, v21, v21
	v_fmac_f32_e32 v22, v18, v18
	v_fmac_f32_e32 v23, v20, v20
	v_add_f32_e32 v22, v22, v23
	v_add_f32_e32 v5, v5, v22
	v_lshlrev_b64 v[22:23], 11, v[178:179]
	v_lshl_add_u64 v[22:23], v[166:167], 0, v[22:23]
	v_cvt_pk_bf16_f32 v14, v14, v15
	v_cvt_pk_bf16_f32 v15, v16, v17
	v_cvt_pk_bf16_f32 v16, v18, v19
	v_cvt_pk_bf16_f32 v17, v20, v21
	global_store_dwordx4 v[22:23], v[14:17], off sc1
	s_nop 1
	v_mov_b32_e32 v14, v5
	s_nop 1
	v_permlane16_swap_b32_e32 v5, v14
	v_add_f32_e32 v5, v5, v14
	v_mov_b32_e32 v14, v5
	s_nop 1
	v_permlane32_swap_b32_e32 v5, v14
	s_and_saveexec_b64 s[2:3], vcc
	v_add_f32_e32 v5, v5, v14
	ds_write_b32 v182, v5 offset:640
	s_or_b64 exec, exec, s[2:3]
	s_waitcnt vmcnt(7)
	v_lshlrev_b32_e32 v14, 16, v94
	v_and_b32_e32 v15, 0xffff0000, v94
	v_lshlrev_b32_e32 v16, 16, v95
	v_and_b32_e32 v17, 0xffff0000, v95
	v_pk_fma_f32 v[16:17], v[76:77], v[140:141], v[16:17]
	v_pk_fma_f32 v[14:15], v[74:75], v[138:139], v[14:15]
	v_lshlrev_b32_e32 v18, 16, v96
	v_and_b32_e32 v19, 0xffff0000, v96
	v_lshlrev_b32_e32 v20, 16, v97
	v_and_b32_e32 v21, 0xffff0000, v97
	v_mul_f32_e32 v5, v15, v15
	v_mul_f32_e32 v22, v17, v17
	v_pk_fma_f32 v[20:21], v[72:73], v[132:133], v[20:21]
	v_pk_fma_f32 v[18:19], v[70:71], v[130:131], v[18:19]
	v_fmac_f32_e32 v5, v14, v14
	v_fmac_f32_e32 v22, v16, v16
	v_add_f32_e32 v5, v5, v22
	v_mul_f32_e32 v22, v19, v19
	v_mul_f32_e32 v23, v21, v21
	v_fmac_f32_e32 v22, v18, v18
	v_fmac_f32_e32 v23, v20, v20
	v_add_f32_e32 v22, v22, v23
	v_add_f32_e32 v5, v5, v22
	v_lshlrev_b64 v[22:23], 11, v[176:177]
	v_lshl_add_u64 v[22:23], v[166:167], 0, v[22:23]
	v_cvt_pk_bf16_f32 v14, v14, v15
	v_cvt_pk_bf16_f32 v15, v16, v17
	v_cvt_pk_bf16_f32 v16, v18, v19
	v_cvt_pk_bf16_f32 v17, v20, v21
	global_store_dwordx4 v[22:23], v[14:17], off sc1
	s_nop 1
	v_mov_b32_e32 v14, v5
	s_nop 1
	v_permlane16_swap_b32_e32 v5, v14
	v_add_f32_e32 v5, v5, v14
	v_mov_b32_e32 v14, v5
	s_nop 1
	v_permlane32_swap_b32_e32 v5, v14
	s_and_saveexec_b64 s[2:3], vcc
	v_add_f32_e32 v5, v5, v14
	ds_write_b32 v182, v5 offset:704
	s_or_b64 exec, exec, s[2:3]
	s_waitcnt vmcnt(7)
	v_lshlrev_b32_e32 v14, 16, v90
	v_and_b32_e32 v15, 0xffff0000, v90
	v_lshlrev_b32_e32 v16, 16, v91
	v_and_b32_e32 v17, 0xffff0000, v91
	v_pk_fma_f32 v[16:17], v[76:77], v[128:129], v[16:17]
	v_pk_fma_f32 v[14:15], v[74:75], v[126:127], v[14:15]
	v_lshlrev_b32_e32 v18, 16, v92
	v_and_b32_e32 v19, 0xffff0000, v92
	v_lshlrev_b32_e32 v20, 16, v93
	v_and_b32_e32 v21, 0xffff0000, v93
	v_mul_f32_e32 v5, v15, v15
	v_mul_f32_e32 v22, v17, v17
	v_pk_fma_f32 v[20:21], v[72:73], v[124:125], v[20:21]
	v_pk_fma_f32 v[18:19], v[70:71], v[122:123], v[18:19]
	v_fmac_f32_e32 v5, v14, v14
	v_fmac_f32_e32 v22, v16, v16
	v_add_f32_e32 v5, v5, v22
	v_mul_f32_e32 v22, v19, v19
	v_mul_f32_e32 v23, v21, v21
	v_fmac_f32_e32 v22, v18, v18
	v_fmac_f32_e32 v23, v20, v20
	v_add_f32_e32 v22, v22, v23
	v_add_f32_e32 v5, v5, v22
	v_lshlrev_b64 v[22:23], 11, v[174:175]
	v_lshl_add_u64 v[22:23], v[166:167], 0, v[22:23]
	v_cvt_pk_bf16_f32 v14, v14, v15
	v_cvt_pk_bf16_f32 v15, v16, v17
	v_cvt_pk_bf16_f32 v16, v18, v19
	v_cvt_pk_bf16_f32 v17, v20, v21
	global_store_dwordx4 v[22:23], v[14:17], off sc1
	s_nop 1
	v_mov_b32_e32 v14, v5
	s_nop 1
	v_permlane16_swap_b32_e32 v5, v14
	v_add_f32_e32 v5, v5, v14
	v_mov_b32_e32 v14, v5
	s_nop 1
	v_permlane32_swap_b32_e32 v5, v14
	s_and_saveexec_b64 s[2:3], vcc
	v_add_f32_e32 v5, v5, v14
	ds_write_b32 v182, v5 offset:768
	s_or_b64 exec, exec, s[2:3]
	s_waitcnt vmcnt(7)
	v_lshlrev_b32_e32 v14, 16, v86
	v_and_b32_e32 v15, 0xffff0000, v86
	v_lshlrev_b32_e32 v16, 16, v87
	v_and_b32_e32 v17, 0xffff0000, v87
	v_pk_fma_f32 v[16:17], v[76:77], v[120:121], v[16:17]
	v_pk_fma_f32 v[14:15], v[74:75], v[118:119], v[14:15]
	v_lshlrev_b32_e32 v18, 16, v88
	v_and_b32_e32 v19, 0xffff0000, v88
	v_lshlrev_b32_e32 v20, 16, v89
	v_and_b32_e32 v21, 0xffff0000, v89
	v_mul_f32_e32 v5, v15, v15
	v_mul_f32_e32 v22, v17, v17
	v_pk_fma_f32 v[20:21], v[72:73], v[116:117], v[20:21]
	v_pk_fma_f32 v[18:19], v[70:71], v[114:115], v[18:19]
	v_fmac_f32_e32 v5, v14, v14
	v_fmac_f32_e32 v22, v16, v16
	v_add_f32_e32 v5, v5, v22
	v_mul_f32_e32 v22, v19, v19
	v_mul_f32_e32 v23, v21, v21
	v_fmac_f32_e32 v22, v18, v18
	v_fmac_f32_e32 v23, v20, v20
	v_add_f32_e32 v22, v22, v23
	v_add_f32_e32 v5, v5, v22
	v_lshlrev_b64 v[22:23], 11, v[172:173]
	v_lshl_add_u64 v[22:23], v[166:167], 0, v[22:23]
	v_cvt_pk_bf16_f32 v14, v14, v15
	v_cvt_pk_bf16_f32 v15, v16, v17
	v_cvt_pk_bf16_f32 v16, v18, v19
	v_cvt_pk_bf16_f32 v17, v20, v21
	global_store_dwordx4 v[22:23], v[14:17], off sc1
	s_nop 1
	v_mov_b32_e32 v14, v5
	s_nop 1
	v_permlane16_swap_b32_e32 v5, v14
	v_add_f32_e32 v5, v5, v14
	v_mov_b32_e32 v14, v5
	s_nop 1
	v_permlane32_swap_b32_e32 v5, v14
	s_and_saveexec_b64 s[2:3], vcc
	v_add_f32_e32 v5, v5, v14
	ds_write_b32 v182, v5 offset:832
	s_or_b64 exec, exec, s[2:3]
	s_waitcnt vmcnt(7)
	v_lshlrev_b32_e32 v14, 16, v82
	v_and_b32_e32 v15, 0xffff0000, v82
	v_lshlrev_b32_e32 v16, 16, v83
	v_and_b32_e32 v17, 0xffff0000, v83
	v_pk_fma_f32 v[16:17], v[76:77], v[108:109], v[16:17]
	v_pk_fma_f32 v[14:15], v[74:75], v[106:107], v[14:15]
	v_lshlrev_b32_e32 v18, 16, v84
	v_and_b32_e32 v19, 0xffff0000, v84
	v_lshlrev_b32_e32 v20, 16, v85
	v_and_b32_e32 v21, 0xffff0000, v85
	v_mul_f32_e32 v5, v15, v15
	v_mul_f32_e32 v22, v17, v17
	v_pk_fma_f32 v[20:21], v[72:73], v[104:105], v[20:21]
	v_pk_fma_f32 v[18:19], v[70:71], v[102:103], v[18:19]
	v_fmac_f32_e32 v5, v14, v14
	v_fmac_f32_e32 v22, v16, v16
	v_add_f32_e32 v5, v5, v22
	v_mul_f32_e32 v22, v19, v19
	v_mul_f32_e32 v23, v21, v21
	v_fmac_f32_e32 v22, v18, v18
	v_fmac_f32_e32 v23, v20, v20
	v_add_f32_e32 v22, v22, v23
	v_add_f32_e32 v5, v5, v22
	v_lshlrev_b64 v[22:23], 11, v[170:171]
	v_lshl_add_u64 v[22:23], v[166:167], 0, v[22:23]
	v_cvt_pk_bf16_f32 v14, v14, v15
	v_cvt_pk_bf16_f32 v15, v16, v17
	v_cvt_pk_bf16_f32 v16, v18, v19
	v_cvt_pk_bf16_f32 v17, v20, v21
	global_store_dwordx4 v[22:23], v[14:17], off sc1
	s_nop 1
	v_mov_b32_e32 v14, v5
	s_nop 1
	v_permlane16_swap_b32_e32 v5, v14
	v_add_f32_e32 v5, v5, v14
	v_mov_b32_e32 v14, v5
	s_nop 1
	v_permlane32_swap_b32_e32 v5, v14
	s_and_saveexec_b64 s[2:3], vcc
	v_add_f32_e32 v5, v5, v14
	ds_write_b32 v182, v5 offset:896
	s_or_b64 exec, exec, s[2:3]
	s_waitcnt vmcnt(7)
	v_lshlrev_b32_e32 v14, 16, v78
	v_and_b32_e32 v15, 0xffff0000, v78
	v_lshlrev_b32_e32 v16, 16, v79
	v_and_b32_e32 v17, 0xffff0000, v79
	v_pk_fma_f32 v[12:13], v[76:77], v[12:13], v[16:17]
	v_pk_fma_f32 v[10:11], v[74:75], v[10:11], v[14:15]
	v_lshlrev_b32_e32 v14, 16, v80
	v_and_b32_e32 v15, 0xffff0000, v80
	v_lshlrev_b32_e32 v16, 16, v81
	v_and_b32_e32 v17, 0xffff0000, v81
	v_pk_fma_f32 v[16:17], v[72:73], v[8:9], v[16:17]
	v_pk_fma_f32 v[8:9], v[70:71], v[6:7], v[14:15]
	v_mul_f32_e32 v5, v11, v11
	v_mul_f32_e32 v6, v13, v13
	v_fmac_f32_e32 v5, v10, v10
	v_fmac_f32_e32 v6, v12, v12
	v_add_f32_e32 v5, v5, v6
	v_mul_f32_e32 v6, v9, v9
	v_mul_f32_e32 v7, v17, v17
	v_fmac_f32_e32 v6, v8, v8
	v_fmac_f32_e32 v7, v16, v16
	v_add_f32_e32 v6, v6, v7
	v_add_f32_e32 v5, v5, v6
	v_lshlrev_b64 v[6:7], 11, v[168:169]
	v_lshl_add_u64 v[14:15], v[166:167], 0, v[6:7]
	v_cvt_pk_bf16_f32 v6, v10, v11
	v_cvt_pk_bf16_f32 v7, v12, v13
	v_cvt_pk_bf16_f32 v8, v8, v9
	v_cvt_pk_bf16_f32 v9, v16, v17
	global_store_dwordx4 v[14:15], v[6:9], off sc1
	s_nop 1
	v_mov_b32_e32 v6, v5
	s_nop 1
	v_permlane16_swap_b32_e32 v5, v6
	v_add_f32_e32 v5, v5, v6
	v_mov_b32_e32 v6, v5
	s_nop 1
	v_permlane32_swap_b32_e32 v5, v6
	s_and_saveexec_b64 s[2:3], vcc
	v_add_f32_e32 v5, v5, v6
	ds_write_b32 v182, v5 offset:960
	s_or_b64 exec, exec, s[2:3]
	s_movk_i32 s2, 0x400
	v_cmp_gt_i32_e32 vcc, s2, v2
	s_waitcnt lgkmcnt(0)
	s_barrier
	s_and_saveexec_b64 s[2:3], vcc
	s_cbranch_execz .LBB0_443
	v_readlane_b32 s5, v253, 6
	s_lshl_b32 s5, s5, 2
	v_readlane_b32 s6, v254, 33
	v_readlane_b32 s7, v254, 34
	s_add_u32 s6, s6, s5
	s_addc_u32 s7, s7, 0
	s_add_i32 s5, 0, 0x21000
	v_lshl_or_b32 v6, s78, 2, v3
	v_lshl_add_u32 v5, v3, 11, s5
	v_ashrrev_i32_e32 v7, 31, v6
	v_max_i32_e32 v3, 0x200, v2
	v_lshlrev_b64 v[6:7], 14, v[6:7]
	v_sub_u32_e32 v3, v3, v2
	v_lshl_add_u64 v[6:7], s[6:7], 0, v[6:7]
	s_mov_b64 s[6:7], 0x300000
	v_add_u32_e32 v3, 0x1ff, v3
	v_lshl_add_u64 v[6:7], v[6:7], 0, s[6:7]
	v_cmp_lt_u32_e32 vcc, s12, v3
	s_mov_b64 s[8:9], -1
	s_and_saveexec_b64 s[6:7], vcc
	s_cbranch_execz .LBB0_440
	v_lshrrev_b32_e32 v10, 9, v3
	v_add_u32_e32 v8, -1, v10
	v_add_u32_e32 v3, 0x200, v2
	v_lshrrev_b32_e32 v9, 1, v8
	v_add_u32_e32 v11, 1, v9
	v_cmp_lt_u32_e32 vcc, 5, v8
	v_mov_b64_e32 v[8:9], v[2:3]
	s_and_saveexec_b64 s[8:9], vcc
	s_cbranch_execz .LBB0_436
	v_and_b32_e32 v12, -4, v11
	s_mov_b64 s[10:11], 0
	v_mov_b64_e32 v[8:9], v[2:3]

.LBB0_493:
	s_waitcnt lgkmcnt(0)
	s_add_i32 s64, s64, 2
	s_barrier
	s_waitcnt lgkmcnt(0)
	v_mfma_f32_16x16x32_bf16 v[70:73], v[154:157], v[194:197], v[70:73]
	v_mfma_f32_16x16x32_bf16 v[66:69], v[162:165], v[194:197], v[66:69]
	v_mfma_f32_16x16x32_bf16 v[54:57], v[154:157], v[186:189], v[54:57]
	v_mfma_f32_16x16x32_bf16 v[50:53], v[162:165], v[186:189], v[50:53]
	v_mfma_f32_16x16x32_bf16 v[34:37], v[154:157], v[178:181], v[34:37]
	v_mfma_f32_16x16x32_bf16 v[30:33], v[162:165], v[178:181], v[30:33]
	v_mfma_f32_16x16x32_bf16 v[18:21], v[154:157], v[170:173], v[18:21]
	v_mfma_f32_16x16x32_bf16 v[14:17], v[162:165], v[170:173], v[14:17]
	v_mfma_f32_16x16x32_bf16 v[70:73], v[158:161], v[198:201], v[70:73]
	v_mfma_f32_16x16x32_bf16 v[66:69], v[166:169], v[198:201], v[66:69]
	v_mfma_f32_16x16x32_bf16 v[54:57], v[158:161], v[190:193], v[54:57]
	v_mfma_f32_16x16x32_bf16 v[50:53], v[166:169], v[190:193], v[50:53]
	v_mfma_f32_16x16x32_bf16 v[34:37], v[158:161], v[182:185], v[34:37]
	v_mfma_f32_16x16x32_bf16 v[30:33], v[166:169], v[182:185], v[30:33]
	v_mfma_f32_16x16x32_bf16 v[18:21], v[158:161], v[174:177], v[18:21]
	v_mfma_f32_16x16x32_bf16 v[14:17], v[166:169], v[174:177], v[14:17]
	v_mfma_f32_16x16x32_bf16 v[62:65], v[138:141], v[194:197], v[62:65]
	v_mfma_f32_16x16x32_bf16 v[58:61], v[146:149], v[194:197], v[58:61]
	v_mfma_f32_16x16x32_bf16 v[46:49], v[138:141], v[186:189], v[46:49]
	v_mfma_f32_16x16x32_bf16 v[42:45], v[146:149], v[186:189], v[42:45]
	v_mfma_f32_16x16x32_bf16 v[26:29], v[138:141], v[178:181], v[26:29]
	v_mfma_f32_16x16x32_bf16 v[22:25], v[146:149], v[178:181], v[22:25]
	v_mfma_f32_16x16x32_bf16 v[10:13], v[138:141], v[170:173], v[10:13]
	v_mfma_f32_16x16x32_bf16 v[6:9], v[146:149], v[170:173], v[6:9]
	v_mfma_f32_16x16x32_bf16 v[62:65], v[142:145], v[198:201], v[62:65]
	v_mfma_f32_16x16x32_bf16 v[58:61], v[150:153], v[198:201], v[58:61]
	v_mfma_f32_16x16x32_bf16 v[46:49], v[142:145], v[190:193], v[46:49]
	v_mfma_f32_16x16x32_bf16 v[42:45], v[150:153], v[190:193], v[42:45]
	v_mfma_f32_16x16x32_bf16 v[26:29], v[142:145], v[182:185], v[26:29]
	v_mfma_f32_16x16x32_bf16 v[22:25], v[150:153], v[182:185], v[22:25]
	v_mfma_f32_16x16x32_bf16 v[10:13], v[142:145], v[174:177], v[10:13]
	v_mfma_f32_16x16x32_bf16 v[6:9], v[150:153], v[174:177], v[6:9]
	s_barrier
	s_add_u32 s62, s62, 0x100
	s_addc_u32 s63, s63, 0
	s_add_u32 s22, s22, 0x100
	s_addc_u32 s23, s23, 0
	s_cmp_ge_i32 s64, s54
	s_cbranch_scc1 .LBB0_504
.LBB0_494:
	v_add_u32_e32 v138, 0x10000, v229
	v_add_u32_e32 v150, 0x14000, v229
	ds_read_b128 v[154:157], v138
	ds_read_b128 v[158:161], v138 offset:1024
	ds_read_b128 v[162:165], v138 offset:2048
	ds_read_b128 v[166:169], v138 offset:3072
	ds_read_b128 v[138:141], v150
	ds_read_b128 v[142:145], v150 offset:1024
	ds_read_b128 v[146:149], v150 offset:2048
	ds_read_b128 v[150:153], v150 offset:3072
	s_cmp_lg_u32 s55, s64
	s_cselect_b64 s[28:29], -1, 0
	s_add_u32 s26, s22, 0xfffc0080
	s_addc_u32 s27, s23, -1
	s_and_b64 s[24:25], s[28:29], exec
	s_cselect_b32 s27, s27, s13
	s_cselect_b32 s26, s26, s15
	s_cselect_b32 s25, s63, s60
	s_cselect_b32 s24, s62, s61
	v_lshl_add_u64 v[220:221], s[22:23], 0, v[208:209]
	s_add_i32 m0, s40, 0xc000
	ds_read_b128 v[170:173], v230
	ds_read_b128 v[174:177], v230 offset:1024
	ds_read_b128 v[178:181], v230 offset:2048
	ds_read_b128 v[182:185], v230 offset:3072
	ds_read_b128 v[186:189], v230 offset:4096
	ds_read_b128 v[190:193], v230 offset:5120
	ds_read_b128 v[194:197], v230 offset:6144
	ds_read_b128 v[198:201], v230 offset:7168
	global_load_lds_dwordx4 v[220:221], off
	v_lshl_add_u64 v[220:221], s[22:23], 0, v[210:211]
	s_add_i32 m0, s40, 0xe000
	s_nop 0
	global_load_lds_dwordx4 v[220:221], off
	s_waitcnt vmcnt(8)
	s_waitcnt lgkmcnt(0)
	s_barrier
	s_waitcnt lgkmcnt(0)
	v_mfma_f32_16x16x32_bf16 v[134:137], v[154:157], v[170:173], v[134:137]
	v_mfma_f32_16x16x32_bf16 v[130:133], v[162:165], v[170:173], v[130:133]
	v_mfma_f32_16x16x32_bf16 v[118:121], v[154:157], v[178:181], v[118:121]
	v_mfma_f32_16x16x32_bf16 v[114:117], v[162:165], v[178:181], v[114:117]
	v_mfma_f32_16x16x32_bf16 v[102:105], v[154:157], v[186:189], v[102:105]
	v_mfma_f32_16x16x32_bf16 v[98:101], v[162:165], v[186:189], v[98:101]
	v_mfma_f32_16x16x32_bf16 v[86:89], v[154:157], v[194:197], v[86:89]
	v_mfma_f32_16x16x32_bf16 v[82:85], v[162:165], v[194:197], v[82:85]
	v_mfma_f32_16x16x32_bf16 v[134:137], v[158:161], v[174:177], v[134:137]
	v_mfma_f32_16x16x32_bf16 v[130:133], v[166:169], v[174:177], v[130:133]
	v_mfma_f32_16x16x32_bf16 v[118:121], v[158:161], v[182:185], v[118:121]
	v_mfma_f32_16x16x32_bf16 v[114:117], v[166:169], v[182:185], v[114:117]
	v_mfma_f32_16x16x32_bf16 v[102:105], v[158:161], v[190:193], v[102:105]
	v_mfma_f32_16x16x32_bf16 v[98:101], v[166:169], v[190:193], v[98:101]
	v_mfma_f32_16x16x32_bf16 v[86:89], v[158:161], v[198:201], v[86:89]
	v_mfma_f32_16x16x32_bf16 v[82:85], v[166:169], v[198:201], v[82:85]
	v_mfma_f32_16x16x32_bf16 v[126:129], v[138:141], v[170:173], v[126:129]
	v_mfma_f32_16x16x32_bf16 v[122:125], v[146:149], v[170:173], v[122:125]
	v_mfma_f32_16x16x32_bf16 v[110:113], v[138:141], v[178:181], v[110:113]
	v_mfma_f32_16x16x32_bf16 v[106:109], v[146:149], v[178:181], v[106:109]
	v_mfma_f32_16x16x32_bf16 v[94:97], v[138:141], v[186:189], v[94:97]
	v_mfma_f32_16x16x32_bf16 v[90:93], v[146:149], v[186:189], v[90:93]
	v_mfma_f32_16x16x32_bf16 v[78:81], v[138:141], v[194:197], v[78:81]
	v_mfma_f32_16x16x32_bf16 v[74:77], v[146:149], v[194:197], v[74:77]
	v_mfma_f32_16x16x32_bf16 v[126:129], v[142:145], v[174:177], v[126:129]
	v_mfma_f32_16x16x32_bf16 v[122:125], v[150:153], v[174:177], v[122:125]
	v_mfma_f32_16x16x32_bf16 v[110:113], v[142:145], v[182:185], v[110:113]
	v_mfma_f32_16x16x32_bf16 v[106:109], v[150:153], v[182:185], v[106:109]
	v_mfma_f32_16x16x32_bf16 v[94:97], v[142:145], v[190:193], v[94:97]
	v_mfma_f32_16x16x32_bf16 v[90:93], v[150:153], v[190:193], v[90:93]
	v_mfma_f32_16x16x32_bf16 v[78:81], v[142:145], v[198:201], v[78:81]
	v_mfma_f32_16x16x32_bf16 v[74:77], v[150:153], v[198:201], v[74:77]
	s_barrier
	ds_read_b128 v[194:197], v230 offset:16384
	ds_read_b128 v[198:201], v230 offset:17408
	ds_read_b128 v[186:189], v230 offset:18432
	ds_read_b128 v[190:193], v230 offset:19456
	ds_read_b128 v[178:181], v230 offset:20480
	ds_read_b128 v[182:185], v230 offset:21504
	ds_read_b128 v[170:173], v230 offset:22528
	ds_read_b128 v[174:177], v230 offset:23552
	s_or_b64 s[28:29], s[20:21], s[28:29]
	s_xor_b64 s[30:31], s[28:29], -1
	s_mov_b64 s[34:35], -1
	s_and_b64 vcc, exec, s[30:31]
	s_cbranch_vccz .LBB0_496
	s_waitcnt vmcnt(2)
	s_mov_b64 s[34:35], 0

.LBB0_498:
	s_waitcnt lgkmcnt(0)
	s_barrier
	s_waitcnt lgkmcnt(0)
	v_mfma_f32_16x16x32_bf16 v[70:73], v[154:157], v[194:197], v[70:73]
	v_mfma_f32_16x16x32_bf16 v[66:69], v[162:165], v[194:197], v[66:69]
	v_mfma_f32_16x16x32_bf16 v[54:57], v[154:157], v[186:189], v[54:57]
	v_mfma_f32_16x16x32_bf16 v[50:53], v[162:165], v[186:189], v[50:53]
	v_mfma_f32_16x16x32_bf16 v[34:37], v[154:157], v[178:181], v[34:37]
	v_mfma_f32_16x16x32_bf16 v[30:33], v[162:165], v[178:181], v[30:33]
	v_mfma_f32_16x16x32_bf16 v[18:21], v[154:157], v[170:173], v[18:21]
	v_mfma_f32_16x16x32_bf16 v[14:17], v[162:165], v[170:173], v[14:17]
	v_mfma_f32_16x16x32_bf16 v[70:73], v[158:161], v[198:201], v[70:73]
	v_mfma_f32_16x16x32_bf16 v[66:69], v[166:169], v[198:201], v[66:69]
	v_mfma_f32_16x16x32_bf16 v[54:57], v[158:161], v[190:193], v[54:57]
	v_mfma_f32_16x16x32_bf16 v[50:53], v[166:169], v[190:193], v[50:53]
	v_mfma_f32_16x16x32_bf16 v[34:37], v[158:161], v[182:185], v[34:37]
	v_mfma_f32_16x16x32_bf16 v[30:33], v[166:169], v[182:185], v[30:33]
	v_mfma_f32_16x16x32_bf16 v[18:21], v[158:161], v[174:177], v[18:21]
	v_mfma_f32_16x16x32_bf16 v[14:17], v[166:169], v[174:177], v[14:17]
	v_mfma_f32_16x16x32_bf16 v[62:65], v[138:141], v[194:197], v[62:65]
	v_mfma_f32_16x16x32_bf16 v[58:61], v[146:149], v[194:197], v[58:61]
	v_mfma_f32_16x16x32_bf16 v[46:49], v[138:141], v[186:189], v[46:49]
	v_mfma_f32_16x16x32_bf16 v[42:45], v[146:149], v[186:189], v[42:45]
	v_mfma_f32_16x16x32_bf16 v[26:29], v[138:141], v[178:181], v[26:29]
	v_mfma_f32_16x16x32_bf16 v[22:25], v[146:149], v[178:181], v[22:25]
	v_mfma_f32_16x16x32_bf16 v[10:13], v[138:141], v[170:173], v[10:13]
	v_mfma_f32_16x16x32_bf16 v[6:9], v[146:149], v[170:173], v[6:9]
	v_mfma_f32_16x16x32_bf16 v[62:65], v[142:145], v[198:201], v[62:65]
	v_mfma_f32_16x16x32_bf16 v[58:61], v[150:153], v[198:201], v[58:61]
	v_mfma_f32_16x16x32_bf16 v[46:49], v[142:145], v[190:193], v[46:49]
	v_mfma_f32_16x16x32_bf16 v[42:45], v[150:153], v[190:193], v[42:45]
	v_mfma_f32_16x16x32_bf16 v[26:29], v[142:145], v[182:185], v[26:29]
	v_mfma_f32_16x16x32_bf16 v[22:25], v[150:153], v[182:185], v[22:25]
	v_mfma_f32_16x16x32_bf16 v[10:13], v[142:145], v[174:177], v[10:13]
	v_mfma_f32_16x16x32_bf16 v[6:9], v[150:153], v[174:177], v[6:9]
	s_barrier
	v_add_u32_e32 v138, 0x18000, v229
	v_add_u32_e32 v150, 0x1c000, v229
	ds_read_b128 v[154:157], v138
	ds_read_b128 v[158:161], v138 offset:1024
	ds_read_b128 v[162:165], v138 offset:2048
	ds_read_b128 v[166:169], v138 offset:3072
	ds_read_b128 v[138:141], v150
	ds_read_b128 v[142:145], v150 offset:1024
	ds_read_b128 v[146:149], v150 offset:2048
	ds_read_b128 v[150:153], v150 offset:3072
	ds_read_b128 v[194:197], v230 offset:32768
	ds_read_b128 v[198:201], v230 offset:33792
	ds_read_b128 v[186:189], v230 offset:34816
	ds_read_b128 v[190:193], v230 offset:35840
	ds_read_b128 v[178:181], v230 offset:36864
	ds_read_b128 v[182:185], v230 offset:37888
	ds_read_b128 v[170:173], v230 offset:38912
	ds_read_b128 v[174:177], v230 offset:39936
	s_mov_b64 s[34:35], -1
	s_and_b64 vcc, exec, s[30:31]
	s_cbranch_vccz .LBB0_500
	s_waitcnt vmcnt(0)
	s_mov_b64 s[34:35], 0

.LBB0_502:
	s_waitcnt lgkmcnt(0)
	s_barrier
	s_waitcnt lgkmcnt(0)
	v_mfma_f32_16x16x32_bf16 v[134:137], v[154:157], v[194:197], v[134:137]
	v_mfma_f32_16x16x32_bf16 v[130:133], v[162:165], v[194:197], v[130:133]
	v_mfma_f32_16x16x32_bf16 v[118:121], v[154:157], v[186:189], v[118:121]
	v_mfma_f32_16x16x32_bf16 v[114:117], v[162:165], v[186:189], v[114:117]
	v_mfma_f32_16x16x32_bf16 v[102:105], v[154:157], v[178:181], v[102:105]
	v_mfma_f32_16x16x32_bf16 v[98:101], v[162:165], v[178:181], v[98:101]
	v_mfma_f32_16x16x32_bf16 v[86:89], v[154:157], v[170:173], v[86:89]
	v_mfma_f32_16x16x32_bf16 v[82:85], v[162:165], v[170:173], v[82:85]
	v_mfma_f32_16x16x32_bf16 v[134:137], v[158:161], v[198:201], v[134:137]
	v_mfma_f32_16x16x32_bf16 v[130:133], v[166:169], v[198:201], v[130:133]
	v_mfma_f32_16x16x32_bf16 v[118:121], v[158:161], v[190:193], v[118:121]
	v_mfma_f32_16x16x32_bf16 v[114:117], v[166:169], v[190:193], v[114:117]
	v_mfma_f32_16x16x32_bf16 v[102:105], v[158:161], v[182:185], v[102:105]
	v_mfma_f32_16x16x32_bf16 v[98:101], v[166:169], v[182:185], v[98:101]
	v_mfma_f32_16x16x32_bf16 v[86:89], v[158:161], v[174:177], v[86:89]
	v_mfma_f32_16x16x32_bf16 v[82:85], v[166:169], v[174:177], v[82:85]
	v_mfma_f32_16x16x32_bf16 v[126:129], v[138:141], v[194:197], v[126:129]
	v_mfma_f32_16x16x32_bf16 v[122:125], v[146:149], v[194:197], v[122:125]
	v_mfma_f32_16x16x32_bf16 v[110:113], v[138:141], v[186:189], v[110:113]
	v_mfma_f32_16x16x32_bf16 v[106:109], v[146:149], v[186:189], v[106:109]
	v_mfma_f32_16x16x32_bf16 v[94:97], v[138:141], v[178:181], v[94:97]
	v_mfma_f32_16x16x32_bf16 v[90:93], v[146:149], v[178:181], v[90:93]
	v_mfma_f32_16x16x32_bf16 v[78:81], v[138:141], v[170:173], v[78:81]
	v_mfma_f32_16x16x32_bf16 v[74:77], v[146:149], v[170:173], v[74:77]
	v_mfma_f32_16x16x32_bf16 v[126:129], v[142:145], v[198:201], v[126:129]
	v_mfma_f32_16x16x32_bf16 v[122:125], v[150:153], v[198:201], v[122:125]
	v_mfma_f32_16x16x32_bf16 v[110:113], v[142:145], v[190:193], v[110:113]
	v_mfma_f32_16x16x32_bf16 v[106:109], v[150:153], v[190:193], v[106:109]
	v_mfma_f32_16x16x32_bf16 v[94:97], v[142:145], v[182:185], v[94:97]
	v_mfma_f32_16x16x32_bf16 v[90:93], v[150:153], v[182:185], v[90:93]
	v_mfma_f32_16x16x32_bf16 v[78:81], v[142:145], v[174:177], v[78:81]
	v_mfma_f32_16x16x32_bf16 v[74:77], v[150:153], v[174:177], v[74:77]
	s_barrier
	ds_read_b128 v[194:197], v230 offset:49152
	ds_read_b128 v[198:201], v230 offset:50176
	ds_read_b128 v[186:189], v230 offset:51200
	ds_read_b128 v[190:193], v230 offset:52224
	ds_read_b128 v[178:181], v230 offset:53248
	ds_read_b128 v[182:185], v230 offset:54272
	ds_read_b128 v[170:173], v230 offset:55296
	ds_read_b128 v[174:177], v230 offset:56320
	s_andn2_b64 vcc, exec, s[28:29]
	s_cbranch_vccnz .LBB0_493
	s_mov_b32 m0, s48
	v_lshl_add_u64 v[226:227], v[226:227], 0, s[68:69]
	s_add_u32 s24, s24, 0x10080
	global_load_lds_dwordx4 v[226:227], off
	v_lshl_add_u64 v[224:225], v[224:225], 0, s[68:69]
	s_mov_b32 m0, s49
	s_addc_u32 s25, s25, 0
	global_load_lds_dwordx4 v[224:225], off
	v_lshl_add_u64 v[224:225], s[24:25], 0, v[204:205]
	s_mov_b32 m0, s52
	v_lshl_add_u64 v[222:223], v[222:223], 0, s[68:69]
	global_load_lds_dwordx4 v[224:225], off
	v_lshl_add_u64 v[224:225], s[24:25], 0, v[2:3]
	s_mov_b32 m0, s53
	v_lshl_add_u64 v[220:221], v[220:221], 0, s[68:69]
	global_load_lds_dwordx4 v[224:225], off
	s_mov_b32 m0, s50
	s_nop 0
	global_load_lds_dwordx4 v[222:223], off
	s_mov_b32 m0, s51
	s_nop 0
	global_load_lds_dwordx4 v[220:221], off
	s_waitcnt vmcnt(8)
	s_branch .LBB0_493

.LBB0_520:
	s_waitcnt lgkmcnt(0)
	s_add_i32 s40, s40, 2
	s_barrier
	s_waitcnt lgkmcnt(0)
	v_mfma_f32_16x16x32_bf16 v[66:69], v[150:153], v[190:193], v[66:69]
	v_mfma_f32_16x16x32_bf16 v[62:65], v[158:161], v[190:193], v[62:65]
	v_mfma_f32_16x16x32_bf16 v[50:53], v[150:153], v[182:185], v[50:53]
	v_mfma_f32_16x16x32_bf16 v[46:49], v[158:161], v[182:185], v[46:49]
	v_mfma_f32_16x16x32_bf16 v[34:37], v[150:153], v[174:177], v[34:37]
	v_mfma_f32_16x16x32_bf16 v[30:33], v[158:161], v[174:177], v[30:33]
	v_mfma_f32_16x16x32_bf16 v[18:21], v[150:153], v[166:169], v[18:21]
	v_mfma_f32_16x16x32_bf16 v[14:17], v[158:161], v[166:169], v[14:17]
	v_mfma_f32_16x16x32_bf16 v[66:69], v[154:157], v[194:197], v[66:69]
	v_mfma_f32_16x16x32_bf16 v[62:65], v[162:165], v[194:197], v[62:65]
	v_mfma_f32_16x16x32_bf16 v[50:53], v[154:157], v[186:189], v[50:53]
	v_mfma_f32_16x16x32_bf16 v[46:49], v[162:165], v[186:189], v[46:49]
	v_mfma_f32_16x16x32_bf16 v[34:37], v[154:157], v[178:181], v[34:37]
	v_mfma_f32_16x16x32_bf16 v[30:33], v[162:165], v[178:181], v[30:33]
	v_mfma_f32_16x16x32_bf16 v[18:21], v[154:157], v[170:173], v[18:21]
	v_mfma_f32_16x16x32_bf16 v[14:17], v[162:165], v[170:173], v[14:17]
	v_mfma_f32_16x16x32_bf16 v[58:61], v[134:137], v[190:193], v[58:61]
	v_mfma_f32_16x16x32_bf16 v[54:57], v[142:145], v[190:193], v[54:57]
	v_mfma_f32_16x16x32_bf16 v[42:45], v[134:137], v[182:185], v[42:45]
	v_mfma_f32_16x16x32_bf16 v[38:41], v[142:145], v[182:185], v[38:41]
	v_mfma_f32_16x16x32_bf16 v[26:29], v[134:137], v[174:177], v[26:29]
	v_mfma_f32_16x16x32_bf16 v[22:25], v[142:145], v[174:177], v[22:25]
	v_mfma_f32_16x16x32_bf16 v[10:13], v[134:137], v[166:169], v[10:13]
	v_mfma_f32_16x16x32_bf16 v[6:9], v[142:145], v[166:169], v[6:9]
	v_mfma_f32_16x16x32_bf16 v[58:61], v[138:141], v[194:197], v[58:61]
	v_mfma_f32_16x16x32_bf16 v[54:57], v[146:149], v[194:197], v[54:57]
	v_mfma_f32_16x16x32_bf16 v[42:45], v[138:141], v[186:189], v[42:45]
	v_mfma_f32_16x16x32_bf16 v[38:41], v[146:149], v[186:189], v[38:41]
	v_mfma_f32_16x16x32_bf16 v[26:29], v[138:141], v[178:181], v[26:29]
	v_mfma_f32_16x16x32_bf16 v[22:25], v[146:149], v[178:181], v[22:25]
	v_mfma_f32_16x16x32_bf16 v[10:13], v[138:141], v[170:173], v[10:13]
	v_mfma_f32_16x16x32_bf16 v[6:9], v[146:149], v[170:173], v[6:9]
	s_barrier
	s_add_u32 s12, s12, 0x100
	s_addc_u32 s13, s13, 0
	s_cmp_ge_i32 s40, s38
	s_cbranch_scc1 .LBB0_531
.LBB0_521:
	s_cmp_eq_u32 s39, s40
	s_cselect_b64 s[6:7], -1, 0
	s_cmp_lg_u32 s39, s40
	s_cselect_b64 s[16:17], -1, 0
	s_add_u32 s14, s12, 0xfffc0080
	v_add_u32_e32 v134, 0x10000, v217
	v_add_u32_e32 v146, 0x14000, v217
	s_addc_u32 s15, s13, -1
	ds_read_b128 v[150:153], v134
	ds_read_b128 v[154:157], v134 offset:1024
	ds_read_b128 v[158:161], v134 offset:2048
	ds_read_b128 v[162:165], v134 offset:3072
	ds_read_b128 v[134:137], v146
	ds_read_b128 v[138:141], v146 offset:1024
	ds_read_b128 v[142:145], v146 offset:2048
	ds_read_b128 v[146:149], v146 offset:3072
	s_and_b64 vcc, s[6:7], exec
	s_cselect_b32 s7, 0, s14
	s_cselect_b32 s6, 0, s15
	s_add_u32 s18, s8, s7
	s_addc_u32 s19, s9, s6
	s_add_u32 s14, s10, s7
	s_addc_u32 s15, s11, s6
	v_lshl_add_u64 v[208:209], v[204:205], 0, s[12:13]
	s_add_i32 m0, s22, 0xc000
	ds_read_b128 v[166:169], v218
	ds_read_b128 v[170:173], v218 offset:1024
	ds_read_b128 v[174:177], v218 offset:2048
	ds_read_b128 v[178:181], v218 offset:3072
	ds_read_b128 v[182:185], v218 offset:4096
	ds_read_b128 v[186:189], v218 offset:5120
	ds_read_b128 v[190:193], v218 offset:6144
	ds_read_b128 v[194:197], v218 offset:7168
	global_load_lds_dwordx4 v[208:209], off
	v_lshl_add_u64 v[208:209], v[206:207], 0, s[12:13]
	s_add_i32 m0, s22, 0xe000
	s_nop 0
	global_load_lds_dwordx4 v[208:209], off
	s_waitcnt vmcnt(8)
	s_waitcnt lgkmcnt(0)
	s_barrier
	s_waitcnt lgkmcnt(0)
	v_mfma_f32_16x16x32_bf16 v[130:133], v[150:153], v[166:169], v[130:133]
	v_mfma_f32_16x16x32_bf16 v[126:129], v[158:161], v[166:169], v[126:129]
	v_mfma_f32_16x16x32_bf16 v[114:117], v[150:153], v[174:177], v[114:117]
	v_mfma_f32_16x16x32_bf16 v[110:113], v[158:161], v[174:177], v[110:113]
	v_mfma_f32_16x16x32_bf16 v[98:101], v[150:153], v[182:185], v[98:101]
	v_mfma_f32_16x16x32_bf16 v[94:97], v[158:161], v[182:185], v[94:97]
	v_mfma_f32_16x16x32_bf16 v[82:85], v[150:153], v[190:193], v[82:85]
	v_mfma_f32_16x16x32_bf16 v[78:81], v[158:161], v[190:193], v[78:81]
	v_mfma_f32_16x16x32_bf16 v[130:133], v[154:157], v[170:173], v[130:133]
	v_mfma_f32_16x16x32_bf16 v[126:129], v[162:165], v[170:173], v[126:129]
	v_mfma_f32_16x16x32_bf16 v[114:117], v[154:157], v[178:181], v[114:117]
	v_mfma_f32_16x16x32_bf16 v[110:113], v[162:165], v[178:181], v[110:113]
	v_mfma_f32_16x16x32_bf16 v[98:101], v[154:157], v[186:189], v[98:101]
	v_mfma_f32_16x16x32_bf16 v[94:97], v[162:165], v[186:189], v[94:97]
	v_mfma_f32_16x16x32_bf16 v[82:85], v[154:157], v[194:197], v[82:85]
	v_mfma_f32_16x16x32_bf16 v[78:81], v[162:165], v[194:197], v[78:81]
	v_mfma_f32_16x16x32_bf16 v[122:125], v[134:137], v[166:169], v[122:125]
	v_mfma_f32_16x16x32_bf16 v[118:121], v[142:145], v[166:169], v[118:121]
	v_mfma_f32_16x16x32_bf16 v[106:109], v[134:137], v[174:177], v[106:109]
	v_mfma_f32_16x16x32_bf16 v[102:105], v[142:145], v[174:177], v[102:105]
	v_mfma_f32_16x16x32_bf16 v[90:93], v[134:137], v[182:185], v[90:93]
	v_mfma_f32_16x16x32_bf16 v[86:89], v[142:145], v[182:185], v[86:89]
	v_mfma_f32_16x16x32_bf16 v[74:77], v[134:137], v[190:193], v[74:77]
	v_mfma_f32_16x16x32_bf16 v[70:73], v[142:145], v[190:193], v[70:73]
	v_mfma_f32_16x16x32_bf16 v[122:125], v[138:141], v[170:173], v[122:125]
	v_mfma_f32_16x16x32_bf16 v[118:121], v[146:149], v[170:173], v[118:121]
	v_mfma_f32_16x16x32_bf16 v[106:109], v[138:141], v[178:181], v[106:109]
	v_mfma_f32_16x16x32_bf16 v[102:105], v[146:149], v[178:181], v[102:105]
	v_mfma_f32_16x16x32_bf16 v[90:93], v[138:141], v[186:189], v[90:93]
	v_mfma_f32_16x16x32_bf16 v[86:89], v[146:149], v[186:189], v[86:89]
	v_mfma_f32_16x16x32_bf16 v[74:77], v[138:141], v[194:197], v[74:77]
	v_mfma_f32_16x16x32_bf16 v[70:73], v[146:149], v[194:197], v[70:73]
	s_barrier
	ds_read_b128 v[190:193], v218 offset:16384
	ds_read_b128 v[194:197], v218 offset:17408
	ds_read_b128 v[182:185], v218 offset:18432
	ds_read_b128 v[186:189], v218 offset:19456
	ds_read_b128 v[174:177], v218 offset:20480
	ds_read_b128 v[178:181], v218 offset:21504
	ds_read_b128 v[166:169], v218 offset:22528
	ds_read_b128 v[170:173], v218 offset:23552
	s_mov_b64 s[6:7], -1
	v_lshl_add_u64 v[214:215], s[14:15], 0, v[200:201]
	v_lshl_add_u64 v[212:213], s[14:15], 0, v[2:3]
	v_lshl_add_u64 v[210:211], s[18:19], 0, v[202:203]
	v_lshl_add_u64 v[208:209], s[18:19], 0, v[198:199]
	s_cbranch_vccnz .LBB0_523
	s_mov_b32 m0, s23
	s_add_u32 s6, s14, 0x10000
	global_load_lds_dwordx4 v[214:215], off
	s_mov_b32 m0, s24
	s_addc_u32 s7, s15, 0
	global_load_lds_dwordx4 v[212:213], off
	v_lshl_add_u64 v[220:221], s[6:7], 0, v[200:201]
	s_mov_b32 m0, s25
	s_nop 0
	global_load_lds_dwordx4 v[220:221], off
	v_lshl_add_u64 v[220:221], s[6:7], 0, v[2:3]
	s_mov_b32 m0, s26
	s_mov_b64 s[6:7], 0
	global_load_lds_dwordx4 v[220:221], off
	s_mov_b32 m0, s22
	s_nop 0
	global_load_lds_dwordx4 v[210:211], off
	s_mov_b32 m0, s27
	s_nop 0
	global_load_lds_dwordx4 v[208:209], off
	s_waitcnt vmcnt(8)

.LBB0_525:
	s_waitcnt lgkmcnt(0)
	s_barrier
	s_waitcnt lgkmcnt(0)
	v_mfma_f32_16x16x32_bf16 v[66:69], v[150:153], v[190:193], v[66:69]
	v_mfma_f32_16x16x32_bf16 v[62:65], v[158:161], v[190:193], v[62:65]
	v_mfma_f32_16x16x32_bf16 v[50:53], v[150:153], v[182:185], v[50:53]
	v_mfma_f32_16x16x32_bf16 v[46:49], v[158:161], v[182:185], v[46:49]
	v_mfma_f32_16x16x32_bf16 v[34:37], v[150:153], v[174:177], v[34:37]
	v_mfma_f32_16x16x32_bf16 v[30:33], v[158:161], v[174:177], v[30:33]
	v_mfma_f32_16x16x32_bf16 v[18:21], v[150:153], v[166:169], v[18:21]
	v_mfma_f32_16x16x32_bf16 v[14:17], v[158:161], v[166:169], v[14:17]
	v_mfma_f32_16x16x32_bf16 v[66:69], v[154:157], v[194:197], v[66:69]
	v_mfma_f32_16x16x32_bf16 v[62:65], v[162:165], v[194:197], v[62:65]
	v_mfma_f32_16x16x32_bf16 v[50:53], v[154:157], v[186:189], v[50:53]
	v_mfma_f32_16x16x32_bf16 v[46:49], v[162:165], v[186:189], v[46:49]
	v_mfma_f32_16x16x32_bf16 v[34:37], v[154:157], v[178:181], v[34:37]
	v_mfma_f32_16x16x32_bf16 v[30:33], v[162:165], v[178:181], v[30:33]
	v_mfma_f32_16x16x32_bf16 v[18:21], v[154:157], v[170:173], v[18:21]
	v_mfma_f32_16x16x32_bf16 v[14:17], v[162:165], v[170:173], v[14:17]
	v_mfma_f32_16x16x32_bf16 v[58:61], v[134:137], v[190:193], v[58:61]
	v_mfma_f32_16x16x32_bf16 v[54:57], v[142:145], v[190:193], v[54:57]
	v_mfma_f32_16x16x32_bf16 v[42:45], v[134:137], v[182:185], v[42:45]
	v_mfma_f32_16x16x32_bf16 v[38:41], v[142:145], v[182:185], v[38:41]
	v_mfma_f32_16x16x32_bf16 v[26:29], v[134:137], v[174:177], v[26:29]
	v_mfma_f32_16x16x32_bf16 v[22:25], v[142:145], v[174:177], v[22:25]
	v_mfma_f32_16x16x32_bf16 v[10:13], v[134:137], v[166:169], v[10:13]
	v_mfma_f32_16x16x32_bf16 v[6:9], v[142:145], v[166:169], v[6:9]
	v_mfma_f32_16x16x32_bf16 v[58:61], v[138:141], v[194:197], v[58:61]
	v_mfma_f32_16x16x32_bf16 v[54:57], v[146:149], v[194:197], v[54:57]
	v_mfma_f32_16x16x32_bf16 v[42:45], v[138:141], v[186:189], v[42:45]
	v_mfma_f32_16x16x32_bf16 v[38:41], v[146:149], v[186:189], v[38:41]
	v_mfma_f32_16x16x32_bf16 v[26:29], v[138:141], v[178:181], v[26:29]
	v_mfma_f32_16x16x32_bf16 v[22:25], v[146:149], v[178:181], v[22:25]
	v_mfma_f32_16x16x32_bf16 v[10:13], v[138:141], v[170:173], v[10:13]
	v_mfma_f32_16x16x32_bf16 v[6:9], v[146:149], v[170:173], v[6:9]
	s_barrier
	v_add_u32_e32 v134, 0x18000, v217
	v_add_u32_e32 v146, 0x1c000, v217
	ds_read_b128 v[150:153], v134
	ds_read_b128 v[154:157], v134 offset:1024
	ds_read_b128 v[158:161], v134 offset:2048
	ds_read_b128 v[162:165], v134 offset:3072
	ds_read_b128 v[134:137], v146
	ds_read_b128 v[138:141], v146 offset:1024
	ds_read_b128 v[142:145], v146 offset:2048
	ds_read_b128 v[146:149], v146 offset:3072
	ds_read_b128 v[190:193], v218 offset:32768
	ds_read_b128 v[194:197], v218 offset:33792
	ds_read_b128 v[182:185], v218 offset:34816
	ds_read_b128 v[186:189], v218 offset:35840
	ds_read_b128 v[174:177], v218 offset:36864
	ds_read_b128 v[178:181], v218 offset:37888
	ds_read_b128 v[166:169], v218 offset:38912
	ds_read_b128 v[170:173], v218 offset:39936
	v_cndmask_b32_e64 v219, 0, 1, s[16:17]
	v_cmp_ne_u32_e64 s[6:7], 1, v219
	s_andn2_b64 vcc, exec, s[16:17]
	s_mov_b64 s[16:17], -1
	s_cbranch_vccnz .LBB0_527
	s_add_u32 s16, s18, 0x40000
	s_addc_u32 s17, s19, 0
	s_mov_b32 m0, s28
	v_lshl_add_u64 v[220:221], s[16:17], 0, v[202:203]
	global_load_lds_dwordx4 v[220:221], off
	v_lshl_add_u64 v[220:221], s[16:17], 0, v[198:199]
	s_mov_b32 m0, s29
	s_mov_b64 s[16:17], 0
	global_load_lds_dwordx4 v[220:221], off
	s_waitcnt vmcnt(8)

.LBB0_529:
	s_waitcnt lgkmcnt(0)
	s_barrier
	s_waitcnt lgkmcnt(0)
	v_mfma_f32_16x16x32_bf16 v[130:133], v[150:153], v[190:193], v[130:133]
	v_mfma_f32_16x16x32_bf16 v[126:129], v[158:161], v[190:193], v[126:129]
	v_mfma_f32_16x16x32_bf16 v[114:117], v[150:153], v[182:185], v[114:117]
	v_mfma_f32_16x16x32_bf16 v[110:113], v[158:161], v[182:185], v[110:113]
	v_mfma_f32_16x16x32_bf16 v[98:101], v[150:153], v[174:177], v[98:101]
	v_mfma_f32_16x16x32_bf16 v[94:97], v[158:161], v[174:177], v[94:97]
	v_mfma_f32_16x16x32_bf16 v[82:85], v[150:153], v[166:169], v[82:85]
	v_mfma_f32_16x16x32_bf16 v[78:81], v[158:161], v[166:169], v[78:81]
	v_mfma_f32_16x16x32_bf16 v[130:133], v[154:157], v[194:197], v[130:133]
	v_mfma_f32_16x16x32_bf16 v[126:129], v[162:165], v[194:197], v[126:129]
	v_mfma_f32_16x16x32_bf16 v[114:117], v[154:157], v[186:189], v[114:117]
	v_mfma_f32_16x16x32_bf16 v[110:113], v[162:165], v[186:189], v[110:113]
	v_mfma_f32_16x16x32_bf16 v[98:101], v[154:157], v[178:181], v[98:101]
	v_mfma_f32_16x16x32_bf16 v[94:97], v[162:165], v[178:181], v[94:97]
	v_mfma_f32_16x16x32_bf16 v[82:85], v[154:157], v[170:173], v[82:85]
	v_mfma_f32_16x16x32_bf16 v[78:81], v[162:165], v[170:173], v[78:81]
	v_mfma_f32_16x16x32_bf16 v[122:125], v[134:137], v[190:193], v[122:125]
	v_mfma_f32_16x16x32_bf16 v[118:121], v[142:145], v[190:193], v[118:121]
	v_mfma_f32_16x16x32_bf16 v[106:109], v[134:137], v[182:185], v[106:109]
	v_mfma_f32_16x16x32_bf16 v[102:105], v[142:145], v[182:185], v[102:105]
	v_mfma_f32_16x16x32_bf16 v[90:93], v[134:137], v[174:177], v[90:93]
	v_mfma_f32_16x16x32_bf16 v[86:89], v[142:145], v[174:177], v[86:89]
	v_mfma_f32_16x16x32_bf16 v[74:77], v[134:137], v[166:169], v[74:77]
	v_mfma_f32_16x16x32_bf16 v[70:73], v[142:145], v[166:169], v[70:73]
	v_mfma_f32_16x16x32_bf16 v[122:125], v[138:141], v[194:197], v[122:125]
	v_mfma_f32_16x16x32_bf16 v[118:121], v[146:149], v[194:197], v[118:121]
	v_mfma_f32_16x16x32_bf16 v[106:109], v[138:141], v[186:189], v[106:109]
	v_mfma_f32_16x16x32_bf16 v[102:105], v[146:149], v[186:189], v[102:105]
	v_mfma_f32_16x16x32_bf16 v[90:93], v[138:141], v[178:181], v[90:93]
	v_mfma_f32_16x16x32_bf16 v[86:89], v[146:149], v[178:181], v[86:89]
	v_mfma_f32_16x16x32_bf16 v[74:77], v[138:141], v[170:173], v[74:77]
	v_mfma_f32_16x16x32_bf16 v[70:73], v[146:149], v[170:173], v[70:73]
	s_barrier
	ds_read_b128 v[190:193], v218 offset:49152
	ds_read_b128 v[194:197], v218 offset:50176
	ds_read_b128 v[182:185], v218 offset:51200
	ds_read_b128 v[186:189], v218 offset:52224
	ds_read_b128 v[174:177], v218 offset:53248
	ds_read_b128 v[178:181], v218 offset:54272
	ds_read_b128 v[166:169], v218 offset:55296
	ds_read_b128 v[170:173], v218 offset:56320
	s_and_b64 vcc, exec, s[6:7]
	s_cbranch_vccnz .LBB0_520
	s_mov_b32 m0, s30
	v_lshl_add_u64 v[214:215], v[214:215], 0, s[68:69]
	s_add_u32 s6, s14, 0x10080
	global_load_lds_dwordx4 v[214:215], off
	v_lshl_add_u64 v[212:213], v[212:213], 0, s[68:69]
	s_mov_b32 m0, s31
	s_addc_u32 s7, s15, 0
	global_load_lds_dwordx4 v[212:213], off
	v_lshl_add_u64 v[212:213], s[6:7], 0, v[200:201]
	s_mov_b32 m0, s36
	v_lshl_add_u64 v[210:211], v[210:211], 0, s[68:69]
	global_load_lds_dwordx4 v[212:213], off
	v_lshl_add_u64 v[212:213], s[6:7], 0, v[2:3]
	s_mov_b32 m0, s37
	v_lshl_add_u64 v[208:209], v[208:209], 0, s[68:69]
	global_load_lds_dwordx4 v[212:213], off
	s_mov_b32 m0, s34
	s_nop 0
	global_load_lds_dwordx4 v[210:211], off
	s_mov_b32 m0, s35
	s_nop 0
	global_load_lds_dwordx4 v[208:209], off
	s_waitcnt vmcnt(8)
	s_branch .LBB0_520

.Lattn_join:
	v_and_b32_e32 v177, 0xffff0000, v90
	v_and_b32_e32 v179, 0xffff0000, v91
	v_add_f32_e32 v94, v94, v176
	v_lshlrev_b32_e32 v176, 16, v90
	v_lshlrev_b32_e32 v178, 16, v91
	v_mul_f32_e32 v183, v177, v177
	v_mul_f32_e32 v184, v179, v179
	v_and_b32_e32 v181, 0xffff0000, v92
	v_and_b32_e32 v186, 0xffff0000, v93
	v_fmac_f32_e32 v183, v176, v176
	v_fmac_f32_e32 v184, v178, v178
	v_lshlrev_b32_e32 v180, 16, v92
	v_lshlrev_b32_e32 v182, 16, v93
	v_add_f32_e32 v183, v183, v184
	v_mul_f32_e32 v184, v181, v181
	v_mul_f32_e32 v185, v186, v186
	v_fmac_f32_e32 v184, v180, v180
	v_fmac_f32_e32 v185, v182, v182
	v_add_f32_e32 v184, v184, v185
	v_add_f32_e32 v183, v183, v184
	v_add_f32_e32 v94, v94, v183
	v_mov_b32_e32 v183, v94
	s_nop 1
	v_permlane16_swap_b32_e32 v94, v183
	v_add_f32_e32 v94, v94, v183
	v_mov_b32_e32 v183, v94
	s_nop 1
	v_permlane32_swap_b32_e32 v94, v183
	v_add_f32_e32 v94, v94, v183
	v_fmamk_f32 v94, v94, 0x3c000000, v236
	v_rsq_f32_e32 v94, v94
	s_waitcnt lgkmcnt(0)
	s_barrier
	v_mul_f32_e32 v187, 0x3e0293ee, v94
	v_mul_f32_e32 v3, v187, v3
	v_mul_f32_e32 v2, v187, v2
	v_mul_f32_e32 v3, v15, v3
	v_mul_f32_e32 v2, v14, v2
	v_cvt_pk_bf16_f32 v94, v2, v3
	v_mul_f32_e32 v3, v187, v95
	v_mul_f32_e32 v2, v187, v5
	v_mul_f32_e32 v3, v17, v3
	v_mul_f32_e32 v2, v16, v2
	v_cvt_pk_bf16_f32 v95, v2, v3
	v_mul_f32_e32 v3, v187, v97
	v_mul_f32_e32 v2, v187, v96
	v_mul_f32_e32 v3, v19, v3
	v_mul_f32_e32 v2, v18, v2
	v_cvt_pk_bf16_f32 v96, v2, v3
	v_mul_f32_e32 v3, v187, v99
	v_mul_f32_e32 v2, v187, v98
	v_mul_f32_e32 v3, v21, v3
	v_mul_f32_e32 v2, v20, v2
	v_cvt_pk_bf16_f32 v97, v2, v3
	v_mul_f32_e32 v3, v187, v101
	v_mul_f32_e32 v2, v187, v100
	v_mul_f32_e32 v3, v23, v3
	v_mul_f32_e32 v2, v22, v2
	v_cvt_pk_bf16_f32 v98, v2, v3
	v_mul_f32_e32 v3, v187, v163
	v_mul_f32_e32 v2, v187, v162
	v_mul_f32_e32 v3, v25, v3
	v_mul_f32_e32 v2, v24, v2
	v_cvt_pk_bf16_f32 v99, v2, v3
	v_mul_f32_e32 v3, v187, v165
	v_mul_f32_e32 v2, v187, v164
	v_mul_f32_e32 v3, v27, v3
	v_mul_f32_e32 v2, v26, v2
	v_cvt_pk_bf16_f32 v100, v2, v3
	v_mul_f32_e32 v3, v187, v167
	v_mul_f32_e32 v2, v187, v166
	v_mul_f32_e32 v3, v29, v3
	v_mul_f32_e32 v2, v28, v2
	v_cvt_pk_bf16_f32 v101, v2, v3
	v_mul_f32_e32 v3, v187, v169
	v_mul_f32_e32 v2, v187, v168
	v_mul_f32_e32 v3, v31, v3
	v_mul_f32_e32 v2, v30, v2
	v_cvt_pk_bf16_f32 v162, v2, v3
	v_mul_f32_e32 v3, v187, v171
	v_mul_f32_e32 v2, v187, v170
	v_mul_f32_e32 v3, v33, v3
	v_mul_f32_e32 v2, v32, v2
	v_cvt_pk_bf16_f32 v163, v2, v3
	v_mul_f32_e32 v3, v187, v173
	v_mul_f32_e32 v2, v187, v172
	v_mul_f32_e32 v3, v35, v3
	v_mul_f32_e32 v2, v34, v2
	v_cvt_pk_bf16_f32 v164, v2, v3
	v_mul_f32_e32 v3, v187, v175
	v_mul_f32_e32 v2, v187, v174
	v_mul_f32_e32 v3, v37, v3
	v_mul_f32_e32 v2, v36, v2
	v_cvt_pk_bf16_f32 v165, v2, v3
	v_mul_f32_e32 v3, v187, v177
	v_mul_f32_e32 v2, v187, v176
	v_mul_f32_e32 v3, v39, v3
	v_mul_f32_e32 v2, v38, v2
	v_cvt_pk_bf16_f32 v166, v2, v3
	v_mul_f32_e32 v3, v187, v179
	v_mul_f32_e32 v2, v187, v178
	v_mul_f32_e32 v3, v41, v3
	v_mul_f32_e32 v2, v40, v2
	v_cvt_pk_bf16_f32 v167, v2, v3
	v_mul_f32_e32 v3, v187, v181
	v_mul_f32_e32 v2, v187, v180
	v_mul_f32_e32 v3, v43, v3
	v_mul_f32_e32 v2, v42, v2
	v_cvt_pk_bf16_f32 v168, v2, v3
	v_add_u32_e32 v3, s61, v161
	v_and_or_b32 v3, v3, s33, v143
	v_lshl_add_u32 v3, v3, 8, 0
	v_add_u32_e32 v5, v3, v126
	v_add_u32_e32 v169, v3, v127
	ds_read_b128 v[170:173], v5
	ds_read_b128 v[174:177], v169
	v_add_u32_e32 v5, v3, v128
	v_mul_f32_e32 v2, v187, v182
	v_add_u32_e32 v3, v3, v129
	ds_read_b128 v[178:181], v5
	ds_read_b128 v[182:185], v3
	s_lshl_b32 s50, s55, s58
	v_mul_f32_e32 v3, v187, v186
	s_add_i32 s52, s50, s56
	v_mul_f32_e32 v2, v44, v2
	v_mul_f32_e32 v3, v45, v3
	s_add_i32 s55, s55, 1
	v_cvt_pk_bf16_f32 v169, v2, v3
	s_waitcnt lgkmcnt(3)
	v_mfma_f32_16x16x32_bf16 v[170:173], v[170:173], v[94:97], 0
	s_waitcnt lgkmcnt(2)
	v_mfma_f32_16x16x32_bf16 v[170:173], v[174:177], v[98:101], v[170:173]
	s_waitcnt lgkmcnt(1)
	v_mfma_f32_16x16x32_bf16 v[170:173], v[178:181], v[162:165], v[170:173]
	s_waitcnt lgkmcnt(0)
	v_mfma_f32_16x16x32_bf16 v[170:173], v[182:185], v[166:169], v[170:173]
	v_add_u32_e32 v2, s61, v160
	v_and_or_b32 v2, v2, s33, v144
	v_lshl_add_u32 v2, v2, 8, 0
	v_add_u32_e32 v3, v2, v126
	v_add_u32_e32 v5, v2, v127
	ds_read_b128 v[174:177], v3
	ds_read_b128 v[178:181], v5
	v_add_u32_e32 v3, v2, v128
	v_add_u32_e32 v2, v2, v129
	ds_read_b128 v[182:185], v3
	ds_read_b128 v[186:189], v2
	s_waitcnt lgkmcnt(3)
	v_mfma_f32_16x16x32_bf16 v[174:177], v[174:177], v[94:97], 0
	s_waitcnt lgkmcnt(2)
	v_mfma_f32_16x16x32_bf16 v[174:177], v[178:181], v[98:101], v[174:177]
	s_waitcnt lgkmcnt(1)
	v_mfma_f32_16x16x32_bf16 v[174:177], v[182:185], v[162:165], v[174:177]
	s_waitcnt lgkmcnt(0)
	v_mfma_f32_16x16x32_bf16 v[174:177], v[186:189], v[166:169], v[174:177]
	v_add_u32_e32 v2, s61, v159
	v_and_or_b32 v2, v2, s33, v145
	v_lshl_add_u32 v2, v2, 8, 0
	v_add_u32_e32 v3, v2, v126
	v_add_u32_e32 v5, v2, v127
	ds_read_b128 v[178:181], v3
	ds_read_b128 v[182:185], v5
	v_add_u32_e32 v3, v2, v128
	v_add_u32_e32 v2, v2, v129
	ds_read_b128 v[186:189], v3
	ds_read_b128 v[190:193], v2
	s_waitcnt lgkmcnt(3)
	v_mfma_f32_16x16x32_bf16 v[178:181], v[178:181], v[94:97], 0
	s_waitcnt lgkmcnt(2)
	v_mfma_f32_16x16x32_bf16 v[178:181], v[182:185], v[98:101], v[178:181]
	s_waitcnt lgkmcnt(1)
	v_mfma_f32_16x16x32_bf16 v[178:181], v[186:189], v[162:165], v[178:181]
	s_waitcnt lgkmcnt(0)
	v_mfma_f32_16x16x32_bf16 v[178:181], v[190:193], v[166:169], v[178:181]
	v_add_u32_e32 v2, s61, v158
	v_and_or_b32 v2, v2, s33, v146
	v_lshl_add_u32 v2, v2, 8, 0
	v_add_u32_e32 v3, v2, v126
	v_add_u32_e32 v5, v2, v127
	ds_read_b128 v[182:185], v3
	ds_read_b128 v[186:189], v5
	v_add_u32_e32 v3, v2, v128
	v_add_u32_e32 v2, v2, v129
	ds_read_b128 v[190:193], v3
	ds_read_b128 v[194:197], v2
	s_waitcnt lgkmcnt(3)
	v_mfma_f32_16x16x32_bf16 v[182:185], v[182:185], v[94:97], 0
	s_waitcnt lgkmcnt(2)
	v_mfma_f32_16x16x32_bf16 v[182:185], v[186:189], v[98:101], v[182:185]
	s_waitcnt lgkmcnt(1)
	v_mfma_f32_16x16x32_bf16 v[182:185], v[190:193], v[162:165], v[182:185]
	s_waitcnt lgkmcnt(0)
	v_mfma_f32_16x16x32_bf16 v[192:195], v[194:197], v[166:169], v[182:185]
	v_add_u32_e32 v2, s61, v157
	v_and_or_b32 v2, v2, s33, v147
	v_lshl_add_u32 v2, v2, 8, 0
	v_add_u32_e32 v3, v2, v126
	v_add_u32_e32 v5, v2, v127
	ds_read_b128 v[182:185], v3
	ds_read_b128 v[186:189], v5
	v_add_u32_e32 v3, v2, v128
	v_add_u32_e32 v2, v2, v129
	ds_read_b128 v[196:199], v3
	ds_read_b128 v[200:203], v2
	s_waitcnt lgkmcnt(3)
	v_mfma_f32_16x16x32_bf16 v[182:185], v[182:185], v[94:97], 0
	s_waitcnt lgkmcnt(2)
	v_mfma_f32_16x16x32_bf16 v[182:185], v[186:189], v[98:101], v[182:185]
	s_waitcnt lgkmcnt(1)
	v_mfma_f32_16x16x32_bf16 v[182:185], v[196:199], v[162:165], v[182:185]
	s_waitcnt lgkmcnt(0)
	v_mfma_f32_16x16x32_bf16 v[196:199], v[200:203], v[166:169], v[182:185]
	v_add_u32_e32 v2, s61, v156
	v_and_or_b32 v2, v2, s33, v148
	v_lshl_add_u32 v2, v2, 8, 0
	v_add_u32_e32 v3, v2, v126
	v_add_u32_e32 v5, v2, v127
	ds_read_b128 v[182:185], v3
	ds_read_b128 v[186:189], v5
	v_add_u32_e32 v3, v2, v128
	v_add_u32_e32 v2, v2, v129
	ds_read_b128 v[200:203], v3
	ds_read_b128 v[204:207], v2
	s_waitcnt lgkmcnt(3)
	v_mfma_f32_16x16x32_bf16 v[182:185], v[182:185], v[94:97], 0
	s_waitcnt lgkmcnt(2)
	v_mfma_f32_16x16x32_bf16 v[182:185], v[186:189], v[98:101], v[182:185]
	s_waitcnt lgkmcnt(1)
	v_mfma_f32_16x16x32_bf16 v[182:185], v[200:203], v[162:165], v[182:185]
	s_waitcnt lgkmcnt(0)
	v_mfma_f32_16x16x32_bf16 v[200:203], v[204:207], v[166:169], v[182:185]
	v_add_u32_e32 v2, s61, v155
	v_and_or_b32 v2, v2, s33, v149
	v_lshl_add_u32 v2, v2, 8, 0
	v_add_u32_e32 v3, v2, v126
	v_add_u32_e32 v5, v2, v127
	ds_read_b128 v[182:185], v3
	ds_read_b128 v[186:189], v5
	v_add_u32_e32 v3, v2, v128
	v_add_u32_e32 v2, v2, v129
	ds_read_b128 v[204:207], v3
	ds_read_b128 v[208:211], v2
	s_waitcnt lgkmcnt(3)
	v_mfma_f32_16x16x32_bf16 v[182:185], v[182:185], v[94:97], 0
	s_waitcnt lgkmcnt(2)
	v_mfma_f32_16x16x32_bf16 v[182:185], v[186:189], v[98:101], v[182:185]
	s_waitcnt lgkmcnt(1)
	v_mfma_f32_16x16x32_bf16 v[182:185], v[204:207], v[162:165], v[182:185]
	s_waitcnt lgkmcnt(0)
	v_mfma_f32_16x16x32_bf16 v[204:207], v[208:211], v[166:169], v[182:185]
	v_add_u32_e32 v2, s61, v154
	v_and_or_b32 v2, v2, s33, v150
	v_lshl_add_u32 v2, v2, 8, 0
	v_add_u32_e32 v3, v2, v126
	v_add_u32_e32 v5, v2, v127
	ds_read_b128 v[182:185], v3
	ds_read_b128 v[186:189], v5
	v_add_u32_e32 v3, v2, v128
	v_add_u32_e32 v2, v2, v129
	ds_read_b128 v[208:211], v3
	ds_read_b128 v[212:215], v2
	s_waitcnt lgkmcnt(3)
	v_mfma_f32_16x16x32_bf16 v[182:185], v[182:185], v[94:97], 0
	s_waitcnt lgkmcnt(2)
	v_mfma_f32_16x16x32_bf16 v[182:185], v[186:189], v[98:101], v[182:185]
	s_waitcnt lgkmcnt(1)
	v_mfma_f32_16x16x32_bf16 v[182:185], v[208:211], v[162:165], v[182:185]
	s_waitcnt lgkmcnt(0)
	v_mfma_f32_16x16x32_bf16 v[208:211], v[212:215], v[166:169], v[182:185]
	v_add_u32_e32 v2, s61, v153
	v_and_or_b32 v2, v2, s33, v151
	v_lshl_add_u32 v2, v2, 8, 0
	v_add_u32_e32 v3, v2, v126
	v_add_u32_e32 v5, v2, v127
	ds_read_b128 v[182:185], v3
	ds_read_b128 v[186:189], v5
	v_add_u32_e32 v3, v2, v128
	v_add_u32_e32 v2, v2, v129
	ds_read_b128 v[212:215], v3
	ds_read_b128 v[216:219], v2
	s_waitcnt lgkmcnt(3)
	v_mfma_f32_16x16x32_bf16 v[94:97], v[182:185], v[94:97], 0
	s_waitcnt lgkmcnt(2)
	v_mfma_f32_16x16x32_bf16 v[94:97], v[186:189], v[98:101], v[94:97]
	s_waitcnt lgkmcnt(1)
	v_mfma_f32_16x16x32_bf16 v[94:97], v[212:215], v[162:165], v[94:97]
	s_waitcnt lgkmcnt(0)
	v_mfma_f32_16x16x32_bf16 v[94:97], v[216:219], v[166:169], v[94:97]
	s_cmp_eq_u32 s60, 0
	v_exp_f32_e32 v2, v170
	s_cselect_b64 s[50:51], -1, 0
	v_exp_f32_e32 v3, v171
	s_and_b64 s[64:65], s[14:15], s[50:51]
	s_or_b64 s[66:67], s[64:65], s[12:13]
	v_cndmask_b32_e64 v99, v2, 0, s[66:67]
	s_or_b64 s[66:67], s[64:65], s[16:17]
	v_cndmask_b32_e64 v163, v3, 0, s[66:67]
	v_exp_f32_e32 v3, v172
	v_exp_f32_e32 v5, v173
	s_or_b64 s[66:67], s[64:65], s[18:19]
	s_or_b64 s[64:65], s[64:65], s[20:21]
	v_cndmask_b32_e64 v165, v3, 0, s[66:67]
	v_exp_f32_e32 v3, v174
	v_cndmask_b32_e64 v169, v5, 0, s[64:65]
	v_exp_f32_e32 v5, v175
	s_and_b64 s[64:65], s[22:23], s[50:51]
	v_cndmask_b32_e64 v187, v3, 0, s[64:65]
	v_exp_f32_e32 v3, v176
	v_cndmask_b32_e64 v188, v5, 0, s[64:65]
	v_exp_f32_e32 v5, v177
	v_add_f32_e32 v2, 0, v99
	v_cndmask_b32_e64 v189, v3, 0, s[64:65]
	v_exp_f32_e32 v3, v178
	v_cndmask_b32_e64 v190, v5, 0, s[64:65]
	v_exp_f32_e32 v5, v179
	s_and_b64 s[64:65], s[24:25], s[50:51]
	v_cndmask_b32_e64 v179, v3, 0, s[64:65]
	v_exp_f32_e32 v3, v180
	v_cndmask_b32_e64 v180, v5, 0, s[64:65]
	v_exp_f32_e32 v5, v181
	v_add_f32_e32 v2, v163, v2
	v_cndmask_b32_e64 v181, v3, 0, s[64:65]
	v_exp_f32_e32 v3, v192
	v_cndmask_b32_e64 v182, v5, 0, s[64:65]
	v_exp_f32_e32 v5, v193
	s_and_b64 s[64:65], s[26:27], s[50:51]
	v_cndmask_b32_e64 v183, v3, 0, s[64:65]
	v_exp_f32_e32 v3, v194
	v_cndmask_b32_e64 v184, v5, 0, s[64:65]
	v_exp_f32_e32 v5, v195
	v_add_f32_e32 v2, v165, v2
	v_cndmask_b32_e64 v185, v3, 0, s[64:65]
	v_exp_f32_e32 v3, v196
	v_cndmask_b32_e64 v186, v5, 0, s[64:65]
	v_exp_f32_e32 v5, v197
	s_and_b64 s[64:65], s[28:29], s[50:51]
	v_cndmask_b32_e64 v171, v3, 0, s[64:65]
	v_exp_f32_e32 v3, v198
	v_cndmask_b32_e64 v172, v5, 0, s[64:65]
	v_exp_f32_e32 v5, v199
	v_add_f32_e32 v2, v169, v2
	v_add_f32_e32 v2, v2, v187
	v_add_f32_e32 v2, v188, v2
	v_cndmask_b32_e64 v173, v3, 0, s[64:65]
	v_exp_f32_e32 v3, v200
	v_add_f32_e32 v2, v189, v2
	v_cndmask_b32_e64 v174, v5, 0, s[64:65]
	v_exp_f32_e32 v5, v201
	v_add_f32_e32 v2, v190, v2
	v_add_f32_e32 v2, v2, v179
	s_and_b64 s[64:65], s[30:31], s[50:51]
	v_add_f32_e32 v2, v180, v2
	v_cndmask_b32_e64 v175, v3, 0, s[64:65]
	v_exp_f32_e32 v3, v202
	v_add_f32_e32 v2, v181, v2
	v_cndmask_b32_e64 v176, v5, 0, s[64:65]
	v_exp_f32_e32 v5, v203
	v_add_f32_e32 v2, v182, v2
	v_add_f32_e32 v2, v2, v183
	v_add_f32_e32 v2, v184, v2
	v_cndmask_b32_e64 v177, v3, 0, s[64:65]
	v_exp_f32_e32 v3, v204
	v_add_f32_e32 v2, v185, v2
	v_cndmask_b32_e64 v178, v5, 0, s[64:65]
	v_exp_f32_e32 v5, v205
	v_add_f32_e32 v2, v186, v2
	v_add_f32_e32 v2, v2, v171
	s_and_b64 s[64:65], s[34:35], s[50:51]
	v_add_f32_e32 v2, v172, v2
	v_cndmask_b32_e64 v100, v3, 0, s[64:65]
	v_exp_f32_e32 v3, v206
	v_add_f32_e32 v2, v173, v2
	v_cndmask_b32_e64 v101, v5, 0, s[64:65]
	v_exp_f32_e32 v5, v207
	v_add_f32_e32 v2, v174, v2
	v_add_f32_e32 v2, v2, v175
	v_add_f32_e32 v2, v176, v2
	v_cndmask_b32_e64 v162, v3, 0, s[64:65]
	v_exp_f32_e32 v3, v208
	v_add_f32_e32 v2, v177, v2
	v_cndmask_b32_e64 v164, v5, 0, s[64:65]
	v_exp_f32_e32 v5, v209
	v_add_f32_e32 v2, v178, v2
	v_add_f32_e32 v2, v2, v100
	s_and_b64 s[64:65], s[36:37], s[50:51]
	v_add_f32_e32 v2, v101, v2
	v_cndmask_b32_e64 v166, v3, 0, s[64:65]
	v_exp_f32_e32 v3, v210
	v_add_f32_e32 v2, v162, v2
	v_cndmask_b32_e64 v167, v5, 0, s[64:65]
	v_exp_f32_e32 v5, v211
	v_add_f32_e32 v2, v164, v2
	v_add_f32_e32 v2, v2, v166
	v_add_f32_e32 v2, v167, v2
	v_cndmask_b32_e64 v168, v3, 0, s[64:65]
	v_add_f32_e32 v2, v168, v2
	v_cndmask_b32_e64 v170, v5, 0, s[64:65]
	v_add_f32_e32 v3, v170, v2
	v_exp_f32_e32 v2, v94
	v_exp_f32_e32 v5, v95
	s_and_b64 s[50:51], s[38:39], s[50:51]
	s_or_b64 s[64:65], s[50:51], s[10:11]
	v_cndmask_b32_e64 v2, v2, 0, s[64:65]
	s_or_b64 s[64:65], s[50:51], s[40:41]
	v_add_f32_e32 v94, v3, v2
	v_cndmask_b32_e64 v3, v5, 0, s[64:65]
	v_exp_f32_e32 v5, v96
	v_exp_f32_e32 v95, v97
	s_or_b64 s[64:65], s[50:51], s[42:43]
	v_add_f32_e32 v94, v3, v94
	v_cndmask_b32_e64 v5, v5, 0, s[64:65]
	s_or_b64 s[50:51], s[50:51], s[44:45]
	v_add_f32_e32 v94, v5, v94
	v_cndmask_b32_e64 v98, v95, 0, s[50:51]
	v_add_f32_e32 v94, v98, v94
	v_mov_b32_e32 v95, v94
	s_nop 1
	v_permlane16_swap_b32_e32 v94, v95
	v_add_f32_e32 v96, v94, v95
	s_cmp_lt_u32 s55, s59
	v_mov_b32_e32 v97, v96
	s_cselect_b64 s[50:51], -1, 0
	s_cmp_ge_u32 s55, s59
	v_permlane32_swap_b32_e32 v96, v97
	s_cbranch_scc1 .LBB0_587
	s_add_i32 s53, s52, s57
	s_ashr_i32 s63, s53, 31
	s_add_u32 s64, s46, s53
	s_addc_u32 s65, s47, s63
	v_lshl_add_u64 v[46:47], s[64:65], 0, v[110:111]
	v_lshl_add_u64 v[54:55], s[64:65], 0, v[112:113]
	v_lshl_add_u64 v[62:63], s[64:65], 0, v[114:115]
	v_lshl_add_u64 v[70:71], s[64:65], 0, v[116:117]
	v_lshl_add_u64 v[78:79], s[64:65], 0, v[118:119]
	v_mad_u64_u32 v[50:51], s[66:67], v46, s77, v[108:109]
	v_mad_u64_u32 v[58:59], s[66:67], v54, s77, v[108:109]
	v_mad_u64_u32 v[66:67], s[66:67], v62, s77, v[108:109]
	v_mad_u64_u32 v[74:75], s[66:67], v70, s77, v[108:109]
	v_mad_u64_u32 v[90:91], s[64:65], v78, s77, v[104:105]
	v_mad_i32_i24 v51, v47, s77, v51
	v_mad_i32_i24 v59, v55, s77, v59
	v_mad_i32_i24 v67, v63, s77, v67
	v_mad_i32_i24 v75, v71, s77, v75
	v_mad_i32_i24 v91, v79, s77, v91
	global_load_dwordx4 v[46:49], v[50:51], off offset:1024
	s_nop 0
	global_load_dwordx4 v[50:53], v[50:51], off offset:2048
	s_nop 0
	global_load_dwordx4 v[54:57], v[58:59], off offset:1024
	s_nop 0
	global_load_dwordx4 v[58:61], v[58:59], off offset:2048
	s_nop 0
	global_load_dwordx4 v[62:65], v[66:67], off offset:1024
	s_nop 0
	global_load_dwordx4 v[66:69], v[66:67], off offset:2048
	s_nop 0
	global_load_dwordx4 v[70:73], v[74:75], off offset:1024
	s_nop 0
	global_load_dwordx4 v[74:77], v[74:75], off offset:2048
	s_nop 0
	global_load_dwordx4 v[78:81], v[90:91], off
	global_load_dwordx4 v[82:85], v[90:91], off offset:64
	global_load_dwordx4 v[86:89], v[90:91], off offset:128
	s_nop 0
	global_load_dwordx4 v[90:93], v[90:91], off offset:192
.LBB0_587:
	v_cvt_pk_bf16_f32 v192, v99, v163
	v_add_u32_e32 v99, s60, v161
	v_and_b32_e32 v99, 0x80, v99
	v_or3_b32 v99, v99, v152, v125
	v_cvt_pk_bf16_f32 v194, v187, v188
	v_lshl_add_u32 v187, v99, 8, s54
	v_lshlrev_b32_e32 v99, 1, v152
	v_cvt_pk_bf16_f32 v193, v165, v169
	v_add_u32_e32 v163, s60, v160
	v_and_b32_e32 v169, 12, v99
	v_and_b32_e32 v163, 0x80, v163
	v_bitop3_b32 v99, v169, v120, v121 bitop3:0x36
	v_or3_b32 v163, v163, v152, v130
	v_lshlrev_b32_e32 v99, 4, v99
	v_lshl_add_u32 v216, v163, 8, s54
	v_add_u32_e32 v163, v187, v99
	v_add_u32_e32 v165, v163, v138
	v_add_u32_e32 v163, v163, v139
	v_cvt_pk_bf16_f32 v195, v189, v190
	ds_read_b64_tr_b16 v[188:189], v165
	ds_read_b64_tr_b16 v[196:197], v163
	v_add_u32_e32 v165, v216, v99
	v_add_u32_e32 v190, v165, v138
	v_add_u32_e32 v163, v165, v139
	ds_read_b64_tr_b16 v[190:191], v190
	ds_read_b64_tr_b16 v[198:199], v163
	v_bitop3_b32 v163, v169, v140, v121 bitop3:0x36
	v_lshlrev_b32_e32 v163, 4, v163
	v_add_u32_e32 v165, v187, v163
	v_add_u32_e32 v200, v165, v138
	v_add_u32_e32 v206, v216, v163
	v_add_u32_e32 v165, v165, v139
	ds_read_b64_tr_b16 v[200:201], v200
	ds_read_b64_tr_b16 v[204:205], v165
	v_add_u32_e32 v202, v206, v138
	v_add_u32_e32 v165, v206, v139
	ds_read_b64_tr_b16 v[202:203], v202
	ds_read_b64_tr_b16 v[206:207], v165
	s_ashr_i32 s53, s52, 31
	v_lshl_add_u64 v[94:95], v[102:103], 0, s[52:53]
	s_waitcnt lgkmcnt(5)
	v_mfma_f32_16x16x32_bf16 v[188:191], v[188:191], v[192:195], 0
	s_waitcnt lgkmcnt(4)
	v_mfma_f32_16x16x32_bf16 v[196:199], v[196:199], v[192:195], 0
	s_waitcnt lgkmcnt(1)
	v_mfma_f32_16x16x32_bf16 v[200:203], v[200:203], v[192:195], 0
	s_waitcnt lgkmcnt(0)
	v_mfma_f32_16x16x32_bf16 v[204:207], v[204:207], v[192:195], 0
	v_bitop3_b32 v165, v169, v141, v121 bitop3:0x36
	v_bitop3_b32 v169, v169, v142, v121 bitop3:0x36
	v_lshlrev_b32_e32 v165, 4, v165
	v_lshlrev_b32_e32 v169, 4, v169
	v_add_u32_e32 v208, v187, v165
	v_add_u32_e32 v210, v216, v165
	v_add_u32_e32 v187, v187, v169
	v_add_u32_e32 v216, v216, v169
	v_add_u32_e32 v209, v208, v138
	v_add_u32_e32 v211, v210, v138
	v_add_u32_e32 v212, v208, v139
	v_add_u32_e32 v214, v210, v139
	v_add_u32_e32 v217, v187, v138
	v_add_u32_e32 v218, v216, v138
	v_add_u32_e32 v222, v216, v139
	ds_read_b64_tr_b16 v[208:209], v209
	ds_read_b64_tr_b16 v[210:211], v211
	ds_read_b64_tr_b16 v[212:213], v212
	ds_read_b64_tr_b16 v[214:215], v214
	v_add_u32_e32 v187, v187, v139
	ds_read_b64_tr_b16 v[216:217], v217
	ds_read_b64_tr_b16 v[218:219], v218
	ds_read_b64_tr_b16 v[220:221], v187
	ds_read_b64_tr_b16 v[222:223], v222
	s_waitcnt lgkmcnt(6)
	v_mfma_f32_16x16x32_bf16 v[208:211], v[208:211], v[192:195], 0
	s_waitcnt lgkmcnt(4)
	v_mfma_f32_16x16x32_bf16 v[212:215], v[212:215], v[192:195], 0
	s_waitcnt lgkmcnt(2)
	v_mfma_f32_16x16x32_bf16 v[216:219], v[216:219], v[192:195], 0
	s_waitcnt lgkmcnt(0)
	v_mfma_f32_16x16x32_bf16 v[192:195], v[220:223], v[192:195], 0
	v_cvt_pk_bf16_f32 v180, v179, v180
	v_cvt_pk_bf16_f32 v181, v181, v182
	v_cvt_pk_bf16_f32 v182, v183, v184
	v_add_u32_e32 v179, s60, v159
	v_add_u32_e32 v184, s60, v158
	v_and_b32_e32 v179, 0x80, v179
	v_and_b32_e32 v184, 0x80, v184
	v_or3_b32 v179, v179, v152, v131
	v_or3_b32 v184, v184, v152, v132
	v_lshl_add_u32 v179, v179, 8, s54
	v_lshl_add_u32 v232, v184, 8, s54
	v_add_u32_e32 v220, v179, v99
	v_add_u32_e32 v222, v232, v99
	v_add_u32_e32 v228, v179, v163
	v_add_u32_e32 v230, v232, v163
	v_cvt_pk_bf16_f32 v183, v185, v186
	v_add_u32_e32 v184, v220, v138
	v_add_u32_e32 v186, v222, v138
	v_add_u32_e32 v220, v220, v139
	v_add_u32_e32 v222, v222, v139
	v_add_u32_e32 v224, v228, v138
	v_add_u32_e32 v226, v230, v138
	v_add_u32_e32 v228, v228, v139
	v_add_u32_e32 v230, v230, v139
	ds_read_b64_tr_b16 v[184:185], v184
	ds_read_b64_tr_b16 v[186:187], v186
	ds_read_b64_tr_b16 v[220:221], v220
	ds_read_b64_tr_b16 v[222:223], v222
	ds_read_b64_tr_b16 v[224:225], v224
	ds_read_b64_tr_b16 v[226:227], v226
	ds_read_b64_tr_b16 v[228:229], v228
	ds_read_b64_tr_b16 v[230:231], v230
	s_waitcnt lgkmcnt(6)
	v_mfma_f32_16x16x32_bf16 v[184:187], v[184:187], v[180:183], v[188:191]
	s_waitcnt lgkmcnt(4)
	v_mfma_f32_16x16x32_bf16 v[188:191], v[220:223], v[180:183], v[196:199]
	s_waitcnt lgkmcnt(2)
	v_mfma_f32_16x16x32_bf16 v[196:199], v[224:227], v[180:183], v[200:203]
	s_waitcnt lgkmcnt(0)
	v_mfma_f32_16x16x32_bf16 v[200:203], v[228:231], v[180:183], v[204:207]
	s_nop 1
	v_add_u32_e32 v204, v179, v165
	v_add_u32_e32 v206, v232, v165
	v_add_u32_e32 v179, v179, v169
	v_add_u32_e32 v225, v232, v169
	v_add_u32_e32 v205, v204, v138
	v_add_u32_e32 v207, v206, v138
	v_add_u32_e32 v220, v204, v139
	v_add_u32_e32 v222, v206, v139
	v_add_u32_e32 v224, v179, v138
	v_add_u32_e32 v226, v225, v138
	v_add_u32_e32 v230, v225, v139
	ds_read_b64_tr_b16 v[204:205], v205
	ds_read_b64_tr_b16 v[206:207], v207
	ds_read_b64_tr_b16 v[220:221], v220
	ds_read_b64_tr_b16 v[222:223], v222
	v_add_u32_e32 v179, v179, v139
	ds_read_b64_tr_b16 v[224:225], v224
	ds_read_b64_tr_b16 v[226:227], v226
	ds_read_b64_tr_b16 v[228:229], v179
	ds_read_b64_tr_b16 v[230:231], v230
	s_waitcnt lgkmcnt(6)
	v_mfma_f32_16x16x32_bf16 v[204:207], v[204:207], v[180:183], v[208:211]
	s_waitcnt lgkmcnt(4)
	v_mfma_f32_16x16x32_bf16 v[208:211], v[220:223], v[180:183], v[212:215]
	s_waitcnt lgkmcnt(2)
	v_mfma_f32_16x16x32_bf16 v[212:215], v[224:227], v[180:183], v[216:219]
	s_waitcnt lgkmcnt(0)
	v_mfma_f32_16x16x32_bf16 v[180:183], v[228:231], v[180:183], v[192:195]
	v_cvt_pk_bf16_f32 v172, v171, v172
	v_cvt_pk_bf16_f32 v173, v173, v174
	v_cvt_pk_bf16_f32 v174, v175, v176
	v_add_u32_e32 v171, s60, v157
	v_add_u32_e32 v176, s60, v156
	v_and_b32_e32 v171, 0x80, v171
	v_and_b32_e32 v176, 0x80, v176
	v_or3_b32 v171, v171, v152, v133
	v_or3_b32 v176, v176, v152, v134
	v_lshl_add_u32 v171, v171, 8, s54
	v_lshl_add_u32 v224, v176, 8, s54
	v_add_u32_e32 v192, v171, v99
	v_add_u32_e32 v194, v224, v99
	v_add_u32_e32 v220, v171, v163
	v_add_u32_e32 v222, v224, v163
	v_cvt_pk_bf16_f32 v175, v177, v178
	v_add_u32_e32 v176, v192, v138
	v_add_u32_e32 v178, v194, v138
	v_add_u32_e32 v192, v192, v139
	v_add_u32_e32 v194, v194, v139
	v_add_u32_e32 v216, v220, v138
	v_add_u32_e32 v218, v222, v138
	v_add_u32_e32 v220, v220, v139
	v_add_u32_e32 v222, v222, v139
	ds_read_b64_tr_b16 v[176:177], v176
	ds_read_b64_tr_b16 v[178:179], v178
	ds_read_b64_tr_b16 v[192:193], v192
	ds_read_b64_tr_b16 v[194:195], v194
	ds_read_b64_tr_b16 v[216:217], v216
	ds_read_b64_tr_b16 v[218:219], v218
	ds_read_b64_tr_b16 v[220:221], v220
	ds_read_b64_tr_b16 v[222:223], v222
	s_waitcnt lgkmcnt(6)
	v_mfma_f32_16x16x32_bf16 v[176:179], v[176:179], v[172:175], v[184:187]
	s_waitcnt lgkmcnt(4)
	v_mfma_f32_16x16x32_bf16 v[184:187], v[192:195], v[172:175], v[188:191]
	s_waitcnt lgkmcnt(2)
	v_mfma_f32_16x16x32_bf16 v[188:191], v[216:219], v[172:175], v[196:199]
	s_waitcnt lgkmcnt(0)
	v_mfma_f32_16x16x32_bf16 v[192:195], v[220:223], v[172:175], v[200:203]
	v_add_u32_e32 v196, v171, v165
	v_add_u32_e32 v198, v224, v165
	v_add_u32_e32 v171, v171, v169
	v_add_u32_e32 v217, v224, v169
	v_add_u32_e32 v197, v196, v138
	v_add_u32_e32 v199, v198, v138
	v_add_u32_e32 v200, v196, v139
	v_add_u32_e32 v202, v198, v139
	v_add_u32_e32 v216, v171, v138
	v_add_u32_e32 v218, v217, v138
	v_add_u32_e32 v222, v217, v139
	ds_read_b64_tr_b16 v[196:197], v197
	ds_read_b64_tr_b16 v[198:199], v199
	ds_read_b64_tr_b16 v[200:201], v200
	ds_read_b64_tr_b16 v[202:203], v202
	v_add_u32_e32 v171, v171, v139
	ds_read_b64_tr_b16 v[216:217], v216
	ds_read_b64_tr_b16 v[218:219], v218
	ds_read_b64_tr_b16 v[220:221], v171
	ds_read_b64_tr_b16 v[222:223], v222
	s_waitcnt lgkmcnt(6)
	v_mfma_f32_16x16x32_bf16 v[196:199], v[196:199], v[172:175], v[204:207]
	s_waitcnt lgkmcnt(4)
	v_mfma_f32_16x16x32_bf16 v[200:203], v[200:203], v[172:175], v[208:211]
	s_waitcnt lgkmcnt(2)
	v_mfma_f32_16x16x32_bf16 v[204:207], v[216:219], v[172:175], v[212:215]
	s_waitcnt lgkmcnt(0)
	v_mfma_f32_16x16x32_bf16 v[172:175], v[220:223], v[172:175], v[180:183]
	v_cvt_pk_bf16_f32 v180, v100, v101
	v_add_u32_e32 v100, s60, v155
	v_and_b32_e32 v100, 0x80, v100
	v_or3_b32 v100, v100, v152, v135
	v_add_u32_e32 v101, s60, v154
	v_and_b32_e32 v101, 0x80, v101
	v_lshl_add_u32 v100, v100, 8, s54
	v_cvt_pk_bf16_f32 v181, v162, v164
	v_or3_b32 v101, v101, v152, v136
	v_add_u32_e32 v162, v100, v99
	v_lshl_add_u32 v101, v101, 8, s54
	v_add_u32_e32 v164, v162, v138
	v_add_u32_e32 v162, v162, v139
	ds_read_b64_tr_b16 v[208:209], v164
	ds_read_b64_tr_b16 v[212:213], v162
	v_add_u32_e32 v164, v101, v99
	v_cvt_pk_bf16_f32 v182, v166, v167
	v_add_u32_e32 v166, v164, v138
	v_add_u32_e32 v162, v164, v139
	ds_read_b64_tr_b16 v[210:211], v166
	ds_read_b64_tr_b16 v[214:215], v162
	v_add_u32_e32 v162, v100, v163
	v_add_u32_e32 v164, v162, v138
	v_add_u32_e32 v162, v162, v139
	ds_read_b64_tr_b16 v[216:217], v164
	ds_read_b64_tr_b16 v[220:221], v162
	v_add_u32_e32 v164, v101, v163
	v_add_u32_e32 v166, v164, v138
	v_add_u32_e32 v162, v164, v139
	ds_read_b64_tr_b16 v[218:219], v166
	ds_read_b64_tr_b16 v[222:223], v162
	v_cvt_pk_bf16_f32 v183, v168, v170
	s_waitcnt lgkmcnt(5)
	v_mfma_f32_16x16x32_bf16 v[176:179], v[208:211], v[180:183], v[176:179]
	s_waitcnt lgkmcnt(4)
	v_mfma_f32_16x16x32_bf16 v[184:187], v[212:215], v[180:183], v[184:187]
	s_waitcnt lgkmcnt(1)
	v_mfma_f32_16x16x32_bf16 v[188:191], v[216:219], v[180:183], v[188:191]
	s_waitcnt lgkmcnt(0)
	v_mfma_f32_16x16x32_bf16 v[192:195], v[220:223], v[180:183], v[192:195]
	v_add_u32_e32 v162, v100, v165
	v_add_u32_e32 v164, v162, v138
	v_add_u32_e32 v166, v101, v165
	v_add_u32_e32 v162, v162, v139
	v_add_u32_e32 v100, v100, v169
	v_add_u32_e32 v167, v166, v138
	v_add_u32_e32 v166, v166, v139
	ds_read_b64_tr_b16 v[208:209], v164
	ds_read_b64_tr_b16 v[210:211], v167
	ds_read_b64_tr_b16 v[212:213], v162
	ds_read_b64_tr_b16 v[214:215], v166
	v_add_u32_e32 v162, v100, v138
	v_add_u32_e32 v101, v101, v169
	v_add_u32_e32 v164, v101, v138
	v_add_u32_e32 v100, v100, v139
	v_add_u32_e32 v101, v101, v139
	ds_read_b64_tr_b16 v[216:217], v162
	ds_read_b64_tr_b16 v[218:219], v164
	ds_read_b64_tr_b16 v[220:221], v100
	ds_read_b64_tr_b16 v[222:223], v101
	s_waitcnt lgkmcnt(6)
	v_mfma_f32_16x16x32_bf16 v[196:199], v[208:211], v[180:183], v[196:199]
	s_waitcnt lgkmcnt(4)
	v_mfma_f32_16x16x32_bf16 v[200:203], v[212:215], v[180:183], v[200:203]
	s_waitcnt lgkmcnt(2)
	v_mfma_f32_16x16x32_bf16 v[204:207], v[216:219], v[180:183], v[204:207]
	s_waitcnt lgkmcnt(0)
	v_mfma_f32_16x16x32_bf16 v[170:173], v[220:223], v[180:183], v[172:175]
	v_cvt_pk_bf16_f32 v2, v2, v3
	v_cvt_pk_bf16_f32 v3, v5, v98
	v_add_u32_e32 v98, s60, v153
	v_and_b32_e32 v98, 0x80, v98
	v_or3_b32 v98, v98, v152, v137
	v_lshl_add_u32 v162, v98, 8, s54
	v_add_u32_e32 v100, v162, v99
	v_add_u32_e32 v98, v100, v138
	v_add_u32_e32 v100, v100, v139
	ds_read_b64_tr_b16 v[98:99], v98
	ds_read_b64_tr_b16 v[174:175], v100
	v_add_u32_e32 v100, v162, v163
	v_add_u32_e32 v101, v100, v138
	v_add_u32_e32 v100, v100, v139
	ds_read_b64_tr_b16 v[180:181], v101
	ds_read_b64_tr_b16 v[208:209], v100
	v_mov_b32_e32 v5, v4
	s_waitcnt lgkmcnt(3)
	v_mov_b32_e32 v100, v98
	v_mov_b32_e32 v101, v99
	s_waitcnt lgkmcnt(1)
	v_mov_b32_e32 v182, v180
	v_mov_b32_e32 v183, v181
	s_waitcnt lgkmcnt(0)
	v_mov_b32_e32 v210, v208
	v_mfma_f32_16x16x32_bf16 v[98:101], v[98:101], v[2:5], v[176:179]
	v_mov_b32_e32 v211, v209
	s_nop 1
	v_mov_b32_e32 v176, v174
	v_mov_b32_e32 v177, v175
	v_mfma_f32_16x16x32_bf16 v[178:181], v[180:183], v[2:5], v[188:191]
	s_nop 0
	v_mfma_f32_16x16x32_bf16 v[174:177], v[174:177], v[2:5], v[184:187]
	v_mfma_f32_16x16x32_bf16 v[182:185], v[208:211], v[2:5], v[192:195]
	v_add_u32_e32 v163, v162, v165
	v_add_u32_e32 v164, v163, v138
	v_add_u32_e32 v162, v162, v169
	v_add_u32_e32 v165, v163, v139
	v_add_u32_e32 v168, v162, v138
	v_add_u32_e32 v169, v162, v139
	ds_read_b64_tr_b16 v[162:163], v164
	ds_read_b64_tr_b16 v[166:167], v165
	ds_read_b64_tr_b16 v[186:187], v168
	ds_read_b64_tr_b16 v[190:191], v169
	s_waitcnt lgkmcnt(3)
	v_mov_b32_e32 v164, v162
	v_mov_b32_e32 v165, v163
	s_waitcnt lgkmcnt(2)
	v_mov_b32_e32 v168, v166
	v_mov_b32_e32 v169, v167
	s_waitcnt lgkmcnt(1)
	v_mov_b32_e32 v188, v186
	v_mov_b32_e32 v189, v187
	s_waitcnt lgkmcnt(0)
	v_mov_b32_e32 v192, v190
	v_mov_b32_e32 v193, v191
	v_mfma_f32_16x16x32_bf16 v[162:165], v[162:165], v[2:5], v[196:199]
	v_mfma_f32_16x16x32_bf16 v[166:169], v[166:169], v[2:5], v[200:203]
	v_mfma_f32_16x16x32_bf16 v[186:189], v[186:189], v[2:5], v[204:207]
	v_mfma_f32_16x16x32_bf16 v[170:173], v[190:193], v[2:5], v[170:173]
	v_lshl_add_u64 v[2:3], v[94:95], 0, s[86:87]
	v_lshlrev_b64 v[2:3], 10, v[2:3]
	v_cvt_pk_bf16_f32 v101, v100, v101
	v_cvt_pk_bf16_f32 v100, v174, v175
	v_lshl_add_u64 v[2:3], v[106:107], 0, v[2:3]
	v_cvt_pk_bf16_f32 v5, v98, v99
	v_cvt_pk_bf16_f32 v174, v176, v177
	s_nop 0
	v_cndmask_b32_e64 v98, v100, v5, s[6:7]
	v_cndmask_b32_e64 v99, v174, v101, s[6:7]
	v_cndmask_b32_e64 v100, v5, v100, s[6:7]
	v_cndmask_b32_e64 v101, v101, v174, s[6:7]
	global_store_dwordx4 v[2:3], v[98:101], off sc1
	v_cvt_pk_bf16_f32 v5, v178, v179
	v_cvt_pk_bf16_f32 v174, v184, v185
	s_nop 1
	v_cvt_pk_bf16_f32 v101, v180, v181
	v_cvt_pk_bf16_f32 v100, v182, v183
	s_nop 0
	v_cndmask_b32_e64 v98, v100, v5, s[6:7]
	v_cndmask_b32_e64 v99, v174, v101, s[6:7]
	v_cndmask_b32_e64 v100, v5, v100, s[6:7]
	v_cndmask_b32_e64 v101, v101, v174, s[6:7]
	global_store_dwordx4 v[2:3], v[98:101], off offset:64 sc1
	v_cvt_pk_bf16_f32 v5, v162, v163
	v_cvt_pk_bf16_f32 v162, v168, v169
	s_nop 1
	v_cvt_pk_bf16_f32 v101, v164, v165
	v_cvt_pk_bf16_f32 v100, v166, v167
	s_nop 0
	v_cndmask_b32_e64 v98, v100, v5, s[6:7]
	v_cndmask_b32_e64 v99, v162, v101, s[6:7]
	v_cndmask_b32_e64 v100, v5, v100, s[6:7]
	v_cndmask_b32_e64 v101, v101, v162, s[6:7]
	global_store_dwordx4 v[2:3], v[98:101], off offset:128 sc1
	v_cvt_pk_bf16_f32 v5, v186, v187
	v_cvt_pk_bf16_f32 v162, v172, v173
	s_nop 1
	v_cvt_pk_bf16_f32 v101, v188, v189
	v_cvt_pk_bf16_f32 v100, v170, v171
	s_nop 0
	v_cndmask_b32_e64 v98, v100, v5, s[6:7]
	v_cndmask_b32_e64 v99, v162, v101, s[6:7]
	v_cndmask_b32_e64 v100, v5, v100, s[6:7]
	v_cndmask_b32_e64 v101, v101, v162, s[6:7]
	global_store_dwordx4 v[2:3], v[98:101], off offset:192 sc1
	s_and_saveexec_b64 s[52:53], s[8:9]
	s_cbranch_execz .LBB0_589
	v_add_f32_e32 v5, v96, v97
	v_lshl_add_u64 v[2:3], v[94:95], 2, s[48:49]
	global_store_dword v[2:3], v5, off sc1

.LBB0_689:
	s_waitcnt lgkmcnt(0)
	s_add_i32 s66, s66, 2
	s_barrier
	s_waitcnt lgkmcnt(0)
	v_mfma_f32_16x16x32_bf16 v[66:69], v[154:157], v[190:193], v[66:69]
	v_mfma_f32_16x16x32_bf16 v[62:65], v[162:165], v[190:193], v[62:65]
	v_mfma_f32_16x16x32_bf16 v[50:53], v[154:157], v[182:185], v[50:53]
	v_mfma_f32_16x16x32_bf16 v[46:49], v[162:165], v[182:185], v[46:49]
	v_mfma_f32_16x16x32_bf16 v[34:37], v[154:157], v[174:177], v[34:37]
	v_mfma_f32_16x16x32_bf16 v[30:33], v[162:165], v[174:177], v[30:33]
	v_mfma_f32_16x16x32_bf16 v[18:21], v[154:157], v[126:129], v[18:21]
	v_mfma_f32_16x16x32_bf16 v[14:17], v[162:165], v[126:129], v[14:17]
	v_mfma_f32_16x16x32_bf16 v[66:69], v[158:161], v[194:197], v[66:69]
	v_mfma_f32_16x16x32_bf16 v[62:65], v[166:169], v[194:197], v[62:65]
	v_mfma_f32_16x16x32_bf16 v[50:53], v[158:161], v[186:189], v[50:53]
	v_mfma_f32_16x16x32_bf16 v[46:49], v[166:169], v[186:189], v[46:49]
	v_mfma_f32_16x16x32_bf16 v[34:37], v[158:161], v[178:181], v[34:37]
	v_mfma_f32_16x16x32_bf16 v[30:33], v[166:169], v[178:181], v[30:33]
	v_mfma_f32_16x16x32_bf16 v[18:21], v[158:161], v[170:173], v[18:21]
	v_mfma_f32_16x16x32_bf16 v[14:17], v[166:169], v[170:173], v[14:17]
	v_mfma_f32_16x16x32_bf16 v[58:61], v[138:141], v[190:193], v[58:61]
	v_mfma_f32_16x16x32_bf16 v[54:57], v[146:149], v[190:193], v[54:57]
	v_mfma_f32_16x16x32_bf16 v[42:45], v[138:141], v[182:185], v[42:45]
	v_mfma_f32_16x16x32_bf16 v[38:41], v[146:149], v[182:185], v[38:41]
	v_mfma_f32_16x16x32_bf16 v[26:29], v[138:141], v[174:177], v[26:29]
	v_mfma_f32_16x16x32_bf16 v[22:25], v[146:149], v[174:177], v[22:25]
	v_mfma_f32_16x16x32_bf16 v[10:13], v[138:141], v[126:129], v[10:13]
	v_mfma_f32_16x16x32_bf16 v[6:9], v[146:149], v[126:129], v[6:9]
	v_mfma_f32_16x16x32_bf16 v[58:61], v[142:145], v[194:197], v[58:61]
	v_mfma_f32_16x16x32_bf16 v[54:57], v[150:153], v[194:197], v[54:57]
	v_mfma_f32_16x16x32_bf16 v[42:45], v[142:145], v[186:189], v[42:45]
	v_mfma_f32_16x16x32_bf16 v[38:41], v[150:153], v[186:189], v[38:41]
	v_mfma_f32_16x16x32_bf16 v[26:29], v[142:145], v[178:181], v[26:29]
	v_mfma_f32_16x16x32_bf16 v[22:25], v[150:153], v[178:181], v[22:25]
	v_mfma_f32_16x16x32_bf16 v[10:13], v[142:145], v[170:173], v[10:13]
	v_mfma_f32_16x16x32_bf16 v[6:9], v[150:153], v[170:173], v[6:9]
	s_barrier
	s_add_u32 s64, s64, 0x100
	s_addc_u32 s65, s65, 0
	s_add_u32 s22, s22, 0x100
	s_addc_u32 s23, s23, 0
	s_cmp_ge_i32 s66, s57
	s_cbranch_scc1 .LBB0_700
.LBB0_690:
	v_add_u32_e32 v126, 0x10000, v227
	ds_read_b128 v[154:157], v126
	ds_read_b128 v[158:161], v126 offset:1024
	ds_read_b128 v[162:165], v126 offset:2048
	ds_read_b128 v[166:169], v126 offset:3072
	v_add_u32_e32 v126, 0x14000, v227
	ds_read_b128 v[138:141], v126
	ds_read_b128 v[142:145], v126 offset:1024
	ds_read_b128 v[146:149], v126 offset:2048
	ds_read_b128 v[150:153], v126 offset:3072
	s_cmp_lg_u32 s58, s66
	s_cselect_b64 s[28:29], -1, 0
	s_add_u32 s26, s22, 0xfffc0080
	s_addc_u32 s27, s23, -1
	s_and_b64 s[24:25], s[28:29], exec
	s_cselect_b32 s27, s27, s13
	s_cselect_b32 s26, s26, s15
	s_cselect_b32 s25, s65, s62
	s_cselect_b32 s24, s64, s63
	v_lshl_add_u64 v[126:127], s[22:23], 0, v[208:209]
	s_add_i32 m0, s40, 0xc000
	ds_read_b128 v[170:173], v228
	ds_read_b128 v[174:177], v228 offset:1024
	ds_read_b128 v[178:181], v228 offset:2048
	ds_read_b128 v[182:185], v228 offset:3072
	ds_read_b128 v[186:189], v228 offset:4096
	ds_read_b128 v[190:193], v228 offset:5120
	ds_read_b128 v[194:197], v228 offset:6144
	ds_read_b128 v[198:201], v228 offset:7168
	global_load_lds_dwordx4 v[126:127], off
	v_lshl_add_u64 v[126:127], s[22:23], 0, v[210:211]
	s_add_i32 m0, s40, 0xe000
	s_nop 0
	global_load_lds_dwordx4 v[126:127], off
	s_waitcnt vmcnt(8)
	s_waitcnt lgkmcnt(0)
	s_barrier
	s_waitcnt lgkmcnt(0)
	v_mfma_f32_16x16x32_bf16 v[126:129], v[154:157], v[170:173], v[130:133]
	v_mfma_f32_16x16x32_bf16 v[130:133], v[162:165], v[170:173], v[134:137]
	v_mfma_f32_16x16x32_bf16 v[114:117], v[154:157], v[178:181], v[114:117]
	v_mfma_f32_16x16x32_bf16 v[110:113], v[162:165], v[178:181], v[110:113]
	v_mfma_f32_16x16x32_bf16 v[98:101], v[154:157], v[186:189], v[98:101]
	v_mfma_f32_16x16x32_bf16 v[94:97], v[162:165], v[186:189], v[94:97]
	v_mfma_f32_16x16x32_bf16 v[82:85], v[154:157], v[194:197], v[82:85]
	v_mfma_f32_16x16x32_bf16 v[78:81], v[162:165], v[194:197], v[78:81]
	v_mfma_f32_16x16x32_bf16 v[126:129], v[158:161], v[174:177], v[126:129]
	v_mfma_f32_16x16x32_bf16 v[134:137], v[166:169], v[174:177], v[130:133]
	v_mfma_f32_16x16x32_bf16 v[114:117], v[158:161], v[182:185], v[114:117]
	v_mfma_f32_16x16x32_bf16 v[110:113], v[166:169], v[182:185], v[110:113]
	v_mfma_f32_16x16x32_bf16 v[98:101], v[158:161], v[190:193], v[98:101]
	v_mfma_f32_16x16x32_bf16 v[94:97], v[166:169], v[190:193], v[94:97]
	v_mfma_f32_16x16x32_bf16 v[82:85], v[158:161], v[198:201], v[82:85]
	v_mfma_f32_16x16x32_bf16 v[78:81], v[166:169], v[198:201], v[78:81]
	v_mfma_f32_16x16x32_bf16 v[122:125], v[138:141], v[170:173], v[122:125]
	v_mfma_f32_16x16x32_bf16 v[118:121], v[146:149], v[170:173], v[118:121]
	v_mfma_f32_16x16x32_bf16 v[106:109], v[138:141], v[178:181], v[106:109]
	v_mfma_f32_16x16x32_bf16 v[102:105], v[146:149], v[178:181], v[102:105]
	v_mfma_f32_16x16x32_bf16 v[90:93], v[138:141], v[186:189], v[90:93]
	v_mfma_f32_16x16x32_bf16 v[86:89], v[146:149], v[186:189], v[86:89]
	v_mfma_f32_16x16x32_bf16 v[74:77], v[138:141], v[194:197], v[74:77]
	v_mfma_f32_16x16x32_bf16 v[70:73], v[146:149], v[194:197], v[70:73]
	v_mfma_f32_16x16x32_bf16 v[122:125], v[142:145], v[174:177], v[122:125]
	v_mfma_f32_16x16x32_bf16 v[118:121], v[150:153], v[174:177], v[118:121]
	v_mfma_f32_16x16x32_bf16 v[106:109], v[142:145], v[182:185], v[106:109]
	v_mfma_f32_16x16x32_bf16 v[102:105], v[150:153], v[182:185], v[102:105]
	v_mfma_f32_16x16x32_bf16 v[90:93], v[142:145], v[190:193], v[90:93]
	v_mfma_f32_16x16x32_bf16 v[86:89], v[150:153], v[190:193], v[86:89]
	v_mfma_f32_16x16x32_bf16 v[74:77], v[142:145], v[198:201], v[74:77]
	v_mfma_f32_16x16x32_bf16 v[70:73], v[150:153], v[198:201], v[70:73]
	s_barrier
	ds_read_b128 v[190:193], v228 offset:16384
	ds_read_b128 v[194:197], v228 offset:17408
	ds_read_b128 v[182:185], v228 offset:18432
	ds_read_b128 v[186:189], v228 offset:19456
	ds_read_b128 v[174:177], v228 offset:20480
	ds_read_b128 v[178:181], v228 offset:21504
	ds_read_b128 v[130:133], v228 offset:22528
	ds_read_b128 v[170:173], v228 offset:23552
	s_or_b64 s[28:29], s[18:19], s[28:29]
	s_xor_b64 s[30:31], s[28:29], -1
	s_mov_b64 s[34:35], -1
	s_and_b64 vcc, exec, s[30:31]
	s_cbranch_vccz .LBB0_692
	s_waitcnt vmcnt(2)
	s_mov_b64 s[34:35], 0

.LBB0_694:
	s_waitcnt lgkmcnt(0)
	s_barrier
	s_waitcnt lgkmcnt(0)
	v_mfma_f32_16x16x32_bf16 v[66:69], v[154:157], v[190:193], v[66:69]
	v_mfma_f32_16x16x32_bf16 v[62:65], v[162:165], v[190:193], v[62:65]
	v_mfma_f32_16x16x32_bf16 v[50:53], v[154:157], v[182:185], v[50:53]
	v_mfma_f32_16x16x32_bf16 v[46:49], v[162:165], v[182:185], v[46:49]
	v_mfma_f32_16x16x32_bf16 v[34:37], v[154:157], v[174:177], v[34:37]
	v_mfma_f32_16x16x32_bf16 v[30:33], v[162:165], v[174:177], v[30:33]
	v_mfma_f32_16x16x32_bf16 v[18:21], v[154:157], v[130:133], v[18:21]
	v_mfma_f32_16x16x32_bf16 v[14:17], v[162:165], v[130:133], v[14:17]
	v_mfma_f32_16x16x32_bf16 v[66:69], v[158:161], v[194:197], v[66:69]
	v_mfma_f32_16x16x32_bf16 v[62:65], v[166:169], v[194:197], v[62:65]
	v_mfma_f32_16x16x32_bf16 v[50:53], v[158:161], v[186:189], v[50:53]
	v_mfma_f32_16x16x32_bf16 v[46:49], v[166:169], v[186:189], v[46:49]
	v_mfma_f32_16x16x32_bf16 v[34:37], v[158:161], v[178:181], v[34:37]
	v_mfma_f32_16x16x32_bf16 v[30:33], v[166:169], v[178:181], v[30:33]
	v_mfma_f32_16x16x32_bf16 v[18:21], v[158:161], v[170:173], v[18:21]
	v_mfma_f32_16x16x32_bf16 v[14:17], v[166:169], v[170:173], v[14:17]
	v_mfma_f32_16x16x32_bf16 v[58:61], v[138:141], v[190:193], v[58:61]
	v_mfma_f32_16x16x32_bf16 v[54:57], v[146:149], v[190:193], v[54:57]
	v_mfma_f32_16x16x32_bf16 v[42:45], v[138:141], v[182:185], v[42:45]
	v_mfma_f32_16x16x32_bf16 v[38:41], v[146:149], v[182:185], v[38:41]
	v_mfma_f32_16x16x32_bf16 v[26:29], v[138:141], v[174:177], v[26:29]
	v_mfma_f32_16x16x32_bf16 v[22:25], v[146:149], v[174:177], v[22:25]
	v_mfma_f32_16x16x32_bf16 v[10:13], v[138:141], v[130:133], v[10:13]
	v_mfma_f32_16x16x32_bf16 v[6:9], v[146:149], v[130:133], v[6:9]
	v_mfma_f32_16x16x32_bf16 v[58:61], v[142:145], v[194:197], v[58:61]
	v_mfma_f32_16x16x32_bf16 v[54:57], v[150:153], v[194:197], v[54:57]
	v_mfma_f32_16x16x32_bf16 v[42:45], v[142:145], v[186:189], v[42:45]
	v_mfma_f32_16x16x32_bf16 v[38:41], v[150:153], v[186:189], v[38:41]
	v_mfma_f32_16x16x32_bf16 v[26:29], v[142:145], v[178:181], v[26:29]
	v_mfma_f32_16x16x32_bf16 v[22:25], v[150:153], v[178:181], v[22:25]
	v_mfma_f32_16x16x32_bf16 v[10:13], v[142:145], v[170:173], v[10:13]
	v_mfma_f32_16x16x32_bf16 v[6:9], v[150:153], v[170:173], v[6:9]
	s_barrier
	v_add_u32_e32 v130, 0x18000, v227
	ds_read_b128 v[154:157], v130
	ds_read_b128 v[158:161], v130 offset:1024
	ds_read_b128 v[162:165], v130 offset:2048
	ds_read_b128 v[166:169], v130 offset:3072
	v_add_u32_e32 v130, 0x1c000, v227
	ds_read_b128 v[138:141], v130
	ds_read_b128 v[142:145], v130 offset:1024
	ds_read_b128 v[146:149], v130 offset:2048
	ds_read_b128 v[150:153], v130 offset:3072
	ds_read_b128 v[194:197], v228 offset:32768
	ds_read_b128 v[198:201], v228 offset:33792
	ds_read_b128 v[186:189], v228 offset:34816
	ds_read_b128 v[190:193], v228 offset:35840
	ds_read_b128 v[178:181], v228 offset:36864
	ds_read_b128 v[182:185], v228 offset:37888
	ds_read_b128 v[170:173], v228 offset:38912
	ds_read_b128 v[174:177], v228 offset:39936
	s_mov_b64 s[34:35], -1
	s_and_b64 vcc, exec, s[30:31]
	s_cbranch_vccz .LBB0_696
	s_waitcnt vmcnt(0)
	s_mov_b64 s[34:35], 0

.LBB0_698:
	s_waitcnt lgkmcnt(0)
	s_barrier
	s_waitcnt lgkmcnt(0)
	v_mfma_f32_16x16x32_bf16 v[126:129], v[154:157], v[194:197], v[126:129]
	v_mfma_f32_16x16x32_bf16 v[130:133], v[158:161], v[198:201], v[126:129]
	v_mfma_f32_16x16x32_bf16 v[126:129], v[162:165], v[194:197], v[134:137]
	v_mfma_f32_16x16x32_bf16 v[114:117], v[154:157], v[186:189], v[114:117]
	v_mfma_f32_16x16x32_bf16 v[110:113], v[162:165], v[186:189], v[110:113]
	v_mfma_f32_16x16x32_bf16 v[98:101], v[154:157], v[178:181], v[98:101]
	v_mfma_f32_16x16x32_bf16 v[94:97], v[162:165], v[178:181], v[94:97]
	v_mfma_f32_16x16x32_bf16 v[82:85], v[154:157], v[170:173], v[82:85]
	v_mfma_f32_16x16x32_bf16 v[78:81], v[162:165], v[170:173], v[78:81]
	v_mfma_f32_16x16x32_bf16 v[134:137], v[166:169], v[198:201], v[126:129]
	v_mfma_f32_16x16x32_bf16 v[114:117], v[158:161], v[190:193], v[114:117]
	v_mfma_f32_16x16x32_bf16 v[110:113], v[166:169], v[190:193], v[110:113]
	v_mfma_f32_16x16x32_bf16 v[98:101], v[158:161], v[182:185], v[98:101]
	v_mfma_f32_16x16x32_bf16 v[94:97], v[166:169], v[182:185], v[94:97]
	v_mfma_f32_16x16x32_bf16 v[82:85], v[158:161], v[174:177], v[82:85]
	v_mfma_f32_16x16x32_bf16 v[78:81], v[166:169], v[174:177], v[78:81]
	v_mfma_f32_16x16x32_bf16 v[122:125], v[138:141], v[194:197], v[122:125]
	v_mfma_f32_16x16x32_bf16 v[118:121], v[146:149], v[194:197], v[118:121]
	v_mfma_f32_16x16x32_bf16 v[106:109], v[138:141], v[186:189], v[106:109]
	v_mfma_f32_16x16x32_bf16 v[102:105], v[146:149], v[186:189], v[102:105]
	v_mfma_f32_16x16x32_bf16 v[90:93], v[138:141], v[178:181], v[90:93]
	v_mfma_f32_16x16x32_bf16 v[86:89], v[146:149], v[178:181], v[86:89]
	v_mfma_f32_16x16x32_bf16 v[74:77], v[138:141], v[170:173], v[74:77]
	v_mfma_f32_16x16x32_bf16 v[70:73], v[146:149], v[170:173], v[70:73]
	v_mfma_f32_16x16x32_bf16 v[122:125], v[142:145], v[198:201], v[122:125]
	v_mfma_f32_16x16x32_bf16 v[118:121], v[150:153], v[198:201], v[118:121]
	v_mfma_f32_16x16x32_bf16 v[106:109], v[142:145], v[190:193], v[106:109]
	v_mfma_f32_16x16x32_bf16 v[102:105], v[150:153], v[190:193], v[102:105]
	v_mfma_f32_16x16x32_bf16 v[90:93], v[142:145], v[182:185], v[90:93]
	v_mfma_f32_16x16x32_bf16 v[86:89], v[150:153], v[182:185], v[86:89]
	v_mfma_f32_16x16x32_bf16 v[74:77], v[142:145], v[174:177], v[74:77]
	v_mfma_f32_16x16x32_bf16 v[70:73], v[150:153], v[174:177], v[70:73]
	s_barrier
	ds_read_b128 v[190:193], v228 offset:49152
	ds_read_b128 v[194:197], v228 offset:50176
	ds_read_b128 v[182:185], v228 offset:51200
	ds_read_b128 v[186:189], v228 offset:52224
	ds_read_b128 v[174:177], v228 offset:53248
	ds_read_b128 v[178:181], v228 offset:54272
	ds_read_b128 v[126:129], v228 offset:55296
	ds_read_b128 v[170:173], v228 offset:56320
	s_andn2_b64 vcc, exec, s[28:29]
	s_cbranch_vccnz .LBB0_689
	s_mov_b32 m0, s48
	v_lshl_add_u64 v[198:199], v[218:219], 0, s[68:69]
	s_add_u32 s24, s24, 0x10080
	global_load_lds_dwordx4 v[198:199], off
	v_lshl_add_u64 v[198:199], v[216:217], 0, s[68:69]
	s_mov_b32 m0, s49
	s_addc_u32 s25, s25, 0
	global_load_lds_dwordx4 v[198:199], off
	v_lshl_add_u64 v[198:199], s[24:25], 0, v[204:205]
	s_mov_b32 m0, s52
	s_nop 0
	global_load_lds_dwordx4 v[198:199], off
	v_lshl_add_u64 v[198:199], s[24:25], 0, v[2:3]
	s_mov_b32 m0, s53
	s_nop 0
	global_load_lds_dwordx4 v[198:199], off
	v_lshl_add_u64 v[198:199], v[214:215], 0, s[68:69]
	s_mov_b32 m0, s50
	s_nop 0
	global_load_lds_dwordx4 v[198:199], off
	v_lshl_add_u64 v[198:199], v[212:213], 0, s[68:69]
	s_mov_b32 m0, s51
	s_nop 0
	global_load_lds_dwordx4 v[198:199], off
	s_waitcnt vmcnt(8)
	s_branch .LBB0_689

.LBB0_774:
	s_waitcnt lgkmcnt(0)
	s_add_i32 s73, s73, 2
	s_barrier
	s_waitcnt lgkmcnt(0)
	v_mfma_f32_16x16x32_bf16 v[66:69], v[150:153], v[190:193], v[66:69]
	v_mfma_f32_16x16x32_bf16 v[62:65], v[158:161], v[190:193], v[62:65]
	v_mfma_f32_16x16x32_bf16 v[50:53], v[150:153], v[182:185], v[50:53]
	v_mfma_f32_16x16x32_bf16 v[46:49], v[158:161], v[182:185], v[46:49]
	v_mfma_f32_16x16x32_bf16 v[34:37], v[150:153], v[174:177], v[34:37]
	v_mfma_f32_16x16x32_bf16 v[30:33], v[158:161], v[174:177], v[30:33]
	v_mfma_f32_16x16x32_bf16 v[18:21], v[150:153], v[166:169], v[18:21]
	v_mfma_f32_16x16x32_bf16 v[14:17], v[158:161], v[166:169], v[14:17]
	v_mfma_f32_16x16x32_bf16 v[66:69], v[154:157], v[194:197], v[66:69]
	v_mfma_f32_16x16x32_bf16 v[62:65], v[162:165], v[194:197], v[62:65]
	v_mfma_f32_16x16x32_bf16 v[50:53], v[154:157], v[186:189], v[50:53]
	v_mfma_f32_16x16x32_bf16 v[46:49], v[162:165], v[186:189], v[46:49]
	v_mfma_f32_16x16x32_bf16 v[34:37], v[154:157], v[178:181], v[34:37]
	v_mfma_f32_16x16x32_bf16 v[30:33], v[162:165], v[178:181], v[30:33]
	v_mfma_f32_16x16x32_bf16 v[18:21], v[154:157], v[170:173], v[18:21]
	v_mfma_f32_16x16x32_bf16 v[14:17], v[162:165], v[170:173], v[14:17]
	v_mfma_f32_16x16x32_bf16 v[58:61], v[134:137], v[190:193], v[58:61]
	v_mfma_f32_16x16x32_bf16 v[54:57], v[142:145], v[190:193], v[54:57]
	v_mfma_f32_16x16x32_bf16 v[42:45], v[134:137], v[182:185], v[42:45]
	v_mfma_f32_16x16x32_bf16 v[38:41], v[142:145], v[182:185], v[38:41]
	v_mfma_f32_16x16x32_bf16 v[26:29], v[134:137], v[174:177], v[26:29]
	v_mfma_f32_16x16x32_bf16 v[22:25], v[142:145], v[174:177], v[22:25]
	v_mfma_f32_16x16x32_bf16 v[10:13], v[134:137], v[166:169], v[10:13]
	v_mfma_f32_16x16x32_bf16 v[6:9], v[142:145], v[166:169], v[6:9]
	v_mfma_f32_16x16x32_bf16 v[58:61], v[138:141], v[194:197], v[58:61]
	v_mfma_f32_16x16x32_bf16 v[54:57], v[146:149], v[194:197], v[54:57]
	v_mfma_f32_16x16x32_bf16 v[42:45], v[138:141], v[186:189], v[42:45]
	v_mfma_f32_16x16x32_bf16 v[38:41], v[146:149], v[186:189], v[38:41]
	v_mfma_f32_16x16x32_bf16 v[26:29], v[138:141], v[178:181], v[26:29]
	v_mfma_f32_16x16x32_bf16 v[22:25], v[146:149], v[178:181], v[22:25]
	v_mfma_f32_16x16x32_bf16 v[10:13], v[138:141], v[170:173], v[10:13]
	v_mfma_f32_16x16x32_bf16 v[6:9], v[146:149], v[170:173], v[6:9]
	s_barrier
	s_add_u32 s67, s67, 0x100
	s_addc_u32 s72, s72, 0
	s_add_u32 s24, s24, 0x100
	s_addc_u32 s25, s25, 0
	s_cmp_ge_i32 s73, s60
	s_cbranch_scc1 .LBB0_785
.LBB0_775:
	v_add_u32_e32 v134, 0x10000, v225
	v_add_u32_e32 v146, 0x14000, v225
	ds_read_b128 v[150:153], v134
	ds_read_b128 v[154:157], v134 offset:1024
	ds_read_b128 v[158:161], v134 offset:2048
	ds_read_b128 v[162:165], v134 offset:3072
	ds_read_b128 v[134:137], v146
	ds_read_b128 v[138:141], v146 offset:1024
	ds_read_b128 v[142:145], v146 offset:2048
	ds_read_b128 v[146:149], v146 offset:3072
	s_cmp_lg_u32 s61, s73
	s_cselect_b64 s[30:31], -1, 0
	s_add_u32 s28, s24, 0xfffc0080
	s_addc_u32 s29, s25, -1
	s_and_b64 s[26:27], s[30:31], exec
	s_cselect_b32 s29, s29, s15
	s_cselect_b32 s28, s28, s17
	s_cselect_b32 s27, s72, s65
	s_cselect_b32 s26, s67, s66
	v_lshl_add_u64 v[216:217], s[24:25], 0, v[204:205]
	s_add_i32 m0, s43, 0xc000
	ds_read_b128 v[166:169], v226
	ds_read_b128 v[170:173], v226 offset:1024
	ds_read_b128 v[174:177], v226 offset:2048
	ds_read_b128 v[178:181], v226 offset:3072
	ds_read_b128 v[182:185], v226 offset:4096
	ds_read_b128 v[186:189], v226 offset:5120
	ds_read_b128 v[190:193], v226 offset:6144
	ds_read_b128 v[194:197], v226 offset:7168
	global_load_lds_dwordx4 v[216:217], off
	v_lshl_add_u64 v[216:217], s[24:25], 0, v[206:207]
	s_add_i32 m0, s43, 0xe000
	s_nop 0
	global_load_lds_dwordx4 v[216:217], off
	s_waitcnt vmcnt(8)
	s_waitcnt lgkmcnt(0)
	s_barrier
	s_waitcnt lgkmcnt(0)
	v_mfma_f32_16x16x32_bf16 v[130:133], v[150:153], v[166:169], v[130:133]
	v_mfma_f32_16x16x32_bf16 v[126:129], v[158:161], v[166:169], v[126:129]
	v_mfma_f32_16x16x32_bf16 v[114:117], v[150:153], v[174:177], v[114:117]
	v_mfma_f32_16x16x32_bf16 v[110:113], v[158:161], v[174:177], v[110:113]
	v_mfma_f32_16x16x32_bf16 v[98:101], v[150:153], v[182:185], v[98:101]
	v_mfma_f32_16x16x32_bf16 v[94:97], v[158:161], v[182:185], v[94:97]
	v_mfma_f32_16x16x32_bf16 v[82:85], v[150:153], v[190:193], v[82:85]
	v_mfma_f32_16x16x32_bf16 v[78:81], v[158:161], v[190:193], v[78:81]
	v_mfma_f32_16x16x32_bf16 v[130:133], v[154:157], v[170:173], v[130:133]
	v_mfma_f32_16x16x32_bf16 v[126:129], v[162:165], v[170:173], v[126:129]
	v_mfma_f32_16x16x32_bf16 v[114:117], v[154:157], v[178:181], v[114:117]
	v_mfma_f32_16x16x32_bf16 v[110:113], v[162:165], v[178:181], v[110:113]
	v_mfma_f32_16x16x32_bf16 v[98:101], v[154:157], v[186:189], v[98:101]
	v_mfma_f32_16x16x32_bf16 v[94:97], v[162:165], v[186:189], v[94:97]
	v_mfma_f32_16x16x32_bf16 v[82:85], v[154:157], v[194:197], v[82:85]
	v_mfma_f32_16x16x32_bf16 v[78:81], v[162:165], v[194:197], v[78:81]
	v_mfma_f32_16x16x32_bf16 v[122:125], v[134:137], v[166:169], v[122:125]
	v_mfma_f32_16x16x32_bf16 v[118:121], v[142:145], v[166:169], v[118:121]
	v_mfma_f32_16x16x32_bf16 v[106:109], v[134:137], v[174:177], v[106:109]
	v_mfma_f32_16x16x32_bf16 v[102:105], v[142:145], v[174:177], v[102:105]
	v_mfma_f32_16x16x32_bf16 v[90:93], v[134:137], v[182:185], v[90:93]
	v_mfma_f32_16x16x32_bf16 v[86:89], v[142:145], v[182:185], v[86:89]
	v_mfma_f32_16x16x32_bf16 v[74:77], v[134:137], v[190:193], v[74:77]
	v_mfma_f32_16x16x32_bf16 v[70:73], v[142:145], v[190:193], v[70:73]
	v_mfma_f32_16x16x32_bf16 v[122:125], v[138:141], v[170:173], v[122:125]
	v_mfma_f32_16x16x32_bf16 v[118:121], v[146:149], v[170:173], v[118:121]
	v_mfma_f32_16x16x32_bf16 v[106:109], v[138:141], v[178:181], v[106:109]
	v_mfma_f32_16x16x32_bf16 v[102:105], v[146:149], v[178:181], v[102:105]
	v_mfma_f32_16x16x32_bf16 v[90:93], v[138:141], v[186:189], v[90:93]
	v_mfma_f32_16x16x32_bf16 v[86:89], v[146:149], v[186:189], v[86:89]
	v_mfma_f32_16x16x32_bf16 v[74:77], v[138:141], v[194:197], v[74:77]
	v_mfma_f32_16x16x32_bf16 v[70:73], v[146:149], v[194:197], v[70:73]
	s_barrier
	ds_read_b128 v[190:193], v226 offset:16384
	ds_read_b128 v[194:197], v226 offset:17408
	ds_read_b128 v[182:185], v226 offset:18432
	ds_read_b128 v[186:189], v226 offset:19456
	ds_read_b128 v[174:177], v226 offset:20480
	ds_read_b128 v[178:181], v226 offset:21504
	ds_read_b128 v[166:169], v226 offset:22528
	ds_read_b128 v[170:173], v226 offset:23552
	s_or_b64 s[30:31], s[20:21], s[30:31]
	s_xor_b64 s[34:35], s[30:31], -1
	s_mov_b64 s[36:37], -1
	s_and_b64 vcc, exec, s[34:35]
	s_cbranch_vccz .LBB0_777
	s_waitcnt vmcnt(2)
	s_mov_b64 s[36:37], 0

.LBB0_779:
	s_waitcnt lgkmcnt(0)
	s_barrier
	s_waitcnt lgkmcnt(0)
	v_mfma_f32_16x16x32_bf16 v[66:69], v[150:153], v[190:193], v[66:69]
	v_mfma_f32_16x16x32_bf16 v[62:65], v[158:161], v[190:193], v[62:65]
	v_mfma_f32_16x16x32_bf16 v[50:53], v[150:153], v[182:185], v[50:53]
	v_mfma_f32_16x16x32_bf16 v[46:49], v[158:161], v[182:185], v[46:49]
	v_mfma_f32_16x16x32_bf16 v[34:37], v[150:153], v[174:177], v[34:37]
	v_mfma_f32_16x16x32_bf16 v[30:33], v[158:161], v[174:177], v[30:33]
	v_mfma_f32_16x16x32_bf16 v[18:21], v[150:153], v[166:169], v[18:21]
	v_mfma_f32_16x16x32_bf16 v[14:17], v[158:161], v[166:169], v[14:17]
	v_mfma_f32_16x16x32_bf16 v[66:69], v[154:157], v[194:197], v[66:69]
	v_mfma_f32_16x16x32_bf16 v[62:65], v[162:165], v[194:197], v[62:65]
	v_mfma_f32_16x16x32_bf16 v[50:53], v[154:157], v[186:189], v[50:53]
	v_mfma_f32_16x16x32_bf16 v[46:49], v[162:165], v[186:189], v[46:49]
	v_mfma_f32_16x16x32_bf16 v[34:37], v[154:157], v[178:181], v[34:37]
	v_mfma_f32_16x16x32_bf16 v[30:33], v[162:165], v[178:181], v[30:33]
	v_mfma_f32_16x16x32_bf16 v[18:21], v[154:157], v[170:173], v[18:21]
	v_mfma_f32_16x16x32_bf16 v[14:17], v[162:165], v[170:173], v[14:17]
	v_mfma_f32_16x16x32_bf16 v[58:61], v[134:137], v[190:193], v[58:61]
	v_mfma_f32_16x16x32_bf16 v[54:57], v[142:145], v[190:193], v[54:57]
	v_mfma_f32_16x16x32_bf16 v[42:45], v[134:137], v[182:185], v[42:45]
	v_mfma_f32_16x16x32_bf16 v[38:41], v[142:145], v[182:185], v[38:41]
	v_mfma_f32_16x16x32_bf16 v[26:29], v[134:137], v[174:177], v[26:29]
	v_mfma_f32_16x16x32_bf16 v[22:25], v[142:145], v[174:177], v[22:25]
	v_mfma_f32_16x16x32_bf16 v[10:13], v[134:137], v[166:169], v[10:13]
	v_mfma_f32_16x16x32_bf16 v[6:9], v[142:145], v[166:169], v[6:9]
	v_mfma_f32_16x16x32_bf16 v[58:61], v[138:141], v[194:197], v[58:61]
	v_mfma_f32_16x16x32_bf16 v[54:57], v[146:149], v[194:197], v[54:57]
	v_mfma_f32_16x16x32_bf16 v[42:45], v[138:141], v[186:189], v[42:45]
	v_mfma_f32_16x16x32_bf16 v[38:41], v[146:149], v[186:189], v[38:41]
	v_mfma_f32_16x16x32_bf16 v[26:29], v[138:141], v[178:181], v[26:29]
	v_mfma_f32_16x16x32_bf16 v[22:25], v[146:149], v[178:181], v[22:25]
	v_mfma_f32_16x16x32_bf16 v[10:13], v[138:141], v[170:173], v[10:13]
	v_mfma_f32_16x16x32_bf16 v[6:9], v[146:149], v[170:173], v[6:9]
	s_barrier
	v_add_u32_e32 v134, 0x18000, v225
	v_add_u32_e32 v146, 0x1c000, v225
	ds_read_b128 v[150:153], v134
	ds_read_b128 v[154:157], v134 offset:1024
	ds_read_b128 v[158:161], v134 offset:2048
	ds_read_b128 v[162:165], v134 offset:3072
	ds_read_b128 v[134:137], v146
	ds_read_b128 v[138:141], v146 offset:1024
	ds_read_b128 v[142:145], v146 offset:2048
	ds_read_b128 v[146:149], v146 offset:3072
	ds_read_b128 v[190:193], v226 offset:32768
	ds_read_b128 v[194:197], v226 offset:33792
	ds_read_b128 v[182:185], v226 offset:34816
	ds_read_b128 v[186:189], v226 offset:35840
	ds_read_b128 v[174:177], v226 offset:36864
	ds_read_b128 v[178:181], v226 offset:37888
	ds_read_b128 v[166:169], v226 offset:38912
	ds_read_b128 v[170:173], v226 offset:39936
	s_mov_b64 s[36:37], -1
	s_and_b64 vcc, exec, s[34:35]
	s_cbranch_vccz .LBB0_781
	s_waitcnt vmcnt(0)
	s_mov_b64 s[36:37], 0

.LBB0_783:
	s_waitcnt lgkmcnt(0)
	s_barrier
	s_waitcnt lgkmcnt(0)
	v_mfma_f32_16x16x32_bf16 v[130:133], v[150:153], v[190:193], v[130:133]
	v_mfma_f32_16x16x32_bf16 v[126:129], v[158:161], v[190:193], v[126:129]
	v_mfma_f32_16x16x32_bf16 v[114:117], v[150:153], v[182:185], v[114:117]
	v_mfma_f32_16x16x32_bf16 v[110:113], v[158:161], v[182:185], v[110:113]
	v_mfma_f32_16x16x32_bf16 v[98:101], v[150:153], v[174:177], v[98:101]
	v_mfma_f32_16x16x32_bf16 v[94:97], v[158:161], v[174:177], v[94:97]
	v_mfma_f32_16x16x32_bf16 v[82:85], v[150:153], v[166:169], v[82:85]
	v_mfma_f32_16x16x32_bf16 v[78:81], v[158:161], v[166:169], v[78:81]
	v_mfma_f32_16x16x32_bf16 v[130:133], v[154:157], v[194:197], v[130:133]
	v_mfma_f32_16x16x32_bf16 v[126:129], v[162:165], v[194:197], v[126:129]
	v_mfma_f32_16x16x32_bf16 v[114:117], v[154:157], v[186:189], v[114:117]
	v_mfma_f32_16x16x32_bf16 v[110:113], v[162:165], v[186:189], v[110:113]
	v_mfma_f32_16x16x32_bf16 v[98:101], v[154:157], v[178:181], v[98:101]
	v_mfma_f32_16x16x32_bf16 v[94:97], v[162:165], v[178:181], v[94:97]
	v_mfma_f32_16x16x32_bf16 v[82:85], v[154:157], v[170:173], v[82:85]
	v_mfma_f32_16x16x32_bf16 v[78:81], v[162:165], v[170:173], v[78:81]
	v_mfma_f32_16x16x32_bf16 v[122:125], v[134:137], v[190:193], v[122:125]
	v_mfma_f32_16x16x32_bf16 v[118:121], v[142:145], v[190:193], v[118:121]
	v_mfma_f32_16x16x32_bf16 v[106:109], v[134:137], v[182:185], v[106:109]
	v_mfma_f32_16x16x32_bf16 v[102:105], v[142:145], v[182:185], v[102:105]
	v_mfma_f32_16x16x32_bf16 v[90:93], v[134:137], v[174:177], v[90:93]
	v_mfma_f32_16x16x32_bf16 v[86:89], v[142:145], v[174:177], v[86:89]
	v_mfma_f32_16x16x32_bf16 v[74:77], v[134:137], v[166:169], v[74:77]
	v_mfma_f32_16x16x32_bf16 v[70:73], v[142:145], v[166:169], v[70:73]
	v_mfma_f32_16x16x32_bf16 v[122:125], v[138:141], v[194:197], v[122:125]
	v_mfma_f32_16x16x32_bf16 v[118:121], v[146:149], v[194:197], v[118:121]
	v_mfma_f32_16x16x32_bf16 v[106:109], v[138:141], v[186:189], v[106:109]
	v_mfma_f32_16x16x32_bf16 v[102:105], v[146:149], v[186:189], v[102:105]
	v_mfma_f32_16x16x32_bf16 v[90:93], v[138:141], v[178:181], v[90:93]
	v_mfma_f32_16x16x32_bf16 v[86:89], v[146:149], v[178:181], v[86:89]
	v_mfma_f32_16x16x32_bf16 v[74:77], v[138:141], v[170:173], v[74:77]
	v_mfma_f32_16x16x32_bf16 v[70:73], v[146:149], v[170:173], v[70:73]
	s_barrier
	ds_read_b128 v[190:193], v226 offset:49152
	ds_read_b128 v[194:197], v226 offset:50176
	ds_read_b128 v[182:185], v226 offset:51200
	ds_read_b128 v[186:189], v226 offset:52224
	ds_read_b128 v[174:177], v226 offset:53248
	ds_read_b128 v[178:181], v226 offset:54272
	ds_read_b128 v[166:169], v226 offset:55296
	ds_read_b128 v[170:173], v226 offset:56320
	s_andn2_b64 vcc, exec, s[30:31]
	s_cbranch_vccnz .LBB0_774
	s_mov_b32 m0, s51
	v_lshl_add_u64 v[222:223], v[222:223], 0, s[68:69]
	s_add_u32 s26, s26, 0x10080
	global_load_lds_dwordx4 v[222:223], off
	v_lshl_add_u64 v[220:221], v[220:221], 0, s[68:69]
	s_mov_b32 m0, s52
	s_addc_u32 s27, s27, 0
	global_load_lds_dwordx4 v[220:221], off
	v_lshl_add_u64 v[220:221], s[26:27], 0, v[200:201]
	s_mov_b32 m0, s55
	v_lshl_add_u64 v[218:219], v[218:219], 0, s[68:69]
	global_load_lds_dwordx4 v[220:221], off
	v_lshl_add_u64 v[220:221], s[26:27], 0, v[2:3]
	s_mov_b32 m0, s56
	v_lshl_add_u64 v[216:217], v[216:217], 0, s[68:69]
	global_load_lds_dwordx4 v[220:221], off
	s_mov_b32 m0, s53
	s_nop 0
	global_load_lds_dwordx4 v[218:219], off
	s_mov_b32 m0, s54
	s_nop 0
	global_load_lds_dwordx4 v[216:217], off
	s_waitcnt vmcnt(8)
	s_branch .LBB0_774

.LBB0_812:
	s_or_b64 exec, exec, s[2:3]
	s_and_b64 vcc, exec, s[50:51]
	s_barrier
	s_cbranch_vccnz .LBB0_814
	s_mov_b32 s2, s87
	s_ashr_i32 s3, s2, 31
	s_lshl_b64 s[2:3], s[2:3], 3
	s_add_u32 s2, s0, s2
	s_addc_u32 s3, s1, s3
	s_mov_b64 s[2:3], s[100:101]
	s_mov_b32 s4, s87
	s_mov_b32 s6, s87
	v_mov_b32_e32 v145, v0
	s_waitcnt lgkmcnt(0)
	s_add_u32 s8, s2, s81
	s_addc_u32 s16, s3, 0
	s_ashr_i32 s5, s4, 31
	s_lshl_b64 s[2:3], s[4:5], 3
	s_add_u32 s2, s0, s2
	s_addc_u32 s3, s1, s3
	s_mov_b64 s[2:3], s[100:101]
	s_mov_b32 s5, s87
	s_mov_b32 s4, s87
	s_waitcnt lgkmcnt(0)
	s_add_u32 s2, s2, s84
	s_addc_u32 s3, s3, 0
	s_add_u32 s17, s2, 0x200000
	s_addc_u32 s18, s3, 0
	s_ashr_i32 s5, s4, 31
	s_lshl_b64 s[2:3], s[4:5], 3
	s_add_u32 s2, s0, s2
	s_addc_u32 s3, s1, s3
	s_load_dwordx2 s[2:3], s[2:3], 0xd0
	v_mov_b32_e32 v143, v4
	s_waitcnt lgkmcnt(0)
	s_add_u32 s2, s2, s80
	s_addc_u32 s3, s3, 0
	s_lshl_b32 s4, s46, 19
	s_add_u32 s2, s2, s4
	s_addc_u32 s3, s3, 0
	v_readlane_b32 s4, v253, 62
	v_readlane_b32 s5, v253, 63
	s_add_u32 s2, s2, s4
	s_addc_u32 s3, s3, s5
	s_add_u32 s4, s2, 0xe00000
	s_addc_u32 s5, s3, 0
	s_ashr_i32 s7, s6, 31
	s_lshl_b64 s[2:3], s[6:7], 3
	s_add_u32 s2, s0, s2
	s_addc_u32 s3, s1, s3
	s_mov_b64 s[2:3], s[100:101]
	s_waitcnt lgkmcnt(0)
	s_add_u32 s2, s2, s81
	v_readfirstlane_b32 s6, v145
	s_addc_u32 s3, s3, 0
	s_ashr_i32 s9, s6, 6
	s_lshl_b32 s10, s9, 5
	s_lshl_b64 s[6:7], s[74:75], 8
	s_ashr_i32 s11, s10, 31
	s_add_u32 s19, s6, s10
	s_addc_u32 s20, s7, s11
	s_lshl_b32 s6, s78, 2
	s_ashr_i32 s7, s6, 31
	s_lshl_b64 s[10:11], s[6:7], 14
	s_add_u32 s10, s17, s10
	s_addc_u32 s11, s18, s11
	s_or_b32 s12, s6, 1
	s_ashr_i32 s13, s12, 31
	s_lshl_b64 s[12:13], s[12:13], 14
	s_add_u32 s12, s17, s12
	s_addc_u32 s13, s18, s13
	s_or_b32 s14, s6, 2
	s_ashr_i32 s15, s14, 31
	s_lshl_b64 s[14:15], s[14:15], 14
	s_add_u32 s14, s17, s14
	s_addc_u32 s15, s18, s15
	s_or_b32 s6, s6, 3
	v_and_b32_e32 v144, 15, v145
	s_ashr_i32 s7, s6, 31
	s_lshl_b64 s[6:7], s[6:7], 14
	v_or_b32_e32 v6, s19, v144
	s_add_u32 s6, s17, s6
	v_mov_b32_e32 v5, v6
	s_addc_u32 s7, s18, s7
	v_ashrrev_i64 v[2:3], 30, v[4:5]
	v_mov_b32_e32 v7, s20
	v_lshl_add_u64 v[8:9], s[10:11], 0, v[2:3]
	v_lshl_add_u64 v[10:11], s[12:13], 0, v[2:3]
	v_lshl_add_u64 v[12:13], s[14:15], 0, v[2:3]
	v_lshl_add_u64 v[2:3], s[6:7], 0, v[2:3]
	global_load_dword v14, v[8:9], off
	global_load_dword v16, v[10:11], off
	global_load_dword v15, v[12:13], off
	global_load_dword v17, v[2:3], off
	v_lshlrev_b64 v[2:3], 11, v[6:7]
	v_or_b32_e32 v6, 16, v6
	v_mov_b32_e32 v5, v6
	v_ashrrev_i64 v[8:9], 30, v[4:5]
	v_lshl_add_u64 v[10:11], s[10:11], 0, v[8:9]
	v_lshl_add_u64 v[12:13], s[12:13], 0, v[8:9]
	v_lshl_add_u64 v[18:19], s[14:15], 0, v[8:9]
	v_lshl_add_u64 v[8:9], s[6:7], 0, v[8:9]
	s_lshl_b32 s6, s78, 8
	s_ashr_i32 s7, s6, 31
	s_lshl_b64 s[6:7], s[6:7], 1
	s_add_u32 s10, s8, s6
	s_addc_u32 s11, s16, s7
	v_and_b32_e32 v142, 48, v145
	global_load_dword v20, v[10:11], off
	global_load_dword v22, v[12:13], off
	global_load_dword v21, v[18:19], off
	global_load_dword v23, v[8:9], off
	v_lshl_add_u64 v[8:9], s[10:11], 0, v[142:143]
	s_mov_b64 s[10:11], 0x9e00000
	v_lshl_add_u64 v[8:9], v[8:9], 0, s[10:11]
	v_lshlrev_b64 v[6:7], 11, v[6:7]
	v_lshl_add_u64 v[10:11], v[8:9], 0, v[2:3]
	v_lshl_add_u64 v[6:7], v[8:9], 0, v[6:7]
	global_load_dwordx4 v[66:69], v[10:11], off
	global_load_dwordx4 v[62:65], v[10:11], off offset:64
	global_load_dwordx4 v[58:61], v[10:11], off offset:128
	global_load_dwordx4 v[54:57], v[10:11], off offset:192
	global_load_dwordx4 v[50:53], v[10:11], off offset:256
	global_load_dwordx4 v[46:49], v[10:11], off offset:320
	global_load_dwordx4 v[42:45], v[10:11], off offset:384
	global_load_dwordx4 v[38:41], v[10:11], off offset:448
	global_load_dwordx4 v[98:101], v[6:7], off
	global_load_dwordx4 v[94:97], v[6:7], off offset:64
	global_load_dwordx4 v[90:93], v[6:7], off offset:128
	global_load_dwordx4 v[86:89], v[6:7], off offset:192
	global_load_dwordx4 v[82:85], v[6:7], off offset:256
	global_load_dwordx4 v[78:81], v[6:7], off offset:320
	global_load_dwordx4 v[74:77], v[6:7], off offset:384
	global_load_dwordx4 v[70:73], v[6:7], off offset:448
	v_bfe_u32 v5, v145, 4, 2
	v_bitop3_b32 v6, v5, v145, 15 bitop3:0x78
	v_bitop3_b32 v8, v5, v144, 8 bitop3:0x36
	v_bitop3_b32 v30, v5, v144, 24 bitop3:0x36
	v_lshl_add_u32 v134, v144, 9, 0
	v_bitop3_b32 v7, v5, v144, 4 bitop3:0x36
	v_bitop3_b32 v9, v5, v144, 12 bitop3:0x36
	v_lshlrev_b32_e32 v149, 4, v6
	v_lshlrev_b32_e32 v136, 4, v8
	v_lshlrev_b32_e32 v152, 4, v30
	v_lshlrev_b32_e32 v137, 4, v7
	v_lshlrev_b32_e32 v135, 4, v9
	v_add_u32_e32 v170, v134, v149
	v_add_u32_e32 v172, v134, v136
	v_add_u32_e32 v176, v134, v152
	v_add_u32_e32 v171, v134, v137
	v_add_u32_e32 v173, v134, v135
	s_waitcnt vmcnt(0)
	s_barrier
	ds_read_b128 v[6:9], v170
	ds_read_b128 v[10:13], v171
	v_lshrrev_b32_e32 v146, 1, v145
	s_lshl_b32 s8, s9, 3
	s_waitcnt vmcnt(20)
	v_pk_add_f32 v[14:15], v[14:15], v[16:17]
	s_nop 0
	v_add_f32_e32 v14, v14, v15
	v_fmamk_f32 v14, v14, 0x3b800000, v236
	v_rsq_f32_e32 v148, v14
	s_waitcnt vmcnt(16)
	v_pk_add_f32 v[16:17], v[20:21], v[22:23]
	v_bitop3_b32 v22, v5, v144, 16 bitop3:0x36
	v_lshlrev_b32_e32 v150, 4, v22
	v_bitop3_b32 v22, v5, v144, 20 bitop3:0x36
	v_bitop3_b32 v5, v5, v144, 28 bitop3:0x36
	v_add_f32_e32 v15, v16, v17
	v_add_u32_e32 v174, v134, v150
	v_lshlrev_b32_e32 v151, 4, v22
	v_lshlrev_b32_e32 v153, 4, v5
	v_fmamk_f32 v102, v15, 0x3b800000, v236
	ds_read_b128 v[14:17], v172
	ds_read_b128 v[18:21], v173
	v_add_u32_e32 v175, v134, v151
	ds_read_b128 v[22:25], v174
	ds_read_b128 v[26:29], v175
	v_add_u32_e32 v177, v134, v153
	ds_read_b128 v[30:33], v176
	ds_read_b128 v[34:37], v177
	v_rsq_f32_e32 v147, v102
	v_and_b32_e32 v5, 63, v145
	s_waitcnt vmcnt(15) lgkmcnt(7)
	v_mfma_f32_16x16x32_bf16 v[102:105], v[6:9], v[66:69], 0
	s_waitcnt vmcnt(7)
	v_mfma_f32_16x16x32_bf16 v[6:9], v[6:9], v[98:101], 0
	s_waitcnt lgkmcnt(6)
	v_mfma_f32_16x16x32_bf16 v[102:105], v[10:13], v[62:65], v[102:105]
	s_waitcnt vmcnt(6)
	v_mfma_f32_16x16x32_bf16 v[6:9], v[10:13], v[94:97], v[6:9]
	s_waitcnt lgkmcnt(5)
	v_mfma_f32_16x16x32_bf16 v[10:13], v[14:17], v[58:61], v[102:105]
	s_waitcnt vmcnt(5)
	v_mfma_f32_16x16x32_bf16 v[6:9], v[14:17], v[90:93], v[6:9]
	s_waitcnt lgkmcnt(4)
	v_mfma_f32_16x16x32_bf16 v[10:13], v[18:21], v[54:57], v[10:13]
	s_waitcnt vmcnt(4)
	v_mfma_f32_16x16x32_bf16 v[6:9], v[18:21], v[86:89], v[6:9]
	ds_read_b128 v[14:17], v170 offset:8192
	ds_read_b128 v[18:21], v171 offset:8192
	ds_read_b128 v[102:105], v172 offset:8192
	ds_read_b128 v[106:109], v173 offset:8192
	s_waitcnt lgkmcnt(7)
	v_mfma_f32_16x16x32_bf16 v[10:13], v[22:25], v[50:53], v[10:13]
	s_waitcnt vmcnt(3)
	v_mfma_f32_16x16x32_bf16 v[6:9], v[22:25], v[82:85], v[6:9]
	s_waitcnt lgkmcnt(6)
	v_mfma_f32_16x16x32_bf16 v[10:13], v[26:29], v[46:49], v[10:13]
	s_waitcnt vmcnt(2)
	v_mfma_f32_16x16x32_bf16 v[6:9], v[26:29], v[78:81], v[6:9]
	s_waitcnt lgkmcnt(5)
	v_mfma_f32_16x16x32_bf16 v[10:13], v[30:33], v[42:45], v[10:13]
	s_waitcnt vmcnt(1)
	v_mfma_f32_16x16x32_bf16 v[6:9], v[30:33], v[74:77], v[6:9]
	s_waitcnt lgkmcnt(4)
	v_mfma_f32_16x16x32_bf16 v[10:13], v[34:37], v[38:41], v[10:13]
	s_waitcnt vmcnt(0)
	v_mfma_f32_16x16x32_bf16 v[22:25], v[34:37], v[70:73], v[6:9]
	s_nop 2
	ds_read_b128 v[6:9], v174 offset:8192
	ds_read_b128 v[26:29], v175 offset:8192
	ds_read_b128 v[30:33], v176 offset:8192
	ds_read_b128 v[34:37], v177 offset:8192
	s_waitcnt lgkmcnt(7)
	v_mfma_f32_16x16x32_bf16 v[110:113], v[14:17], v[66:69], 0
	v_mfma_f32_16x16x32_bf16 v[14:17], v[14:17], v[98:101], 0
	s_waitcnt lgkmcnt(6)
	v_mfma_f32_16x16x32_bf16 v[110:113], v[18:21], v[62:65], v[110:113]
	v_mfma_f32_16x16x32_bf16 v[14:17], v[18:21], v[94:97], v[14:17]
	s_waitcnt lgkmcnt(5)
	v_mfma_f32_16x16x32_bf16 v[18:21], v[102:105], v[58:61], v[110:113]
	v_mfma_f32_16x16x32_bf16 v[14:17], v[102:105], v[90:93], v[14:17]
	s_waitcnt lgkmcnt(4)
	v_mfma_f32_16x16x32_bf16 v[18:21], v[106:109], v[54:57], v[18:21]
	v_mfma_f32_16x16x32_bf16 v[14:17], v[106:109], v[86:89], v[14:17]
	ds_read_b128 v[102:105], v170 offset:16384
	ds_read_b128 v[106:109], v171 offset:16384
	ds_read_b128 v[110:113], v172 offset:16384
	ds_read_b128 v[114:117], v173 offset:16384
	s_waitcnt lgkmcnt(7)
	v_mfma_f32_16x16x32_bf16 v[18:21], v[6:9], v[50:53], v[18:21]
	v_mfma_f32_16x16x32_bf16 v[6:9], v[6:9], v[82:85], v[14:17]
	s_waitcnt lgkmcnt(6)
	v_mfma_f32_16x16x32_bf16 v[14:17], v[26:29], v[46:49], v[18:21]
	v_mfma_f32_16x16x32_bf16 v[6:9], v[26:29], v[78:81], v[6:9]
	s_waitcnt lgkmcnt(5)
	v_mfma_f32_16x16x32_bf16 v[14:17], v[30:33], v[42:45], v[14:17]
	v_mfma_f32_16x16x32_bf16 v[6:9], v[30:33], v[74:77], v[6:9]
	s_waitcnt lgkmcnt(4)
	v_mfma_f32_16x16x32_bf16 v[14:17], v[34:37], v[38:41], v[14:17]
	v_mfma_f32_16x16x32_bf16 v[26:29], v[34:37], v[70:73], v[6:9]
	s_nop 3
	ds_read_b128 v[6:9], v174 offset:16384
	ds_read_b128 v[18:21], v175 offset:16384
	ds_read_b128 v[30:33], v176 offset:16384
	ds_read_b128 v[34:37], v177 offset:16384
	s_waitcnt lgkmcnt(7)
	v_mfma_f32_16x16x32_bf16 v[118:121], v[102:105], v[66:69], 0
	v_mfma_f32_16x16x32_bf16 v[102:105], v[102:105], v[98:101], 0
	s_waitcnt lgkmcnt(6)
	v_mfma_f32_16x16x32_bf16 v[118:121], v[106:109], v[62:65], v[118:121]
	v_mfma_f32_16x16x32_bf16 v[102:105], v[106:109], v[94:97], v[102:105]
	s_waitcnt lgkmcnt(5)
	v_mfma_f32_16x16x32_bf16 v[106:109], v[110:113], v[58:61], v[118:121]
	v_mfma_f32_16x16x32_bf16 v[102:105], v[110:113], v[90:93], v[102:105]
	s_waitcnt lgkmcnt(4)
	v_mfma_f32_16x16x32_bf16 v[106:109], v[114:117], v[54:57], v[106:109]
	v_mfma_f32_16x16x32_bf16 v[102:105], v[114:117], v[86:89], v[102:105]
	ds_read_b128 v[110:113], v170 offset:24576
	ds_read_b128 v[114:117], v171 offset:24576
	ds_read_b128 v[118:121], v172 offset:24576
	ds_read_b128 v[122:125], v173 offset:24576
	s_waitcnt lgkmcnt(7)
	v_mfma_f32_16x16x32_bf16 v[106:109], v[6:9], v[50:53], v[106:109]
	v_mfma_f32_16x16x32_bf16 v[6:9], v[6:9], v[82:85], v[102:105]
	s_waitcnt lgkmcnt(6)
	v_mfma_f32_16x16x32_bf16 v[102:105], v[18:21], v[46:49], v[106:109]
	v_mfma_f32_16x16x32_bf16 v[6:9], v[18:21], v[78:81], v[6:9]
	s_waitcnt lgkmcnt(5)
	v_mfma_f32_16x16x32_bf16 v[18:21], v[30:33], v[42:45], v[102:105]
	v_mfma_f32_16x16x32_bf16 v[6:9], v[30:33], v[74:77], v[6:9]
	s_waitcnt lgkmcnt(4)
	v_mfma_f32_16x16x32_bf16 v[18:21], v[34:37], v[38:41], v[18:21]
	v_mfma_f32_16x16x32_bf16 v[30:33], v[34:37], v[70:73], v[6:9]
	s_nop 3
	ds_read_b128 v[6:9], v174 offset:24576
	ds_read_b128 v[34:37], v175 offset:24576
	ds_read_b128 v[102:105], v176 offset:24576
	ds_read_b128 v[106:109], v177 offset:24576
	s_waitcnt lgkmcnt(7)
	v_mfma_f32_16x16x32_bf16 v[126:129], v[110:113], v[66:69], 0
	v_mfma_f32_16x16x32_bf16 v[110:113], v[110:113], v[98:101], 0
	s_waitcnt lgkmcnt(6)
	v_mfma_f32_16x16x32_bf16 v[126:129], v[114:117], v[62:65], v[126:129]
	v_mfma_f32_16x16x32_bf16 v[110:113], v[114:117], v[94:97], v[110:113]
	s_waitcnt lgkmcnt(5)
	v_mfma_f32_16x16x32_bf16 v[114:117], v[118:121], v[58:61], v[126:129]
	v_mfma_f32_16x16x32_bf16 v[110:113], v[118:121], v[90:93], v[110:113]
	s_waitcnt lgkmcnt(4)
	v_mfma_f32_16x16x32_bf16 v[114:117], v[122:125], v[54:57], v[114:117]
	v_mfma_f32_16x16x32_bf16 v[110:113], v[122:125], v[86:89], v[110:113]
	ds_read_b128 v[118:121], v170 offset:32768
	ds_read_b128 v[122:125], v171 offset:32768
	ds_read_b128 v[126:129], v172 offset:32768
	ds_read_b128 v[130:133], v173 offset:32768
	s_waitcnt lgkmcnt(7)
	v_mfma_f32_16x16x32_bf16 v[114:117], v[6:9], v[50:53], v[114:117]
	v_mfma_f32_16x16x32_bf16 v[6:9], v[6:9], v[82:85], v[110:113]
	s_waitcnt lgkmcnt(6)
	v_mfma_f32_16x16x32_bf16 v[110:113], v[34:37], v[46:49], v[114:117]
	v_mfma_f32_16x16x32_bf16 v[6:9], v[34:37], v[78:81], v[6:9]
	s_waitcnt lgkmcnt(5)
	v_mfma_f32_16x16x32_bf16 v[34:37], v[102:105], v[42:45], v[110:113]
	v_mfma_f32_16x16x32_bf16 v[6:9], v[102:105], v[74:77], v[6:9]
	s_waitcnt lgkmcnt(4)
	v_mfma_f32_16x16x32_bf16 v[114:117], v[106:109], v[38:41], v[34:37]
	v_mfma_f32_16x16x32_bf16 v[34:37], v[106:109], v[70:73], v[6:9]
	s_nop 3
	ds_read_b128 v[6:9], v174 offset:32768
	ds_read_b128 v[102:105], v175 offset:32768
	ds_read_b128 v[106:109], v176 offset:32768
	ds_read_b128 v[110:113], v177 offset:32768
	s_waitcnt lgkmcnt(7)
	v_mfma_f32_16x16x32_bf16 v[138:141], v[118:121], v[66:69], 0
	v_mfma_f32_16x16x32_bf16 v[118:121], v[118:121], v[98:101], 0
	s_waitcnt lgkmcnt(6)
	v_mfma_f32_16x16x32_bf16 v[138:141], v[122:125], v[62:65], v[138:141]
	v_mfma_f32_16x16x32_bf16 v[118:121], v[122:125], v[94:97], v[118:121]
	s_waitcnt lgkmcnt(5)
	v_mfma_f32_16x16x32_bf16 v[122:125], v[126:129], v[58:61], v[138:141]
	v_mfma_f32_16x16x32_bf16 v[118:121], v[126:129], v[90:93], v[118:121]
	s_waitcnt lgkmcnt(4)
	v_mfma_f32_16x16x32_bf16 v[122:125], v[130:133], v[54:57], v[122:125]
	v_mfma_f32_16x16x32_bf16 v[118:121], v[130:133], v[86:89], v[118:121]
	ds_read_b128 v[126:129], v170 offset:40960
	ds_read_b128 v[130:133], v171 offset:40960
	ds_read_b128 v[138:141], v172 offset:40960
	ds_read_b128 v[154:157], v173 offset:40960
	s_waitcnt lgkmcnt(7)
	v_mfma_f32_16x16x32_bf16 v[122:125], v[6:9], v[50:53], v[122:125]
	v_mfma_f32_16x16x32_bf16 v[6:9], v[6:9], v[82:85], v[118:121]
	s_waitcnt lgkmcnt(6)
	v_mfma_f32_16x16x32_bf16 v[118:121], v[102:105], v[46:49], v[122:125]
	v_mfma_f32_16x16x32_bf16 v[6:9], v[102:105], v[78:81], v[6:9]
	s_waitcnt lgkmcnt(5)
	v_mfma_f32_16x16x32_bf16 v[102:105], v[106:109], v[42:45], v[118:121]
	v_mfma_f32_16x16x32_bf16 v[6:9], v[106:109], v[74:77], v[6:9]
	s_waitcnt lgkmcnt(4)
	v_mfma_f32_16x16x32_bf16 v[118:121], v[110:113], v[38:41], v[102:105]
	v_mfma_f32_16x16x32_bf16 v[102:105], v[110:113], v[70:73], v[6:9]
	s_nop 3
	ds_read_b128 v[6:9], v174 offset:40960
	ds_read_b128 v[106:109], v175 offset:40960
	ds_read_b128 v[110:113], v176 offset:40960
	ds_read_b128 v[122:125], v177 offset:40960
	s_waitcnt lgkmcnt(7)
	v_mfma_f32_16x16x32_bf16 v[158:161], v[126:129], v[66:69], 0
	v_mfma_f32_16x16x32_bf16 v[126:129], v[126:129], v[98:101], 0
	s_waitcnt lgkmcnt(6)
	v_mfma_f32_16x16x32_bf16 v[158:161], v[130:133], v[62:65], v[158:161]
	v_mfma_f32_16x16x32_bf16 v[126:129], v[130:133], v[94:97], v[126:129]
	s_waitcnt lgkmcnt(5)
	v_mfma_f32_16x16x32_bf16 v[130:133], v[138:141], v[58:61], v[158:161]
	v_mfma_f32_16x16x32_bf16 v[126:129], v[138:141], v[90:93], v[126:129]
	s_waitcnt lgkmcnt(4)
	v_mfma_f32_16x16x32_bf16 v[130:133], v[154:157], v[54:57], v[130:133]
	v_mfma_f32_16x16x32_bf16 v[126:129], v[154:157], v[86:89], v[126:129]
	ds_read_b128 v[138:141], v170 offset:49152
	ds_read_b128 v[154:157], v171 offset:49152
	ds_read_b128 v[158:161], v172 offset:49152
	ds_read_b128 v[162:165], v173 offset:49152
	s_waitcnt lgkmcnt(7)
	v_mfma_f32_16x16x32_bf16 v[130:133], v[6:9], v[50:53], v[130:133]
	v_mfma_f32_16x16x32_bf16 v[6:9], v[6:9], v[82:85], v[126:129]
	s_waitcnt lgkmcnt(6)
	v_mfma_f32_16x16x32_bf16 v[126:129], v[106:109], v[46:49], v[130:133]
	v_mfma_f32_16x16x32_bf16 v[6:9], v[106:109], v[78:81], v[6:9]
	s_waitcnt lgkmcnt(5)
	v_mfma_f32_16x16x32_bf16 v[106:109], v[110:113], v[42:45], v[126:129]
	v_mfma_f32_16x16x32_bf16 v[6:9], v[110:113], v[74:77], v[6:9]
	s_waitcnt lgkmcnt(4)
	v_mfma_f32_16x16x32_bf16 v[126:129], v[122:125], v[38:41], v[106:109]
	v_mfma_f32_16x16x32_bf16 v[106:109], v[122:125], v[70:73], v[6:9]
	s_nop 3
	ds_read_b128 v[6:9], v174 offset:49152
	ds_read_b128 v[110:113], v175 offset:49152
	ds_read_b128 v[122:125], v176 offset:49152
	ds_read_b128 v[130:133], v177 offset:49152
	s_waitcnt lgkmcnt(7)
	v_mfma_f32_16x16x32_bf16 v[166:169], v[138:141], v[66:69], 0
	v_mfma_f32_16x16x32_bf16 v[138:141], v[138:141], v[98:101], 0
	s_waitcnt lgkmcnt(6)
	v_mfma_f32_16x16x32_bf16 v[166:169], v[154:157], v[62:65], v[166:169]
	v_mfma_f32_16x16x32_bf16 v[138:141], v[154:157], v[94:97], v[138:141]
	s_waitcnt lgkmcnt(5)
	v_mfma_f32_16x16x32_bf16 v[154:157], v[158:161], v[58:61], v[166:169]
	v_mfma_f32_16x16x32_bf16 v[138:141], v[158:161], v[90:93], v[138:141]
	s_waitcnt lgkmcnt(4)
	v_mfma_f32_16x16x32_bf16 v[154:157], v[162:165], v[54:57], v[154:157]
	v_mfma_f32_16x16x32_bf16 v[138:141], v[162:165], v[86:89], v[138:141]
	ds_read_b128 v[158:161], v170 offset:57344
	ds_read_b128 v[162:165], v171 offset:57344
	ds_read_b128 v[166:169], v172 offset:57344
	ds_read_b128 v[170:173], v173 offset:57344
	s_waitcnt lgkmcnt(7)
	v_mfma_f32_16x16x32_bf16 v[154:157], v[6:9], v[50:53], v[154:157]
	v_mfma_f32_16x16x32_bf16 v[6:9], v[6:9], v[82:85], v[138:141]
	s_waitcnt lgkmcnt(6)
	v_mfma_f32_16x16x32_bf16 v[138:141], v[110:113], v[46:49], v[154:157]
	v_mfma_f32_16x16x32_bf16 v[6:9], v[110:113], v[78:81], v[6:9]
	s_waitcnt lgkmcnt(5)
	v_mfma_f32_16x16x32_bf16 v[110:113], v[122:125], v[42:45], v[138:141]
	v_mfma_f32_16x16x32_bf16 v[6:9], v[122:125], v[74:77], v[6:9]
	s_waitcnt lgkmcnt(4)
	v_mfma_f32_16x16x32_bf16 v[122:125], v[130:133], v[38:41], v[110:113]
	v_mfma_f32_16x16x32_bf16 v[110:113], v[130:133], v[70:73], v[6:9]
	s_nop 3
	ds_read_b128 v[6:9], v174 offset:57344
	ds_read_b128 v[130:133], v175 offset:57344
	ds_read_b128 v[138:141], v176 offset:57344
	ds_read_b128 v[154:157], v177 offset:57344
	s_waitcnt lgkmcnt(7)
	v_mfma_f32_16x16x32_bf16 v[174:177], v[158:161], v[66:69], 0
	v_mfma_f32_16x16x32_bf16 v[158:161], v[158:161], v[98:101], 0
	s_waitcnt lgkmcnt(6)
	v_mfma_f32_16x16x32_bf16 v[174:177], v[162:165], v[62:65], v[174:177]
	v_mfma_f32_16x16x32_bf16 v[158:161], v[162:165], v[94:97], v[158:161]
	s_waitcnt lgkmcnt(5)
	v_mfma_f32_16x16x32_bf16 v[162:165], v[166:169], v[58:61], v[174:177]
	v_mfma_f32_16x16x32_bf16 v[158:161], v[166:169], v[90:93], v[158:161]
	s_waitcnt lgkmcnt(4)
	v_mfma_f32_16x16x32_bf16 v[162:165], v[170:173], v[54:57], v[162:165]
	v_mfma_f32_16x16x32_bf16 v[158:161], v[170:173], v[86:89], v[158:161]
	s_waitcnt lgkmcnt(3)
	v_mfma_f32_16x16x32_bf16 v[162:165], v[6:9], v[50:53], v[162:165]
	v_mfma_f32_16x16x32_bf16 v[6:9], v[6:9], v[82:85], v[158:161]
	s_waitcnt lgkmcnt(2)
	v_mfma_f32_16x16x32_bf16 v[158:161], v[130:133], v[46:49], v[162:165]
	v_mfma_f32_16x16x32_bf16 v[6:9], v[130:133], v[78:81], v[6:9]
	s_waitcnt lgkmcnt(1)
	v_mfma_f32_16x16x32_bf16 v[130:133], v[138:141], v[42:45], v[158:161]
	v_mfma_f32_16x16x32_bf16 v[6:9], v[138:141], v[74:77], v[6:9]
	s_waitcnt lgkmcnt(0)
	v_mfma_f32_16x16x32_bf16 v[130:133], v[154:157], v[38:41], v[130:133]
	v_mfma_f32_16x16x32_bf16 v[138:141], v[154:157], v[70:73], v[6:9]
	s_nop 3
	v_mul_f32_e32 v7, v148, v14
	v_mul_f32_e32 v6, v148, v10
	v_exp_f32_e32 v8, v7
	v_mul_f32_e32 v7, v148, v11
	v_mul_f32_e32 v10, v148, v12
	v_mul_f32_e32 v12, v148, v13
	v_exp_f32_e32 v6, v6
	v_exp_f32_e32 v7, v7
	v_mul_f32_e32 v9, v148, v15
	v_exp_f32_e32 v10, v10
	v_mul_f32_e32 v11, v148, v16
	v_exp_f32_e32 v12, v12
	v_mul_f32_e32 v13, v148, v17
	v_exp_f32_e32 v9, v9
	v_exp_f32_e32 v11, v11
	v_exp_f32_e32 v13, v13
	v_add_f32_e32 v14, v6, v7
	v_add_f32_e32 v15, v10, v12
	v_add_f32_e32 v14, v14, v15
	v_add_f32_e32 v15, v8, v9
	v_add_f32_e32 v16, v11, v13
	v_add_f32_e32 v15, v15, v16
	v_cvt_pk_bf16_f32 v8, v8, v9
	v_cvt_pk_bf16_f32 v9, v11, v13
	v_mul_f32_e32 v11, v148, v114
	v_add_f32_e32 v14, v14, v15
	v_cvt_pk_bf16_f32 v6, v6, v7
	v_cvt_pk_bf16_f32 v7, v10, v12
	v_mul_f32_e32 v10, v148, v18
	v_exp_f32_e32 v12, v11
	v_mul_f32_e32 v11, v148, v19
	v_mul_f32_e32 v15, v148, v20
	v_mul_f32_e32 v17, v148, v21
	v_exp_f32_e32 v10, v10
	v_exp_f32_e32 v11, v11
	v_mul_f32_e32 v13, v148, v115
	v_exp_f32_e32 v15, v15
	v_mul_f32_e32 v16, v148, v116
	v_exp_f32_e32 v17, v17
	v_mul_f32_e32 v18, v148, v117
	v_exp_f32_e32 v13, v13
	v_exp_f32_e32 v16, v16
	v_exp_f32_e32 v18, v18
	v_add_f32_e32 v19, v10, v11
	v_add_f32_e32 v20, v15, v17
	v_add_f32_e32 v19, v19, v20
	v_add_f32_e32 v20, v12, v13
	v_add_f32_e32 v21, v16, v18
	v_add_f32_e32 v20, v20, v21
	v_add_f32_e32 v14, 0, v14
	v_add_f32_e32 v19, v19, v20
	v_add_f32_e32 v14, v14, v19
	v_cvt_pk_bf16_f32 v10, v10, v11
	v_cvt_pk_bf16_f32 v11, v15, v17
	v_mul_f32_e32 v15, v148, v118
	v_mul_f32_e32 v17, v148, v119
	v_mul_f32_e32 v19, v148, v120
	v_mul_f32_e32 v21, v148, v121
	v_cvt_pk_bf16_f32 v12, v12, v13
	v_cvt_pk_bf16_f32 v13, v16, v18
	v_exp_f32_e32 v15, v15
	v_mul_f32_e32 v16, v148, v126
	v_exp_f32_e32 v17, v17
	v_mul_f32_e32 v18, v148, v127
	v_exp_f32_e32 v19, v19
	v_mul_f32_e32 v20, v148, v128
	v_exp_f32_e32 v21, v21
	v_mul_f32_e32 v114, v148, v129
	v_exp_f32_e32 v16, v16
	v_exp_f32_e32 v18, v18
	v_exp_f32_e32 v20, v20
	v_exp_f32_e32 v114, v114
	v_add_f32_e32 v115, v15, v17
	v_add_f32_e32 v116, v19, v21
	v_add_f32_e32 v115, v115, v116
	v_add_f32_e32 v116, v16, v18
	v_add_f32_e32 v117, v20, v114
	v_add_f32_e32 v116, v116, v117
	v_add_f32_e32 v115, v115, v116
	v_add_f32_e32 v115, v14, v115
	v_cvt_pk_bf16_f32 v14, v15, v17
	v_cvt_pk_bf16_f32 v15, v19, v21
	v_mul_f32_e32 v19, v148, v130
	v_cvt_pk_bf16_f32 v16, v16, v18
	v_cvt_pk_bf16_f32 v17, v20, v114
	v_mul_f32_e32 v18, v148, v122
	v_exp_f32_e32 v20, v19
	v_mul_f32_e32 v19, v148, v123
	v_mul_f32_e32 v114, v148, v124
	v_mul_f32_e32 v117, v148, v125
	v_exp_f32_e32 v18, v18
	v_exp_f32_e32 v19, v19
	v_mul_f32_e32 v21, v148, v131
	v_exp_f32_e32 v114, v114
	v_mul_f32_e32 v116, v148, v132
	v_exp_f32_e32 v117, v117
	v_mul_f32_e32 v118, v148, v133
	v_exp_f32_e32 v21, v21
	v_exp_f32_e32 v116, v116
	v_exp_f32_e32 v118, v118
	v_mul_f32_e32 v22, v147, v22
	v_mul_f32_e32 v23, v147, v23
	v_mul_f32_e32 v24, v147, v24
	v_mul_f32_e32 v25, v147, v25
	v_add_f32_e32 v119, v18, v19
	v_add_f32_e32 v120, v114, v117
	v_exp_f32_e32 v22, v22
	v_mul_f32_e32 v26, v147, v26
	v_exp_f32_e32 v23, v23
	v_mul_f32_e32 v27, v147, v27
	v_exp_f32_e32 v24, v24
	v_exp_f32_e32 v25, v25
	v_add_f32_e32 v119, v119, v120
	v_add_f32_e32 v120, v20, v21
	v_add_f32_e32 v121, v116, v118
	v_exp_f32_e32 v26, v26
	v_exp_f32_e32 v27, v27
	v_mul_f32_e32 v28, v147, v28
	v_mul_f32_e32 v29, v147, v29
	v_add_f32_e32 v120, v120, v121
	v_exp_f32_e32 v28, v28
	v_exp_f32_e32 v29, v29
	v_add_f32_e32 v119, v119, v120
	v_add_f32_e32 v155, v115, v119
	v_cvt_pk_bf16_f32 v18, v18, v19
	v_cvt_pk_bf16_f32 v19, v114, v117
	v_add_f32_e32 v114, v22, v23
	v_add_f32_e32 v115, v24, v25
	v_add_f32_e32 v114, v114, v115
	v_add_f32_e32 v115, v26, v27
	v_cvt_pk_bf16_f32 v22, v22, v23
	v_cvt_pk_bf16_f32 v23, v24, v25
	v_cvt_pk_bf16_f32 v24, v26, v27
	v_mul_f32_e32 v27, v147, v34
	v_cvt_pk_bf16_f32 v20, v20, v21
	v_cvt_pk_bf16_f32 v21, v116, v118
	v_add_f32_e32 v116, v28, v29
	v_cvt_pk_bf16_f32 v25, v28, v29
	v_mul_f32_e32 v26, v147, v30
	v_exp_f32_e32 v28, v27
	v_mul_f32_e32 v27, v147, v31
	v_mul_f32_e32 v30, v147, v32
	v_mul_f32_e32 v32, v147, v33
	v_exp_f32_e32 v26, v26
	v_exp_f32_e32 v27, v27
	v_mul_f32_e32 v29, v147, v35
	v_exp_f32_e32 v30, v30
	v_mul_f32_e32 v31, v147, v36
	v_exp_f32_e32 v32, v32
	v_mul_f32_e32 v33, v147, v37
	v_exp_f32_e32 v29, v29
	v_exp_f32_e32 v31, v31
	v_exp_f32_e32 v33, v33
	v_add_f32_e32 v34, v26, v27
	v_add_f32_e32 v35, v30, v32
	v_add_f32_e32 v34, v34, v35
	v_add_f32_e32 v35, v28, v29
	v_add_f32_e32 v36, v31, v33
	v_add_f32_e32 v35, v35, v36
	v_cvt_pk_bf16_f32 v28, v28, v29
	v_cvt_pk_bf16_f32 v29, v31, v33
	v_mul_f32_e32 v31, v147, v106
	v_add_f32_e32 v34, v34, v35
	v_cvt_pk_bf16_f32 v26, v26, v27
	v_cvt_pk_bf16_f32 v27, v30, v32
	v_mul_f32_e32 v30, v147, v102
	v_exp_f32_e32 v32, v31
	v_mul_f32_e32 v31, v147, v103
	v_mul_f32_e32 v35, v147, v104
	v_mul_f32_e32 v37, v147, v105
	v_exp_f32_e32 v30, v30
	v_exp_f32_e32 v31, v31
	v_mul_f32_e32 v33, v147, v107
	v_exp_f32_e32 v35, v35
	v_mul_f32_e32 v36, v147, v108
	v_exp_f32_e32 v37, v37
	v_mul_f32_e32 v102, v147, v109
	v_exp_f32_e32 v33, v33
	v_exp_f32_e32 v36, v36
	v_exp_f32_e32 v102, v102
	v_add_f32_e32 v115, v115, v116
	v_add_f32_e32 v103, v30, v31
	v_add_f32_e32 v104, v35, v37
	v_add_f32_e32 v114, v114, v115
	v_add_f32_e32 v103, v103, v104
	v_add_f32_e32 v104, v32, v33
	v_add_f32_e32 v105, v36, v102
	v_add_f32_e32 v114, 0, v114
	v_add_f32_e32 v104, v104, v105
	v_add_f32_e32 v34, v114, v34
	v_add_f32_e32 v103, v103, v104
	v_add_f32_e32 v34, v34, v103
	v_cvt_pk_bf16_f32 v30, v30, v31
	v_cvt_pk_bf16_f32 v31, v35, v37
	v_mul_f32_e32 v35, v147, v110
	v_mul_f32_e32 v37, v147, v111
	v_mul_f32_e32 v103, v147, v112
	v_mul_f32_e32 v105, v147, v113
	v_cvt_pk_bf16_f32 v32, v32, v33
	v_cvt_pk_bf16_f32 v33, v36, v102
	v_exp_f32_e32 v35, v35
	v_mul_f32_e32 v36, v147, v138
	v_exp_f32_e32 v37, v37
	v_mul_f32_e32 v102, v147, v139
	v_exp_f32_e32 v103, v103
	v_mul_f32_e32 v104, v147, v140
	v_exp_f32_e32 v105, v105
	v_mul_f32_e32 v106, v147, v141
	v_exp_f32_e32 v36, v36
	v_exp_f32_e32 v102, v102
	v_exp_f32_e32 v104, v104
	v_exp_f32_e32 v106, v106
	v_add_f32_e32 v107, v35, v37
	v_add_f32_e32 v108, v103, v105
	v_add_f32_e32 v107, v107, v108
	v_add_f32_e32 v108, v36, v102
	v_add_f32_e32 v109, v104, v106
	v_add_f32_e32 v108, v108, v109
	v_add_f32_e32 v107, v107, v108
	v_cvt_pk_bf16_f32 v36, v36, v102
	v_mov_b32_e32 v102, v5
	v_add_f32_e32 v154, v34, v107
	v_cvt_pk_bf16_f32 v34, v35, v37
	v_cvt_pk_bf16_f32 v37, v104, v106
	s_barrier
	v_cvt_pk_bf16_f32 v35, v103, v105
	v_mov_b32_e32 v105, v4
	v_ashrrev_i32_e32 v106, 5, v102
	v_and_b32_e32 v107, 31, v102
	v_lshl_add_u32 v102, s9, 4, v106
	v_lshrrev_b32_e32 v103, 1, v102
	v_and_b32_e32 v103, 12, v103
	v_and_b32_e32 v108, 3, v106
	v_bitop3_b32 v104, v103, v107, v108 bitop3:0x36
	v_ashrrev_i32_e32 v103, 31, v102
	v_lshlrev_b64 v[102:103], 9, v[102:103]
	v_lshl_add_u64 v[102:103], s[4:5], 0, v[102:103]
	v_lshlrev_b32_e32 v104, 4, v104
	s_lshl_b32 s9, s9, 13
	v_lshl_add_u64 v[102:103], v[102:103], 0, v[104:105]
	s_add_i32 m0, s9, 0
	s_or_b32 s9, s8, 1
	global_load_lds_dwordx4 v[102:103], off
	v_lshl_add_u32 v102, s9, 1, v106
	v_lshrrev_b32_e32 v103, 1, v102
	v_and_b32_e32 v103, 12, v103
	v_and_b32_e32 v104, 3, v102
	v_bitop3_b32 v104, v103, v107, v104 bitop3:0x36
	v_ashrrev_i32_e32 v103, 31, v102
	v_lshlrev_b64 v[102:103], 9, v[102:103]
	v_lshl_add_u64 v[102:103], s[4:5], 0, v[102:103]
	v_lshlrev_b32_e32 v104, 4, v104
	s_lshl_b32 s9, s9, 10
	v_lshl_add_u64 v[102:103], v[102:103], 0, v[104:105]
	s_add_i32 m0, s9, 0
	s_or_b32 s9, s8, 2
	global_load_lds_dwordx4 v[102:103], off
	v_lshl_add_u32 v102, s9, 1, v106
	v_lshrrev_b32_e32 v103, 1, v102
	v_and_b32_e32 v103, 12, v103
	v_bitop3_b32 v104, v103, v107, v108 bitop3:0x36
	v_ashrrev_i32_e32 v103, 31, v102
	v_lshlrev_b64 v[102:103], 9, v[102:103]
	v_lshl_add_u64 v[102:103], s[4:5], 0, v[102:103]
	v_lshlrev_b32_e32 v104, 4, v104
	s_lshl_b32 s9, s9, 10
	v_lshl_add_u64 v[102:103], v[102:103], 0, v[104:105]
	s_add_i32 m0, s9, 0
	s_or_b32 s9, s8, 3
	global_load_lds_dwordx4 v[102:103], off
	v_lshl_add_u32 v102, s9, 1, v106
	v_lshrrev_b32_e32 v103, 1, v102
	v_and_b32_e32 v103, 12, v103
	v_and_b32_e32 v104, 3, v102
	v_bitop3_b32 v104, v103, v107, v104 bitop3:0x36
	v_ashrrev_i32_e32 v103, 31, v102
	v_lshlrev_b64 v[102:103], 9, v[102:103]
	v_lshl_add_u64 v[102:103], s[4:5], 0, v[102:103]
	v_lshlrev_b32_e32 v104, 4, v104
	s_lshl_b32 s9, s9, 10
	v_lshl_add_u64 v[102:103], v[102:103], 0, v[104:105]
	s_add_i32 m0, s9, 0
	s_or_b32 s9, s8, 4
	global_load_lds_dwordx4 v[102:103], off
	v_lshl_add_u32 v102, s9, 1, v106
	v_lshrrev_b32_e32 v103, 1, v102
	v_and_b32_e32 v103, 12, v103
	v_bitop3_b32 v104, v103, v107, v108 bitop3:0x36
	v_ashrrev_i32_e32 v103, 31, v102
	v_lshlrev_b64 v[102:103], 9, v[102:103]
	v_lshl_add_u64 v[102:103], s[4:5], 0, v[102:103]
	v_lshlrev_b32_e32 v104, 4, v104
	s_lshl_b32 s9, s9, 10
	v_lshl_add_u64 v[102:103], v[102:103], 0, v[104:105]
	s_add_i32 m0, s9, 0
	s_or_b32 s9, s8, 5
	global_load_lds_dwordx4 v[102:103], off
	v_lshl_add_u32 v102, s9, 1, v106
	v_lshrrev_b32_e32 v103, 1, v102
	v_and_b32_e32 v103, 12, v103
	v_and_b32_e32 v104, 3, v102
	v_bitop3_b32 v104, v103, v107, v104 bitop3:0x36
	v_ashrrev_i32_e32 v103, 31, v102
	v_lshlrev_b64 v[102:103], 9, v[102:103]
	v_lshl_add_u64 v[102:103], s[4:5], 0, v[102:103]
	v_lshlrev_b32_e32 v104, 4, v104
	s_lshl_b32 s9, s9, 10
	v_lshl_add_u64 v[102:103], v[102:103], 0, v[104:105]
	s_add_i32 m0, s9, 0
	s_or_b32 s9, s8, 6
	global_load_lds_dwordx4 v[102:103], off
	v_lshl_add_u32 v102, s9, 1, v106
	v_lshrrev_b32_e32 v103, 1, v102
	v_and_b32_e32 v103, 12, v103
	v_bitop3_b32 v104, v103, v107, v108 bitop3:0x36
	v_ashrrev_i32_e32 v103, 31, v102
	v_lshlrev_b64 v[102:103], 9, v[102:103]
	v_lshl_add_u64 v[102:103], s[4:5], 0, v[102:103]
	v_lshlrev_b32_e32 v104, 4, v104
	s_lshl_b32 s9, s9, 10
	v_lshl_add_u64 v[102:103], v[102:103], 0, v[104:105]
	s_add_i32 m0, s9, 0
	s_or_b32 s9, s8, 7
	global_load_lds_dwordx4 v[102:103], off
	v_lshl_add_u32 v102, s9, 1, v106
	v_lshrrev_b32_e32 v103, 1, v102
	v_and_b32_e32 v103, 12, v103
	v_and_b32_e32 v104, 3, v102
	v_bitop3_b32 v104, v103, v107, v104 bitop3:0x36
	v_ashrrev_i32_e32 v103, 31, v102
	v_lshlrev_b64 v[102:103], 9, v[102:103]
	v_lshl_add_u64 v[102:103], s[4:5], 0, v[102:103]
	v_lshlrev_b32_e32 v104, 4, v104
	s_lshl_b32 s9, s9, 10
	v_lshl_add_u64 v[102:103], v[102:103], 0, v[104:105]
	s_add_i32 m0, s9, 0
	v_add_u32_e32 v130, 0x10000, v134
	global_load_lds_dwordx4 v[102:103], off
	v_add_u32_e32 v102, v130, v149
	v_add_u32_e32 v106, v130, v137
	v_add_u32_e32 v110, v130, v136
	v_add_u32_e32 v114, v130, v135
	v_add_u32_e32 v118, v130, v150
	v_add_u32_e32 v122, v130, v151
	v_add_u32_e32 v126, v130, v152
	v_add_u32_e32 v130, v130, v153
	ds_read_b128 v[102:105], v102
	ds_read_b128 v[106:109], v106
	ds_read_b128 v[110:113], v110
	ds_read_b128 v[114:117], v114
	ds_read_b128 v[118:121], v118
	ds_read_b128 v[122:125], v122
	ds_read_b128 v[126:129], v126
	ds_read_b128 v[130:133], v130
	s_waitcnt lgkmcnt(0)
	v_mfma_f32_16x16x32_bf16 v[138:141], v[102:105], v[66:69], 0
	v_mfma_f32_16x16x32_bf16 v[102:105], v[102:105], v[98:101], 0
	v_mfma_f32_16x16x32_bf16 v[138:141], v[106:109], v[62:65], v[138:141]
	v_mfma_f32_16x16x32_bf16 v[102:105], v[106:109], v[94:97], v[102:105]
	v_mfma_f32_16x16x32_bf16 v[106:109], v[110:113], v[58:61], v[138:141]
	v_mfma_f32_16x16x32_bf16 v[102:105], v[110:113], v[90:93], v[102:105]
	v_mfma_f32_16x16x32_bf16 v[106:109], v[114:117], v[54:57], v[106:109]
	v_mfma_f32_16x16x32_bf16 v[102:105], v[114:117], v[86:89], v[102:105]
	v_add_u32_e32 v160, 0x12000, v134
	v_add_u32_e32 v110, v160, v149
	v_add_u32_e32 v114, v160, v137
	v_add_u32_e32 v138, v160, v136
	v_add_u32_e32 v156, v160, v135
	ds_read_b128 v[110:113], v110
	ds_read_b128 v[114:117], v114
	ds_read_b128 v[138:141], v138
	ds_read_b128 v[156:159], v156
	v_mfma_f32_16x16x32_bf16 v[106:109], v[118:121], v[50:53], v[106:109]
	v_mfma_f32_16x16x32_bf16 v[102:105], v[118:121], v[82:85], v[102:105]
	v_mfma_f32_16x16x32_bf16 v[106:109], v[122:125], v[46:49], v[106:109]
	v_mfma_f32_16x16x32_bf16 v[102:105], v[122:125], v[78:81], v[102:105]
	v_mfma_f32_16x16x32_bf16 v[106:109], v[126:129], v[42:45], v[106:109]
	v_mfma_f32_16x16x32_bf16 v[102:105], v[126:129], v[74:77], v[102:105]
	v_mfma_f32_16x16x32_bf16 v[122:125], v[130:133], v[38:41], v[106:109]
	v_mfma_f32_16x16x32_bf16 v[102:105], v[130:133], v[70:73], v[102:105]
	s_nop 3
	v_add_u32_e32 v106, v160, v150
	v_add_u32_e32 v118, v160, v151
	v_add_u32_e32 v126, v160, v152
	ds_read_b128 v[106:109], v106
	ds_read_b128 v[118:121], v118
	v_add_u32_e32 v130, v160, v153
	ds_read_b128 v[126:129], v126
	ds_read_b128 v[160:163], v130
	s_waitcnt lgkmcnt(0)
	v_mfma_f32_16x16x32_bf16 v[130:133], v[110:113], v[66:69], 0
	v_mfma_f32_16x16x32_bf16 v[110:113], v[110:113], v[98:101], 0
	v_mfma_f32_16x16x32_bf16 v[130:133], v[114:117], v[62:65], v[130:133]
	v_mfma_f32_16x16x32_bf16 v[110:113], v[114:117], v[94:97], v[110:113]
	v_mfma_f32_16x16x32_bf16 v[114:117], v[138:141], v[58:61], v[130:133]
	v_mfma_f32_16x16x32_bf16 v[110:113], v[138:141], v[90:93], v[110:113]
	v_mfma_f32_16x16x32_bf16 v[114:117], v[156:159], v[54:57], v[114:117]
	v_mfma_f32_16x16x32_bf16 v[110:113], v[156:159], v[86:89], v[110:113]
	v_add_u32_e32 v172, 0x14000, v134
	s_nop 0
	v_add_u32_e32 v130, v172, v149
	v_add_u32_e32 v131, v172, v137
	ds_read_b128 v[138:141], v130
	ds_read_b128 v[156:159], v131
	v_add_u32_e32 v130, v172, v136
	v_add_u32_e32 v131, v172, v135
	ds_read_b128 v[164:167], v130
	ds_read_b128 v[168:171], v131
	v_mfma_f32_16x16x32_bf16 v[114:117], v[106:109], v[50:53], v[114:117]
	v_mfma_f32_16x16x32_bf16 v[106:109], v[106:109], v[82:85], v[110:113]
	v_mfma_f32_16x16x32_bf16 v[110:113], v[118:121], v[46:49], v[114:117]
	v_mfma_f32_16x16x32_bf16 v[106:109], v[118:121], v[78:81], v[106:109]
	v_mfma_f32_16x16x32_bf16 v[110:113], v[126:129], v[42:45], v[110:113]
	v_mfma_f32_16x16x32_bf16 v[106:109], v[126:129], v[74:77], v[106:109]
	v_mfma_f32_16x16x32_bf16 v[130:133], v[160:163], v[38:41], v[110:113]
	v_mfma_f32_16x16x32_bf16 v[106:109], v[160:163], v[70:73], v[106:109]
	s_nop 3
	v_add_u32_e32 v110, v172, v150
	v_add_u32_e32 v114, v172, v151
	v_add_u32_e32 v118, v172, v152
	v_add_u32_e32 v126, v172, v153
	ds_read_b128 v[110:113], v110
	ds_read_b128 v[114:117], v114
	ds_read_b128 v[118:121], v118
	ds_read_b128 v[126:129], v126
	s_waitcnt lgkmcnt(0)
	v_mfma_f32_16x16x32_bf16 v[160:163], v[138:141], v[66:69], 0
	v_mfma_f32_16x16x32_bf16 v[138:141], v[138:141], v[98:101], 0
	v_mfma_f32_16x16x32_bf16 v[160:163], v[156:159], v[62:65], v[160:163]
	v_mfma_f32_16x16x32_bf16 v[138:141], v[156:159], v[94:97], v[138:141]
	v_mfma_f32_16x16x32_bf16 v[156:159], v[164:167], v[58:61], v[160:163]
	v_mfma_f32_16x16x32_bf16 v[138:141], v[164:167], v[90:93], v[138:141]
	v_mfma_f32_16x16x32_bf16 v[156:159], v[168:171], v[54:57], v[156:159]
	v_mfma_f32_16x16x32_bf16 v[138:141], v[168:171], v[86:89], v[138:141]
	v_add_u32_e32 v176, 0x16000, v134
	s_nop 0
	v_add_u32_e32 v160, v176, v149
	v_add_u32_e32 v164, v176, v137
	v_add_u32_e32 v168, v176, v136
	v_add_u32_e32 v172, v176, v135
	ds_read_b128 v[160:163], v160
	ds_read_b128 v[164:167], v164
	ds_read_b128 v[168:171], v168
	ds_read_b128 v[172:175], v172
	v_mfma_f32_16x16x32_bf16 v[156:159], v[110:113], v[50:53], v[156:159]
	v_mfma_f32_16x16x32_bf16 v[110:113], v[110:113], v[82:85], v[138:141]
	v_mfma_f32_16x16x32_bf16 v[138:141], v[114:117], v[46:49], v[156:159]
	v_mfma_f32_16x16x32_bf16 v[110:113], v[114:117], v[78:81], v[110:113]
	v_mfma_f32_16x16x32_bf16 v[114:117], v[118:121], v[42:45], v[138:141]
	v_mfma_f32_16x16x32_bf16 v[110:113], v[118:121], v[74:77], v[110:113]
	v_mfma_f32_16x16x32_bf16 v[138:141], v[126:129], v[38:41], v[114:117]
	v_mfma_f32_16x16x32_bf16 v[110:113], v[126:129], v[70:73], v[110:113]
	s_nop 3
	v_add_u32_e32 v114, v176, v150
	v_add_u32_e32 v118, v176, v151
	v_add_u32_e32 v126, v176, v152
	v_add_u32_e32 v156, v176, v153
	ds_read_b128 v[114:117], v114
	ds_read_b128 v[118:121], v118
	ds_read_b128 v[126:129], v126
	ds_read_b128 v[156:159], v156
	s_waitcnt lgkmcnt(0)
	v_mfma_f32_16x16x32_bf16 v[176:179], v[160:163], v[66:69], 0
	v_mfma_f32_16x16x32_bf16 v[160:163], v[160:163], v[98:101], 0
	v_mfma_f32_16x16x32_bf16 v[176:179], v[164:167], v[62:65], v[176:179]
	v_mfma_f32_16x16x32_bf16 v[160:163], v[164:167], v[94:97], v[160:163]
	v_mfma_f32_16x16x32_bf16 v[164:167], v[168:171], v[58:61], v[176:179]
	v_mfma_f32_16x16x32_bf16 v[160:163], v[168:171], v[90:93], v[160:163]
	v_mfma_f32_16x16x32_bf16 v[164:167], v[172:175], v[54:57], v[164:167]
	v_mfma_f32_16x16x32_bf16 v[160:163], v[172:175], v[86:89], v[160:163]
	v_add_u32_e32 v184, 0x18000, v134
	v_add_u32_e32 v168, v184, v149
	v_add_u32_e32 v172, v184, v137
	v_add_u32_e32 v176, v184, v136
	v_add_u32_e32 v180, v184, v135
	ds_read_b128 v[168:171], v168
	ds_read_b128 v[172:175], v172
	ds_read_b128 v[176:179], v176
	ds_read_b128 v[180:183], v180
	v_mfma_f32_16x16x32_bf16 v[164:167], v[114:117], v[50:53], v[164:167]
	v_mfma_f32_16x16x32_bf16 v[114:117], v[114:117], v[82:85], v[160:163]
	v_mfma_f32_16x16x32_bf16 v[160:163], v[118:121], v[46:49], v[164:167]
	v_mfma_f32_16x16x32_bf16 v[114:117], v[118:121], v[78:81], v[114:117]
	v_mfma_f32_16x16x32_bf16 v[118:121], v[126:129], v[42:45], v[160:163]
	v_mfma_f32_16x16x32_bf16 v[114:117], v[126:129], v[74:77], v[114:117]
	v_mfma_f32_16x16x32_bf16 v[160:163], v[156:159], v[38:41], v[118:121]
	v_mfma_f32_16x16x32_bf16 v[114:117], v[156:159], v[70:73], v[114:117]
	s_nop 3
	v_add_u32_e32 v118, v184, v150
	v_add_u32_e32 v126, v184, v151
	v_add_u32_e32 v156, v184, v152
	v_add_u32_e32 v164, v184, v153
	ds_read_b128 v[118:121], v118
	ds_read_b128 v[126:129], v126
	ds_read_b128 v[156:159], v156
	ds_read_b128 v[164:167], v164
	s_waitcnt lgkmcnt(0)
	v_mfma_f32_16x16x32_bf16 v[184:187], v[168:171], v[66:69], 0
	v_mfma_f32_16x16x32_bf16 v[168:171], v[168:171], v[98:101], 0
	v_mfma_f32_16x16x32_bf16 v[184:187], v[172:175], v[62:65], v[184:187]
	v_mfma_f32_16x16x32_bf16 v[168:171], v[172:175], v[94:97], v[168:171]
	v_mfma_f32_16x16x32_bf16 v[172:175], v[176:179], v[58:61], v[184:187]
	v_mfma_f32_16x16x32_bf16 v[168:171], v[176:179], v[90:93], v[168:171]
	v_mfma_f32_16x16x32_bf16 v[172:175], v[180:183], v[54:57], v[172:175]
	v_mfma_f32_16x16x32_bf16 v[168:171], v[180:183], v[86:89], v[168:171]
	v_add_u32_e32 v192, 0x1a000, v134
	v_add_u32_e32 v176, v192, v149
	v_add_u32_e32 v180, v192, v137
	v_add_u32_e32 v184, v192, v136
	v_add_u32_e32 v188, v192, v135
	ds_read_b128 v[176:179], v176
	ds_read_b128 v[180:183], v180
	ds_read_b128 v[184:187], v184
	ds_read_b128 v[188:191], v188
	v_mfma_f32_16x16x32_bf16 v[172:175], v[118:121], v[50:53], v[172:175]
	v_mfma_f32_16x16x32_bf16 v[118:121], v[118:121], v[82:85], v[168:171]
	v_mfma_f32_16x16x32_bf16 v[168:171], v[126:129], v[46:49], v[172:175]
	v_mfma_f32_16x16x32_bf16 v[118:121], v[126:129], v[78:81], v[118:121]
	v_mfma_f32_16x16x32_bf16 v[126:129], v[156:159], v[42:45], v[168:171]
	v_mfma_f32_16x16x32_bf16 v[118:121], v[156:159], v[74:77], v[118:121]
	v_mfma_f32_16x16x32_bf16 v[156:159], v[164:167], v[38:41], v[126:129]
	v_mfma_f32_16x16x32_bf16 v[118:121], v[164:167], v[70:73], v[118:121]
	s_nop 3
	v_add_u32_e32 v126, v192, v150
	v_add_u32_e32 v164, v192, v151
	v_add_u32_e32 v168, v192, v152
	v_add_u32_e32 v172, v192, v153
	ds_read_b128 v[126:129], v126
	ds_read_b128 v[164:167], v164
	ds_read_b128 v[168:171], v168
	ds_read_b128 v[172:175], v172
	s_waitcnt lgkmcnt(0)
	v_mfma_f32_16x16x32_bf16 v[192:195], v[176:179], v[66:69], 0
	v_mfma_f32_16x16x32_bf16 v[176:179], v[176:179], v[98:101], 0
	v_mfma_f32_16x16x32_bf16 v[192:195], v[180:183], v[62:65], v[192:195]
	v_mfma_f32_16x16x32_bf16 v[176:179], v[180:183], v[94:97], v[176:179]
	v_mfma_f32_16x16x32_bf16 v[180:183], v[184:187], v[58:61], v[192:195]
	v_mfma_f32_16x16x32_bf16 v[176:179], v[184:187], v[90:93], v[176:179]
	v_mfma_f32_16x16x32_bf16 v[180:183], v[188:191], v[54:57], v[180:183]
	v_mfma_f32_16x16x32_bf16 v[176:179], v[188:191], v[86:89], v[176:179]
	v_add_u32_e32 v200, 0x1c000, v134
	v_add_u32_e32 v184, v200, v149
	v_add_u32_e32 v188, v200, v137
	v_add_u32_e32 v192, v200, v136
	v_add_u32_e32 v196, v200, v135
	ds_read_b128 v[184:187], v184
	ds_read_b128 v[188:191], v188
	ds_read_b128 v[192:195], v192
	ds_read_b128 v[196:199], v196
	v_mfma_f32_16x16x32_bf16 v[180:183], v[126:129], v[50:53], v[180:183]
	v_mfma_f32_16x16x32_bf16 v[126:129], v[126:129], v[82:85], v[176:179]
	v_mfma_f32_16x16x32_bf16 v[176:179], v[164:167], v[46:49], v[180:183]
	v_mfma_f32_16x16x32_bf16 v[126:129], v[164:167], v[78:81], v[126:129]
	v_mfma_f32_16x16x32_bf16 v[164:167], v[168:171], v[42:45], v[176:179]
	v_mfma_f32_16x16x32_bf16 v[126:129], v[168:171], v[74:77], v[126:129]
	v_mfma_f32_16x16x32_bf16 v[164:167], v[172:175], v[38:41], v[164:167]
	v_mfma_f32_16x16x32_bf16 v[126:129], v[172:175], v[70:73], v[126:129]
	v_add_u32_e32 v168, v200, v150
	v_add_u32_e32 v172, v200, v151
	v_add_u32_e32 v176, v200, v152
	v_add_u32_e32 v180, v200, v153
	ds_read_b128 v[168:171], v168
	ds_read_b128 v[172:175], v172
	ds_read_b128 v[176:179], v176
	ds_read_b128 v[180:183], v180
	s_waitcnt lgkmcnt(0)
	v_mfma_f32_16x16x32_bf16 v[200:203], v[184:187], v[66:69], 0
	v_mfma_f32_16x16x32_bf16 v[184:187], v[184:187], v[98:101], 0
	v_mfma_f32_16x16x32_bf16 v[200:203], v[188:191], v[62:65], v[200:203]
	v_mfma_f32_16x16x32_bf16 v[184:187], v[188:191], v[94:97], v[184:187]
	v_mfma_f32_16x16x32_bf16 v[188:191], v[192:195], v[58:61], v[200:203]
	v_mfma_f32_16x16x32_bf16 v[184:187], v[192:195], v[90:93], v[184:187]
	v_mfma_f32_16x16x32_bf16 v[188:191], v[196:199], v[54:57], v[188:191]
	v_mfma_f32_16x16x32_bf16 v[184:187], v[196:199], v[86:89], v[184:187]
	v_add_u32_e32 v208, 0x1e000, v134
	v_add_u32_e32 v134, v208, v149
	v_add_u32_e32 v137, v208, v137
	ds_read_b128 v[192:195], v134
	ds_read_b128 v[196:199], v137
	v_add_u32_e32 v134, v208, v136
	v_add_u32_e32 v135, v208, v135
	ds_read_b128 v[200:203], v134
	ds_read_b128 v[204:207], v135
	v_mfma_f32_16x16x32_bf16 v[134:137], v[168:171], v[50:53], v[188:191]
	v_mfma_f32_16x16x32_bf16 v[168:171], v[168:171], v[82:85], v[184:187]
	v_mfma_f32_16x16x32_bf16 v[134:137], v[172:175], v[46:49], v[134:137]
	v_mfma_f32_16x16x32_bf16 v[168:171], v[172:175], v[78:81], v[168:171]
	v_mfma_f32_16x16x32_bf16 v[134:137], v[176:179], v[42:45], v[134:137]
	v_mfma_f32_16x16x32_bf16 v[168:171], v[176:179], v[74:77], v[168:171]
	v_mfma_f32_16x16x32_bf16 v[172:175], v[180:183], v[38:41], v[134:137]
	v_mfma_f32_16x16x32_bf16 v[134:137], v[180:183], v[70:73], v[168:171]
	v_add_u32_e32 v149, v208, v150
	v_add_u32_e32 v150, v208, v151
	s_nop 2
	ds_read_b128 v[168:171], v149
	ds_read_b128 v[176:179], v150
	v_add_u32_e32 v149, v208, v152
	v_add_u32_e32 v180, v208, v153
	ds_read_b128 v[150:153], v149
	ds_read_b128 v[180:183], v180
	s_waitcnt lgkmcnt(0)
	v_mfma_f32_16x16x32_bf16 v[66:69], v[192:195], v[66:69], 0
	v_mfma_f32_16x16x32_bf16 v[98:101], v[192:195], v[98:101], 0
	v_mfma_f32_16x16x32_bf16 v[62:65], v[196:199], v[62:65], v[66:69]
	v_mfma_f32_16x16x32_bf16 v[66:69], v[196:199], v[94:97], v[98:101]
	v_mfma_f32_16x16x32_bf16 v[58:61], v[200:203], v[58:61], v[62:65]
	v_mfma_f32_16x16x32_bf16 v[62:65], v[200:203], v[90:93], v[66:69]
	v_mfma_f32_16x16x32_bf16 v[54:57], v[204:207], v[54:57], v[58:61]
	v_mfma_f32_16x16x32_bf16 v[58:61], v[204:207], v[86:89], v[62:65]
	v_mfma_f32_16x16x32_bf16 v[50:53], v[168:171], v[50:53], v[54:57]
	v_mfma_f32_16x16x32_bf16 v[54:57], v[168:171], v[82:85], v[58:61]
	v_mfma_f32_16x16x32_bf16 v[46:49], v[176:179], v[46:49], v[50:53]
	v_mfma_f32_16x16x32_bf16 v[50:53], v[176:179], v[78:81], v[54:57]
	v_mfma_f32_16x16x32_bf16 v[42:45], v[150:153], v[42:45], v[46:49]
	v_mfma_f32_16x16x32_bf16 v[46:49], v[150:153], v[74:77], v[50:53]
	v_mfma_f32_16x16x32_bf16 v[50:53], v[180:183], v[38:41], v[42:45]
	v_mfma_f32_16x16x32_bf16 v[66:69], v[180:183], v[70:73], v[46:49]
	v_mul_f32_e32 v39, v148, v130
	v_mul_f32_e32 v38, v148, v122
	v_exp_f32_e32 v40, v39
	v_mul_f32_e32 v39, v148, v123
	v_mul_f32_e32 v42, v148, v124
	v_mul_f32_e32 v44, v148, v125
	v_exp_f32_e32 v38, v38
	v_exp_f32_e32 v39, v39
	v_mul_f32_e32 v41, v148, v131
	v_exp_f32_e32 v42, v42
	v_mul_f32_e32 v43, v148, v132
	v_exp_f32_e32 v44, v44
	v_mul_f32_e32 v45, v148, v133
	v_exp_f32_e32 v41, v41
	v_exp_f32_e32 v43, v43
	v_exp_f32_e32 v45, v45
	v_add_f32_e32 v46, v38, v39
	v_add_f32_e32 v47, v42, v44
	v_add_f32_e32 v46, v46, v47
	v_add_f32_e32 v47, v40, v41
	v_add_f32_e32 v48, v43, v45
	v_add_f32_e32 v47, v47, v48
	v_cvt_pk_bf16_f32 v40, v40, v41
	v_cvt_pk_bf16_f32 v41, v43, v45
	v_mul_f32_e32 v43, v148, v160
	v_add_f32_e32 v46, v46, v47
	v_cvt_pk_bf16_f32 v38, v38, v39
	v_cvt_pk_bf16_f32 v39, v42, v44
	v_mul_f32_e32 v42, v148, v138
	v_exp_f32_e32 v44, v43
	v_mul_f32_e32 v43, v148, v139
	v_mul_f32_e32 v47, v148, v140
	v_mul_f32_e32 v49, v148, v141
	v_exp_f32_e32 v42, v42
	v_exp_f32_e32 v43, v43
	v_mul_f32_e32 v45, v148, v161
	v_exp_f32_e32 v47, v47
	v_mul_f32_e32 v48, v148, v162
	v_exp_f32_e32 v49, v49
	v_mul_f32_e32 v54, v148, v163
	v_exp_f32_e32 v45, v45
	v_exp_f32_e32 v48, v48
	v_exp_f32_e32 v54, v54
	v_add_f32_e32 v55, v42, v43
	v_add_f32_e32 v56, v47, v49
	v_add_f32_e32 v55, v55, v56
	v_add_f32_e32 v56, v44, v45
	v_add_f32_e32 v57, v48, v54
	v_add_f32_e32 v56, v56, v57
	v_add_f32_e32 v46, v155, v46
	v_add_f32_e32 v55, v55, v56
	v_add_f32_e32 v46, v46, v55
	v_cvt_pk_bf16_f32 v42, v42, v43
	v_cvt_pk_bf16_f32 v43, v47, v49
	v_mul_f32_e32 v47, v148, v156
	v_mul_f32_e32 v49, v148, v157
	v_mul_f32_e32 v55, v148, v158
	v_mul_f32_e32 v57, v148, v159
	v_cvt_pk_bf16_f32 v44, v44, v45
	v_cvt_pk_bf16_f32 v45, v48, v54
	v_exp_f32_e32 v47, v47
	v_mul_f32_e32 v48, v148, v164
	v_exp_f32_e32 v49, v49
	v_mul_f32_e32 v54, v148, v165
	v_exp_f32_e32 v55, v55
	v_mul_f32_e32 v56, v148, v166
	v_exp_f32_e32 v57, v57
	v_mul_f32_e32 v58, v148, v167
	v_exp_f32_e32 v48, v48
	v_exp_f32_e32 v54, v54
	v_exp_f32_e32 v56, v56
	v_exp_f32_e32 v58, v58
	v_add_f32_e32 v59, v47, v49
	v_add_f32_e32 v60, v55, v57
	v_add_f32_e32 v59, v59, v60
	v_add_f32_e32 v60, v48, v54
	v_add_f32_e32 v61, v56, v58
	v_add_f32_e32 v60, v60, v61
	v_add_f32_e32 v59, v59, v60
	v_mul_f32_e32 v50, v148, v50
	v_mul_f32_e32 v51, v148, v51
	v_mul_f32_e32 v52, v148, v52
	v_add_f32_e32 v59, v46, v59
	v_cvt_pk_bf16_f32 v46, v47, v49
	v_cvt_pk_bf16_f32 v47, v55, v57
	v_cvt_pk_bf16_f32 v48, v48, v54
	v_cvt_pk_bf16_f32 v49, v56, v58
	v_mul_f32_e32 v54, v148, v172
	v_exp_f32_e32 v55, v50
	v_mul_f32_e32 v50, v148, v173
	v_exp_f32_e32 v56, v51
	v_mul_f32_e32 v51, v148, v174
	v_exp_f32_e32 v57, v52
	v_mul_f32_e32 v52, v148, v175
	v_exp_f32_e32 v54, v54
	v_exp_f32_e32 v50, v50
	v_exp_f32_e32 v51, v51
	v_exp_f32_e32 v52, v52
	v_mul_f32_e32 v53, v148, v53
	v_exp_f32_e32 v53, v53
	v_add_f32_e32 v58, v54, v50
	v_add_f32_e32 v60, v51, v52
	v_add_f32_e32 v58, v58, v60
	v_add_f32_e32 v60, v55, v56
	v_add_f32_e32 v61, v57, v53
	v_add_f32_e32 v60, v60, v61
	v_add_f32_e32 v58, v58, v60
	v_cvt_pk_bf16_f32 v51, v51, v52
	v_cvt_pk_bf16_f32 v52, v55, v56
	v_mul_f32_e32 v55, v147, v106
	v_add_f32_e32 v74, v59, v58
	v_cvt_pk_bf16_f32 v50, v54, v50
	v_mul_f32_e32 v54, v147, v102
	v_exp_f32_e32 v56, v55
	v_mul_f32_e32 v55, v147, v103
	v_mul_f32_e32 v58, v147, v104
	v_mul_f32_e32 v60, v147, v105
	v_cvt_pk_bf16_f32 v53, v57, v53
	v_exp_f32_e32 v54, v54
	v_exp_f32_e32 v55, v55
	v_mul_f32_e32 v57, v147, v107
	v_exp_f32_e32 v58, v58
	v_mul_f32_e32 v59, v147, v108
	v_exp_f32_e32 v60, v60
	v_mul_f32_e32 v61, v147, v109
	v_exp_f32_e32 v57, v57
	v_exp_f32_e32 v59, v59
	v_exp_f32_e32 v61, v61
	v_add_f32_e32 v62, v54, v55
	v_add_f32_e32 v63, v58, v60
	v_add_f32_e32 v62, v62, v63
	v_add_f32_e32 v63, v56, v57
	v_add_f32_e32 v64, v59, v61
	v_add_f32_e32 v63, v63, v64
	v_cvt_pk_bf16_f32 v56, v56, v57
	v_cvt_pk_bf16_f32 v57, v59, v61
	v_mul_f32_e32 v59, v147, v114
	v_add_f32_e32 v62, v62, v63
	v_cvt_pk_bf16_f32 v54, v54, v55
	v_cvt_pk_bf16_f32 v55, v58, v60
	v_mul_f32_e32 v58, v147, v110
	v_exp_f32_e32 v60, v59
	v_mul_f32_e32 v59, v147, v111
	v_mul_f32_e32 v63, v147, v112
	v_mul_f32_e32 v65, v147, v113
	v_exp_f32_e32 v58, v58
	v_exp_f32_e32 v59, v59
	v_mul_f32_e32 v61, v147, v115
	v_exp_f32_e32 v63, v63
	v_mul_f32_e32 v64, v147, v116
	v_exp_f32_e32 v65, v65
	v_mul_f32_e32 v70, v147, v117
	v_exp_f32_e32 v61, v61
	v_exp_f32_e32 v64, v64
	v_exp_f32_e32 v70, v70
	v_add_f32_e32 v71, v58, v59
	v_add_f32_e32 v72, v63, v65
	v_add_f32_e32 v71, v71, v72
	v_add_f32_e32 v72, v60, v61
	v_add_f32_e32 v73, v64, v70
	v_add_f32_e32 v72, v72, v73
	v_add_f32_e32 v62, v154, v62
	v_add_f32_e32 v71, v71, v72
	v_add_f32_e32 v62, v62, v71
	v_cvt_pk_bf16_f32 v58, v58, v59
	v_cvt_pk_bf16_f32 v59, v63, v65
	v_mul_f32_e32 v63, v147, v118
	v_mul_f32_e32 v65, v147, v119
	v_mul_f32_e32 v71, v147, v120
	v_mul_f32_e32 v73, v147, v121
	v_cvt_pk_bf16_f32 v60, v60, v61
	v_cvt_pk_bf16_f32 v61, v64, v70
	v_exp_f32_e32 v63, v63
	v_mul_f32_e32 v64, v147, v126
	v_exp_f32_e32 v65, v65
	v_mul_f32_e32 v70, v147, v127
	v_exp_f32_e32 v71, v71
	v_mul_f32_e32 v72, v147, v128
	v_exp_f32_e32 v73, v73
	v_mul_f32_e32 v75, v147, v129
	v_exp_f32_e32 v64, v64
	v_exp_f32_e32 v70, v70
	v_exp_f32_e32 v72, v72
	v_exp_f32_e32 v75, v75
	v_add_f32_e32 v76, v63, v65
	v_add_f32_e32 v77, v71, v73
	v_add_f32_e32 v76, v76, v77
	v_add_f32_e32 v77, v64, v70
	v_add_f32_e32 v78, v72, v75
	v_add_f32_e32 v77, v77, v78
	v_add_f32_e32 v76, v76, v77
	v_mul_f32_e32 v66, v147, v66
	v_mul_f32_e32 v67, v147, v67
	v_mul_f32_e32 v68, v147, v68
	v_add_f32_e32 v76, v62, v76
	v_cvt_pk_bf16_f32 v62, v63, v65
	v_cvt_pk_bf16_f32 v63, v71, v73
	v_cvt_pk_bf16_f32 v64, v64, v70
	v_cvt_pk_bf16_f32 v65, v72, v75
	v_mul_f32_e32 v70, v147, v134
	v_exp_f32_e32 v71, v66
	v_mul_f32_e32 v66, v147, v135
	v_exp_f32_e32 v72, v67
	v_mul_f32_e32 v67, v147, v136
	v_exp_f32_e32 v73, v68
	v_mul_f32_e32 v68, v147, v137
	v_exp_f32_e32 v70, v70
	v_exp_f32_e32 v66, v66
	v_exp_f32_e32 v67, v67
	v_exp_f32_e32 v68, v68
	v_mul_f32_e32 v69, v147, v69
	v_exp_f32_e32 v69, v69
	v_add_f32_e32 v75, v70, v66
	v_add_f32_e32 v77, v67, v68
	v_add_f32_e32 v75, v75, v77
	v_add_f32_e32 v77, v71, v72
	v_add_f32_e32 v78, v73, v69
	v_add_f32_e32 v77, v77, v78
	v_add_f32_e32 v75, v75, v77
	v_add_f32_e32 v75, v76, v75
	s_waitcnt vmcnt(0)
	s_barrier
	s_add_i32 s9, s8, 64
	v_ashrrev_i32_e32 v76, 5, v5
	v_cvt_pk_bf16_f32 v66, v70, v66
	v_lshl_add_u32 v70, s9, 1, v76
	v_cvt_pk_bf16_f32 v67, v67, v68
	v_cvt_pk_bf16_f32 v68, v71, v72
	v_lshrrev_b32_e32 v71, 1, v70
	v_and_b32_e32 v5, 31, v5
	v_and_b32_e32 v71, 12, v71
	v_and_b32_e32 v77, 3, v76
	v_bitop3_b32 v72, v71, v5, v77 bitop3:0x36
	v_ashrrev_i32_e32 v71, 31, v70
	v_lshlrev_b64 v[70:71], 9, v[70:71]
	v_cvt_pk_bf16_f32 v69, v73, v69
	v_lshl_add_u64 v[70:71], s[4:5], 0, v[70:71]
	v_lshlrev_b32_e32 v72, 4, v72
	v_mov_b32_e32 v73, v4
	s_lshl_b32 s9, s9, 10
	v_lshl_add_u64 v[70:71], v[70:71], 0, v[72:73]
	s_add_i32 m0, s9, 0
	s_add_i32 s9, s8, 0x41
	global_load_lds_dwordx4 v[70:71], off
	v_lshl_add_u32 v70, s9, 1, v76
	v_lshrrev_b32_e32 v71, 1, v70
	v_and_b32_e32 v71, 12, v71
	v_and_b32_e32 v72, 3, v70
	v_bitop3_b32 v72, v71, v5, v72 bitop3:0x36
	v_ashrrev_i32_e32 v71, 31, v70
	v_lshlrev_b64 v[70:71], 9, v[70:71]
	v_lshl_add_u64 v[70:71], s[4:5], 0, v[70:71]
	v_lshlrev_b32_e32 v72, 4, v72
	s_lshl_b32 s9, s9, 10
	v_lshl_add_u64 v[70:71], v[70:71], 0, v[72:73]
	s_add_i32 m0, s9, 0
	s_add_i32 s9, s8, 0x42
	global_load_lds_dwordx4 v[70:71], off
	v_lshl_add_u32 v70, s9, 1, v76
	v_lshrrev_b32_e32 v71, 1, v70
	v_and_b32_e32 v71, 12, v71
	v_bitop3_b32 v72, v71, v5, v77 bitop3:0x36
	v_ashrrev_i32_e32 v71, 31, v70
	v_lshlrev_b64 v[70:71], 9, v[70:71]
	v_lshl_add_u64 v[70:71], s[4:5], 0, v[70:71]
	v_lshlrev_b32_e32 v72, 4, v72
	s_lshl_b32 s9, s9, 10
	v_lshl_add_u64 v[70:71], v[70:71], 0, v[72:73]
	s_add_i32 m0, s9, 0
	s_add_i32 s9, s8, 0x43
	global_load_lds_dwordx4 v[70:71], off
	v_lshl_add_u32 v70, s9, 1, v76
	v_lshrrev_b32_e32 v71, 1, v70
	v_and_b32_e32 v71, 12, v71
	v_and_b32_e32 v72, 3, v70
	v_bitop3_b32 v72, v71, v5, v72 bitop3:0x36
	v_ashrrev_i32_e32 v71, 31, v70
	v_lshlrev_b64 v[70:71], 9, v[70:71]
	v_lshl_add_u64 v[70:71], s[4:5], 0, v[70:71]
	v_lshlrev_b32_e32 v72, 4, v72
	s_lshl_b32 s9, s9, 10
	v_lshl_add_u64 v[70:71], v[70:71], 0, v[72:73]
	s_add_i32 m0, s9, 0
	s_add_i32 s9, s8, 0x44
	global_load_lds_dwordx4 v[70:71], off
	v_lshl_add_u32 v70, s9, 1, v76
	v_lshrrev_b32_e32 v71, 1, v70
	v_and_b32_e32 v71, 12, v71
	v_bitop3_b32 v72, v71, v5, v77 bitop3:0x36
	v_ashrrev_i32_e32 v71, 31, v70
	v_lshlrev_b64 v[70:71], 9, v[70:71]
	v_lshl_add_u64 v[70:71], s[4:5], 0, v[70:71]
	v_lshlrev_b32_e32 v72, 4, v72
	s_lshl_b32 s9, s9, 10
	v_lshl_add_u64 v[70:71], v[70:71], 0, v[72:73]
	s_add_i32 m0, s9, 0
	s_add_i32 s9, s8, 0x45
	global_load_lds_dwordx4 v[70:71], off
	v_lshl_add_u32 v70, s9, 1, v76
	v_lshrrev_b32_e32 v71, 1, v70
	v_and_b32_e32 v71, 12, v71
	v_and_b32_e32 v72, 3, v70
	v_bitop3_b32 v72, v71, v5, v72 bitop3:0x36
	v_ashrrev_i32_e32 v71, 31, v70
	v_lshlrev_b64 v[70:71], 9, v[70:71]
	v_lshl_add_u64 v[70:71], s[4:5], 0, v[70:71]
	v_lshlrev_b32_e32 v72, 4, v72
	s_lshl_b32 s9, s9, 10
	v_lshl_add_u64 v[70:71], v[70:71], 0, v[72:73]
	s_add_i32 m0, s9, 0
	s_add_i32 s9, s8, 0x46
	global_load_lds_dwordx4 v[70:71], off
	v_lshl_add_u32 v70, s9, 1, v76
	v_lshrrev_b32_e32 v71, 1, v70
	v_and_b32_e32 v71, 12, v71
	v_bitop3_b32 v72, v71, v5, v77 bitop3:0x36
	v_ashrrev_i32_e32 v71, 31, v70
	v_lshlrev_b64 v[70:71], 9, v[70:71]
	v_lshl_add_u64 v[70:71], s[4:5], 0, v[70:71]
	v_lshlrev_b32_e32 v72, 4, v72
	s_lshl_b32 s9, s9, 10
	v_lshl_add_u64 v[70:71], v[70:71], 0, v[72:73]
	s_add_i32 m0, s9, 0
	s_addk_i32 s8, 0x47
	global_load_lds_dwordx4 v[70:71], off
	v_lshl_add_u32 v70, s8, 1, v76
	v_lshrrev_b32_e32 v71, 1, v70
	v_and_b32_e32 v71, 12, v71
	v_and_b32_e32 v72, 3, v70
	v_bitop3_b32 v5, v71, v5, v72 bitop3:0x36
	v_ashrrev_i32_e32 v71, 31, v70
	v_lshlrev_b64 v[70:71], 9, v[70:71]
	v_lshl_add_u64 v[70:71], s[4:5], 0, v[70:71]
	v_lshlrev_b32_e32 v72, 4, v5
	s_lshl_b32 s4, s8, 10
	v_lshl_add_u64 v[70:71], v[70:71], 0, v[72:73]
	s_add_i32 m0, s4, 0
	v_mov_b32_e32 v5, v74
	global_load_lds_dwordx4 v[70:71], off
	s_nop 0
	v_permlane16_swap_b32_e32 v74, v5
	v_add_f32_e32 v5, v74, v5
	v_mov_b32_e32 v70, v5
	s_nop 1
	v_permlane32_swap_b32_e32 v5, v70
	v_add_f32_e32 v5, v5, v70
	v_div_scale_f32 v70, s[4:5], v5, v5, 1.0
	v_rcp_f32_e32 v71, v70
	v_lshl_add_u64 v[2:3], s[2:3], 0, v[2:3]
	v_bfe_u32 v87, v145, 5, 1
	v_lshl_add_u64 v[2:3], v[2:3], 0, s[6:7]
	v_fma_f32 v72, -v70, v71, 1.0
	v_fmac_f32_e32 v71, v72, v71
	v_div_scale_f32 v72, vcc, 1.0, v5, 1.0
	v_mul_f32_e32 v73, v72, v71
	v_fma_f32 v74, -v70, v73, v72
	v_fmac_f32_e32 v73, v74, v71
	v_fma_f32 v70, -v70, v73, v72
	v_div_fmas_f32 v70, v70, v71, v73
	v_div_fixup_f32 v5, v70, v5, 1.0
	v_mov_b32_e32 v70, v75
	s_nop 1
	v_permlane16_swap_b32_e32 v75, v70
	v_add_f32_e32 v70, v75, v70
	v_mov_b32_e32 v71, v70
	s_nop 1
	v_permlane32_swap_b32_e32 v70, v71
	v_add_f32_e32 v70, v70, v71
	v_div_scale_f32 v71, s[4:5], v70, v70, 1.0
	v_rcp_f32_e32 v72, v71
	v_bitop3_b32 v76, v87, v144, 8 bitop3:0x36
	v_bitop3_b32 v77, v87, v144, 10 bitop3:0x36
	v_bitop3_b32 v78, v87, v144, 12 bitop3:0x36
	v_fma_f32 v73, -v71, v72, 1.0
	v_fmac_f32_e32 v72, v73, v72
	v_div_scale_f32 v73, vcc, 1.0, v70, 1.0
	v_mul_f32_e32 v74, v73, v72
	v_fma_f32 v75, -v71, v74, v73
	v_fmac_f32_e32 v74, v75, v72
	v_fma_f32 v71, -v71, v74, v73
	v_div_fmas_f32 v71, v71, v72, v74
	v_lshlrev_b32_e32 v72, 1, v145
	v_and_b32_e32 v73, 3, v145
	v_and_or_b32 v72, v72, 24, v73
	v_and_b32_e32 v73, 8, v146
	v_lshlrev_b32_e32 v72, 9, v72
	v_add3_u32 v146, 0, v73, v72
	v_bitop3_b32 v72, v87, v145, 15 bitop3:0x78
	v_bitop3_b32 v73, v87, v144, 2 bitop3:0x36
	v_bitop3_b32 v74, v87, v144, 4 bitop3:0x36
	v_bitop3_b32 v75, v87, v144, 6 bitop3:0x36
	v_bitop3_b32 v79, v87, v144, 14 bitop3:0x36
	v_bitop3_b32 v80, v87, v144, 16 bitop3:0x36
	v_bitop3_b32 v81, v87, v144, 18 bitop3:0x36
	v_bitop3_b32 v82, v87, v144, 20 bitop3:0x36
	v_bitop3_b32 v83, v87, v144, 22 bitop3:0x36
	v_bitop3_b32 v84, v87, v144, 24 bitop3:0x36
	v_bitop3_b32 v85, v87, v144, 26 bitop3:0x36
	v_bitop3_b32 v86, v87, v144, 28 bitop3:0x36
	v_bitop3_b32 v87, v87, v144, 30 bitop3:0x36
	v_div_fixup_f32 v136, v71, v70, 1.0
	v_lshl_add_u64 v[70:71], v[2:3], 0, v[142:143]
	v_lshlrev_b32_e32 v149, 4, v72
	v_lshlrev_b32_e32 v151, 4, v73
	v_lshlrev_b32_e32 v153, 4, v74
	v_lshlrev_b32_e32 v154, 4, v75
	v_lshlrev_b32_e32 v143, 4, v76
	v_lshlrev_b32_e32 v147, 4, v77
	v_lshlrev_b32_e32 v150, 4, v78
	v_lshlrev_b32_e32 v152, 4, v79
	v_lshlrev_b32_e32 v139, 4, v80
	v_lshlrev_b32_e32 v141, 4, v81
	v_lshlrev_b32_e32 v145, 4, v82
	v_lshlrev_b32_e32 v148, 4, v83
	v_lshlrev_b32_e32 v137, 4, v84
	v_lshlrev_b32_e32 v138, 4, v85
	v_lshlrev_b32_e32 v140, 4, v86
	v_lshlrev_b32_e32 v142, 4, v87
	v_add_u32_e32 v72, v146, v149
	v_add_u32_e32 v73, v146, v151
	v_add_u32_e32 v74, v146, v153
	v_add_u32_e32 v75, v146, v154
	v_add_u32_e32 v76, v146, v143
	v_add_u32_e32 v77, v146, v147
	v_add_u32_e32 v78, v146, v150
	v_add_u32_e32 v79, v146, v152
	v_add_u32_e32 v80, v146, v139
	v_add_u32_e32 v81, v146, v141
	v_add_u32_e32 v82, v146, v145
	v_add_u32_e32 v83, v146, v148
	v_add_u32_e32 v84, v146, v137
	v_add_u32_e32 v85, v146, v138
	v_add_u32_e32 v86, v146, v140
	v_add_u32_e32 v87, v146, v142
	s_waitcnt vmcnt(8)
	s_waitcnt lgkmcnt(0)
	s_barrier
	ds_read2st64_b64 v[88:91], v72 offset1:4
	ds_read2st64_b64 v[92:95], v73 offset1:4
	ds_read2st64_b64 v[96:99], v74 offset1:4
	ds_read2st64_b64 v[100:103], v75 offset1:4
	ds_read2st64_b64 v[104:107], v76 offset1:4
	ds_read2st64_b64 v[108:111], v77 offset1:4
	ds_read2st64_b64 v[112:115], v78 offset1:4
	ds_read2st64_b64 v[116:119], v79 offset1:4
	ds_read2st64_b64 v[120:123], v80 offset1:4
	ds_read2st64_b64 v[124:127], v81 offset1:4
	ds_read2st64_b64 v[128:131], v82 offset1:4
	ds_read2st64_b64 v[132:135], v83 offset1:4
	ds_read2st64_b64 v[156:159], v84 offset1:4
	ds_read2st64_b64 v[160:163], v85 offset1:4
	ds_read2st64_b64 v[164:167], v86 offset1:4
	ds_read2st64_b64 v[168:171], v87 offset1:4
	s_mov_b64 s[2:3], 0xae00000
	v_lshl_add_u64 v[2:3], v[70:71], 0, s[2:3]
	s_waitcnt lgkmcnt(14)
	v_mov_b32_e32 v172, v88
	v_mov_b32_e32 v173, v89
	v_mov_b32_e32 v174, v92
	v_mov_b32_e32 v175, v93
	s_waitcnt lgkmcnt(13)
	v_mov_b32_e32 v180, v96
	v_mov_b32_e32 v181, v97
	s_waitcnt lgkmcnt(12)
	v_mov_b32_e32 v182, v100
	v_mov_b32_e32 v183, v101
	v_mfma_f32_16x16x32_bf16 v[176:179], v[172:175], v[6:9], 0
	v_mfma_f32_16x16x32_bf16 v[172:175], v[172:175], v[22:25], 0
	v_mfma_f32_16x16x32_bf16 v[176:179], v[180:183], v[10:13], v[176:179]
	v_mfma_f32_16x16x32_bf16 v[172:175], v[180:183], v[26:29], v[172:175]
	s_waitcnt lgkmcnt(11)
	v_mov_b32_e32 v180, v104
	v_mov_b32_e32 v181, v105
	s_waitcnt lgkmcnt(10)
	v_mov_b32_e32 v182, v108
	v_mov_b32_e32 v183, v109
	s_nop 1
	v_mfma_f32_16x16x32_bf16 v[176:179], v[180:183], v[14:17], v[176:179]
	v_mfma_f32_16x16x32_bf16 v[172:175], v[180:183], v[30:33], v[172:175]
	s_waitcnt lgkmcnt(9)
	v_mov_b32_e32 v180, v112
	v_mov_b32_e32 v181, v113
	s_waitcnt lgkmcnt(8)
	v_mov_b32_e32 v182, v116
	v_mov_b32_e32 v183, v117
	s_nop 1
	v_mfma_f32_16x16x32_bf16 v[176:179], v[180:183], v[18:21], v[176:179]
	v_mfma_f32_16x16x32_bf16 v[172:175], v[180:183], v[34:37], v[172:175]
	s_waitcnt lgkmcnt(7)
	v_mov_b32_e32 v180, v120
	v_mov_b32_e32 v181, v121
	s_waitcnt lgkmcnt(6)
	v_mov_b32_e32 v182, v124
	v_mov_b32_e32 v183, v125
	s_nop 1
	v_mfma_f32_16x16x32_bf16 v[176:179], v[180:183], v[38:41], v[176:179]
	v_mfma_f32_16x16x32_bf16 v[172:175], v[180:183], v[54:57], v[172:175]
	s_waitcnt lgkmcnt(5)
	v_mov_b32_e32 v180, v128
	v_mov_b32_e32 v181, v129
	s_waitcnt lgkmcnt(4)
	v_mov_b32_e32 v182, v132
	v_mov_b32_e32 v183, v133
	s_nop 1
	v_mfma_f32_16x16x32_bf16 v[176:179], v[180:183], v[42:45], v[176:179]
	v_mfma_f32_16x16x32_bf16 v[172:175], v[180:183], v[58:61], v[172:175]
	s_waitcnt lgkmcnt(3)
	v_mov_b32_e32 v180, v156
	v_mov_b32_e32 v181, v157
	s_waitcnt lgkmcnt(2)
	v_mov_b32_e32 v182, v160
	v_mov_b32_e32 v183, v161
	s_nop 1
	v_mfma_f32_16x16x32_bf16 v[176:179], v[180:183], v[46:49], v[176:179]
	v_mfma_f32_16x16x32_bf16 v[172:175], v[180:183], v[62:65], v[172:175]
	s_waitcnt lgkmcnt(1)
	v_mov_b32_e32 v180, v164
	v_mov_b32_e32 v181, v165
	s_waitcnt lgkmcnt(0)
	v_mov_b32_e32 v182, v168
	v_mov_b32_e32 v183, v169
	s_nop 1
	v_mfma_f32_16x16x32_bf16 v[176:179], v[180:183], v[50:53], v[176:179]
	v_mfma_f32_16x16x32_bf16 v[172:175], v[180:183], v[66:69], v[172:175]
	s_nop 5
	v_mul_f32_e32 v88, v5, v176
	v_mul_f32_e32 v89, v5, v177
	v_cvt_pk_bf16_f32 v88, v88, v89
	v_mul_f32_e32 v89, v5, v178
	v_mul_f32_e32 v92, v5, v179
	v_cvt_pk_bf16_f32 v89, v89, v92
	v_mul_f32_e32 v92, v136, v172
	v_mul_f32_e32 v93, v136, v173
	v_cvt_pk_bf16_f32 v96, v92, v93
	v_mul_f32_e32 v92, v136, v174
	v_mul_f32_e32 v93, v136, v175
	ds_read_b64 v[172:173], v72 offset:16384
	ds_read_b64 v[174:175], v73 offset:16384
	ds_read_b64 v[176:177], v74 offset:16384
	ds_read_b64 v[178:179], v75 offset:16384
	ds_read_b64 v[180:181], v76 offset:16384
	ds_read_b64 v[182:183], v77 offset:16384
	ds_read_b64 v[184:185], v78 offset:16384
	ds_read_b64 v[186:187], v79 offset:16384
	ds_read_b64 v[188:189], v80 offset:16384
	ds_read_b64 v[190:191], v81 offset:16384
	ds_read_b64 v[192:193], v82 offset:16384
	ds_read_b64 v[194:195], v83 offset:16384
	ds_read_b64 v[196:197], v84 offset:16384
	ds_read_b64 v[198:199], v85 offset:16384
	ds_read_b64 v[200:201], v86 offset:16384
	ds_read_b64 v[202:203], v87 offset:16384
	v_cvt_pk_bf16_f32 v97, v92, v93
	v_mov_b32_e32 v92, v90
	v_mov_b32_e32 v93, v91
	v_mov_b32_e32 v100, v98
	v_mov_b32_e32 v101, v99
	v_mov_b32_e32 v108, v106
	v_mfma_f32_16x16x32_bf16 v[204:207], v[92:95], v[6:9], 0
	v_mov_b32_e32 v109, v107
	v_mov_b32_e32 v116, v114
	v_mov_b32_e32 v117, v115
	v_mfma_f32_16x16x32_bf16 v[90:93], v[92:95], v[22:25], 0
	v_mov_b32_e32 v124, v122
	v_mov_b32_e32 v125, v123
	v_mov_b32_e32 v132, v130
	v_mfma_f32_16x16x32_bf16 v[204:207], v[100:103], v[10:13], v[204:207]
	v_mov_b32_e32 v133, v131
	v_mov_b32_e32 v160, v158
	v_mov_b32_e32 v161, v159
	v_mfma_f32_16x16x32_bf16 v[90:93], v[100:103], v[26:29], v[90:93]
	v_mov_b32_e32 v168, v166
	v_mov_b32_e32 v169, v167
	v_mfma_f32_16x16x32_bf16 v[98:101], v[108:111], v[14:17], v[204:207]
	v_mfma_f32_16x16x32_bf16 v[90:93], v[108:111], v[30:33], v[90:93]
	v_mfma_f32_16x16x32_bf16 v[98:101], v[116:119], v[18:21], v[98:101]
	v_mfma_f32_16x16x32_bf16 v[90:93], v[116:119], v[34:37], v[90:93]
	v_mfma_f32_16x16x32_bf16 v[98:101], v[124:127], v[38:41], v[98:101]
	v_mfma_f32_16x16x32_bf16 v[90:93], v[124:127], v[54:57], v[90:93]
	v_mfma_f32_16x16x32_bf16 v[98:101], v[132:135], v[42:45], v[98:101]
	v_mfma_f32_16x16x32_bf16 v[90:93], v[132:135], v[58:61], v[90:93]
	v_mfma_f32_16x16x32_bf16 v[98:101], v[160:163], v[46:49], v[98:101]
	v_mfma_f32_16x16x32_bf16 v[90:93], v[160:163], v[62:65], v[90:93]
	v_mfma_f32_16x16x32_bf16 v[98:101], v[168:171], v[50:53], v[98:101]
	v_mfma_f32_16x16x32_bf16 v[92:95], v[168:171], v[66:69], v[90:93]
	s_nop 5
	v_mul_f32_e32 v90, v5, v98
	v_mul_f32_e32 v91, v5, v99
	v_cvt_pk_bf16_f32 v90, v90, v91
	v_mul_f32_e32 v91, v5, v100
	v_mul_f32_e32 v98, v5, v101
	v_mul_f32_e32 v92, v136, v92
	v_cvt_pk_bf16_f32 v91, v91, v98
	v_mul_f32_e32 v93, v136, v93
	v_cvt_pk_bf16_f32 v98, v92, v93
	v_mul_f32_e32 v92, v136, v94
	s_mov_b32 s2, 0xae00000
	v_mul_f32_e32 v93, v136, v95
	v_cvt_pk_bf16_f32 v99, v92, v93
	v_add_co_u32_e32 v92, vcc, s2, v70
	s_mov_b32 s2, 0xae08000
	s_nop 0
	v_addc_co_u32_e32 v93, vcc, 0, v71, vcc
	v_add_co_u32_e32 v134, vcc, s2, v70
	global_store_dwordx4 v[92:93], v[88:91], off sc1
	s_nop 0
	v_addc_co_u32_e32 v135, vcc, 0, v71, vcc
	global_store_dwordx4 v[134:135], v[96:99], off sc1
	ds_read_b64 v[88:89], v72 offset:18432
	ds_read_b64 v[90:91], v73 offset:18432
	ds_read_b64 v[92:93], v74 offset:18432
	ds_read_b64 v[94:95], v75 offset:18432
	ds_read_b64 v[96:97], v76 offset:18432
	ds_read_b64 v[98:99], v77 offset:18432
	ds_read_b64 v[100:101], v78 offset:18432
	ds_read_b64 v[102:103], v79 offset:18432
	ds_read_b64 v[104:105], v80 offset:18432
	ds_read_b64 v[106:107], v81 offset:18432
	ds_read_b64 v[108:109], v82 offset:18432
	ds_read_b64 v[110:111], v83 offset:18432
	ds_read_b64 v[112:113], v84 offset:18432
	ds_read_b64 v[114:115], v85 offset:18432
	ds_read_b64 v[116:117], v86 offset:18432
	ds_read_b64 v[118:119], v87 offset:18432
	s_waitcnt lgkmcnt(14)
	v_mfma_f32_16x16x32_bf16 v[120:123], v[172:175], v[6:9], 0
	v_mfma_f32_16x16x32_bf16 v[124:127], v[172:175], v[22:25], 0
	v_mfma_f32_16x16x32_bf16 v[120:123], v[176:179], v[10:13], v[120:123]
	v_mfma_f32_16x16x32_bf16 v[124:127], v[176:179], v[26:29], v[124:127]
	v_mfma_f32_16x16x32_bf16 v[120:123], v[180:183], v[14:17], v[120:123]
	v_mfma_f32_16x16x32_bf16 v[124:127], v[180:183], v[30:33], v[124:127]
	v_mfma_f32_16x16x32_bf16 v[120:123], v[184:187], v[18:21], v[120:123]
	v_mfma_f32_16x16x32_bf16 v[124:127], v[184:187], v[34:37], v[124:127]
	v_mfma_f32_16x16x32_bf16 v[120:123], v[188:191], v[38:41], v[120:123]
	v_mfma_f32_16x16x32_bf16 v[124:127], v[188:191], v[54:57], v[124:127]
	v_mfma_f32_16x16x32_bf16 v[120:123], v[192:195], v[42:45], v[120:123]
	v_mfma_f32_16x16x32_bf16 v[124:127], v[192:195], v[58:61], v[124:127]
	v_mfma_f32_16x16x32_bf16 v[120:123], v[196:199], v[46:49], v[120:123]
	v_mfma_f32_16x16x32_bf16 v[124:127], v[196:199], v[62:65], v[124:127]
	v_mfma_f32_16x16x32_bf16 v[120:123], v[200:203], v[50:53], v[120:123]
	v_mfma_f32_16x16x32_bf16 v[124:127], v[200:203], v[66:69], v[124:127]
	ds_read_b64 v[128:129], v72 offset:32768
	ds_read_b64 v[130:131], v73 offset:32768
	ds_read_b64 v[156:157], v74 offset:32768
	ds_read_b64 v[158:159], v75 offset:32768
	ds_read_b64 v[160:161], v76 offset:32768
	ds_read_b64 v[162:163], v77 offset:32768
	ds_read_b64 v[164:165], v78 offset:32768
	ds_read_b64 v[166:167], v79 offset:32768
	ds_read_b64 v[168:169], v80 offset:32768
	ds_read_b64 v[170:171], v81 offset:32768
	ds_read_b64 v[172:173], v82 offset:32768
	ds_read_b64 v[174:175], v83 offset:32768
	ds_read_b64 v[176:177], v84 offset:32768
	ds_read_b64 v[178:179], v85 offset:32768
	ds_read_b64 v[180:181], v86 offset:32768
	ds_read_b64 v[182:183], v87 offset:32768
	v_mul_f32_e32 v70, v5, v120
	v_mul_f32_e32 v71, v5, v121
	v_cvt_pk_bf16_f32 v120, v70, v71
	v_mul_f32_e32 v70, v5, v122
	v_mul_f32_e32 v71, v5, v123
	v_cvt_pk_bf16_f32 v121, v70, v71
	v_mul_f32_e32 v70, v136, v124
	v_mul_f32_e32 v71, v136, v125
	v_cvt_pk_bf16_f32 v124, v70, v71
	v_mul_f32_e32 v70, v136, v126
	v_mul_f32_e32 v71, v136, v127
	v_cvt_pk_bf16_f32 v125, v70, v71
	v_mfma_f32_16x16x32_bf16 v[184:187], v[88:91], v[6:9], 0
	v_mfma_f32_16x16x32_bf16 v[88:91], v[88:91], v[22:25], 0
	s_waitcnt lgkmcnt(14)
	v_mfma_f32_16x16x32_bf16 v[184:187], v[92:95], v[10:13], v[184:187]
	v_mfma_f32_16x16x32_bf16 v[88:91], v[92:95], v[26:29], v[88:91]
	v_mfma_f32_16x16x32_bf16 v[92:95], v[96:99], v[14:17], v[184:187]
	v_mfma_f32_16x16x32_bf16 v[88:91], v[96:99], v[30:33], v[88:91]
	v_mfma_f32_16x16x32_bf16 v[92:95], v[100:103], v[18:21], v[92:95]
	v_mfma_f32_16x16x32_bf16 v[88:91], v[100:103], v[34:37], v[88:91]
	v_mfma_f32_16x16x32_bf16 v[92:95], v[104:107], v[38:41], v[92:95]
	v_mfma_f32_16x16x32_bf16 v[88:91], v[104:107], v[54:57], v[88:91]
	v_mfma_f32_16x16x32_bf16 v[92:95], v[108:111], v[42:45], v[92:95]
	v_mfma_f32_16x16x32_bf16 v[88:91], v[108:111], v[58:61], v[88:91]
	v_mfma_f32_16x16x32_bf16 v[92:95], v[112:115], v[46:49], v[92:95]
	v_mfma_f32_16x16x32_bf16 v[88:91], v[112:115], v[62:65], v[88:91]
	v_mfma_f32_16x16x32_bf16 v[92:95], v[116:119], v[50:53], v[92:95]
	v_mfma_f32_16x16x32_bf16 v[88:91], v[116:119], v[66:69], v[88:91]
	s_nop 5
	v_mul_f32_e32 v70, v5, v92
	v_mul_f32_e32 v71, v5, v93
	v_cvt_pk_bf16_f32 v122, v70, v71
	v_mul_f32_e32 v70, v5, v94
	v_mul_f32_e32 v71, v5, v95
	v_cvt_pk_bf16_f32 v123, v70, v71
	v_mul_f32_e32 v70, v136, v88
	v_mul_f32_e32 v71, v136, v89
	v_cvt_pk_bf16_f32 v126, v70, v71
	v_mul_f32_e32 v70, v136, v90
	v_mul_f32_e32 v71, v136, v91
	v_cvt_pk_bf16_f32 v127, v70, v71
	global_store_dwordx4 v[2:3], v[120:123], off offset:64 sc1
	global_store_dwordx4 v[134:135], v[124:127], off offset:64 sc1
	ds_read_b64 v[88:89], v72 offset:34816
	ds_read_b64 v[90:91], v73 offset:34816
	ds_read_b64 v[92:93], v74 offset:34816
	ds_read_b64 v[94:95], v75 offset:34816
	ds_read_b64 v[96:97], v76 offset:34816
	ds_read_b64 v[98:99], v77 offset:34816
	ds_read_b64 v[100:101], v78 offset:34816
	ds_read_b64 v[102:103], v79 offset:34816
	ds_read_b64 v[104:105], v80 offset:34816
	ds_read_b64 v[106:107], v81 offset:34816
	ds_read_b64 v[108:109], v82 offset:34816
	ds_read_b64 v[110:111], v83 offset:34816
	ds_read_b64 v[112:113], v84 offset:34816
	ds_read_b64 v[114:115], v85 offset:34816
	ds_read_b64 v[116:117], v86 offset:34816
	ds_read_b64 v[118:119], v87 offset:34816
	v_mfma_f32_16x16x32_bf16 v[120:123], v[128:131], v[6:9], 0
	v_mfma_f32_16x16x32_bf16 v[124:127], v[128:131], v[22:25], 0
	s_waitcnt lgkmcnt(14)
	v_mfma_f32_16x16x32_bf16 v[120:123], v[156:159], v[10:13], v[120:123]
	v_mfma_f32_16x16x32_bf16 v[124:127], v[156:159], v[26:29], v[124:127]
	v_mfma_f32_16x16x32_bf16 v[120:123], v[160:163], v[14:17], v[120:123]
	v_mfma_f32_16x16x32_bf16 v[124:127], v[160:163], v[30:33], v[124:127]
	v_mfma_f32_16x16x32_bf16 v[120:123], v[164:167], v[18:21], v[120:123]
	v_mfma_f32_16x16x32_bf16 v[124:127], v[164:167], v[34:37], v[124:127]
	v_mfma_f32_16x16x32_bf16 v[120:123], v[168:171], v[38:41], v[120:123]
	v_mfma_f32_16x16x32_bf16 v[124:127], v[168:171], v[54:57], v[124:127]
	v_mfma_f32_16x16x32_bf16 v[120:123], v[172:175], v[42:45], v[120:123]
	v_mfma_f32_16x16x32_bf16 v[124:127], v[172:175], v[58:61], v[124:127]
	v_mfma_f32_16x16x32_bf16 v[120:123], v[176:179], v[46:49], v[120:123]
	v_mfma_f32_16x16x32_bf16 v[124:127], v[176:179], v[62:65], v[124:127]
	v_mfma_f32_16x16x32_bf16 v[120:123], v[180:183], v[50:53], v[120:123]
	v_mfma_f32_16x16x32_bf16 v[124:127], v[180:183], v[66:69], v[124:127]
	ds_read_b64 v[128:129], v72 offset:49152
	ds_read_b64 v[130:131], v73 offset:49152
	ds_read_b64 v[156:157], v74 offset:49152
	ds_read_b64 v[158:159], v75 offset:49152
	ds_read_b64 v[160:161], v76 offset:49152
	ds_read_b64 v[162:163], v77 offset:49152
	ds_read_b64 v[164:165], v78 offset:49152
	ds_read_b64 v[166:167], v79 offset:49152
	ds_read_b64 v[168:169], v80 offset:49152
	ds_read_b64 v[170:171], v81 offset:49152
	ds_read_b64 v[172:173], v82 offset:49152
	ds_read_b64 v[174:175], v83 offset:49152
	ds_read_b64 v[176:177], v84 offset:49152
	ds_read_b64 v[178:179], v85 offset:49152
	ds_read_b64 v[180:181], v86 offset:49152
	ds_read_b64 v[182:183], v87 offset:49152
	v_mul_f32_e32 v70, v5, v120
	v_mul_f32_e32 v71, v5, v121
	v_cvt_pk_bf16_f32 v120, v70, v71
	v_mul_f32_e32 v70, v5, v122
	v_mul_f32_e32 v71, v5, v123
	v_cvt_pk_bf16_f32 v121, v70, v71
	v_mul_f32_e32 v70, v136, v124
	v_mul_f32_e32 v71, v136, v125
	v_cvt_pk_bf16_f32 v124, v70, v71
	v_mul_f32_e32 v70, v136, v126
	v_mul_f32_e32 v71, v136, v127
	v_cvt_pk_bf16_f32 v125, v70, v71
	v_mfma_f32_16x16x32_bf16 v[184:187], v[88:91], v[6:9], 0
	v_mfma_f32_16x16x32_bf16 v[88:91], v[88:91], v[22:25], 0
	s_waitcnt lgkmcnt(14)
	v_mfma_f32_16x16x32_bf16 v[184:187], v[92:95], v[10:13], v[184:187]
	v_mfma_f32_16x16x32_bf16 v[88:91], v[92:95], v[26:29], v[88:91]
	v_mfma_f32_16x16x32_bf16 v[92:95], v[96:99], v[14:17], v[184:187]
	v_mfma_f32_16x16x32_bf16 v[88:91], v[96:99], v[30:33], v[88:91]
	v_mfma_f32_16x16x32_bf16 v[92:95], v[100:103], v[18:21], v[92:95]
	v_mfma_f32_16x16x32_bf16 v[88:91], v[100:103], v[34:37], v[88:91]
	v_mfma_f32_16x16x32_bf16 v[92:95], v[104:107], v[38:41], v[92:95]
	v_mfma_f32_16x16x32_bf16 v[88:91], v[104:107], v[54:57], v[88:91]
	v_mfma_f32_16x16x32_bf16 v[92:95], v[108:111], v[42:45], v[92:95]
	v_mfma_f32_16x16x32_bf16 v[88:91], v[108:111], v[58:61], v[88:91]
	v_mfma_f32_16x16x32_bf16 v[92:95], v[112:115], v[46:49], v[92:95]
	v_mfma_f32_16x16x32_bf16 v[88:91], v[112:115], v[62:65], v[88:91]
	v_mfma_f32_16x16x32_bf16 v[92:95], v[116:119], v[50:53], v[92:95]
	v_mfma_f32_16x16x32_bf16 v[88:91], v[116:119], v[66:69], v[88:91]
	s_nop 5
	v_mul_f32_e32 v70, v5, v92
	v_mul_f32_e32 v71, v5, v93
	v_cvt_pk_bf16_f32 v122, v70, v71
	v_mul_f32_e32 v70, v5, v94
	v_mul_f32_e32 v71, v5, v95
	v_cvt_pk_bf16_f32 v123, v70, v71
	v_mul_f32_e32 v70, v136, v88
	v_mul_f32_e32 v71, v136, v89
	v_cvt_pk_bf16_f32 v126, v70, v71
	v_mul_f32_e32 v70, v136, v90
	v_mul_f32_e32 v71, v136, v91
	v_cvt_pk_bf16_f32 v127, v70, v71
	global_store_dwordx4 v[2:3], v[120:123], off offset:128 sc1
	global_store_dwordx4 v[134:135], v[124:127], off offset:128 sc1
	ds_read_b64 v[70:71], v72 offset:51200
	ds_read_b64 v[72:73], v73 offset:51200
	ds_read_b64 v[88:89], v74 offset:51200
	ds_read_b64 v[90:91], v75 offset:51200
	ds_read_b64 v[74:75], v76 offset:51200
	ds_read_b64 v[76:77], v77 offset:51200
	ds_read_b64 v[92:93], v78 offset:51200
	ds_read_b64 v[94:95], v79 offset:51200
	ds_read_b64 v[78:79], v80 offset:51200
	ds_read_b64 v[80:81], v81 offset:51200
	ds_read_b64 v[96:97], v82 offset:51200
	ds_read_b64 v[98:99], v83 offset:51200
	ds_read_b64 v[82:83], v84 offset:51200
	ds_read_b64 v[84:85], v85 offset:51200
	ds_read_b64 v[100:101], v86 offset:51200
	ds_read_b64 v[102:103], v87 offset:51200
	v_mfma_f32_16x16x32_bf16 v[104:107], v[128:131], v[6:9], 0
	v_mfma_f32_16x16x32_bf16 v[108:111], v[128:131], v[22:25], 0
	s_waitcnt lgkmcnt(14)
	v_mfma_f32_16x16x32_bf16 v[104:107], v[156:159], v[10:13], v[104:107]
	v_mfma_f32_16x16x32_bf16 v[108:111], v[156:159], v[26:29], v[108:111]
	v_mfma_f32_16x16x32_bf16 v[104:107], v[160:163], v[14:17], v[104:107]
	v_mfma_f32_16x16x32_bf16 v[108:111], v[160:163], v[30:33], v[108:111]
	v_mfma_f32_16x16x32_bf16 v[104:107], v[164:167], v[18:21], v[104:107]
	v_mfma_f32_16x16x32_bf16 v[108:111], v[164:167], v[34:37], v[108:111]
	v_mfma_f32_16x16x32_bf16 v[104:107], v[168:171], v[38:41], v[104:107]
	v_mfma_f32_16x16x32_bf16 v[108:111], v[168:171], v[54:57], v[108:111]
	v_mfma_f32_16x16x32_bf16 v[104:107], v[172:175], v[42:45], v[104:107]
	v_mfma_f32_16x16x32_bf16 v[108:111], v[172:175], v[58:61], v[108:111]
	v_mfma_f32_16x16x32_bf16 v[104:107], v[176:179], v[46:49], v[104:107]
	v_mfma_f32_16x16x32_bf16 v[108:111], v[176:179], v[62:65], v[108:111]
	v_mfma_f32_16x16x32_bf16 v[104:107], v[180:183], v[50:53], v[104:107]
	v_mfma_f32_16x16x32_bf16 v[108:111], v[180:183], v[66:69], v[108:111]
	s_nop 5
	v_mul_f32_e32 v86, v5, v104
	v_mul_f32_e32 v87, v5, v105
	v_cvt_pk_bf16_f32 v86, v86, v87
	v_mul_f32_e32 v87, v5, v106
	v_mul_f32_e32 v104, v5, v107
	v_cvt_pk_bf16_f32 v87, v87, v104
	v_mul_f32_e32 v104, v136, v108
	v_mul_f32_e32 v105, v136, v109
	v_cvt_pk_bf16_f32 v104, v104, v105
	v_mul_f32_e32 v105, v136, v110
	v_mul_f32_e32 v106, v136, v111
	v_cvt_pk_bf16_f32 v105, v105, v106
	v_mfma_f32_16x16x32_bf16 v[106:109], v[70:73], v[6:9], 0
	v_mfma_f32_16x16x32_bf16 v[70:73], v[70:73], v[22:25], 0
	s_waitcnt lgkmcnt(12)
	v_mfma_f32_16x16x32_bf16 v[106:109], v[88:91], v[10:13], v[106:109]
	v_mfma_f32_16x16x32_bf16 v[70:73], v[88:91], v[26:29], v[70:73]
	s_waitcnt lgkmcnt(10)
	v_mfma_f32_16x16x32_bf16 v[88:91], v[74:77], v[14:17], v[106:109]
	v_mfma_f32_16x16x32_bf16 v[70:73], v[74:77], v[30:33], v[70:73]
	s_waitcnt lgkmcnt(8)
	v_mfma_f32_16x16x32_bf16 v[74:77], v[92:95], v[18:21], v[88:91]
	v_mfma_f32_16x16x32_bf16 v[70:73], v[92:95], v[34:37], v[70:73]
	s_waitcnt lgkmcnt(6)
	v_mfma_f32_16x16x32_bf16 v[74:77], v[78:81], v[38:41], v[74:77]
	v_mfma_f32_16x16x32_bf16 v[70:73], v[78:81], v[54:57], v[70:73]
	s_waitcnt lgkmcnt(4)
	v_mfma_f32_16x16x32_bf16 v[74:77], v[96:99], v[42:45], v[74:77]
	v_mfma_f32_16x16x32_bf16 v[70:73], v[96:99], v[58:61], v[70:73]
	s_waitcnt lgkmcnt(2)
	v_mfma_f32_16x16x32_bf16 v[74:77], v[82:85], v[46:49], v[74:77]
	v_mfma_f32_16x16x32_bf16 v[70:73], v[82:85], v[62:65], v[70:73]
	s_waitcnt lgkmcnt(0)
	v_mfma_f32_16x16x32_bf16 v[74:77], v[100:103], v[50:53], v[74:77]
	v_mfma_f32_16x16x32_bf16 v[70:73], v[100:103], v[66:69], v[70:73]
	s_nop 5
	v_mul_f32_e32 v74, v5, v74
	v_mul_f32_e32 v75, v5, v75
	v_mul_f32_e32 v70, v136, v70
	v_cvt_pk_bf16_f32 v88, v74, v75
	v_mul_f32_e32 v74, v5, v76
	v_mul_f32_e32 v75, v5, v77
	v_cvt_pk_bf16_f32 v89, v74, v75
	v_mul_f32_e32 v71, v136, v71
	v_cvt_pk_bf16_f32 v106, v70, v71
	v_mul_f32_e32 v70, v136, v72
	v_add_u32_e32 v78, 0x10000, v146
	v_mul_f32_e32 v71, v136, v73
	v_cvt_pk_bf16_f32 v107, v70, v71
	global_store_dwordx4 v[2:3], v[86:89], off offset:192 sc1
	global_store_dwordx4 v[134:135], v[104:107], off offset:192 sc1
	v_add_u32_e32 v70, v78, v149
	v_add_u32_e32 v72, v78, v151
	v_add_u32_e32 v74, v78, v153
	v_add_u32_e32 v76, v78, v154
	v_add_u32_e32 v79, v78, v143
	v_add_u32_e32 v80, v78, v147
	v_add_u32_e32 v81, v78, v150
	s_waitcnt vmcnt(8)
	s_barrier
	ds_read_b64 v[70:71], v70
	ds_read_b64 v[72:73], v72
	ds_read_b64 v[74:75], v74
	ds_read_b64 v[76:77], v76
	v_add_u32_e32 v86, v78, v152
	ds_read_b64 v[82:83], v79
	ds_read_b64 v[84:85], v80
	ds_read_b64 v[90:91], v81
	ds_read_b64 v[92:93], v86
	v_add_u32_e32 v79, v78, v139
	v_add_u32_e32 v80, v78, v141
	v_add_u32_e32 v81, v78, v145
	v_add_u32_e32 v86, v78, v148
	ds_read_b64 v[94:95], v79
	ds_read_b64 v[96:97], v80
	ds_read_b64 v[98:99], v81
	ds_read_b64 v[100:101], v86
	v_add_u32_e32 v79, v78, v137
	v_add_u32_e32 v80, v78, v138
	v_add_u32_e32 v81, v78, v140
	v_add_u32_e32 v78, v78, v142
	ds_read_b64 v[102:103], v79
	ds_read_b64 v[104:105], v80
	ds_read_b64 v[106:107], v81
	ds_read_b64 v[108:109], v78
	v_add_u32_e32 v78, 0x10800, v146
	v_add_u32_e32 v79, v78, v149
	v_add_u32_e32 v80, v78, v151
	v_add_u32_e32 v81, v78, v153
	v_add_u32_e32 v86, v78, v154
	ds_read_b64 v[110:111], v79
	ds_read_b64 v[112:113], v80
	ds_read_b64 v[118:119], v81
	ds_read_b64 v[120:121], v86
	v_add_u32_e32 v79, v78, v143
	v_add_u32_e32 v80, v78, v147
	v_add_u32_e32 v81, v78, v150
	v_add_u32_e32 v86, v78, v152
	ds_read_b64 v[126:127], v79
	ds_read_b64 v[128:129], v80
	ds_read_b64 v[130:131], v81
	ds_read_b64 v[132:133], v86
	v_add_u32_e32 v79, v78, v139
	v_add_u32_e32 v80, v78, v141
	v_add_u32_e32 v81, v78, v145
	v_add_u32_e32 v88, v78, v148
	ds_read_b64 v[156:157], v79
	ds_read_b64 v[158:159], v80
	ds_read_b64 v[86:87], v81
	ds_read_b64 v[88:89], v88
	v_add_u32_e32 v79, v78, v137
	v_add_u32_e32 v80, v78, v138
	v_add_u32_e32 v81, v78, v140
	v_add_u32_e32 v114, v78, v142
	ds_read_b64 v[160:161], v79
	ds_read_b64 v[162:163], v80
	ds_read_b64 v[78:79], v81
	ds_read_b64 v[80:81], v114
	s_waitcnt lgkmcnt(14)
	v_mfma_f32_16x16x32_bf16 v[114:117], v[70:73], v[6:9], 0
	v_mfma_f32_16x16x32_bf16 v[70:73], v[70:73], v[22:25], 0
	v_mfma_f32_16x16x32_bf16 v[114:117], v[74:77], v[10:13], v[114:117]
	v_mfma_f32_16x16x32_bf16 v[70:73], v[74:77], v[26:29], v[70:73]
	v_mfma_f32_16x16x32_bf16 v[74:77], v[82:85], v[14:17], v[114:117]
	v_mfma_f32_16x16x32_bf16 v[70:73], v[82:85], v[30:33], v[70:73]
	v_mfma_f32_16x16x32_bf16 v[74:77], v[90:93], v[18:21], v[74:77]
	v_mfma_f32_16x16x32_bf16 v[70:73], v[90:93], v[34:37], v[70:73]
	v_mfma_f32_16x16x32_bf16 v[74:77], v[94:97], v[38:41], v[74:77]
	v_mfma_f32_16x16x32_bf16 v[70:73], v[94:97], v[54:57], v[70:73]
	v_mfma_f32_16x16x32_bf16 v[74:77], v[98:101], v[42:45], v[74:77]
	v_mfma_f32_16x16x32_bf16 v[70:73], v[98:101], v[58:61], v[70:73]
	v_mfma_f32_16x16x32_bf16 v[74:77], v[102:105], v[46:49], v[74:77]
	v_mfma_f32_16x16x32_bf16 v[70:73], v[102:105], v[62:65], v[70:73]
	v_mfma_f32_16x16x32_bf16 v[74:77], v[106:109], v[50:53], v[74:77]
	v_mfma_f32_16x16x32_bf16 v[70:73], v[106:109], v[66:69], v[70:73]
	v_add_u32_e32 v96, 0x14000, v146
	v_add_u32_e32 v97, v96, v139
	ds_read_b64 v[98:99], v97
	v_add_u32_e32 v97, v96, v141
	ds_read_b64 v[100:101], v97
	v_add_u32_e32 v97, v96, v145
	ds_read_b64 v[106:107], v97
	v_add_u32_e32 v97, v96, v148
	v_mul_f32_e32 v74, v5, v74
	v_mul_f32_e32 v70, v136, v70
	ds_read_b64 v[108:109], v97
	v_add_u32_e32 v97, v96, v137
	v_mul_f32_e32 v75, v5, v75
	v_cvt_pk_bf16_f32 v94, v74, v75
	v_mul_f32_e32 v74, v5, v76
	v_mul_f32_e32 v71, v136, v71
	v_cvt_pk_bf16_f32 v102, v70, v71
	v_mul_f32_e32 v70, v136, v72
	ds_read_b64 v[114:115], v97
	v_add_u32_e32 v97, v96, v138
	v_mul_f32_e32 v75, v5, v77
	v_cvt_pk_bf16_f32 v95, v74, v75
	v_mul_f32_e32 v71, v136, v73
	v_cvt_pk_bf16_f32 v103, v70, v71
	v_add_u32_e32 v70, v96, v149
	v_add_u32_e32 v72, v96, v151
	v_add_u32_e32 v74, v96, v153
	v_add_u32_e32 v76, v96, v154
	v_add_u32_e32 v82, v96, v143
	v_add_u32_e32 v84, v96, v147
	v_add_u32_e32 v90, v96, v150
	v_add_u32_e32 v92, v96, v152
	ds_read_b64 v[116:117], v97
	v_add_u32_e32 v97, v96, v140
	v_add_u32_e32 v96, v96, v142
	ds_read_b64 v[70:71], v70
	ds_read_b64 v[72:73], v72
	ds_read_b64 v[74:75], v74
	ds_read_b64 v[76:77], v76
	ds_read_b64 v[82:83], v82
	ds_read_b64 v[84:85], v84
	ds_read_b64 v[90:91], v90
	ds_read_b64 v[92:93], v92
	ds_read_b64 v[122:123], v97
	ds_read_b64 v[124:125], v96
	v_mfma_f32_16x16x32_bf16 v[164:167], v[110:113], v[6:9], 0
	v_mfma_f32_16x16x32_bf16 v[110:113], v[110:113], v[22:25], 0
	s_waitcnt lgkmcnt(14)
	v_mfma_f32_16x16x32_bf16 v[164:167], v[118:121], v[10:13], v[164:167]
	v_mfma_f32_16x16x32_bf16 v[110:113], v[118:121], v[26:29], v[110:113]
	v_mfma_f32_16x16x32_bf16 v[118:121], v[126:129], v[14:17], v[164:167]
	v_mfma_f32_16x16x32_bf16 v[110:113], v[126:129], v[30:33], v[110:113]
	v_mfma_f32_16x16x32_bf16 v[118:121], v[130:133], v[18:21], v[118:121]
	v_mfma_f32_16x16x32_bf16 v[110:113], v[130:133], v[34:37], v[110:113]
	v_mfma_f32_16x16x32_bf16 v[118:121], v[156:159], v[38:41], v[118:121]
	v_mfma_f32_16x16x32_bf16 v[110:113], v[156:159], v[54:57], v[110:113]
	v_mfma_f32_16x16x32_bf16 v[118:121], v[86:89], v[42:45], v[118:121]
	v_mfma_f32_16x16x32_bf16 v[86:89], v[86:89], v[58:61], v[110:113]
	v_mfma_f32_16x16x32_bf16 v[110:113], v[160:163], v[46:49], v[118:121]
	v_mfma_f32_16x16x32_bf16 v[86:89], v[160:163], v[62:65], v[86:89]
	v_mfma_f32_16x16x32_bf16 v[110:113], v[78:81], v[50:53], v[110:113]
	v_mfma_f32_16x16x32_bf16 v[78:81], v[78:81], v[66:69], v[86:89]
	s_nop 5
	v_mul_f32_e32 v86, v5, v110
	v_mul_f32_e32 v87, v5, v111
	v_mul_f32_e32 v78, v136, v78
	v_cvt_pk_bf16_f32 v96, v86, v87
	v_mul_f32_e32 v86, v5, v112
	v_mul_f32_e32 v87, v5, v113
	v_cvt_pk_bf16_f32 v97, v86, v87
	v_mul_f32_e32 v79, v136, v79
	v_cvt_pk_bf16_f32 v104, v78, v79
	v_mul_f32_e32 v78, v136, v80
	v_add_u32_e32 v132, 0x14800, v146
	v_mul_f32_e32 v79, v136, v81
	v_cvt_pk_bf16_f32 v105, v78, v79
	global_store_dwordx4 v[2:3], v[94:97], off offset:256 sc1
	global_store_dwordx4 v[134:135], v[102:105], off offset:256 sc1
	v_add_u32_e32 v78, v132, v149
	v_add_u32_e32 v80, v132, v151
	v_add_u32_e32 v86, v132, v153
	v_add_u32_e32 v88, v132, v154
	v_add_u32_e32 v94, v132, v143
	v_add_u32_e32 v96, v132, v147
	v_add_u32_e32 v102, v132, v150
	v_add_u32_e32 v104, v132, v152
	v_add_u32_e32 v110, v132, v139
	v_add_u32_e32 v112, v132, v141
	v_add_u32_e32 v118, v132, v145
	v_add_u32_e32 v120, v132, v148
	v_add_u32_e32 v126, v132, v137
	v_add_u32_e32 v128, v132, v138
	v_add_u32_e32 v130, v132, v140
	v_add_u32_e32 v132, v132, v142
	ds_read_b64 v[78:79], v78
	ds_read_b64 v[80:81], v80
	ds_read_b64 v[86:87], v86
	ds_read_b64 v[88:89], v88
	ds_read_b64 v[94:95], v94
	ds_read_b64 v[96:97], v96
	ds_read_b64 v[102:103], v102
	ds_read_b64 v[104:105], v104
	ds_read_b64 v[110:111], v110
	ds_read_b64 v[112:113], v112
	ds_read_b64 v[118:119], v118
	ds_read_b64 v[120:121], v120
	ds_read_b64 v[126:127], v126
	ds_read_b64 v[128:129], v128
	ds_read_b64 v[130:131], v130
	ds_read_b64 v[132:133], v132
	s_waitcnt lgkmcnt(14)
	v_mfma_f32_16x16x32_bf16 v[156:159], v[70:73], v[6:9], 0
	v_mfma_f32_16x16x32_bf16 v[70:73], v[70:73], v[22:25], 0
	v_mfma_f32_16x16x32_bf16 v[156:159], v[74:77], v[10:13], v[156:159]
	v_mfma_f32_16x16x32_bf16 v[70:73], v[74:77], v[26:29], v[70:73]
	v_mfma_f32_16x16x32_bf16 v[74:77], v[82:85], v[14:17], v[156:159]
	v_mfma_f32_16x16x32_bf16 v[70:73], v[82:85], v[30:33], v[70:73]
	v_mfma_f32_16x16x32_bf16 v[74:77], v[90:93], v[18:21], v[74:77]
	v_mfma_f32_16x16x32_bf16 v[70:73], v[90:93], v[34:37], v[70:73]
	v_mfma_f32_16x16x32_bf16 v[74:77], v[98:101], v[38:41], v[74:77]
	v_mfma_f32_16x16x32_bf16 v[70:73], v[98:101], v[54:57], v[70:73]
	v_mfma_f32_16x16x32_bf16 v[74:77], v[106:109], v[42:45], v[74:77]
	v_mfma_f32_16x16x32_bf16 v[70:73], v[106:109], v[58:61], v[70:73]
	v_mfma_f32_16x16x32_bf16 v[74:77], v[114:117], v[46:49], v[74:77]
	v_mfma_f32_16x16x32_bf16 v[70:73], v[114:117], v[62:65], v[70:73]
	v_mfma_f32_16x16x32_bf16 v[74:77], v[122:125], v[50:53], v[74:77]
	v_mfma_f32_16x16x32_bf16 v[70:73], v[122:125], v[66:69], v[70:73]
	s_nop 5
	v_mul_f32_e32 v74, v5, v74
	v_mul_f32_e32 v70, v136, v70
	v_mul_f32_e32 v75, v5, v75
	v_cvt_pk_bf16_f32 v156, v74, v75
	v_mul_f32_e32 v74, v5, v76
	v_mul_f32_e32 v71, v136, v71
	v_cvt_pk_bf16_f32 v160, v70, v71
	v_mul_f32_e32 v70, v136, v72
	v_add_u32_e32 v124, 0x18000, v146
	v_mul_f32_e32 v75, v5, v77
	v_cvt_pk_bf16_f32 v157, v74, v75
	v_mul_f32_e32 v71, v136, v73
	v_cvt_pk_bf16_f32 v161, v70, v71
	v_add_u32_e32 v70, v124, v149
	v_add_u32_e32 v72, v124, v151
	v_add_u32_e32 v74, v124, v153
	v_add_u32_e32 v76, v124, v154
	v_add_u32_e32 v82, v124, v143
	v_add_u32_e32 v84, v124, v147
	v_add_u32_e32 v90, v124, v150
	v_add_u32_e32 v92, v124, v152
	v_add_u32_e32 v98, v124, v139
	v_add_u32_e32 v100, v124, v141
	v_add_u32_e32 v106, v124, v145
	v_add_u32_e32 v108, v124, v148
	v_add_u32_e32 v114, v124, v137
	v_add_u32_e32 v116, v124, v138
	v_add_u32_e32 v122, v124, v140
	v_add_u32_e32 v124, v124, v142
	ds_read_b64 v[70:71], v70
	ds_read_b64 v[72:73], v72
	ds_read_b64 v[74:75], v74
	ds_read_b64 v[76:77], v76
	ds_read_b64 v[82:83], v82
	ds_read_b64 v[84:85], v84
	ds_read_b64 v[90:91], v90
	ds_read_b64 v[92:93], v92
	ds_read_b64 v[98:99], v98
	ds_read_b64 v[100:101], v100
	ds_read_b64 v[106:107], v106
	ds_read_b64 v[108:109], v108
	ds_read_b64 v[114:115], v114
	ds_read_b64 v[116:117], v116
	ds_read_b64 v[122:123], v122
	ds_read_b64 v[124:125], v124
	v_mfma_f32_16x16x32_bf16 v[162:165], v[78:81], v[6:9], 0
	v_mfma_f32_16x16x32_bf16 v[78:81], v[78:81], v[22:25], 0
	s_waitcnt lgkmcnt(14)
	v_mfma_f32_16x16x32_bf16 v[162:165], v[86:89], v[10:13], v[162:165]
	v_mfma_f32_16x16x32_bf16 v[78:81], v[86:89], v[26:29], v[78:81]
	v_mfma_f32_16x16x32_bf16 v[86:89], v[94:97], v[14:17], v[162:165]
	v_mfma_f32_16x16x32_bf16 v[78:81], v[94:97], v[30:33], v[78:81]
	v_mfma_f32_16x16x32_bf16 v[86:89], v[102:105], v[18:21], v[86:89]
	v_mfma_f32_16x16x32_bf16 v[78:81], v[102:105], v[34:37], v[78:81]
	v_mfma_f32_16x16x32_bf16 v[86:89], v[110:113], v[38:41], v[86:89]
	v_mfma_f32_16x16x32_bf16 v[78:81], v[110:113], v[54:57], v[78:81]
	v_mfma_f32_16x16x32_bf16 v[86:89], v[118:121], v[42:45], v[86:89]
	v_mfma_f32_16x16x32_bf16 v[78:81], v[118:121], v[58:61], v[78:81]
	v_mfma_f32_16x16x32_bf16 v[86:89], v[126:129], v[46:49], v[86:89]
	v_mfma_f32_16x16x32_bf16 v[78:81], v[126:129], v[62:65], v[78:81]
	v_mfma_f32_16x16x32_bf16 v[86:89], v[130:133], v[50:53], v[86:89]
	v_mfma_f32_16x16x32_bf16 v[78:81], v[130:133], v[66:69], v[78:81]
	s_nop 5
	v_mul_f32_e32 v86, v5, v86
	v_mul_f32_e32 v87, v5, v87
	v_mul_f32_e32 v78, v136, v78
	v_cvt_pk_bf16_f32 v158, v86, v87
	v_mul_f32_e32 v86, v5, v88
	v_mul_f32_e32 v87, v5, v89
	v_cvt_pk_bf16_f32 v159, v86, v87
	v_mul_f32_e32 v79, v136, v79
	v_cvt_pk_bf16_f32 v162, v78, v79
	v_mul_f32_e32 v78, v136, v80
	v_add_u32_e32 v132, 0x18800, v146
	v_mul_f32_e32 v79, v136, v81
	v_cvt_pk_bf16_f32 v163, v78, v79
	global_store_dwordx4 v[2:3], v[156:159], off offset:320 sc1
	global_store_dwordx4 v[134:135], v[160:163], off offset:320 sc1
	v_add_u32_e32 v78, v132, v149
	v_add_u32_e32 v80, v132, v151
	v_add_u32_e32 v86, v132, v153
	v_add_u32_e32 v88, v132, v154
	v_add_u32_e32 v94, v132, v143
	v_add_u32_e32 v96, v132, v147
	v_add_u32_e32 v102, v132, v150
	v_add_u32_e32 v104, v132, v152
	v_add_u32_e32 v110, v132, v139
	v_add_u32_e32 v112, v132, v141
	v_add_u32_e32 v118, v132, v145
	v_add_u32_e32 v120, v132, v148
	v_add_u32_e32 v126, v132, v137
	v_add_u32_e32 v128, v132, v138
	v_add_u32_e32 v130, v132, v140
	v_add_u32_e32 v132, v132, v142
	ds_read_b64 v[78:79], v78
	ds_read_b64 v[80:81], v80
	ds_read_b64 v[86:87], v86
	ds_read_b64 v[88:89], v88
	ds_read_b64 v[94:95], v94
	ds_read_b64 v[96:97], v96
	ds_read_b64 v[102:103], v102
	ds_read_b64 v[104:105], v104
	ds_read_b64 v[110:111], v110
	ds_read_b64 v[112:113], v112
	ds_read_b64 v[118:119], v118
	ds_read_b64 v[120:121], v120
	ds_read_b64 v[126:127], v126
	ds_read_b64 v[128:129], v128
	ds_read_b64 v[130:131], v130
	ds_read_b64 v[132:133], v132
	v_mfma_f32_16x16x32_bf16 v[156:159], v[70:73], v[6:9], 0
	v_mfma_f32_16x16x32_bf16 v[70:73], v[70:73], v[22:25], 0
	s_waitcnt lgkmcnt(14)
	v_mfma_f32_16x16x32_bf16 v[156:159], v[74:77], v[10:13], v[156:159]
	v_mfma_f32_16x16x32_bf16 v[70:73], v[74:77], v[26:29], v[70:73]
	v_mfma_f32_16x16x32_bf16 v[74:77], v[82:85], v[14:17], v[156:159]
	v_mfma_f32_16x16x32_bf16 v[70:73], v[82:85], v[30:33], v[70:73]
	v_mfma_f32_16x16x32_bf16 v[74:77], v[90:93], v[18:21], v[74:77]
	v_mfma_f32_16x16x32_bf16 v[70:73], v[90:93], v[34:37], v[70:73]
	v_mfma_f32_16x16x32_bf16 v[74:77], v[98:101], v[38:41], v[74:77]
	v_mfma_f32_16x16x32_bf16 v[70:73], v[98:101], v[54:57], v[70:73]
	v_mfma_f32_16x16x32_bf16 v[74:77], v[106:109], v[42:45], v[74:77]
	v_mfma_f32_16x16x32_bf16 v[70:73], v[106:109], v[58:61], v[70:73]
	v_mfma_f32_16x16x32_bf16 v[74:77], v[114:117], v[46:49], v[74:77]
	v_mfma_f32_16x16x32_bf16 v[70:73], v[114:117], v[62:65], v[70:73]
	v_mfma_f32_16x16x32_bf16 v[74:77], v[122:125], v[50:53], v[74:77]
	v_mfma_f32_16x16x32_bf16 v[70:73], v[122:125], v[66:69], v[70:73]
	s_nop 5
	v_mul_f32_e32 v74, v5, v74
	v_mul_f32_e32 v70, v136, v70
	v_mul_f32_e32 v75, v5, v75
	v_cvt_pk_bf16_f32 v156, v74, v75
	v_mul_f32_e32 v74, v5, v76
	v_mul_f32_e32 v71, v136, v71
	v_cvt_pk_bf16_f32 v160, v70, v71
	v_mul_f32_e32 v70, v136, v72
	v_add_u32_e32 v124, 0x1c000, v146
	v_mul_f32_e32 v75, v5, v77
	v_cvt_pk_bf16_f32 v157, v74, v75
	v_mul_f32_e32 v71, v136, v73
	v_cvt_pk_bf16_f32 v161, v70, v71
	v_add_u32_e32 v70, v124, v149
	v_add_u32_e32 v72, v124, v151
	v_add_u32_e32 v74, v124, v153
	v_add_u32_e32 v76, v124, v154
	v_add_u32_e32 v82, v124, v143
	v_add_u32_e32 v84, v124, v147
	v_add_u32_e32 v90, v124, v150
	v_add_u32_e32 v92, v124, v152
	v_add_u32_e32 v98, v124, v139
	v_add_u32_e32 v100, v124, v141
	v_add_u32_e32 v106, v124, v145
	v_add_u32_e32 v108, v124, v148
	v_add_u32_e32 v114, v124, v137
	v_add_u32_e32 v116, v124, v138
	v_add_u32_e32 v122, v124, v140
	v_add_u32_e32 v124, v124, v142
	ds_read_b64 v[70:71], v70
	ds_read_b64 v[72:73], v72
	ds_read_b64 v[74:75], v74
	ds_read_b64 v[76:77], v76
	ds_read_b64 v[82:83], v82
	ds_read_b64 v[84:85], v84
	ds_read_b64 v[90:91], v90
	ds_read_b64 v[92:93], v92
	ds_read_b64 v[98:99], v98
	ds_read_b64 v[100:101], v100
	ds_read_b64 v[106:107], v106
	ds_read_b64 v[108:109], v108
	ds_read_b64 v[114:115], v114
	ds_read_b64 v[116:117], v116
	ds_read_b64 v[122:123], v122
	ds_read_b64 v[124:125], v124
	v_mfma_f32_16x16x32_bf16 v[162:165], v[78:81], v[6:9], 0
	v_mfma_f32_16x16x32_bf16 v[78:81], v[78:81], v[22:25], 0
	s_waitcnt lgkmcnt(14)
	v_mfma_f32_16x16x32_bf16 v[162:165], v[86:89], v[10:13], v[162:165]
	v_mfma_f32_16x16x32_bf16 v[78:81], v[86:89], v[26:29], v[78:81]
	v_mfma_f32_16x16x32_bf16 v[86:89], v[94:97], v[14:17], v[162:165]
	v_mfma_f32_16x16x32_bf16 v[78:81], v[94:97], v[30:33], v[78:81]
	v_mfma_f32_16x16x32_bf16 v[86:89], v[102:105], v[18:21], v[86:89]
	v_mfma_f32_16x16x32_bf16 v[78:81], v[102:105], v[34:37], v[78:81]
	v_mfma_f32_16x16x32_bf16 v[86:89], v[110:113], v[38:41], v[86:89]
	v_mfma_f32_16x16x32_bf16 v[78:81], v[110:113], v[54:57], v[78:81]
	v_mfma_f32_16x16x32_bf16 v[86:89], v[118:121], v[42:45], v[86:89]
	v_mfma_f32_16x16x32_bf16 v[78:81], v[118:121], v[58:61], v[78:81]
	v_mfma_f32_16x16x32_bf16 v[86:89], v[126:129], v[46:49], v[86:89]
	v_mfma_f32_16x16x32_bf16 v[78:81], v[126:129], v[62:65], v[78:81]
	v_mfma_f32_16x16x32_bf16 v[86:89], v[130:133], v[50:53], v[86:89]
	v_mfma_f32_16x16x32_bf16 v[78:81], v[130:133], v[66:69], v[78:81]
	s_nop 5
	v_mul_f32_e32 v86, v5, v86
	v_mul_f32_e32 v87, v5, v87
	v_mul_f32_e32 v78, v136, v78
	v_cvt_pk_bf16_f32 v158, v86, v87
	v_mul_f32_e32 v86, v5, v88
	v_mul_f32_e32 v87, v5, v89
	v_cvt_pk_bf16_f32 v159, v86, v87
	v_mul_f32_e32 v79, v136, v79
	v_cvt_pk_bf16_f32 v162, v78, v79
	v_mul_f32_e32 v78, v136, v80
	v_add_u32_e32 v132, 0x1c800, v146
	v_mul_f32_e32 v79, v136, v81
	v_cvt_pk_bf16_f32 v163, v78, v79
	global_store_dwordx4 v[2:3], v[156:159], off offset:384 sc1
	global_store_dwordx4 v[134:135], v[160:163], off offset:384 sc1
	v_add_u32_e32 v78, v132, v149
	v_add_u32_e32 v80, v132, v151
	v_add_u32_e32 v86, v132, v153
	v_add_u32_e32 v88, v132, v154
	v_add_u32_e32 v94, v132, v143
	v_add_u32_e32 v96, v132, v147
	v_add_u32_e32 v102, v132, v150
	v_add_u32_e32 v104, v132, v152
	v_add_u32_e32 v110, v132, v139
	v_add_u32_e32 v112, v132, v141
	v_add_u32_e32 v118, v132, v145
	v_add_u32_e32 v120, v132, v148
	v_add_u32_e32 v126, v132, v137
	v_add_u32_e32 v128, v132, v138
	v_add_u32_e32 v130, v132, v140
	v_add_u32_e32 v132, v132, v142
	ds_read_b64 v[78:79], v78
	ds_read_b64 v[80:81], v80
	ds_read_b64 v[86:87], v86
	ds_read_b64 v[88:89], v88
	ds_read_b64 v[94:95], v94
	ds_read_b64 v[96:97], v96
	ds_read_b64 v[102:103], v102
	ds_read_b64 v[104:105], v104
	ds_read_b64 v[110:111], v110
	ds_read_b64 v[112:113], v112
	ds_read_b64 v[118:119], v118
	ds_read_b64 v[120:121], v120
	ds_read_b64 v[126:127], v126
	ds_read_b64 v[128:129], v128
	ds_read_b64 v[130:131], v130
	ds_read_b64 v[132:133], v132
	v_mfma_f32_16x16x32_bf16 v[138:141], v[70:73], v[6:9], 0
	v_mfma_f32_16x16x32_bf16 v[70:73], v[70:73], v[22:25], 0
	s_waitcnt lgkmcnt(14)
	v_mfma_f32_16x16x32_bf16 v[138:141], v[74:77], v[10:13], v[138:141]
	v_mfma_f32_16x16x32_bf16 v[70:73], v[74:77], v[26:29], v[70:73]
	v_mfma_f32_16x16x32_bf16 v[74:77], v[82:85], v[14:17], v[138:141]
	v_mfma_f32_16x16x32_bf16 v[70:73], v[82:85], v[30:33], v[70:73]
	v_mfma_f32_16x16x32_bf16 v[74:77], v[90:93], v[18:21], v[74:77]
	v_mfma_f32_16x16x32_bf16 v[70:73], v[90:93], v[34:37], v[70:73]
	v_mfma_f32_16x16x32_bf16 v[74:77], v[98:101], v[38:41], v[74:77]
	v_mfma_f32_16x16x32_bf16 v[70:73], v[98:101], v[54:57], v[70:73]
	v_mfma_f32_16x16x32_bf16 v[74:77], v[106:109], v[42:45], v[74:77]
	v_mfma_f32_16x16x32_bf16 v[70:73], v[106:109], v[58:61], v[70:73]
	v_mfma_f32_16x16x32_bf16 v[74:77], v[114:117], v[46:49], v[74:77]
	v_mfma_f32_16x16x32_bf16 v[70:73], v[114:117], v[62:65], v[70:73]
	v_mfma_f32_16x16x32_bf16 v[74:77], v[122:125], v[50:53], v[74:77]
	v_mfma_f32_16x16x32_bf16 v[70:73], v[122:125], v[66:69], v[70:73]
	s_nop 5
	v_mul_f32_e32 v74, v5, v74
	v_mul_f32_e32 v75, v5, v75
	v_mul_f32_e32 v70, v136, v70
	v_mul_f32_e32 v71, v136, v71
	v_cvt_pk_bf16_f32 v74, v74, v75
	v_mul_f32_e32 v75, v5, v76
	v_cvt_pk_bf16_f32 v70, v70, v71
	v_mul_f32_e32 v71, v136, v72
	v_mul_f32_e32 v76, v5, v77
	v_cvt_pk_bf16_f32 v75, v75, v76
	v_mul_f32_e32 v72, v136, v73
	v_cvt_pk_bf16_f32 v71, v71, v72
	v_mfma_f32_16x16x32_bf16 v[6:9], v[78:81], v[6:9], 0
	v_mfma_f32_16x16x32_bf16 v[22:25], v[78:81], v[22:25], 0
	s_waitcnt lgkmcnt(12)
	v_mfma_f32_16x16x32_bf16 v[6:9], v[86:89], v[10:13], v[6:9]
	v_mfma_f32_16x16x32_bf16 v[10:13], v[86:89], v[26:29], v[22:25]
	s_waitcnt lgkmcnt(10)
	v_mfma_f32_16x16x32_bf16 v[6:9], v[94:97], v[14:17], v[6:9]
	v_mfma_f32_16x16x32_bf16 v[10:13], v[94:97], v[30:33], v[10:13]
	s_waitcnt lgkmcnt(8)
	v_mfma_f32_16x16x32_bf16 v[6:9], v[102:105], v[18:21], v[6:9]
	v_mfma_f32_16x16x32_bf16 v[10:13], v[102:105], v[34:37], v[10:13]
	s_waitcnt lgkmcnt(6)
	v_mfma_f32_16x16x32_bf16 v[6:9], v[110:113], v[38:41], v[6:9]
	v_mfma_f32_16x16x32_bf16 v[10:13], v[110:113], v[54:57], v[10:13]
	s_waitcnt lgkmcnt(4)
	v_mfma_f32_16x16x32_bf16 v[6:9], v[118:121], v[42:45], v[6:9]
	v_mfma_f32_16x16x32_bf16 v[10:13], v[118:121], v[58:61], v[10:13]
	s_waitcnt lgkmcnt(2)
	v_mfma_f32_16x16x32_bf16 v[6:9], v[126:129], v[46:49], v[6:9]
	v_mfma_f32_16x16x32_bf16 v[10:13], v[126:129], v[62:65], v[10:13]
	s_waitcnt lgkmcnt(0)
	v_mfma_f32_16x16x32_bf16 v[6:9], v[130:133], v[50:53], v[6:9]
	v_mfma_f32_16x16x32_bf16 v[10:13], v[130:133], v[66:69], v[10:13]
	s_nop 5
	v_mul_f32_e32 v6, v5, v6
	v_mul_f32_e32 v7, v5, v7
	v_cvt_pk_bf16_f32 v76, v6, v7
	v_mul_f32_e32 v6, v5, v8
	v_mul_f32_e32 v5, v5, v9
	v_cvt_pk_bf16_f32 v77, v6, v5
	v_mul_f32_e32 v5, v136, v10
	v_mul_f32_e32 v6, v136, v11
	v_cvt_pk_bf16_f32 v72, v5, v6
	v_mul_f32_e32 v5, v136, v12
	v_mul_f32_e32 v6, v136, v13
	v_cvt_pk_bf16_f32 v73, v5, v6
	global_store_dwordx4 v[2:3], v[74:77], off offset:448 sc1
	global_store_dwordx4 v[134:135], v[70:73], off offset:448 sc1
	s_barrier

.LBB0_941:
	s_waitcnt lgkmcnt(0)
	s_add_i32 s65, s65, 2
	s_barrier
	s_waitcnt lgkmcnt(0)
	v_mfma_f32_16x16x32_bf16 v[66:69], v[190:193], v[150:153], v[66:69]
	v_mfma_f32_16x16x32_bf16 v[62:65], v[190:193], v[158:161], v[62:65]
	v_mfma_f32_16x16x32_bf16 v[50:53], v[182:185], v[150:153], v[50:53]
	v_mfma_f32_16x16x32_bf16 v[46:49], v[182:185], v[158:161], v[46:49]
	v_mfma_f32_16x16x32_bf16 v[34:37], v[174:177], v[150:153], v[34:37]
	v_mfma_f32_16x16x32_bf16 v[30:33], v[174:177], v[158:161], v[30:33]
	v_mfma_f32_16x16x32_bf16 v[18:21], v[166:169], v[150:153], v[18:21]
	v_mfma_f32_16x16x32_bf16 v[14:17], v[166:169], v[158:161], v[14:17]
	v_mfma_f32_16x16x32_bf16 v[66:69], v[194:197], v[154:157], v[66:69]
	v_mfma_f32_16x16x32_bf16 v[62:65], v[194:197], v[162:165], v[62:65]
	v_mfma_f32_16x16x32_bf16 v[50:53], v[186:189], v[154:157], v[50:53]
	v_mfma_f32_16x16x32_bf16 v[46:49], v[186:189], v[162:165], v[46:49]
	v_mfma_f32_16x16x32_bf16 v[34:37], v[178:181], v[154:157], v[34:37]
	v_mfma_f32_16x16x32_bf16 v[30:33], v[178:181], v[162:165], v[30:33]
	v_mfma_f32_16x16x32_bf16 v[18:21], v[170:173], v[154:157], v[18:21]
	v_mfma_f32_16x16x32_bf16 v[14:17], v[170:173], v[162:165], v[14:17]
	v_mfma_f32_16x16x32_bf16 v[58:61], v[190:193], v[134:137], v[58:61]
	v_mfma_f32_16x16x32_bf16 v[54:57], v[190:193], v[142:145], v[54:57]
	v_mfma_f32_16x16x32_bf16 v[42:45], v[182:185], v[134:137], v[42:45]
	v_mfma_f32_16x16x32_bf16 v[38:41], v[182:185], v[142:145], v[38:41]
	v_mfma_f32_16x16x32_bf16 v[26:29], v[174:177], v[134:137], v[26:29]
	v_mfma_f32_16x16x32_bf16 v[22:25], v[174:177], v[142:145], v[22:25]
	v_mfma_f32_16x16x32_bf16 v[10:13], v[166:169], v[134:137], v[10:13]
	v_mfma_f32_16x16x32_bf16 v[6:9], v[166:169], v[142:145], v[6:9]
	v_mfma_f32_16x16x32_bf16 v[58:61], v[194:197], v[138:141], v[58:61]
	v_mfma_f32_16x16x32_bf16 v[54:57], v[194:197], v[146:149], v[54:57]
	v_mfma_f32_16x16x32_bf16 v[42:45], v[186:189], v[138:141], v[42:45]
	v_mfma_f32_16x16x32_bf16 v[38:41], v[186:189], v[146:149], v[38:41]
	v_mfma_f32_16x16x32_bf16 v[26:29], v[178:181], v[138:141], v[26:29]
	v_mfma_f32_16x16x32_bf16 v[22:25], v[178:181], v[146:149], v[22:25]
	v_mfma_f32_16x16x32_bf16 v[10:13], v[170:173], v[138:141], v[10:13]
	v_mfma_f32_16x16x32_bf16 v[6:9], v[170:173], v[146:149], v[6:9]
	s_barrier
	s_add_u32 s63, s63, 0x100
	s_addc_u32 s64, s64, 0
	s_add_u32 s22, s22, 0x100
	s_addc_u32 s23, s23, 0
	s_cmp_ge_i32 s65, s55
	s_cbranch_scc1 .LBB0_952
.LBB0_942:
	v_add_u32_e32 v134, 0x10000, v227
	v_add_u32_e32 v146, 0x14000, v227
	ds_read_b128 v[150:153], v134
	ds_read_b128 v[154:157], v134 offset:1024
	ds_read_b128 v[158:161], v134 offset:2048
	ds_read_b128 v[162:165], v134 offset:3072
	ds_read_b128 v[134:137], v146
	ds_read_b128 v[138:141], v146 offset:1024
	ds_read_b128 v[142:145], v146 offset:2048
	ds_read_b128 v[146:149], v146 offset:3072
	s_cmp_lg_u32 s56, s65
	s_cselect_b64 s[28:29], -1, 0
	s_add_u32 s26, s22, 0xfffc0080
	s_addc_u32 s27, s23, -1
	s_and_b64 s[24:25], s[28:29], exec
	s_cselect_b32 s27, s27, s13
	s_cselect_b32 s26, s26, s15
	s_cselect_b32 s25, s64, s61
	s_cselect_b32 s24, s63, s62
	v_lshl_add_u64 v[218:219], s[22:23], 0, v[206:207]
	s_add_i32 m0, s41, 0xc000
	ds_read_b128 v[166:169], v228
	ds_read_b128 v[170:173], v228 offset:1024
	ds_read_b128 v[174:177], v228 offset:2048
	ds_read_b128 v[178:181], v228 offset:3072
	ds_read_b128 v[182:185], v228 offset:4096
	ds_read_b128 v[186:189], v228 offset:5120
	ds_read_b128 v[190:193], v228 offset:6144
	ds_read_b128 v[194:197], v228 offset:7168
	global_load_lds_dwordx4 v[218:219], off
	v_lshl_add_u64 v[218:219], s[22:23], 0, v[208:209]
	s_add_i32 m0, s41, 0xe000
	s_nop 0
	global_load_lds_dwordx4 v[218:219], off
	s_waitcnt vmcnt(8)
	s_waitcnt lgkmcnt(0)
	s_barrier
	s_waitcnt lgkmcnt(0)
	v_mfma_f32_16x16x32_bf16 v[130:133], v[166:169], v[150:153], v[130:133]
	v_mfma_f32_16x16x32_bf16 v[126:129], v[166:169], v[158:161], v[126:129]
	v_mfma_f32_16x16x32_bf16 v[114:117], v[174:177], v[150:153], v[114:117]
	v_mfma_f32_16x16x32_bf16 v[110:113], v[174:177], v[158:161], v[110:113]
	v_mfma_f32_16x16x32_bf16 v[98:101], v[182:185], v[150:153], v[98:101]
	v_mfma_f32_16x16x32_bf16 v[94:97], v[182:185], v[158:161], v[94:97]
	v_mfma_f32_16x16x32_bf16 v[82:85], v[190:193], v[150:153], v[82:85]
	v_mfma_f32_16x16x32_bf16 v[78:81], v[190:193], v[158:161], v[78:81]
	v_mfma_f32_16x16x32_bf16 v[130:133], v[170:173], v[154:157], v[130:133]
	v_mfma_f32_16x16x32_bf16 v[126:129], v[170:173], v[162:165], v[126:129]
	v_mfma_f32_16x16x32_bf16 v[114:117], v[178:181], v[154:157], v[114:117]
	v_mfma_f32_16x16x32_bf16 v[110:113], v[178:181], v[162:165], v[110:113]
	v_mfma_f32_16x16x32_bf16 v[98:101], v[186:189], v[154:157], v[98:101]
	v_mfma_f32_16x16x32_bf16 v[94:97], v[186:189], v[162:165], v[94:97]
	v_mfma_f32_16x16x32_bf16 v[82:85], v[194:197], v[154:157], v[82:85]
	v_mfma_f32_16x16x32_bf16 v[78:81], v[194:197], v[162:165], v[78:81]
	v_mfma_f32_16x16x32_bf16 v[122:125], v[166:169], v[134:137], v[122:125]
	v_mfma_f32_16x16x32_bf16 v[118:121], v[166:169], v[142:145], v[118:121]
	v_mfma_f32_16x16x32_bf16 v[106:109], v[174:177], v[134:137], v[106:109]
	v_mfma_f32_16x16x32_bf16 v[102:105], v[174:177], v[142:145], v[102:105]
	v_mfma_f32_16x16x32_bf16 v[90:93], v[182:185], v[134:137], v[90:93]
	v_mfma_f32_16x16x32_bf16 v[86:89], v[182:185], v[142:145], v[86:89]
	v_mfma_f32_16x16x32_bf16 v[74:77], v[190:193], v[134:137], v[74:77]
	v_mfma_f32_16x16x32_bf16 v[70:73], v[190:193], v[142:145], v[70:73]
	v_mfma_f32_16x16x32_bf16 v[122:125], v[170:173], v[138:141], v[122:125]
	v_mfma_f32_16x16x32_bf16 v[118:121], v[170:173], v[146:149], v[118:121]
	v_mfma_f32_16x16x32_bf16 v[106:109], v[178:181], v[138:141], v[106:109]
	v_mfma_f32_16x16x32_bf16 v[102:105], v[178:181], v[146:149], v[102:105]
	v_mfma_f32_16x16x32_bf16 v[90:93], v[186:189], v[138:141], v[90:93]
	v_mfma_f32_16x16x32_bf16 v[86:89], v[186:189], v[146:149], v[86:89]
	v_mfma_f32_16x16x32_bf16 v[74:77], v[194:197], v[138:141], v[74:77]
	v_mfma_f32_16x16x32_bf16 v[70:73], v[194:197], v[146:149], v[70:73]
	s_barrier
	ds_read_b128 v[190:193], v228 offset:16384
	ds_read_b128 v[194:197], v228 offset:17408
	ds_read_b128 v[182:185], v228 offset:18432
	ds_read_b128 v[186:189], v228 offset:19456
	ds_read_b128 v[174:177], v228 offset:20480
	ds_read_b128 v[178:181], v228 offset:21504
	ds_read_b128 v[166:169], v228 offset:22528
	ds_read_b128 v[170:173], v228 offset:23552
	s_or_b64 s[28:29], s[20:21], s[28:29]
	s_xor_b64 s[30:31], s[28:29], -1
	s_mov_b64 s[34:35], -1
	s_and_b64 vcc, exec, s[30:31]
	s_cbranch_vccz .LBB0_944
	s_waitcnt vmcnt(2)
	s_mov_b64 s[34:35], 0

.LBB0_946:
	s_waitcnt lgkmcnt(0)
	s_barrier
	s_waitcnt lgkmcnt(0)
	v_mfma_f32_16x16x32_bf16 v[66:69], v[190:193], v[150:153], v[66:69]
	v_mfma_f32_16x16x32_bf16 v[62:65], v[190:193], v[158:161], v[62:65]
	v_mfma_f32_16x16x32_bf16 v[50:53], v[182:185], v[150:153], v[50:53]
	v_mfma_f32_16x16x32_bf16 v[46:49], v[182:185], v[158:161], v[46:49]
	v_mfma_f32_16x16x32_bf16 v[34:37], v[174:177], v[150:153], v[34:37]
	v_mfma_f32_16x16x32_bf16 v[30:33], v[174:177], v[158:161], v[30:33]
	v_mfma_f32_16x16x32_bf16 v[18:21], v[166:169], v[150:153], v[18:21]
	v_mfma_f32_16x16x32_bf16 v[14:17], v[166:169], v[158:161], v[14:17]
	v_mfma_f32_16x16x32_bf16 v[66:69], v[194:197], v[154:157], v[66:69]
	v_mfma_f32_16x16x32_bf16 v[62:65], v[194:197], v[162:165], v[62:65]
	v_mfma_f32_16x16x32_bf16 v[50:53], v[186:189], v[154:157], v[50:53]
	v_mfma_f32_16x16x32_bf16 v[46:49], v[186:189], v[162:165], v[46:49]
	v_mfma_f32_16x16x32_bf16 v[34:37], v[178:181], v[154:157], v[34:37]
	v_mfma_f32_16x16x32_bf16 v[30:33], v[178:181], v[162:165], v[30:33]
	v_mfma_f32_16x16x32_bf16 v[18:21], v[170:173], v[154:157], v[18:21]
	v_mfma_f32_16x16x32_bf16 v[14:17], v[170:173], v[162:165], v[14:17]
	v_mfma_f32_16x16x32_bf16 v[58:61], v[190:193], v[134:137], v[58:61]
	v_mfma_f32_16x16x32_bf16 v[54:57], v[190:193], v[142:145], v[54:57]
	v_mfma_f32_16x16x32_bf16 v[42:45], v[182:185], v[134:137], v[42:45]
	v_mfma_f32_16x16x32_bf16 v[38:41], v[182:185], v[142:145], v[38:41]
	v_mfma_f32_16x16x32_bf16 v[26:29], v[174:177], v[134:137], v[26:29]
	v_mfma_f32_16x16x32_bf16 v[22:25], v[174:177], v[142:145], v[22:25]
	v_mfma_f32_16x16x32_bf16 v[10:13], v[166:169], v[134:137], v[10:13]
	v_mfma_f32_16x16x32_bf16 v[6:9], v[166:169], v[142:145], v[6:9]
	v_mfma_f32_16x16x32_bf16 v[58:61], v[194:197], v[138:141], v[58:61]
	v_mfma_f32_16x16x32_bf16 v[54:57], v[194:197], v[146:149], v[54:57]
	v_mfma_f32_16x16x32_bf16 v[42:45], v[186:189], v[138:141], v[42:45]
	v_mfma_f32_16x16x32_bf16 v[38:41], v[186:189], v[146:149], v[38:41]
	v_mfma_f32_16x16x32_bf16 v[26:29], v[178:181], v[138:141], v[26:29]
	v_mfma_f32_16x16x32_bf16 v[22:25], v[178:181], v[146:149], v[22:25]
	v_mfma_f32_16x16x32_bf16 v[10:13], v[170:173], v[138:141], v[10:13]
	v_mfma_f32_16x16x32_bf16 v[6:9], v[170:173], v[146:149], v[6:9]
	s_barrier
	v_add_u32_e32 v134, 0x18000, v227
	v_add_u32_e32 v146, 0x1c000, v227
	ds_read_b128 v[150:153], v134
	ds_read_b128 v[154:157], v134 offset:1024
	ds_read_b128 v[158:161], v134 offset:2048
	ds_read_b128 v[162:165], v134 offset:3072
	ds_read_b128 v[134:137], v146
	ds_read_b128 v[138:141], v146 offset:1024
	ds_read_b128 v[142:145], v146 offset:2048
	ds_read_b128 v[146:149], v146 offset:3072
	ds_read_b128 v[190:193], v228 offset:32768
	ds_read_b128 v[194:197], v228 offset:33792
	ds_read_b128 v[182:185], v228 offset:34816
	ds_read_b128 v[186:189], v228 offset:35840
	ds_read_b128 v[174:177], v228 offset:36864
	ds_read_b128 v[178:181], v228 offset:37888
	ds_read_b128 v[166:169], v228 offset:38912
	ds_read_b128 v[170:173], v228 offset:39936
	s_mov_b64 s[34:35], -1
	s_and_b64 vcc, exec, s[30:31]
	s_cbranch_vccz .LBB0_948
	s_waitcnt vmcnt(0)
	s_mov_b64 s[34:35], 0

.LBB0_950:
	s_waitcnt lgkmcnt(0)
	s_barrier
	s_waitcnt lgkmcnt(0)
	v_mfma_f32_16x16x32_bf16 v[130:133], v[190:193], v[150:153], v[130:133]
	v_mfma_f32_16x16x32_bf16 v[126:129], v[190:193], v[158:161], v[126:129]
	v_mfma_f32_16x16x32_bf16 v[114:117], v[182:185], v[150:153], v[114:117]
	v_mfma_f32_16x16x32_bf16 v[110:113], v[182:185], v[158:161], v[110:113]
	v_mfma_f32_16x16x32_bf16 v[98:101], v[174:177], v[150:153], v[98:101]
	v_mfma_f32_16x16x32_bf16 v[94:97], v[174:177], v[158:161], v[94:97]
	v_mfma_f32_16x16x32_bf16 v[82:85], v[166:169], v[150:153], v[82:85]
	v_mfma_f32_16x16x32_bf16 v[78:81], v[166:169], v[158:161], v[78:81]
	v_mfma_f32_16x16x32_bf16 v[130:133], v[194:197], v[154:157], v[130:133]
	v_mfma_f32_16x16x32_bf16 v[126:129], v[194:197], v[162:165], v[126:129]
	v_mfma_f32_16x16x32_bf16 v[114:117], v[186:189], v[154:157], v[114:117]
	v_mfma_f32_16x16x32_bf16 v[110:113], v[186:189], v[162:165], v[110:113]
	v_mfma_f32_16x16x32_bf16 v[98:101], v[178:181], v[154:157], v[98:101]
	v_mfma_f32_16x16x32_bf16 v[94:97], v[178:181], v[162:165], v[94:97]
	v_mfma_f32_16x16x32_bf16 v[82:85], v[170:173], v[154:157], v[82:85]
	v_mfma_f32_16x16x32_bf16 v[78:81], v[170:173], v[162:165], v[78:81]
	v_mfma_f32_16x16x32_bf16 v[122:125], v[190:193], v[134:137], v[122:125]
	v_mfma_f32_16x16x32_bf16 v[118:121], v[190:193], v[142:145], v[118:121]
	v_mfma_f32_16x16x32_bf16 v[106:109], v[182:185], v[134:137], v[106:109]
	v_mfma_f32_16x16x32_bf16 v[102:105], v[182:185], v[142:145], v[102:105]
	v_mfma_f32_16x16x32_bf16 v[90:93], v[174:177], v[134:137], v[90:93]
	v_mfma_f32_16x16x32_bf16 v[86:89], v[174:177], v[142:145], v[86:89]
	v_mfma_f32_16x16x32_bf16 v[74:77], v[166:169], v[134:137], v[74:77]
	v_mfma_f32_16x16x32_bf16 v[70:73], v[166:169], v[142:145], v[70:73]
	v_mfma_f32_16x16x32_bf16 v[122:125], v[194:197], v[138:141], v[122:125]
	v_mfma_f32_16x16x32_bf16 v[118:121], v[194:197], v[146:149], v[118:121]
	v_mfma_f32_16x16x32_bf16 v[106:109], v[186:189], v[138:141], v[106:109]
	v_mfma_f32_16x16x32_bf16 v[102:105], v[186:189], v[146:149], v[102:105]
	v_mfma_f32_16x16x32_bf16 v[90:93], v[178:181], v[138:141], v[90:93]
	v_mfma_f32_16x16x32_bf16 v[86:89], v[178:181], v[146:149], v[86:89]
	v_mfma_f32_16x16x32_bf16 v[74:77], v[170:173], v[138:141], v[74:77]
	v_mfma_f32_16x16x32_bf16 v[70:73], v[170:173], v[146:149], v[70:73]
	s_barrier
	ds_read_b128 v[190:193], v228 offset:49152
	ds_read_b128 v[194:197], v228 offset:50176
	ds_read_b128 v[182:185], v228 offset:51200
	ds_read_b128 v[186:189], v228 offset:52224
	ds_read_b128 v[174:177], v228 offset:53248
	ds_read_b128 v[178:181], v228 offset:54272
	ds_read_b128 v[166:169], v228 offset:55296
	ds_read_b128 v[170:173], v228 offset:56320
	s_andn2_b64 vcc, exec, s[28:29]
	s_cbranch_vccnz .LBB0_941
	s_mov_b32 m0, s49
	v_lshl_add_u64 v[224:225], v[224:225], 0, s[68:69]
	s_add_u32 s24, s24, 0x1080
	global_load_lds_dwordx4 v[224:225], off
	v_lshl_add_u64 v[222:223], v[222:223], 0, s[68:69]
	s_mov_b32 m0, s50
	s_addc_u32 s25, s25, 0
	global_load_lds_dwordx4 v[222:223], off
	v_lshl_add_u64 v[222:223], s[24:25], 0, v[202:203]
	s_mov_b32 m0, s53
	v_lshl_add_u64 v[220:221], v[220:221], 0, s[68:69]
	global_load_lds_dwordx4 v[222:223], off
	v_lshl_add_u64 v[222:223], s[24:25], 0, v[198:199]
	s_mov_b32 m0, s54
	v_lshl_add_u64 v[218:219], v[218:219], 0, s[68:69]
	global_load_lds_dwordx4 v[222:223], off
	s_mov_b32 m0, s51
	s_nop 0
	global_load_lds_dwordx4 v[220:221], off
	s_mov_b32 m0, s52
	s_nop 0
	global_load_lds_dwordx4 v[218:219], off
	s_waitcnt vmcnt(8)
	s_branch .LBB0_941

.LBB0_1014:
	s_waitcnt lgkmcnt(0)
	s_add_i32 s84, s84, 2
	s_barrier
	s_waitcnt lgkmcnt(0)
	v_mfma_f32_16x16x32_bf16 v[66:69], v[170:173], v[190:193], v[66:69]
	v_mfma_f32_16x16x32_bf16 v[62:65], v[178:181], v[190:193], v[62:65]
	v_mfma_f32_16x16x32_bf16 v[50:53], v[170:173], v[134:137], v[50:53]
	v_mfma_f32_16x16x32_bf16 v[46:49], v[178:181], v[134:137], v[46:49]
	v_mfma_f32_16x16x32_bf16 v[34:37], v[170:173], v[114:117], v[34:37]
	v_mfma_f32_16x16x32_bf16 v[30:33], v[178:181], v[114:117], v[30:33]
	v_mfma_f32_16x16x32_bf16 v[18:21], v[170:173], v[90:93], v[18:21]
	v_mfma_f32_16x16x32_bf16 v[14:17], v[178:181], v[90:93], v[14:17]
	v_mfma_f32_16x16x32_bf16 v[66:69], v[174:177], v[194:197], v[66:69]
	v_mfma_f32_16x16x32_bf16 v[62:65], v[182:185], v[194:197], v[62:65]
	v_mfma_f32_16x16x32_bf16 v[50:53], v[174:177], v[186:189], v[50:53]
	v_mfma_f32_16x16x32_bf16 v[46:49], v[182:185], v[186:189], v[46:49]
	v_mfma_f32_16x16x32_bf16 v[34:37], v[174:177], v[126:129], v[34:37]
	v_mfma_f32_16x16x32_bf16 v[30:33], v[182:185], v[126:129], v[30:33]
	v_mfma_f32_16x16x32_bf16 v[18:21], v[174:177], v[106:109], v[18:21]
	v_mfma_f32_16x16x32_bf16 v[14:17], v[182:185], v[106:109], v[14:17]
	v_mfma_f32_16x16x32_bf16 v[58:61], v[146:149], v[190:193], v[58:61]
	v_mfma_f32_16x16x32_bf16 v[54:57], v[162:165], v[190:193], v[54:57]
	v_mfma_f32_16x16x32_bf16 v[42:45], v[146:149], v[134:137], v[42:45]
	v_mfma_f32_16x16x32_bf16 v[38:41], v[162:165], v[134:137], v[38:41]
	v_mfma_f32_16x16x32_bf16 v[26:29], v[146:149], v[114:117], v[26:29]
	v_mfma_f32_16x16x32_bf16 v[22:25], v[162:165], v[114:117], v[22:25]
	v_mfma_f32_16x16x32_bf16 v[10:13], v[146:149], v[90:93], v[10:13]
	v_mfma_f32_16x16x32_bf16 v[6:9], v[162:165], v[90:93], v[6:9]
	v_mfma_f32_16x16x32_bf16 v[58:61], v[158:161], v[194:197], v[58:61]
	v_mfma_f32_16x16x32_bf16 v[54:57], v[166:169], v[194:197], v[54:57]
	v_mfma_f32_16x16x32_bf16 v[42:45], v[158:161], v[186:189], v[42:45]
	v_mfma_f32_16x16x32_bf16 v[38:41], v[166:169], v[186:189], v[38:41]
	v_mfma_f32_16x16x32_bf16 v[26:29], v[158:161], v[126:129], v[26:29]
	v_mfma_f32_16x16x32_bf16 v[22:25], v[166:169], v[126:129], v[22:25]
	v_mfma_f32_16x16x32_bf16 v[10:13], v[158:161], v[106:109], v[10:13]
	v_mfma_f32_16x16x32_bf16 v[6:9], v[166:169], v[106:109], v[6:9]
	s_barrier
	s_add_u32 s82, s82, 0x100
	s_addc_u32 s83, s83, 0
	s_add_u32 s6, s6, 0x100
	s_addc_u32 s7, s7, 0
	s_cmp_ge_i32 s84, s67
	s_cbranch_scc1 .LBB0_1025
.LBB0_1015:
	v_add_u32_e32 v90, 0x10000, v243
	ds_read_b128 v[170:173], v90
	ds_read_b128 v[174:177], v90 offset:1024
	ds_read_b128 v[178:181], v90 offset:2048
	ds_read_b128 v[182:185], v90 offset:3072
	v_add_u32_e32 v90, 0x14000, v243
	ds_read_b128 v[146:149], v90
	ds_read_b128 v[158:161], v90 offset:1024
	ds_read_b128 v[162:165], v90 offset:2048
	ds_read_b128 v[166:169], v90 offset:3072
	s_cmp_lg_u32 s74, s84
	s_cselect_b64 s[42:43], -1, 0
	s_add_u32 s40, s6, 0xfff00080
	s_addc_u32 s41, s7, -1
	s_and_b64 s[8:9], s[42:43], exec
	s_cselect_b32 s41, s41, s29
	s_cselect_b32 s40, s40, s31
	s_cselect_b32 s9, s83, s80
	s_cselect_b32 s8, s82, s81
	v_lshl_add_u64 v[90:91], s[6:7], 0, v[222:223]
	s_add_i32 m0, s52, 0xc000
	ds_read_b128 v[134:137], v244
	ds_read_b128 v[186:189], v244 offset:1024
	ds_read_b128 v[190:193], v244 offset:2048
	ds_read_b128 v[194:197], v244 offset:3072
	ds_read_b128 v[198:201], v244 offset:4096
	ds_read_b128 v[202:205], v244 offset:5120
	ds_read_b128 v[206:209], v244 offset:6144
	ds_read_b128 v[210:213], v244 offset:7168
	global_load_lds_dwordx4 v[90:91], off
	v_lshl_add_u64 v[90:91], s[6:7], 0, v[224:225]
	s_add_i32 m0, s52, 0xe000
	s_nop 0
	global_load_lds_dwordx4 v[90:91], off
	s_waitcnt vmcnt(8)
	s_waitcnt lgkmcnt(0)
	s_barrier
	s_waitcnt lgkmcnt(0)
	v_mfma_f32_16x16x32_bf16 v[90:93], v[170:173], v[134:137], v[150:153]
	v_mfma_f32_16x16x32_bf16 v[106:109], v[178:181], v[134:137], v[154:157]
	v_mfma_f32_16x16x32_bf16 v[114:117], v[170:173], v[190:193], v[130:133]
	v_mfma_f32_16x16x32_bf16 v[122:125], v[178:181], v[190:193], v[122:125]
	v_mfma_f32_16x16x32_bf16 v[102:105], v[170:173], v[198:201], v[102:105]
	v_mfma_f32_16x16x32_bf16 v[98:101], v[178:181], v[198:201], v[98:101]
	v_mfma_f32_16x16x32_bf16 v[82:85], v[170:173], v[206:209], v[82:85]
	v_mfma_f32_16x16x32_bf16 v[78:81], v[178:181], v[206:209], v[78:81]
	v_mfma_f32_16x16x32_bf16 v[90:93], v[174:177], v[186:189], v[90:93]
	v_mfma_f32_16x16x32_bf16 v[106:109], v[182:185], v[186:189], v[106:109]
	v_mfma_f32_16x16x32_bf16 v[114:117], v[174:177], v[194:197], v[114:117]
	v_mfma_f32_16x16x32_bf16 v[122:125], v[182:185], v[194:197], v[122:125]
	v_mfma_f32_16x16x32_bf16 v[102:105], v[174:177], v[202:205], v[102:105]
	v_mfma_f32_16x16x32_bf16 v[98:101], v[182:185], v[202:205], v[98:101]
	v_mfma_f32_16x16x32_bf16 v[82:85], v[174:177], v[210:213], v[82:85]
	v_mfma_f32_16x16x32_bf16 v[78:81], v[182:185], v[210:213], v[78:81]
	v_mfma_f32_16x16x32_bf16 v[126:129], v[146:149], v[134:137], v[142:145]
	v_mfma_f32_16x16x32_bf16 v[130:133], v[162:165], v[134:137], v[138:141]
	v_mfma_f32_16x16x32_bf16 v[118:121], v[146:149], v[190:193], v[118:121]
	v_mfma_f32_16x16x32_bf16 v[110:113], v[162:165], v[190:193], v[110:113]
	v_mfma_f32_16x16x32_bf16 v[94:97], v[146:149], v[198:201], v[94:97]
	v_mfma_f32_16x16x32_bf16 v[86:89], v[162:165], v[198:201], v[86:89]
	v_mfma_f32_16x16x32_bf16 v[74:77], v[146:149], v[206:209], v[74:77]
	v_mfma_f32_16x16x32_bf16 v[70:73], v[162:165], v[206:209], v[70:73]
	v_mfma_f32_16x16x32_bf16 v[126:129], v[158:161], v[186:189], v[126:129]
	v_mfma_f32_16x16x32_bf16 v[134:137], v[166:169], v[186:189], v[130:133]
	v_mfma_f32_16x16x32_bf16 v[118:121], v[158:161], v[194:197], v[118:121]
	v_mfma_f32_16x16x32_bf16 v[110:113], v[166:169], v[194:197], v[110:113]
	v_mfma_f32_16x16x32_bf16 v[94:97], v[158:161], v[202:205], v[94:97]
	v_mfma_f32_16x16x32_bf16 v[86:89], v[166:169], v[202:205], v[86:89]
	v_mfma_f32_16x16x32_bf16 v[74:77], v[158:161], v[210:213], v[74:77]
	v_mfma_f32_16x16x32_bf16 v[70:73], v[166:169], v[210:213], v[70:73]
	s_barrier
	ds_read_b128 v[190:193], v244 offset:16384
	ds_read_b128 v[194:197], v244 offset:17408
	ds_read_b128 v[154:157], v244 offset:18432
	ds_read_b128 v[186:189], v244 offset:19456
	ds_read_b128 v[142:145], v244 offset:20480
	ds_read_b128 v[150:153], v244 offset:21504
	ds_read_b128 v[130:133], v244 offset:22528
	ds_read_b128 v[138:141], v244 offset:23552
	s_or_b64 s[42:43], s[36:37], s[42:43]
	s_xor_b64 s[44:45], s[42:43], -1
	s_mov_b64 s[46:47], -1
	s_and_b64 vcc, exec, s[44:45]
	s_cbranch_vccz .LBB0_1017
	s_waitcnt vmcnt(2)
	s_mov_b64 s[46:47], 0

.LBB0_1019:
	s_waitcnt lgkmcnt(0)
	s_barrier
	s_waitcnt lgkmcnt(0)
	v_mfma_f32_16x16x32_bf16 v[66:69], v[170:173], v[190:193], v[66:69]
	v_mfma_f32_16x16x32_bf16 v[62:65], v[178:181], v[190:193], v[62:65]
	v_mfma_f32_16x16x32_bf16 v[50:53], v[170:173], v[154:157], v[50:53]
	v_mfma_f32_16x16x32_bf16 v[46:49], v[178:181], v[154:157], v[46:49]
	v_mfma_f32_16x16x32_bf16 v[34:37], v[170:173], v[142:145], v[34:37]
	v_mfma_f32_16x16x32_bf16 v[30:33], v[178:181], v[142:145], v[30:33]
	v_mfma_f32_16x16x32_bf16 v[18:21], v[170:173], v[130:133], v[18:21]
	v_mfma_f32_16x16x32_bf16 v[14:17], v[178:181], v[130:133], v[14:17]
	v_mfma_f32_16x16x32_bf16 v[66:69], v[174:177], v[194:197], v[66:69]
	v_mfma_f32_16x16x32_bf16 v[62:65], v[182:185], v[194:197], v[62:65]
	v_mfma_f32_16x16x32_bf16 v[50:53], v[174:177], v[186:189], v[50:53]
	v_mfma_f32_16x16x32_bf16 v[46:49], v[182:185], v[186:189], v[46:49]
	v_mfma_f32_16x16x32_bf16 v[34:37], v[174:177], v[150:153], v[34:37]
	v_mfma_f32_16x16x32_bf16 v[30:33], v[182:185], v[150:153], v[30:33]
	v_mfma_f32_16x16x32_bf16 v[18:21], v[174:177], v[138:141], v[18:21]
	v_mfma_f32_16x16x32_bf16 v[14:17], v[182:185], v[138:141], v[14:17]
	v_mfma_f32_16x16x32_bf16 v[58:61], v[146:149], v[190:193], v[58:61]
	v_mfma_f32_16x16x32_bf16 v[54:57], v[162:165], v[190:193], v[54:57]
	v_mfma_f32_16x16x32_bf16 v[42:45], v[146:149], v[154:157], v[42:45]
	v_mfma_f32_16x16x32_bf16 v[38:41], v[162:165], v[154:157], v[38:41]
	v_mfma_f32_16x16x32_bf16 v[26:29], v[146:149], v[142:145], v[26:29]
	v_mfma_f32_16x16x32_bf16 v[22:25], v[162:165], v[142:145], v[22:25]
	v_mfma_f32_16x16x32_bf16 v[10:13], v[146:149], v[130:133], v[10:13]
	v_mfma_f32_16x16x32_bf16 v[6:9], v[162:165], v[130:133], v[6:9]
	v_mfma_f32_16x16x32_bf16 v[58:61], v[158:161], v[194:197], v[58:61]
	v_mfma_f32_16x16x32_bf16 v[54:57], v[166:169], v[194:197], v[54:57]
	v_mfma_f32_16x16x32_bf16 v[42:45], v[158:161], v[186:189], v[42:45]
	v_mfma_f32_16x16x32_bf16 v[38:41], v[166:169], v[186:189], v[38:41]
	v_mfma_f32_16x16x32_bf16 v[26:29], v[158:161], v[150:153], v[26:29]
	v_mfma_f32_16x16x32_bf16 v[22:25], v[166:169], v[150:153], v[22:25]
	v_mfma_f32_16x16x32_bf16 v[10:13], v[158:161], v[138:141], v[10:13]
	v_mfma_f32_16x16x32_bf16 v[6:9], v[166:169], v[138:141], v[6:9]
	s_barrier
	v_add_u32_e32 v130, 0x18000, v243
	ds_read_b128 v[170:173], v130
	ds_read_b128 v[174:177], v130 offset:1024
	ds_read_b128 v[178:181], v130 offset:2048
	ds_read_b128 v[182:185], v130 offset:3072
	v_add_u32_e32 v130, 0x1c000, v243
	ds_read_b128 v[146:149], v130
	ds_read_b128 v[158:161], v130 offset:1024
	ds_read_b128 v[162:165], v130 offset:2048
	ds_read_b128 v[166:169], v130 offset:3072
	ds_read_b128 v[138:141], v244 offset:32768
	ds_read_b128 v[210:213], v244 offset:33792
	ds_read_b128 v[202:205], v244 offset:34816
	ds_read_b128 v[206:209], v244 offset:35840
	ds_read_b128 v[194:197], v244 offset:36864
	ds_read_b128 v[198:201], v244 offset:37888
	ds_read_b128 v[186:189], v244 offset:38912
	ds_read_b128 v[190:193], v244 offset:39936
	s_mov_b64 s[46:47], -1
	s_and_b64 vcc, exec, s[44:45]
	s_cbranch_vccz .LBB0_1021
	s_waitcnt vmcnt(0)
	s_mov_b64 s[46:47], 0

.LBB0_1023:
	s_waitcnt lgkmcnt(0)
	s_barrier
	s_waitcnt lgkmcnt(0)
	v_mfma_f32_16x16x32_bf16 v[90:93], v[170:173], v[138:141], v[90:93]
	v_mfma_f32_16x16x32_bf16 v[150:153], v[174:177], v[210:213], v[90:93]
	v_mfma_f32_16x16x32_bf16 v[90:93], v[178:181], v[138:141], v[106:109]
	v_mfma_f32_16x16x32_bf16 v[154:157], v[182:185], v[210:213], v[90:93]
	v_mfma_f32_16x16x32_bf16 v[90:93], v[170:173], v[202:205], v[114:117]
	v_mfma_f32_16x16x32_bf16 v[130:133], v[174:177], v[206:209], v[90:93]
	v_mfma_f32_16x16x32_bf16 v[90:93], v[178:181], v[202:205], v[122:125]
	v_mfma_f32_16x16x32_bf16 v[122:125], v[182:185], v[206:209], v[90:93]
	v_mfma_f32_16x16x32_bf16 v[90:93], v[170:173], v[194:197], v[102:105]
	v_mfma_f32_16x16x32_bf16 v[102:105], v[174:177], v[198:201], v[90:93]
	v_mfma_f32_16x16x32_bf16 v[90:93], v[178:181], v[194:197], v[98:101]
	v_mfma_f32_16x16x32_bf16 v[82:85], v[170:173], v[186:189], v[82:85]
	v_mfma_f32_16x16x32_bf16 v[78:81], v[178:181], v[186:189], v[78:81]
	v_mfma_f32_16x16x32_bf16 v[98:101], v[182:185], v[198:201], v[90:93]
	v_mfma_f32_16x16x32_bf16 v[82:85], v[174:177], v[190:193], v[82:85]
	v_mfma_f32_16x16x32_bf16 v[78:81], v[182:185], v[190:193], v[78:81]
	v_mfma_f32_16x16x32_bf16 v[90:93], v[146:149], v[138:141], v[126:129]
	v_mfma_f32_16x16x32_bf16 v[142:145], v[158:161], v[210:213], v[90:93]
	v_mfma_f32_16x16x32_bf16 v[90:93], v[162:165], v[138:141], v[134:137]
	v_mfma_f32_16x16x32_bf16 v[138:141], v[166:169], v[210:213], v[90:93]
	v_mfma_f32_16x16x32_bf16 v[90:93], v[146:149], v[202:205], v[118:121]
	v_mfma_f32_16x16x32_bf16 v[118:121], v[158:161], v[206:209], v[90:93]
	v_mfma_f32_16x16x32_bf16 v[90:93], v[162:165], v[202:205], v[110:113]
	v_mfma_f32_16x16x32_bf16 v[110:113], v[166:169], v[206:209], v[90:93]
	v_mfma_f32_16x16x32_bf16 v[90:93], v[146:149], v[194:197], v[94:97]
	v_mfma_f32_16x16x32_bf16 v[86:89], v[162:165], v[194:197], v[86:89]
	v_mfma_f32_16x16x32_bf16 v[74:77], v[146:149], v[186:189], v[74:77]
	v_mfma_f32_16x16x32_bf16 v[70:73], v[162:165], v[186:189], v[70:73]
	v_mfma_f32_16x16x32_bf16 v[94:97], v[158:161], v[198:201], v[90:93]
	v_mfma_f32_16x16x32_bf16 v[86:89], v[166:169], v[198:201], v[86:89]
	v_mfma_f32_16x16x32_bf16 v[74:77], v[158:161], v[190:193], v[74:77]
	v_mfma_f32_16x16x32_bf16 v[70:73], v[166:169], v[190:193], v[70:73]
	s_barrier
	ds_read_b128 v[190:193], v244 offset:49152
	ds_read_b128 v[194:197], v244 offset:50176
	ds_read_b128 v[134:137], v244 offset:51200
	ds_read_b128 v[186:189], v244 offset:52224
	ds_read_b128 v[114:117], v244 offset:53248
	ds_read_b128 v[126:129], v244 offset:54272
	ds_read_b128 v[90:93], v244 offset:55296
	ds_read_b128 v[106:109], v244 offset:56320
	s_andn2_b64 vcc, exec, s[42:43]
	s_cbranch_vccnz .LBB0_1014
	s_mov_b32 m0, s60
	v_lshl_add_u64 v[198:199], v[232:233], 0, s[68:69]
	s_add_u32 s8, s8, 0x40080
	global_load_lds_dwordx4 v[198:199], off
	v_lshl_add_u64 v[198:199], v[230:231], 0, s[68:69]
	s_mov_b32 m0, s61
	s_addc_u32 s9, s9, 0
	global_load_lds_dwordx4 v[198:199], off
	v_lshl_add_u64 v[198:199], s[8:9], 0, v[216:217]
	s_mov_b32 m0, s64
	s_nop 0
	global_load_lds_dwordx4 v[198:199], off
	v_lshl_add_u64 v[198:199], s[8:9], 0, v[2:3]
	s_mov_b32 m0, s65
	s_nop 0
	global_load_lds_dwordx4 v[198:199], off
	v_lshl_add_u64 v[198:199], v[228:229], 0, s[68:69]
	s_mov_b32 m0, s62
	s_nop 0
	global_load_lds_dwordx4 v[198:199], off
	v_lshl_add_u64 v[198:199], v[226:227], 0, s[68:69]
	s_mov_b32 m0, s63
	s_nop 0
	global_load_lds_dwordx4 v[198:199], off
	s_waitcnt vmcnt(8)
	s_branch .LBB0_1014
